# v60 + LOAD segments: M0 wait state supplied by the address VALU op instead of s_nop 0 (170 nops removed), vmcnt+lgkmcnt waits merged
# speedup vs baseline: 1.0115x; 1.0106x over previous
.LBB0_297:
	s_add_u32 s47, s38, s46
	s_addc_u32 s66, s39, 0
	s_add_u32 s64, s47, 0x100
	s_addc_u32 s65, s66, 0
	s_and_b64 s[48:49], s[44:45], exec
	s_cselect_b32 s49, s70, s65
	s_cselect_b32 s48, s71, s64
	s_add_u32 s46, s36, s46
	s_addc_u32 s64, s37, 0
	s_add_u32 s46, s46, 0x100
	s_addc_u32 s64, s64, 0
	s_and_b64 s[44:45], s[44:45], exec
	s_cselect_b32 s65, s72, s64
	s_cselect_b32 s64, s73, s46
	s_add_u32 s68, s47, 0x10080
	ds_read_b128 v[150:153], v146
	ds_read_b128 v[154:157], v146 offset:1024
	ds_read_b128 v[158:161], v146 offset:2048
	ds_read_b128 v[162:165], v146 offset:3072
	ds_read_b128 v[166:169], v147
	ds_read_b128 v[170:173], v147 offset:1024
	ds_read_b128 v[174:177], v147 offset:2048
	ds_read_b128 v[178:181], v147 offset:3072
	s_addc_u32 s69, s66, 0
	s_add_i32 s83, s30, s2
	s_add_i32 m0, s16, 0xc000
	s_add_i32 s84, s16, 0xe000
	s_add_i32 s80, s83, 0x2000
	s_add_u32 s66, s64, 0x40000
	s_addc_u32 s67, s65, 0
	s_add_i32 s82, s31, s2
	s_add_i32 s81, s82, 0x2000
	s_add_i32 s79, 0, 0x18000
	s_add_i32 s78, 0, 0x1c000
	s_add_u32 s46, s48, 0x10000
	s_addc_u32 s47, s49, 0
	s_add_i32 s77, s79, s2
	s_add_i32 s75, s77, 0x2000
	s_add_u32 s44, s64, 0x40080
	s_addc_u32 s45, s65, 0
	s_add_i32 s76, s78, s2
	s_add_i32 s74, s76, 0x2000
	v_lshl_add_u64 v[202:203], s[68:69], 0, v[130:131]
	ds_read_b128 v[182:185], v148
	ds_read_b128 v[186:189], v148 offset:1024
	ds_read_b128 v[190:193], v148 offset:2048
	ds_read_b128 v[194:197], v148 offset:3072
	ds_read_b128 v[198:201], v148 offset:4096
	ds_read_b128 v[206:209], v148 offset:5120
	ds_read_b128 v[210:213], v148 offset:6144
	ds_read_b128 v[214:217], v148 offset:7168
	global_load_lds_dwordx4 v[202:203], off
	s_mov_b32 m0, s84
	v_lshl_add_u64 v[202:203], s[68:69], 0, v[132:133]
	global_load_lds_dwordx4 v[202:203], off
	s_waitcnt vmcnt(8) lgkmcnt(0)
	s_setprio 1
	s_barrier
	v_mfma_f32_16x16x32_bf16 v[126:129], v[150:153], v[182:185], v[126:129]
	v_mfma_f32_16x16x32_bf16 v[122:125], v[158:161], v[182:185], v[122:125]
	v_mfma_f32_16x16x32_bf16 v[118:121], v[150:153], v[190:193], v[118:121]
	v_mfma_f32_16x16x32_bf16 v[114:117], v[158:161], v[190:193], v[114:117]
	v_mfma_f32_16x16x32_bf16 v[102:105], v[150:153], v[198:201], v[102:105]
	v_mfma_f32_16x16x32_bf16 v[98:101], v[158:161], v[198:201], v[98:101]
	v_mfma_f32_16x16x32_bf16 v[86:89], v[150:153], v[210:213], v[86:89]
	v_mfma_f32_16x16x32_bf16 v[82:85], v[158:161], v[210:213], v[82:85]
	v_mfma_f32_16x16x32_bf16 v[126:129], v[154:157], v[186:189], v[126:129]
	v_mfma_f32_16x16x32_bf16 v[122:125], v[162:165], v[186:189], v[122:125]
	v_mfma_f32_16x16x32_bf16 v[118:121], v[154:157], v[194:197], v[118:121]
	v_mfma_f32_16x16x32_bf16 v[114:117], v[162:165], v[194:197], v[114:117]
	v_mfma_f32_16x16x32_bf16 v[102:105], v[154:157], v[206:209], v[102:105]
	v_mfma_f32_16x16x32_bf16 v[98:101], v[162:165], v[206:209], v[98:101]
	v_mfma_f32_16x16x32_bf16 v[86:89], v[154:157], v[214:217], v[86:89]
	v_mfma_f32_16x16x32_bf16 v[82:85], v[162:165], v[214:217], v[82:85]
	v_mfma_f32_16x16x32_bf16 v[110:113], v[166:169], v[182:185], v[110:113]
	v_mfma_f32_16x16x32_bf16 v[106:109], v[174:177], v[182:185], v[106:109]
	v_mfma_f32_16x16x32_bf16 v[94:97], v[166:169], v[190:193], v[94:97]
	v_mfma_f32_16x16x32_bf16 v[90:93], v[174:177], v[190:193], v[90:93]
	v_mfma_f32_16x16x32_bf16 v[78:81], v[166:169], v[198:201], v[78:81]
	v_mfma_f32_16x16x32_bf16 v[74:77], v[174:177], v[198:201], v[74:77]
	v_mfma_f32_16x16x32_bf16 v[70:73], v[166:169], v[210:213], v[70:73]
	v_mfma_f32_16x16x32_bf16 v[66:69], v[174:177], v[210:213], v[66:69]
	v_mfma_f32_16x16x32_bf16 v[110:113], v[170:173], v[186:189], v[110:113]
	v_mfma_f32_16x16x32_bf16 v[106:109], v[178:181], v[186:189], v[106:109]
	v_mfma_f32_16x16x32_bf16 v[94:97], v[170:173], v[194:197], v[94:97]
	v_mfma_f32_16x16x32_bf16 v[90:93], v[178:181], v[194:197], v[90:93]
	v_mfma_f32_16x16x32_bf16 v[78:81], v[170:173], v[206:209], v[78:81]
	v_mfma_f32_16x16x32_bf16 v[74:77], v[178:181], v[206:209], v[74:77]
	v_mfma_f32_16x16x32_bf16 v[70:73], v[170:173], v[214:217], v[70:73]
	v_mfma_f32_16x16x32_bf16 v[66:69], v[178:181], v[214:217], v[66:69]
	s_setprio 0
	s_barrier
	s_mov_b32 m0, s83
	v_lshl_add_u64 v[202:203], s[64:65], 0, v[136:137]
	ds_read_b128 v[182:185], v148 offset:16384
	ds_read_b128 v[186:189], v148 offset:17408
	ds_read_b128 v[190:193], v148 offset:18432
	ds_read_b128 v[194:197], v148 offset:19456
	ds_read_b128 v[198:201], v148 offset:20480
	ds_read_b128 v[206:209], v148 offset:21504
	ds_read_b128 v[210:213], v148 offset:22528
	ds_read_b128 v[214:217], v148 offset:23552
	global_load_lds_dwordx4 v[202:203], off
	v_lshl_add_u64 v[218:219], s[64:65], 0, v[134:135]
	s_mov_b32 m0, s80
	v_lshl_add_u64 v[220:221], s[66:67], 0, v[136:137]
	global_load_lds_dwordx4 v[218:219], off
	s_mov_b32 m0, s82
	v_lshl_add_u64 v[222:223], s[48:49], 0, v[132:133]
	global_load_lds_dwordx4 v[220:221], off
	s_mov_b32 m0, s81
	v_lshl_add_u64 v[220:221], s[66:67], 0, v[134:135]
	global_load_lds_dwordx4 v[220:221], off
	s_mov_b32 m0, s16
	v_lshl_add_u64 v[220:221], s[48:49], 0, v[130:131]
	global_load_lds_dwordx4 v[220:221], off
	s_mov_b32 m0, s17
	s_nop 0
	global_load_lds_dwordx4 v[222:223], off
	s_waitcnt vmcnt(8) lgkmcnt(0)
	s_setprio 1
	s_barrier
	v_mfma_f32_16x16x32_bf16 v[62:65], v[150:153], v[182:185], v[62:65]
	v_mfma_f32_16x16x32_bf16 v[58:61], v[158:161], v[182:185], v[58:61]
	v_mfma_f32_16x16x32_bf16 v[54:57], v[150:153], v[190:193], v[54:57]
	v_mfma_f32_16x16x32_bf16 v[50:53], v[158:161], v[190:193], v[50:53]
	v_mfma_f32_16x16x32_bf16 v[38:41], v[150:153], v[198:201], v[38:41]
	v_mfma_f32_16x16x32_bf16 v[34:37], v[158:161], v[198:201], v[34:37]
	v_mfma_f32_16x16x32_bf16 v[22:25], v[150:153], v[210:213], v[22:25]
	v_mfma_f32_16x16x32_bf16 v[18:21], v[158:161], v[210:213], v[18:21]
	v_mfma_f32_16x16x32_bf16 v[62:65], v[154:157], v[186:189], v[62:65]
	v_mfma_f32_16x16x32_bf16 v[58:61], v[162:165], v[186:189], v[58:61]
	v_mfma_f32_16x16x32_bf16 v[54:57], v[154:157], v[194:197], v[54:57]
	v_mfma_f32_16x16x32_bf16 v[50:53], v[162:165], v[194:197], v[50:53]
	v_mfma_f32_16x16x32_bf16 v[38:41], v[154:157], v[206:209], v[38:41]
	v_mfma_f32_16x16x32_bf16 v[34:37], v[162:165], v[206:209], v[34:37]
	v_mfma_f32_16x16x32_bf16 v[22:25], v[154:157], v[214:217], v[22:25]
	v_mfma_f32_16x16x32_bf16 v[18:21], v[162:165], v[214:217], v[18:21]
	v_mfma_f32_16x16x32_bf16 v[46:49], v[166:169], v[182:185], v[46:49]
	v_mfma_f32_16x16x32_bf16 v[42:45], v[174:177], v[182:185], v[42:45]
	v_mfma_f32_16x16x32_bf16 v[30:33], v[166:169], v[190:193], v[30:33]
	v_mfma_f32_16x16x32_bf16 v[26:29], v[174:177], v[190:193], v[26:29]
	v_mfma_f32_16x16x32_bf16 v[14:17], v[166:169], v[198:201], v[14:17]
	v_mfma_f32_16x16x32_bf16 v[10:13], v[174:177], v[198:201], v[10:13]
	v_mfma_f32_16x16x32_bf16 v[6:9], v[166:169], v[210:213], v[6:9]
	v_mfma_f32_16x16x32_bf16 v[2:5], v[174:177], v[210:213], v[2:5]
	v_mfma_f32_16x16x32_bf16 v[46:49], v[170:173], v[186:189], v[46:49]
	v_mfma_f32_16x16x32_bf16 v[42:45], v[178:181], v[186:189], v[42:45]
	v_mfma_f32_16x16x32_bf16 v[30:33], v[170:173], v[194:197], v[30:33]
	v_mfma_f32_16x16x32_bf16 v[26:29], v[178:181], v[194:197], v[26:29]
	v_mfma_f32_16x16x32_bf16 v[14:17], v[170:173], v[206:209], v[14:17]
	v_mfma_f32_16x16x32_bf16 v[10:13], v[178:181], v[206:209], v[10:13]
	v_mfma_f32_16x16x32_bf16 v[6:9], v[170:173], v[214:217], v[6:9]
	v_mfma_f32_16x16x32_bf16 v[2:5], v[178:181], v[214:217], v[2:5]
	s_setprio 0
	s_barrier
	v_add_u32_e32 v149, s79, v145
	ds_read_b128 v[150:153], v149
	ds_read_b128 v[154:157], v149 offset:1024
	ds_read_b128 v[158:161], v149 offset:2048
	ds_read_b128 v[162:165], v149 offset:3072
	v_add_u32_e32 v149, s78, v145
	ds_read_b128 v[166:169], v149
	ds_read_b128 v[170:173], v149 offset:1024
	ds_read_b128 v[174:177], v149 offset:2048
	ds_read_b128 v[178:181], v149 offset:3072
	s_mov_b32 m0, s18
	v_lshl_add_u64 v[224:225], s[46:47], 0, v[130:131]
	ds_read_b128 v[182:185], v148 offset:32768
	ds_read_b128 v[186:189], v148 offset:33792
	ds_read_b128 v[190:193], v148 offset:34816
	ds_read_b128 v[194:197], v148 offset:35840
	ds_read_b128 v[198:201], v148 offset:36864
	ds_read_b128 v[206:209], v148 offset:37888
	ds_read_b128 v[210:213], v148 offset:38912
	ds_read_b128 v[214:217], v148 offset:39936
	global_load_lds_dwordx4 v[224:225], off
	s_mov_b32 m0, s19
	v_lshl_add_u64 v[224:225], s[46:47], 0, v[132:133]
	global_load_lds_dwordx4 v[224:225], off
	s_waitcnt vmcnt(8) lgkmcnt(0)
	s_setprio 1
	s_barrier
	v_mfma_f32_16x16x32_bf16 v[126:129], v[150:153], v[182:185], v[126:129]
	v_mfma_f32_16x16x32_bf16 v[122:125], v[158:161], v[182:185], v[122:125]
	v_mfma_f32_16x16x32_bf16 v[118:121], v[150:153], v[190:193], v[118:121]
	v_mfma_f32_16x16x32_bf16 v[114:117], v[158:161], v[190:193], v[114:117]
	v_mfma_f32_16x16x32_bf16 v[102:105], v[150:153], v[198:201], v[102:105]
	v_mfma_f32_16x16x32_bf16 v[98:101], v[158:161], v[198:201], v[98:101]
	v_mfma_f32_16x16x32_bf16 v[86:89], v[150:153], v[210:213], v[86:89]
	v_mfma_f32_16x16x32_bf16 v[82:85], v[158:161], v[210:213], v[82:85]
	v_mfma_f32_16x16x32_bf16 v[126:129], v[154:157], v[186:189], v[126:129]
	v_mfma_f32_16x16x32_bf16 v[122:125], v[162:165], v[186:189], v[122:125]
	v_mfma_f32_16x16x32_bf16 v[118:121], v[154:157], v[194:197], v[118:121]
	v_mfma_f32_16x16x32_bf16 v[114:117], v[162:165], v[194:197], v[114:117]
	v_mfma_f32_16x16x32_bf16 v[102:105], v[154:157], v[206:209], v[102:105]
	v_mfma_f32_16x16x32_bf16 v[98:101], v[162:165], v[206:209], v[98:101]
	v_mfma_f32_16x16x32_bf16 v[86:89], v[154:157], v[214:217], v[86:89]
	v_mfma_f32_16x16x32_bf16 v[82:85], v[162:165], v[214:217], v[82:85]
	v_mfma_f32_16x16x32_bf16 v[110:113], v[166:169], v[182:185], v[110:113]
	v_mfma_f32_16x16x32_bf16 v[106:109], v[174:177], v[182:185], v[106:109]
	v_mfma_f32_16x16x32_bf16 v[94:97], v[166:169], v[190:193], v[94:97]
	v_mfma_f32_16x16x32_bf16 v[90:93], v[174:177], v[190:193], v[90:93]
	v_mfma_f32_16x16x32_bf16 v[78:81], v[166:169], v[198:201], v[78:81]
	v_mfma_f32_16x16x32_bf16 v[74:77], v[174:177], v[198:201], v[74:77]
	v_mfma_f32_16x16x32_bf16 v[70:73], v[166:169], v[210:213], v[70:73]
	v_mfma_f32_16x16x32_bf16 v[66:69], v[174:177], v[210:213], v[66:69]
	v_mfma_f32_16x16x32_bf16 v[110:113], v[170:173], v[186:189], v[110:113]
	v_mfma_f32_16x16x32_bf16 v[106:109], v[178:181], v[186:189], v[106:109]
	v_mfma_f32_16x16x32_bf16 v[94:97], v[170:173], v[194:197], v[94:97]
	v_mfma_f32_16x16x32_bf16 v[90:93], v[178:181], v[194:197], v[90:93]
	v_mfma_f32_16x16x32_bf16 v[78:81], v[170:173], v[206:209], v[78:81]
	v_mfma_f32_16x16x32_bf16 v[74:77], v[178:181], v[206:209], v[74:77]
	v_mfma_f32_16x16x32_bf16 v[70:73], v[170:173], v[214:217], v[70:73]
	v_mfma_f32_16x16x32_bf16 v[66:69], v[178:181], v[214:217], v[66:69]
	s_setprio 0
	s_barrier
	s_mov_b32 m0, s77
	v_lshl_add_u64 v[202:203], v[202:203], 0, s[8:9]
	ds_read_b128 v[182:185], v148 offset:49152
	ds_read_b128 v[186:189], v148 offset:50176
	ds_read_b128 v[190:193], v148 offset:51200
	ds_read_b128 v[194:197], v148 offset:52224
	ds_read_b128 v[198:201], v148 offset:53248
	ds_read_b128 v[206:209], v148 offset:54272
	ds_read_b128 v[210:213], v148 offset:55296
	ds_read_b128 v[214:217], v148 offset:56320
	global_load_lds_dwordx4 v[202:203], off
	s_mov_b32 m0, s75
	v_lshl_add_u64 v[202:203], v[218:219], 0, s[8:9]
	global_load_lds_dwordx4 v[202:203], off
	s_mov_b32 m0, s76
	v_lshl_add_u64 v[202:203], s[44:45], 0, v[136:137]
	global_load_lds_dwordx4 v[202:203], off
	s_mov_b32 m0, s74
	v_lshl_add_u64 v[202:203], s[44:45], 0, v[134:135]
	global_load_lds_dwordx4 v[202:203], off
	s_mov_b32 m0, s28
	v_lshl_add_u64 v[202:203], v[220:221], 0, s[8:9]
	global_load_lds_dwordx4 v[202:203], off
	s_mov_b32 m0, s29
	v_lshl_add_u64 v[202:203], v[222:223], 0, s[8:9]
	global_load_lds_dwordx4 v[202:203], off
	s_waitcnt vmcnt(8) lgkmcnt(0)
	s_setprio 1
	s_barrier
	v_mfma_f32_16x16x32_bf16 v[62:65], v[150:153], v[182:185], v[62:65]
	v_mfma_f32_16x16x32_bf16 v[58:61], v[158:161], v[182:185], v[58:61]
	v_mfma_f32_16x16x32_bf16 v[54:57], v[150:153], v[190:193], v[54:57]
	v_mfma_f32_16x16x32_bf16 v[50:53], v[158:161], v[190:193], v[50:53]
	v_mfma_f32_16x16x32_bf16 v[38:41], v[150:153], v[198:201], v[38:41]
	v_mfma_f32_16x16x32_bf16 v[34:37], v[158:161], v[198:201], v[34:37]
	v_mfma_f32_16x16x32_bf16 v[22:25], v[150:153], v[210:213], v[22:25]
	v_mfma_f32_16x16x32_bf16 v[18:21], v[158:161], v[210:213], v[18:21]
	v_mfma_f32_16x16x32_bf16 v[62:65], v[154:157], v[186:189], v[62:65]
	v_mfma_f32_16x16x32_bf16 v[58:61], v[162:165], v[186:189], v[58:61]
	v_mfma_f32_16x16x32_bf16 v[54:57], v[154:157], v[194:197], v[54:57]
	v_mfma_f32_16x16x32_bf16 v[50:53], v[162:165], v[194:197], v[50:53]
	v_mfma_f32_16x16x32_bf16 v[38:41], v[154:157], v[206:209], v[38:41]
	v_mfma_f32_16x16x32_bf16 v[34:37], v[162:165], v[206:209], v[34:37]
	v_mfma_f32_16x16x32_bf16 v[22:25], v[154:157], v[214:217], v[22:25]
	v_mfma_f32_16x16x32_bf16 v[18:21], v[162:165], v[214:217], v[18:21]
	v_mfma_f32_16x16x32_bf16 v[46:49], v[166:169], v[182:185], v[46:49]
	v_mfma_f32_16x16x32_bf16 v[42:45], v[174:177], v[182:185], v[42:45]
	v_mfma_f32_16x16x32_bf16 v[30:33], v[166:169], v[190:193], v[30:33]
	v_mfma_f32_16x16x32_bf16 v[26:29], v[174:177], v[190:193], v[26:29]
	v_mfma_f32_16x16x32_bf16 v[14:17], v[166:169], v[198:201], v[14:17]
	v_mfma_f32_16x16x32_bf16 v[10:13], v[174:177], v[198:201], v[10:13]
	v_mfma_f32_16x16x32_bf16 v[6:9], v[166:169], v[210:213], v[6:9]
	v_mfma_f32_16x16x32_bf16 v[2:5], v[174:177], v[210:213], v[2:5]
	v_mfma_f32_16x16x32_bf16 v[46:49], v[170:173], v[186:189], v[46:49]
	v_mfma_f32_16x16x32_bf16 v[42:45], v[178:181], v[186:189], v[42:45]
	v_mfma_f32_16x16x32_bf16 v[30:33], v[170:173], v[194:197], v[30:33]
	v_mfma_f32_16x16x32_bf16 v[26:29], v[178:181], v[194:197], v[26:29]
	v_mfma_f32_16x16x32_bf16 v[14:17], v[170:173], v[206:209], v[14:17]
	v_mfma_f32_16x16x32_bf16 v[10:13], v[178:181], v[206:209], v[10:13]
	v_mfma_f32_16x16x32_bf16 v[6:9], v[170:173], v[214:217], v[6:9]
	v_mfma_f32_16x16x32_bf16 v[2:5], v[178:181], v[214:217], v[2:5]
	s_setprio 0
	s_barrier
	s_movk_i32 s46, 0x100
	s_andn2_b64 vcc, exec, s[42:43]
	s_mov_b64 s[44:45], -1
	s_mov_b64 s[42:43], 0
	s_cbranch_vccz .LBB0_297
	s_and_b64 vcc, exec, s[10:11]
	s_cbranch_vccz .LBB0_300
	s_barrier

.LBB0_313:
	s_add_u32 s49, s38, s48
	s_addc_u32 s68, s39, 0
	s_add_u32 s66, s49, 0x100
	s_addc_u32 s67, s68, 0
	s_and_b64 s[64:65], s[46:47], exec
	s_cselect_b32 s65, s43, s67
	s_cselect_b32 s64, s75, s66
	s_add_u32 s48, s36, s48
	s_addc_u32 s66, s37, 0
	s_add_u32 s48, s48, 0x100
	s_addc_u32 s66, s66, 0
	s_and_b64 s[46:47], s[46:47], exec
	s_cselect_b32 s67, s76, s66
	s_cselect_b32 s66, s77, s48
	s_add_u32 s70, s49, 0x10080
	ds_read_b128 v[144:147], v140
	ds_read_b128 v[148:151], v140 offset:1024
	ds_read_b128 v[152:155], v140 offset:2048
	ds_read_b128 v[156:159], v140 offset:3072
	ds_read_b128 v[160:163], v141
	ds_read_b128 v[164:167], v141 offset:1024
	ds_read_b128 v[168:171], v141 offset:2048
	ds_read_b128 v[172:175], v141 offset:3072
	s_addc_u32 s71, s68, 0
	s_add_i32 s87, s33, s2
	s_add_i32 m0, s16, 0xc000
	s_add_i32 s88, s16, 0xe000
	s_add_i32 s84, s87, 0x2000
	s_add_u32 s68, s66, 0x1000
	s_addc_u32 s69, s67, 0
	s_add_i32 s86, s34, s2
	s_add_i32 s85, s86, 0x2000
	s_add_i32 s83, 0, 0x18000
	s_add_i32 s82, 0, 0x1c000
	s_add_u32 s48, s64, 0x10000
	s_addc_u32 s49, s65, 0
	s_add_i32 s81, s83, s2
	s_add_i32 s79, s81, 0x2000
	s_add_u32 s46, s66, 0x1080
	s_addc_u32 s47, s67, 0
	s_add_i32 s80, s82, s2
	s_add_i32 s78, s80, 0x2000
	v_lshl_add_u64 v[210:211], s[70:71], 0, v[130:131]
	ds_read_b128 v[176:179], v142
	ds_read_b128 v[180:183], v142 offset:1024
	ds_read_b128 v[184:187], v142 offset:2048
	ds_read_b128 v[188:191], v142 offset:3072
	ds_read_b128 v[192:195], v142 offset:4096
	ds_read_b128 v[196:199], v142 offset:5120
	ds_read_b128 v[200:203], v142 offset:6144
	ds_read_b128 v[206:209], v142 offset:7168
	global_load_lds_dwordx4 v[210:211], off
	s_mov_b32 m0, s88
	v_lshl_add_u64 v[210:211], s[70:71], 0, v[132:133]
	global_load_lds_dwordx4 v[210:211], off
	s_waitcnt vmcnt(8) lgkmcnt(0)
	s_setprio 1
	s_barrier
	v_mfma_f32_16x16x32_bf16 v[126:129], v[144:147], v[176:179], v[126:129]
	v_mfma_f32_16x16x32_bf16 v[122:125], v[152:155], v[176:179], v[122:125]
	v_mfma_f32_16x16x32_bf16 v[118:121], v[144:147], v[184:187], v[118:121]
	v_mfma_f32_16x16x32_bf16 v[114:117], v[152:155], v[184:187], v[114:117]
	v_mfma_f32_16x16x32_bf16 v[102:105], v[144:147], v[192:195], v[102:105]
	v_mfma_f32_16x16x32_bf16 v[98:101], v[152:155], v[192:195], v[98:101]
	v_mfma_f32_16x16x32_bf16 v[86:89], v[144:147], v[200:203], v[86:89]
	v_mfma_f32_16x16x32_bf16 v[82:85], v[152:155], v[200:203], v[82:85]
	v_mfma_f32_16x16x32_bf16 v[126:129], v[148:151], v[180:183], v[126:129]
	v_mfma_f32_16x16x32_bf16 v[122:125], v[156:159], v[180:183], v[122:125]
	v_mfma_f32_16x16x32_bf16 v[118:121], v[148:151], v[188:191], v[118:121]
	v_mfma_f32_16x16x32_bf16 v[114:117], v[156:159], v[188:191], v[114:117]
	v_mfma_f32_16x16x32_bf16 v[102:105], v[148:151], v[196:199], v[102:105]
	v_mfma_f32_16x16x32_bf16 v[98:101], v[156:159], v[196:199], v[98:101]
	v_mfma_f32_16x16x32_bf16 v[86:89], v[148:151], v[206:209], v[86:89]
	v_mfma_f32_16x16x32_bf16 v[82:85], v[156:159], v[206:209], v[82:85]
	v_mfma_f32_16x16x32_bf16 v[110:113], v[160:163], v[176:179], v[110:113]
	v_mfma_f32_16x16x32_bf16 v[106:109], v[168:171], v[176:179], v[106:109]
	v_mfma_f32_16x16x32_bf16 v[94:97], v[160:163], v[184:187], v[94:97]
	v_mfma_f32_16x16x32_bf16 v[90:93], v[168:171], v[184:187], v[90:93]
	v_mfma_f32_16x16x32_bf16 v[78:81], v[160:163], v[192:195], v[78:81]
	v_mfma_f32_16x16x32_bf16 v[74:77], v[168:171], v[192:195], v[74:77]
	v_mfma_f32_16x16x32_bf16 v[70:73], v[160:163], v[200:203], v[70:73]
	v_mfma_f32_16x16x32_bf16 v[66:69], v[168:171], v[200:203], v[66:69]
	v_mfma_f32_16x16x32_bf16 v[110:113], v[164:167], v[180:183], v[110:113]
	v_mfma_f32_16x16x32_bf16 v[106:109], v[172:175], v[180:183], v[106:109]
	v_mfma_f32_16x16x32_bf16 v[94:97], v[164:167], v[188:191], v[94:97]
	v_mfma_f32_16x16x32_bf16 v[90:93], v[172:175], v[188:191], v[90:93]
	v_mfma_f32_16x16x32_bf16 v[78:81], v[164:167], v[196:199], v[78:81]
	v_mfma_f32_16x16x32_bf16 v[74:77], v[172:175], v[196:199], v[74:77]
	v_mfma_f32_16x16x32_bf16 v[70:73], v[164:167], v[206:209], v[70:73]
	v_mfma_f32_16x16x32_bf16 v[66:69], v[172:175], v[206:209], v[66:69]
	s_setprio 0
	s_barrier
	s_mov_b32 m0, s87
	v_lshl_add_u64 v[210:211], s[66:67], 0, v[136:137]
	ds_read_b128 v[176:179], v142 offset:16384
	ds_read_b128 v[180:183], v142 offset:17408
	ds_read_b128 v[184:187], v142 offset:18432
	ds_read_b128 v[188:191], v142 offset:19456
	ds_read_b128 v[192:195], v142 offset:20480
	ds_read_b128 v[196:199], v142 offset:21504
	ds_read_b128 v[200:203], v142 offset:22528
	ds_read_b128 v[206:209], v142 offset:23552
	global_load_lds_dwordx4 v[210:211], off
	v_lshl_add_u64 v[212:213], s[66:67], 0, v[134:135]
	s_mov_b32 m0, s84
	v_lshl_add_u64 v[214:215], s[68:69], 0, v[136:137]
	global_load_lds_dwordx4 v[212:213], off
	s_mov_b32 m0, s86
	v_lshl_add_u64 v[216:217], s[64:65], 0, v[132:133]
	global_load_lds_dwordx4 v[214:215], off
	s_mov_b32 m0, s85
	v_lshl_add_u64 v[214:215], s[68:69], 0, v[134:135]
	global_load_lds_dwordx4 v[214:215], off
	s_mov_b32 m0, s16
	v_lshl_add_u64 v[214:215], s[64:65], 0, v[130:131]
	global_load_lds_dwordx4 v[214:215], off
	s_mov_b32 m0, s17
	s_nop 0
	global_load_lds_dwordx4 v[216:217], off
	s_waitcnt vmcnt(8) lgkmcnt(0)
	s_setprio 1
	s_barrier
	v_mfma_f32_16x16x32_bf16 v[62:65], v[144:147], v[176:179], v[62:65]
	v_mfma_f32_16x16x32_bf16 v[58:61], v[152:155], v[176:179], v[58:61]
	v_mfma_f32_16x16x32_bf16 v[54:57], v[144:147], v[184:187], v[54:57]
	v_mfma_f32_16x16x32_bf16 v[50:53], v[152:155], v[184:187], v[50:53]
	v_mfma_f32_16x16x32_bf16 v[38:41], v[144:147], v[192:195], v[38:41]
	v_mfma_f32_16x16x32_bf16 v[34:37], v[152:155], v[192:195], v[34:37]
	v_mfma_f32_16x16x32_bf16 v[22:25], v[144:147], v[200:203], v[22:25]
	v_mfma_f32_16x16x32_bf16 v[18:21], v[152:155], v[200:203], v[18:21]
	v_mfma_f32_16x16x32_bf16 v[62:65], v[148:151], v[180:183], v[62:65]
	v_mfma_f32_16x16x32_bf16 v[58:61], v[156:159], v[180:183], v[58:61]
	v_mfma_f32_16x16x32_bf16 v[54:57], v[148:151], v[188:191], v[54:57]
	v_mfma_f32_16x16x32_bf16 v[50:53], v[156:159], v[188:191], v[50:53]
	v_mfma_f32_16x16x32_bf16 v[38:41], v[148:151], v[196:199], v[38:41]
	v_mfma_f32_16x16x32_bf16 v[34:37], v[156:159], v[196:199], v[34:37]
	v_mfma_f32_16x16x32_bf16 v[22:25], v[148:151], v[206:209], v[22:25]
	v_mfma_f32_16x16x32_bf16 v[18:21], v[156:159], v[206:209], v[18:21]
	v_mfma_f32_16x16x32_bf16 v[46:49], v[160:163], v[176:179], v[46:49]
	v_mfma_f32_16x16x32_bf16 v[42:45], v[168:171], v[176:179], v[42:45]
	v_mfma_f32_16x16x32_bf16 v[30:33], v[160:163], v[184:187], v[30:33]
	v_mfma_f32_16x16x32_bf16 v[26:29], v[168:171], v[184:187], v[26:29]
	v_mfma_f32_16x16x32_bf16 v[14:17], v[160:163], v[192:195], v[14:17]
	v_mfma_f32_16x16x32_bf16 v[10:13], v[168:171], v[192:195], v[10:13]
	v_mfma_f32_16x16x32_bf16 v[6:9], v[160:163], v[200:203], v[6:9]
	v_mfma_f32_16x16x32_bf16 v[2:5], v[168:171], v[200:203], v[2:5]
	v_mfma_f32_16x16x32_bf16 v[46:49], v[164:167], v[180:183], v[46:49]
	v_mfma_f32_16x16x32_bf16 v[42:45], v[172:175], v[180:183], v[42:45]
	v_mfma_f32_16x16x32_bf16 v[30:33], v[164:167], v[188:191], v[30:33]
	v_mfma_f32_16x16x32_bf16 v[26:29], v[172:175], v[188:191], v[26:29]
	v_mfma_f32_16x16x32_bf16 v[14:17], v[164:167], v[196:199], v[14:17]
	v_mfma_f32_16x16x32_bf16 v[10:13], v[172:175], v[196:199], v[10:13]
	v_mfma_f32_16x16x32_bf16 v[6:9], v[164:167], v[206:209], v[6:9]
	v_mfma_f32_16x16x32_bf16 v[2:5], v[172:175], v[206:209], v[2:5]
	s_setprio 0
	s_barrier
	v_add_u32_e32 v143, s83, v139
	ds_read_b128 v[144:147], v143
	ds_read_b128 v[148:151], v143 offset:1024
	ds_read_b128 v[152:155], v143 offset:2048
	ds_read_b128 v[156:159], v143 offset:3072
	v_add_u32_e32 v143, s82, v139
	ds_read_b128 v[160:163], v143
	ds_read_b128 v[164:167], v143 offset:1024
	ds_read_b128 v[168:171], v143 offset:2048
	ds_read_b128 v[172:175], v143 offset:3072
	s_mov_b32 m0, s18
	v_lshl_add_u64 v[218:219], s[48:49], 0, v[130:131]
	ds_read_b128 v[176:179], v142 offset:32768
	ds_read_b128 v[180:183], v142 offset:33792
	ds_read_b128 v[184:187], v142 offset:34816
	ds_read_b128 v[188:191], v142 offset:35840
	ds_read_b128 v[192:195], v142 offset:36864
	ds_read_b128 v[196:199], v142 offset:37888
	ds_read_b128 v[200:203], v142 offset:38912
	ds_read_b128 v[206:209], v142 offset:39936
	global_load_lds_dwordx4 v[218:219], off
	s_mov_b32 m0, s19
	v_lshl_add_u64 v[218:219], s[48:49], 0, v[132:133]
	global_load_lds_dwordx4 v[218:219], off
	s_waitcnt vmcnt(8) lgkmcnt(0)
	s_setprio 1
	s_barrier
	v_mfma_f32_16x16x32_bf16 v[126:129], v[144:147], v[176:179], v[126:129]
	v_mfma_f32_16x16x32_bf16 v[122:125], v[152:155], v[176:179], v[122:125]
	v_mfma_f32_16x16x32_bf16 v[118:121], v[144:147], v[184:187], v[118:121]
	v_mfma_f32_16x16x32_bf16 v[114:117], v[152:155], v[184:187], v[114:117]
	v_mfma_f32_16x16x32_bf16 v[102:105], v[144:147], v[192:195], v[102:105]
	v_mfma_f32_16x16x32_bf16 v[98:101], v[152:155], v[192:195], v[98:101]
	v_mfma_f32_16x16x32_bf16 v[86:89], v[144:147], v[200:203], v[86:89]
	v_mfma_f32_16x16x32_bf16 v[82:85], v[152:155], v[200:203], v[82:85]
	v_mfma_f32_16x16x32_bf16 v[126:129], v[148:151], v[180:183], v[126:129]
	v_mfma_f32_16x16x32_bf16 v[122:125], v[156:159], v[180:183], v[122:125]
	v_mfma_f32_16x16x32_bf16 v[118:121], v[148:151], v[188:191], v[118:121]
	v_mfma_f32_16x16x32_bf16 v[114:117], v[156:159], v[188:191], v[114:117]
	v_mfma_f32_16x16x32_bf16 v[102:105], v[148:151], v[196:199], v[102:105]
	v_mfma_f32_16x16x32_bf16 v[98:101], v[156:159], v[196:199], v[98:101]
	v_mfma_f32_16x16x32_bf16 v[86:89], v[148:151], v[206:209], v[86:89]
	v_mfma_f32_16x16x32_bf16 v[82:85], v[156:159], v[206:209], v[82:85]
	v_mfma_f32_16x16x32_bf16 v[110:113], v[160:163], v[176:179], v[110:113]
	v_mfma_f32_16x16x32_bf16 v[106:109], v[168:171], v[176:179], v[106:109]
	v_mfma_f32_16x16x32_bf16 v[94:97], v[160:163], v[184:187], v[94:97]
	v_mfma_f32_16x16x32_bf16 v[90:93], v[168:171], v[184:187], v[90:93]
	v_mfma_f32_16x16x32_bf16 v[78:81], v[160:163], v[192:195], v[78:81]
	v_mfma_f32_16x16x32_bf16 v[74:77], v[168:171], v[192:195], v[74:77]
	v_mfma_f32_16x16x32_bf16 v[70:73], v[160:163], v[200:203], v[70:73]
	v_mfma_f32_16x16x32_bf16 v[66:69], v[168:171], v[200:203], v[66:69]
	v_mfma_f32_16x16x32_bf16 v[110:113], v[164:167], v[180:183], v[110:113]
	v_mfma_f32_16x16x32_bf16 v[106:109], v[172:175], v[180:183], v[106:109]
	v_mfma_f32_16x16x32_bf16 v[94:97], v[164:167], v[188:191], v[94:97]
	v_mfma_f32_16x16x32_bf16 v[90:93], v[172:175], v[188:191], v[90:93]
	v_mfma_f32_16x16x32_bf16 v[78:81], v[164:167], v[196:199], v[78:81]
	v_mfma_f32_16x16x32_bf16 v[74:77], v[172:175], v[196:199], v[74:77]
	v_mfma_f32_16x16x32_bf16 v[70:73], v[164:167], v[206:209], v[70:73]
	v_mfma_f32_16x16x32_bf16 v[66:69], v[172:175], v[206:209], v[66:69]
	s_setprio 0
	s_barrier
	s_mov_b32 m0, s81
	v_lshl_add_u64 v[210:211], v[210:211], 0, s[8:9]
	ds_read_b128 v[176:179], v142 offset:49152
	ds_read_b128 v[180:183], v142 offset:50176
	ds_read_b128 v[184:187], v142 offset:51200
	ds_read_b128 v[188:191], v142 offset:52224
	ds_read_b128 v[192:195], v142 offset:53248
	ds_read_b128 v[196:199], v142 offset:54272
	ds_read_b128 v[200:203], v142 offset:55296
	ds_read_b128 v[206:209], v142 offset:56320
	global_load_lds_dwordx4 v[210:211], off
	s_mov_b32 m0, s79
	v_lshl_add_u64 v[210:211], v[212:213], 0, s[8:9]
	global_load_lds_dwordx4 v[210:211], off
	s_mov_b32 m0, s80
	v_lshl_add_u64 v[210:211], s[46:47], 0, v[136:137]
	global_load_lds_dwordx4 v[210:211], off
	s_mov_b32 m0, s78
	v_lshl_add_u64 v[210:211], s[46:47], 0, v[134:135]
	global_load_lds_dwordx4 v[210:211], off
	s_mov_b32 m0, s30
	v_lshl_add_u64 v[210:211], v[214:215], 0, s[8:9]
	global_load_lds_dwordx4 v[210:211], off
	s_mov_b32 m0, s31
	v_lshl_add_u64 v[210:211], v[216:217], 0, s[8:9]
	global_load_lds_dwordx4 v[210:211], off
	s_waitcnt vmcnt(8) lgkmcnt(0)
	s_setprio 1
	s_barrier
	v_mfma_f32_16x16x32_bf16 v[62:65], v[144:147], v[176:179], v[62:65]
	v_mfma_f32_16x16x32_bf16 v[58:61], v[152:155], v[176:179], v[58:61]
	v_mfma_f32_16x16x32_bf16 v[54:57], v[144:147], v[184:187], v[54:57]
	v_mfma_f32_16x16x32_bf16 v[50:53], v[152:155], v[184:187], v[50:53]
	v_mfma_f32_16x16x32_bf16 v[38:41], v[144:147], v[192:195], v[38:41]
	v_mfma_f32_16x16x32_bf16 v[34:37], v[152:155], v[192:195], v[34:37]
	v_mfma_f32_16x16x32_bf16 v[22:25], v[144:147], v[200:203], v[22:25]
	v_mfma_f32_16x16x32_bf16 v[18:21], v[152:155], v[200:203], v[18:21]
	v_mfma_f32_16x16x32_bf16 v[62:65], v[148:151], v[180:183], v[62:65]
	v_mfma_f32_16x16x32_bf16 v[58:61], v[156:159], v[180:183], v[58:61]
	v_mfma_f32_16x16x32_bf16 v[54:57], v[148:151], v[188:191], v[54:57]
	v_mfma_f32_16x16x32_bf16 v[50:53], v[156:159], v[188:191], v[50:53]
	v_mfma_f32_16x16x32_bf16 v[38:41], v[148:151], v[196:199], v[38:41]
	v_mfma_f32_16x16x32_bf16 v[34:37], v[156:159], v[196:199], v[34:37]
	v_mfma_f32_16x16x32_bf16 v[22:25], v[148:151], v[206:209], v[22:25]
	v_mfma_f32_16x16x32_bf16 v[18:21], v[156:159], v[206:209], v[18:21]
	v_mfma_f32_16x16x32_bf16 v[46:49], v[160:163], v[176:179], v[46:49]
	v_mfma_f32_16x16x32_bf16 v[42:45], v[168:171], v[176:179], v[42:45]
	v_mfma_f32_16x16x32_bf16 v[30:33], v[160:163], v[184:187], v[30:33]
	v_mfma_f32_16x16x32_bf16 v[26:29], v[168:171], v[184:187], v[26:29]
	v_mfma_f32_16x16x32_bf16 v[14:17], v[160:163], v[192:195], v[14:17]
	v_mfma_f32_16x16x32_bf16 v[10:13], v[168:171], v[192:195], v[10:13]
	v_mfma_f32_16x16x32_bf16 v[6:9], v[160:163], v[200:203], v[6:9]
	v_mfma_f32_16x16x32_bf16 v[2:5], v[168:171], v[200:203], v[2:5]
	v_mfma_f32_16x16x32_bf16 v[46:49], v[164:167], v[180:183], v[46:49]
	v_mfma_f32_16x16x32_bf16 v[42:45], v[172:175], v[180:183], v[42:45]
	v_mfma_f32_16x16x32_bf16 v[30:33], v[164:167], v[188:191], v[30:33]
	v_mfma_f32_16x16x32_bf16 v[26:29], v[172:175], v[188:191], v[26:29]
	v_mfma_f32_16x16x32_bf16 v[14:17], v[164:167], v[196:199], v[14:17]
	v_mfma_f32_16x16x32_bf16 v[10:13], v[172:175], v[196:199], v[10:13]
	v_mfma_f32_16x16x32_bf16 v[6:9], v[164:167], v[206:209], v[6:9]
	v_mfma_f32_16x16x32_bf16 v[2:5], v[172:175], v[206:209], v[2:5]
	s_setprio 0
	s_barrier
	s_movk_i32 s48, 0x100
	s_andn2_b64 vcc, exec, s[44:45]
	s_mov_b64 s[46:47], -1
	s_mov_b64 s[44:45], 0
	s_cbranch_vccz .LBB0_313
	s_and_b64 vcc, exec, s[10:11]
	s_cbranch_vccz .LBB0_316
	s_barrier

.LBB0_383:
	s_add_u32 s26, s0, s22
	s_addc_u32 s27, s1, s23
	s_and_b64 s[44:45], s[36:37], exec
	s_cselect_b32 s15, s27, s43
	s_cselect_b32 s39, s26, s42
	s_add_u32 s66, s42, 0x100
	s_addc_u32 s67, s43, 0
	s_mov_b32 s68, -2
	s_mov_b64 s[42:43], 0
	ds_read_b128 v[152:155], v146
	ds_read_b128 v[156:159], v146 offset:1024
	ds_read_b128 v[160:163], v146 offset:2048
	ds_read_b128 v[164:167], v146 offset:3072
	ds_read_b128 v[168:171], v147
	ds_read_b128 v[172:175], v147 offset:1024
	ds_read_b128 v[176:179], v147 offset:2048
	ds_read_b128 v[180:183], v147 offset:3072
	s_add_u32 s44, s42, 0x100
	s_addc_u32 s45, s43, 0
	s_add_u32 s46, s66, s42
	s_addc_u32 s47, s67, s43
	s_cmp_eq_u32 s68, 4
	s_cselect_b32 s48, 0, s44
	s_cselect_b32 s49, 0, s45
	s_cselect_b32 s46, s39, s46
	s_cselect_b32 s47, s15, s47
	s_add_u32 s48, s6, s48
	s_addc_u32 s49, s7, s49
	s_mov_b32 m0, s29
	v_lshl_add_u64 v[218:219], v[138:139], 0, s[42:43]
	ds_read_b128 v[184:187], v148
	ds_read_b128 v[188:191], v148 offset:1024
	ds_read_b128 v[192:195], v148 offset:2048
	ds_read_b128 v[196:199], v148 offset:3072
	ds_read_b128 v[200:203], v148 offset:4096
	ds_read_b128 v[206:209], v148 offset:5120
	ds_read_b128 v[210:213], v148 offset:6144
	ds_read_b128 v[214:217], v148 offset:7168
	global_load_lds_dwordx4 v[218:219], off
	s_mov_b32 m0, s30
	v_lshl_add_u64 v[218:219], v[140:141], 0, s[42:43]
	global_load_lds_dwordx4 v[218:219], off
	s_waitcnt vmcnt(8) lgkmcnt(0)
	s_setprio 1
	s_barrier
	v_mfma_f32_16x16x32_bf16 v[126:129], v[152:155], v[184:187], 0
	v_mfma_f32_16x16x32_bf16 v[122:125], v[160:163], v[184:187], 0
	v_mfma_f32_16x16x32_bf16 v[118:121], v[152:155], v[192:195], 0
	v_mfma_f32_16x16x32_bf16 v[114:117], v[160:163], v[192:195], 0
	v_mfma_f32_16x16x32_bf16 v[102:105], v[152:155], v[200:203], 0
	v_mfma_f32_16x16x32_bf16 v[98:101], v[160:163], v[200:203], 0
	v_mfma_f32_16x16x32_bf16 v[86:89], v[152:155], v[210:213], 0
	v_mfma_f32_16x16x32_bf16 v[82:85], v[160:163], v[210:213], 0
	v_mfma_f32_16x16x32_bf16 v[126:129], v[156:159], v[188:191], v[126:129]
	v_mfma_f32_16x16x32_bf16 v[122:125], v[164:167], v[188:191], v[122:125]
	v_mfma_f32_16x16x32_bf16 v[118:121], v[156:159], v[196:199], v[118:121]
	v_mfma_f32_16x16x32_bf16 v[114:117], v[164:167], v[196:199], v[114:117]
	v_mfma_f32_16x16x32_bf16 v[102:105], v[156:159], v[206:209], v[102:105]
	v_mfma_f32_16x16x32_bf16 v[98:101], v[164:167], v[206:209], v[98:101]
	v_mfma_f32_16x16x32_bf16 v[86:89], v[156:159], v[214:217], v[86:89]
	v_mfma_f32_16x16x32_bf16 v[82:85], v[164:167], v[214:217], v[82:85]
	v_mfma_f32_16x16x32_bf16 v[110:113], v[168:171], v[184:187], 0
	v_mfma_f32_16x16x32_bf16 v[106:109], v[176:179], v[184:187], 0
	v_mfma_f32_16x16x32_bf16 v[94:97], v[168:171], v[192:195], 0
	v_mfma_f32_16x16x32_bf16 v[90:93], v[176:179], v[192:195], 0
	v_mfma_f32_16x16x32_bf16 v[78:81], v[168:171], v[200:203], 0
	v_mfma_f32_16x16x32_bf16 v[74:77], v[176:179], v[200:203], 0
	v_mfma_f32_16x16x32_bf16 v[70:73], v[168:171], v[210:213], 0
	v_mfma_f32_16x16x32_bf16 v[66:69], v[176:179], v[210:213], 0
	v_mfma_f32_16x16x32_bf16 v[110:113], v[172:175], v[188:191], v[110:113]
	v_mfma_f32_16x16x32_bf16 v[106:109], v[180:183], v[188:191], v[106:109]
	v_mfma_f32_16x16x32_bf16 v[94:97], v[172:175], v[196:199], v[94:97]
	v_mfma_f32_16x16x32_bf16 v[90:93], v[180:183], v[196:199], v[90:93]
	v_mfma_f32_16x16x32_bf16 v[78:81], v[172:175], v[206:209], v[78:81]
	v_mfma_f32_16x16x32_bf16 v[74:77], v[180:183], v[206:209], v[74:77]
	v_mfma_f32_16x16x32_bf16 v[70:73], v[172:175], v[214:217], v[70:73]
	v_mfma_f32_16x16x32_bf16 v[66:69], v[180:183], v[214:217], v[66:69]
	s_setprio 0
	s_barrier
	s_mov_b32 m0, s31
	v_lshl_add_u64 v[218:219], s[46:47], 0, v[134:135]
	s_add_u32 s42, s46, 0x20000
	ds_read_b128 v[184:187], v148 offset:16384
	ds_read_b128 v[188:191], v148 offset:17408
	ds_read_b128 v[192:195], v148 offset:18432
	ds_read_b128 v[196:199], v148 offset:19456
	ds_read_b128 v[200:203], v148 offset:20480
	ds_read_b128 v[206:209], v148 offset:21504
	ds_read_b128 v[210:213], v148 offset:22528
	ds_read_b128 v[214:217], v148 offset:23552
	global_load_lds_dwordx4 v[218:219], off
	v_lshl_add_u64 v[220:221], s[46:47], 0, v[130:131]
	s_mov_b32 m0, s33
	s_addc_u32 s43, s47, 0
	global_load_lds_dwordx4 v[220:221], off
	v_lshl_add_u64 v[222:223], s[42:43], 0, v[134:135]
	s_mov_b32 m0, s34
	v_lshl_add_u64 v[224:225], s[48:49], 0, v[132:133]
	global_load_lds_dwordx4 v[222:223], off
	s_mov_b32 m0, s35
	v_lshl_add_u64 v[222:223], s[42:43], 0, v[130:131]
	global_load_lds_dwordx4 v[222:223], off
	s_mov_b32 m0, s2
	v_lshl_add_u64 v[222:223], s[48:49], 0, v[136:137]
	global_load_lds_dwordx4 v[222:223], off
	s_mov_b32 m0, s3
	s_nop 0
	global_load_lds_dwordx4 v[224:225], off
	s_waitcnt vmcnt(8) lgkmcnt(0)
	s_setprio 1
	s_barrier
	v_mfma_f32_16x16x32_bf16 v[62:65], v[152:155], v[184:187], 0
	v_mfma_f32_16x16x32_bf16 v[58:61], v[160:163], v[184:187], 0
	v_mfma_f32_16x16x32_bf16 v[54:57], v[152:155], v[192:195], 0
	v_mfma_f32_16x16x32_bf16 v[50:53], v[160:163], v[192:195], 0
	v_mfma_f32_16x16x32_bf16 v[38:41], v[152:155], v[200:203], 0
	v_mfma_f32_16x16x32_bf16 v[34:37], v[160:163], v[200:203], 0
	v_mfma_f32_16x16x32_bf16 v[22:25], v[152:155], v[210:213], 0
	v_mfma_f32_16x16x32_bf16 v[18:21], v[160:163], v[210:213], 0
	v_mfma_f32_16x16x32_bf16 v[62:65], v[156:159], v[188:191], v[62:65]
	v_mfma_f32_16x16x32_bf16 v[58:61], v[164:167], v[188:191], v[58:61]
	v_mfma_f32_16x16x32_bf16 v[54:57], v[156:159], v[196:199], v[54:57]
	v_mfma_f32_16x16x32_bf16 v[50:53], v[164:167], v[196:199], v[50:53]
	v_mfma_f32_16x16x32_bf16 v[38:41], v[156:159], v[206:209], v[38:41]
	v_mfma_f32_16x16x32_bf16 v[34:37], v[164:167], v[206:209], v[34:37]
	v_mfma_f32_16x16x32_bf16 v[22:25], v[156:159], v[214:217], v[22:25]
	v_mfma_f32_16x16x32_bf16 v[18:21], v[164:167], v[214:217], v[18:21]
	v_mfma_f32_16x16x32_bf16 v[46:49], v[168:171], v[184:187], 0
	v_mfma_f32_16x16x32_bf16 v[42:45], v[176:179], v[184:187], 0
	v_mfma_f32_16x16x32_bf16 v[30:33], v[168:171], v[192:195], 0
	v_mfma_f32_16x16x32_bf16 v[26:29], v[176:179], v[192:195], 0
	v_mfma_f32_16x16x32_bf16 v[14:17], v[168:171], v[200:203], 0
	v_mfma_f32_16x16x32_bf16 v[10:13], v[176:179], v[200:203], 0
	v_mfma_f32_16x16x32_bf16 v[6:9], v[168:171], v[210:213], 0
	v_mfma_f32_16x16x32_bf16 v[2:5], v[176:179], v[210:213], 0
	v_mfma_f32_16x16x32_bf16 v[46:49], v[172:175], v[188:191], v[46:49]
	v_mfma_f32_16x16x32_bf16 v[42:45], v[180:183], v[188:191], v[42:45]
	v_mfma_f32_16x16x32_bf16 v[30:33], v[172:175], v[196:199], v[30:33]
	v_mfma_f32_16x16x32_bf16 v[26:29], v[180:183], v[196:199], v[26:29]
	v_mfma_f32_16x16x32_bf16 v[14:17], v[172:175], v[206:209], v[14:17]
	v_mfma_f32_16x16x32_bf16 v[10:13], v[180:183], v[206:209], v[10:13]
	v_mfma_f32_16x16x32_bf16 v[6:9], v[172:175], v[214:217], v[6:9]
	v_mfma_f32_16x16x32_bf16 v[2:5], v[180:183], v[214:217], v[2:5]
	s_setprio 0
	s_barrier
	ds_read_b128 v[152:155], v149
	ds_read_b128 v[156:159], v149 offset:1024
	ds_read_b128 v[160:163], v149 offset:2048
	ds_read_b128 v[164:167], v149 offset:3072
	ds_read_b128 v[168:171], v150
	ds_read_b128 v[172:175], v150 offset:1024
	ds_read_b128 v[176:179], v150 offset:2048
	ds_read_b128 v[180:183], v150 offset:3072
	s_add_u32 s42, s48, 0x20000
	s_addc_u32 s43, s49, 0
	s_mov_b32 m0, s16
	v_lshl_add_u64 v[226:227], s[42:43], 0, v[136:137]
	ds_read_b128 v[184:187], v148 offset:32768
	ds_read_b128 v[188:191], v148 offset:33792
	ds_read_b128 v[192:195], v148 offset:34816
	ds_read_b128 v[196:199], v148 offset:35840
	ds_read_b128 v[200:203], v148 offset:36864
	ds_read_b128 v[206:209], v148 offset:37888
	ds_read_b128 v[210:213], v148 offset:38912
	ds_read_b128 v[214:217], v148 offset:39936
	global_load_lds_dwordx4 v[226:227], off
	s_mov_b32 m0, s17
	v_lshl_add_u64 v[226:227], s[42:43], 0, v[132:133]
	global_load_lds_dwordx4 v[226:227], off
	s_waitcnt vmcnt(8) lgkmcnt(0)
	s_setprio 1
	s_barrier
	v_mfma_f32_16x16x32_bf16 v[126:129], v[152:155], v[184:187], v[126:129]
	v_mfma_f32_16x16x32_bf16 v[122:125], v[160:163], v[184:187], v[122:125]
	v_mfma_f32_16x16x32_bf16 v[118:121], v[152:155], v[192:195], v[118:121]
	v_mfma_f32_16x16x32_bf16 v[114:117], v[160:163], v[192:195], v[114:117]
	v_mfma_f32_16x16x32_bf16 v[102:105], v[152:155], v[200:203], v[102:105]
	v_mfma_f32_16x16x32_bf16 v[98:101], v[160:163], v[200:203], v[98:101]
	v_mfma_f32_16x16x32_bf16 v[86:89], v[152:155], v[210:213], v[86:89]
	v_mfma_f32_16x16x32_bf16 v[82:85], v[160:163], v[210:213], v[82:85]
	v_mfma_f32_16x16x32_bf16 v[126:129], v[156:159], v[188:191], v[126:129]
	v_mfma_f32_16x16x32_bf16 v[122:125], v[164:167], v[188:191], v[122:125]
	v_mfma_f32_16x16x32_bf16 v[118:121], v[156:159], v[196:199], v[118:121]
	v_mfma_f32_16x16x32_bf16 v[114:117], v[164:167], v[196:199], v[114:117]
	v_mfma_f32_16x16x32_bf16 v[102:105], v[156:159], v[206:209], v[102:105]
	v_mfma_f32_16x16x32_bf16 v[98:101], v[164:167], v[206:209], v[98:101]
	v_mfma_f32_16x16x32_bf16 v[86:89], v[156:159], v[214:217], v[86:89]
	v_mfma_f32_16x16x32_bf16 v[82:85], v[164:167], v[214:217], v[82:85]
	v_mfma_f32_16x16x32_bf16 v[110:113], v[168:171], v[184:187], v[110:113]
	v_mfma_f32_16x16x32_bf16 v[106:109], v[176:179], v[184:187], v[106:109]
	v_mfma_f32_16x16x32_bf16 v[94:97], v[168:171], v[192:195], v[94:97]
	v_mfma_f32_16x16x32_bf16 v[90:93], v[176:179], v[192:195], v[90:93]
	v_mfma_f32_16x16x32_bf16 v[78:81], v[168:171], v[200:203], v[78:81]
	v_mfma_f32_16x16x32_bf16 v[74:77], v[176:179], v[200:203], v[74:77]
	v_mfma_f32_16x16x32_bf16 v[70:73], v[168:171], v[210:213], v[70:73]
	v_mfma_f32_16x16x32_bf16 v[66:69], v[176:179], v[210:213], v[66:69]
	v_mfma_f32_16x16x32_bf16 v[110:113], v[172:175], v[188:191], v[110:113]
	v_mfma_f32_16x16x32_bf16 v[106:109], v[180:183], v[188:191], v[106:109]
	v_mfma_f32_16x16x32_bf16 v[94:97], v[172:175], v[196:199], v[94:97]
	v_mfma_f32_16x16x32_bf16 v[90:93], v[180:183], v[196:199], v[90:93]
	v_mfma_f32_16x16x32_bf16 v[78:81], v[172:175], v[206:209], v[78:81]
	v_mfma_f32_16x16x32_bf16 v[74:77], v[180:183], v[206:209], v[74:77]
	v_mfma_f32_16x16x32_bf16 v[70:73], v[172:175], v[214:217], v[70:73]
	v_mfma_f32_16x16x32_bf16 v[66:69], v[180:183], v[214:217], v[66:69]
	s_setprio 0
	s_barrier
	s_mov_b32 m0, s62
	v_lshl_add_u64 v[218:219], v[218:219], 0, s[10:11]
	s_add_u32 s42, s46, 0x20080
	ds_read_b128 v[184:187], v148 offset:49152
	ds_read_b128 v[188:191], v148 offset:50176
	ds_read_b128 v[192:195], v148 offset:51200
	ds_read_b128 v[196:199], v148 offset:52224
	ds_read_b128 v[200:203], v148 offset:53248
	ds_read_b128 v[206:209], v148 offset:54272
	ds_read_b128 v[210:213], v148 offset:55296
	ds_read_b128 v[214:217], v148 offset:56320
	global_load_lds_dwordx4 v[218:219], off
	v_lshl_add_u64 v[218:219], v[220:221], 0, s[10:11]
	s_mov_b32 m0, s63
	s_addc_u32 s43, s47, 0
	global_load_lds_dwordx4 v[218:219], off
	s_mov_b32 m0, s64
	v_lshl_add_u64 v[218:219], s[42:43], 0, v[134:135]
	global_load_lds_dwordx4 v[218:219], off
	s_mov_b32 m0, s65
	v_lshl_add_u64 v[218:219], s[42:43], 0, v[130:131]
	global_load_lds_dwordx4 v[218:219], off
	s_mov_b32 m0, s25
	v_lshl_add_u64 v[218:219], v[222:223], 0, s[10:11]
	global_load_lds_dwordx4 v[218:219], off
	s_mov_b32 m0, s28
	v_lshl_add_u64 v[218:219], v[224:225], 0, s[10:11]
	global_load_lds_dwordx4 v[218:219], off
	s_waitcnt vmcnt(8) lgkmcnt(0)
	s_setprio 1
	s_barrier
	v_mfma_f32_16x16x32_bf16 v[62:65], v[152:155], v[184:187], v[62:65]
	v_mfma_f32_16x16x32_bf16 v[58:61], v[160:163], v[184:187], v[58:61]
	v_mfma_f32_16x16x32_bf16 v[54:57], v[152:155], v[192:195], v[54:57]
	v_mfma_f32_16x16x32_bf16 v[50:53], v[160:163], v[192:195], v[50:53]
	v_mfma_f32_16x16x32_bf16 v[38:41], v[152:155], v[200:203], v[38:41]
	v_mfma_f32_16x16x32_bf16 v[34:37], v[160:163], v[200:203], v[34:37]
	v_mfma_f32_16x16x32_bf16 v[22:25], v[152:155], v[210:213], v[22:25]
	v_mfma_f32_16x16x32_bf16 v[18:21], v[160:163], v[210:213], v[18:21]
	v_mfma_f32_16x16x32_bf16 v[62:65], v[156:159], v[188:191], v[62:65]
	v_mfma_f32_16x16x32_bf16 v[58:61], v[164:167], v[188:191], v[58:61]
	v_mfma_f32_16x16x32_bf16 v[54:57], v[156:159], v[196:199], v[54:57]
	v_mfma_f32_16x16x32_bf16 v[50:53], v[164:167], v[196:199], v[50:53]
	v_mfma_f32_16x16x32_bf16 v[38:41], v[156:159], v[206:209], v[38:41]
	v_mfma_f32_16x16x32_bf16 v[34:37], v[164:167], v[206:209], v[34:37]
	v_mfma_f32_16x16x32_bf16 v[22:25], v[156:159], v[214:217], v[22:25]
	v_mfma_f32_16x16x32_bf16 v[18:21], v[164:167], v[214:217], v[18:21]
	v_mfma_f32_16x16x32_bf16 v[46:49], v[168:171], v[184:187], v[46:49]
	v_mfma_f32_16x16x32_bf16 v[42:45], v[176:179], v[184:187], v[42:45]
	v_mfma_f32_16x16x32_bf16 v[30:33], v[168:171], v[192:195], v[30:33]
	v_mfma_f32_16x16x32_bf16 v[26:29], v[176:179], v[192:195], v[26:29]
	v_mfma_f32_16x16x32_bf16 v[14:17], v[168:171], v[200:203], v[14:17]
	v_mfma_f32_16x16x32_bf16 v[10:13], v[176:179], v[200:203], v[10:13]
	v_mfma_f32_16x16x32_bf16 v[6:9], v[168:171], v[210:213], v[6:9]
	v_mfma_f32_16x16x32_bf16 v[2:5], v[176:179], v[210:213], v[2:5]
	v_mfma_f32_16x16x32_bf16 v[46:49], v[172:175], v[188:191], v[46:49]
	v_mfma_f32_16x16x32_bf16 v[42:45], v[180:183], v[188:191], v[42:45]
	v_mfma_f32_16x16x32_bf16 v[30:33], v[172:175], v[196:199], v[30:33]
	v_mfma_f32_16x16x32_bf16 v[26:29], v[180:183], v[196:199], v[26:29]
	v_mfma_f32_16x16x32_bf16 v[14:17], v[172:175], v[206:209], v[14:17]
	v_mfma_f32_16x16x32_bf16 v[10:13], v[180:183], v[206:209], v[10:13]
	v_mfma_f32_16x16x32_bf16 v[6:9], v[172:175], v[214:217], v[6:9]
	v_mfma_f32_16x16x32_bf16 v[2:5], v[180:183], v[214:217], v[2:5]
	s_setprio 0
	s_barrier
	s_add_i32 s68, s68, 2
	s_cmp_gt_u32 s68, 5
	s_mov_b64 s[42:43], s[44:45]
.LBB0_384:
	ds_read_b128 v[152:155], v146
	ds_read_b128 v[156:159], v146 offset:1024
	ds_read_b128 v[160:163], v146 offset:2048
	ds_read_b128 v[164:167], v146 offset:3072
	ds_read_b128 v[168:171], v147
	ds_read_b128 v[172:175], v147 offset:1024
	ds_read_b128 v[176:179], v147 offset:2048
	ds_read_b128 v[180:183], v147 offset:3072
	s_add_u32 s44, s42, 0x100
	s_addc_u32 s45, s43, 0
	s_add_u32 s46, s66, s42
	s_addc_u32 s47, s67, s43
	s_cmp_eq_u32 s68, 4
	s_cselect_b32 s48, 0, s44
	s_cselect_b32 s49, 0, s45
	s_cselect_b32 s46, s39, s46
	s_cselect_b32 s47, s15, s47
	s_add_u32 s48, s6, s48
	s_addc_u32 s49, s7, s49
	s_mov_b32 m0, s29
	v_lshl_add_u64 v[218:219], v[138:139], 0, s[42:43]
	ds_read_b128 v[184:187], v148
	ds_read_b128 v[188:191], v148 offset:1024
	ds_read_b128 v[192:195], v148 offset:2048
	ds_read_b128 v[196:199], v148 offset:3072
	ds_read_b128 v[200:203], v148 offset:4096
	ds_read_b128 v[206:209], v148 offset:5120
	ds_read_b128 v[210:213], v148 offset:6144
	ds_read_b128 v[214:217], v148 offset:7168
	global_load_lds_dwordx4 v[218:219], off
	s_mov_b32 m0, s30
	v_lshl_add_u64 v[218:219], v[140:141], 0, s[42:43]
	global_load_lds_dwordx4 v[218:219], off
	s_waitcnt vmcnt(8) lgkmcnt(0)
	s_setprio 1
	s_barrier
	v_mfma_f32_16x16x32_bf16 v[126:129], v[152:155], v[184:187], v[126:129]
	v_mfma_f32_16x16x32_bf16 v[122:125], v[160:163], v[184:187], v[122:125]
	v_mfma_f32_16x16x32_bf16 v[118:121], v[152:155], v[192:195], v[118:121]
	v_mfma_f32_16x16x32_bf16 v[114:117], v[160:163], v[192:195], v[114:117]
	v_mfma_f32_16x16x32_bf16 v[102:105], v[152:155], v[200:203], v[102:105]
	v_mfma_f32_16x16x32_bf16 v[98:101], v[160:163], v[200:203], v[98:101]
	v_mfma_f32_16x16x32_bf16 v[86:89], v[152:155], v[210:213], v[86:89]
	v_mfma_f32_16x16x32_bf16 v[82:85], v[160:163], v[210:213], v[82:85]
	v_mfma_f32_16x16x32_bf16 v[126:129], v[156:159], v[188:191], v[126:129]
	v_mfma_f32_16x16x32_bf16 v[122:125], v[164:167], v[188:191], v[122:125]
	v_mfma_f32_16x16x32_bf16 v[118:121], v[156:159], v[196:199], v[118:121]
	v_mfma_f32_16x16x32_bf16 v[114:117], v[164:167], v[196:199], v[114:117]
	v_mfma_f32_16x16x32_bf16 v[102:105], v[156:159], v[206:209], v[102:105]
	v_mfma_f32_16x16x32_bf16 v[98:101], v[164:167], v[206:209], v[98:101]
	v_mfma_f32_16x16x32_bf16 v[86:89], v[156:159], v[214:217], v[86:89]
	v_mfma_f32_16x16x32_bf16 v[82:85], v[164:167], v[214:217], v[82:85]
	v_mfma_f32_16x16x32_bf16 v[110:113], v[168:171], v[184:187], v[110:113]
	v_mfma_f32_16x16x32_bf16 v[106:109], v[176:179], v[184:187], v[106:109]
	v_mfma_f32_16x16x32_bf16 v[94:97], v[168:171], v[192:195], v[94:97]
	v_mfma_f32_16x16x32_bf16 v[90:93], v[176:179], v[192:195], v[90:93]
	v_mfma_f32_16x16x32_bf16 v[78:81], v[168:171], v[200:203], v[78:81]
	v_mfma_f32_16x16x32_bf16 v[74:77], v[176:179], v[200:203], v[74:77]
	v_mfma_f32_16x16x32_bf16 v[70:73], v[168:171], v[210:213], v[70:73]
	v_mfma_f32_16x16x32_bf16 v[66:69], v[176:179], v[210:213], v[66:69]
	v_mfma_f32_16x16x32_bf16 v[110:113], v[172:175], v[188:191], v[110:113]
	v_mfma_f32_16x16x32_bf16 v[106:109], v[180:183], v[188:191], v[106:109]
	v_mfma_f32_16x16x32_bf16 v[94:97], v[172:175], v[196:199], v[94:97]
	v_mfma_f32_16x16x32_bf16 v[90:93], v[180:183], v[196:199], v[90:93]
	v_mfma_f32_16x16x32_bf16 v[78:81], v[172:175], v[206:209], v[78:81]
	v_mfma_f32_16x16x32_bf16 v[74:77], v[180:183], v[206:209], v[74:77]
	v_mfma_f32_16x16x32_bf16 v[70:73], v[172:175], v[214:217], v[70:73]
	v_mfma_f32_16x16x32_bf16 v[66:69], v[180:183], v[214:217], v[66:69]
	s_setprio 0
	s_barrier
	s_mov_b32 m0, s31
	v_lshl_add_u64 v[218:219], s[46:47], 0, v[134:135]
	s_add_u32 s42, s46, 0x20000
	ds_read_b128 v[184:187], v148 offset:16384
	ds_read_b128 v[188:191], v148 offset:17408
	ds_read_b128 v[192:195], v148 offset:18432
	ds_read_b128 v[196:199], v148 offset:19456
	ds_read_b128 v[200:203], v148 offset:20480
	ds_read_b128 v[206:209], v148 offset:21504
	ds_read_b128 v[210:213], v148 offset:22528
	ds_read_b128 v[214:217], v148 offset:23552
	global_load_lds_dwordx4 v[218:219], off
	v_lshl_add_u64 v[220:221], s[46:47], 0, v[130:131]
	s_mov_b32 m0, s33
	s_addc_u32 s43, s47, 0
	global_load_lds_dwordx4 v[220:221], off
	v_lshl_add_u64 v[222:223], s[42:43], 0, v[134:135]
	s_mov_b32 m0, s34
	v_lshl_add_u64 v[224:225], s[48:49], 0, v[132:133]
	global_load_lds_dwordx4 v[222:223], off
	s_mov_b32 m0, s35
	v_lshl_add_u64 v[222:223], s[42:43], 0, v[130:131]
	global_load_lds_dwordx4 v[222:223], off
	s_mov_b32 m0, s2
	v_lshl_add_u64 v[222:223], s[48:49], 0, v[136:137]
	global_load_lds_dwordx4 v[222:223], off
	s_mov_b32 m0, s3
	s_nop 0
	global_load_lds_dwordx4 v[224:225], off
	s_waitcnt vmcnt(8) lgkmcnt(0)
	s_setprio 1
	s_barrier
	v_mfma_f32_16x16x32_bf16 v[62:65], v[152:155], v[184:187], v[62:65]
	v_mfma_f32_16x16x32_bf16 v[58:61], v[160:163], v[184:187], v[58:61]
	v_mfma_f32_16x16x32_bf16 v[54:57], v[152:155], v[192:195], v[54:57]
	v_mfma_f32_16x16x32_bf16 v[50:53], v[160:163], v[192:195], v[50:53]
	v_mfma_f32_16x16x32_bf16 v[38:41], v[152:155], v[200:203], v[38:41]
	v_mfma_f32_16x16x32_bf16 v[34:37], v[160:163], v[200:203], v[34:37]
	v_mfma_f32_16x16x32_bf16 v[22:25], v[152:155], v[210:213], v[22:25]
	v_mfma_f32_16x16x32_bf16 v[18:21], v[160:163], v[210:213], v[18:21]
	v_mfma_f32_16x16x32_bf16 v[62:65], v[156:159], v[188:191], v[62:65]
	v_mfma_f32_16x16x32_bf16 v[58:61], v[164:167], v[188:191], v[58:61]
	v_mfma_f32_16x16x32_bf16 v[54:57], v[156:159], v[196:199], v[54:57]
	v_mfma_f32_16x16x32_bf16 v[50:53], v[164:167], v[196:199], v[50:53]
	v_mfma_f32_16x16x32_bf16 v[38:41], v[156:159], v[206:209], v[38:41]
	v_mfma_f32_16x16x32_bf16 v[34:37], v[164:167], v[206:209], v[34:37]
	v_mfma_f32_16x16x32_bf16 v[22:25], v[156:159], v[214:217], v[22:25]
	v_mfma_f32_16x16x32_bf16 v[18:21], v[164:167], v[214:217], v[18:21]
	v_mfma_f32_16x16x32_bf16 v[46:49], v[168:171], v[184:187], v[46:49]
	v_mfma_f32_16x16x32_bf16 v[42:45], v[176:179], v[184:187], v[42:45]
	v_mfma_f32_16x16x32_bf16 v[30:33], v[168:171], v[192:195], v[30:33]
	v_mfma_f32_16x16x32_bf16 v[26:29], v[176:179], v[192:195], v[26:29]
	v_mfma_f32_16x16x32_bf16 v[14:17], v[168:171], v[200:203], v[14:17]
	v_mfma_f32_16x16x32_bf16 v[10:13], v[176:179], v[200:203], v[10:13]
	v_mfma_f32_16x16x32_bf16 v[6:9], v[168:171], v[210:213], v[6:9]
	v_mfma_f32_16x16x32_bf16 v[2:5], v[176:179], v[210:213], v[2:5]
	v_mfma_f32_16x16x32_bf16 v[46:49], v[172:175], v[188:191], v[46:49]
	v_mfma_f32_16x16x32_bf16 v[42:45], v[180:183], v[188:191], v[42:45]
	v_mfma_f32_16x16x32_bf16 v[30:33], v[172:175], v[196:199], v[30:33]
	v_mfma_f32_16x16x32_bf16 v[26:29], v[180:183], v[196:199], v[26:29]
	v_mfma_f32_16x16x32_bf16 v[14:17], v[172:175], v[206:209], v[14:17]
	v_mfma_f32_16x16x32_bf16 v[10:13], v[180:183], v[206:209], v[10:13]
	v_mfma_f32_16x16x32_bf16 v[6:9], v[172:175], v[214:217], v[6:9]
	v_mfma_f32_16x16x32_bf16 v[2:5], v[180:183], v[214:217], v[2:5]
	s_setprio 0
	s_barrier
	ds_read_b128 v[152:155], v149
	ds_read_b128 v[156:159], v149 offset:1024
	ds_read_b128 v[160:163], v149 offset:2048
	ds_read_b128 v[164:167], v149 offset:3072
	ds_read_b128 v[168:171], v150
	ds_read_b128 v[172:175], v150 offset:1024
	ds_read_b128 v[176:179], v150 offset:2048
	ds_read_b128 v[180:183], v150 offset:3072
	s_add_u32 s42, s48, 0x20000
	s_addc_u32 s43, s49, 0
	s_mov_b32 m0, s16
	v_lshl_add_u64 v[226:227], s[42:43], 0, v[136:137]
	ds_read_b128 v[184:187], v148 offset:32768
	ds_read_b128 v[188:191], v148 offset:33792
	ds_read_b128 v[192:195], v148 offset:34816
	ds_read_b128 v[196:199], v148 offset:35840
	ds_read_b128 v[200:203], v148 offset:36864
	ds_read_b128 v[206:209], v148 offset:37888
	ds_read_b128 v[210:213], v148 offset:38912
	ds_read_b128 v[214:217], v148 offset:39936
	global_load_lds_dwordx4 v[226:227], off
	s_mov_b32 m0, s17
	v_lshl_add_u64 v[226:227], s[42:43], 0, v[132:133]
	global_load_lds_dwordx4 v[226:227], off
	s_waitcnt vmcnt(8) lgkmcnt(0)
	s_setprio 1
	s_barrier
	v_mfma_f32_16x16x32_bf16 v[126:129], v[152:155], v[184:187], v[126:129]
	v_mfma_f32_16x16x32_bf16 v[122:125], v[160:163], v[184:187], v[122:125]
	v_mfma_f32_16x16x32_bf16 v[118:121], v[152:155], v[192:195], v[118:121]
	v_mfma_f32_16x16x32_bf16 v[114:117], v[160:163], v[192:195], v[114:117]
	v_mfma_f32_16x16x32_bf16 v[102:105], v[152:155], v[200:203], v[102:105]
	v_mfma_f32_16x16x32_bf16 v[98:101], v[160:163], v[200:203], v[98:101]
	v_mfma_f32_16x16x32_bf16 v[86:89], v[152:155], v[210:213], v[86:89]
	v_mfma_f32_16x16x32_bf16 v[82:85], v[160:163], v[210:213], v[82:85]
	v_mfma_f32_16x16x32_bf16 v[126:129], v[156:159], v[188:191], v[126:129]
	v_mfma_f32_16x16x32_bf16 v[122:125], v[164:167], v[188:191], v[122:125]
	v_mfma_f32_16x16x32_bf16 v[118:121], v[156:159], v[196:199], v[118:121]
	v_mfma_f32_16x16x32_bf16 v[114:117], v[164:167], v[196:199], v[114:117]
	v_mfma_f32_16x16x32_bf16 v[102:105], v[156:159], v[206:209], v[102:105]
	v_mfma_f32_16x16x32_bf16 v[98:101], v[164:167], v[206:209], v[98:101]
	v_mfma_f32_16x16x32_bf16 v[86:89], v[156:159], v[214:217], v[86:89]
	v_mfma_f32_16x16x32_bf16 v[82:85], v[164:167], v[214:217], v[82:85]
	v_mfma_f32_16x16x32_bf16 v[110:113], v[168:171], v[184:187], v[110:113]
	v_mfma_f32_16x16x32_bf16 v[106:109], v[176:179], v[184:187], v[106:109]
	v_mfma_f32_16x16x32_bf16 v[94:97], v[168:171], v[192:195], v[94:97]
	v_mfma_f32_16x16x32_bf16 v[90:93], v[176:179], v[192:195], v[90:93]
	v_mfma_f32_16x16x32_bf16 v[78:81], v[168:171], v[200:203], v[78:81]
	v_mfma_f32_16x16x32_bf16 v[74:77], v[176:179], v[200:203], v[74:77]
	v_mfma_f32_16x16x32_bf16 v[70:73], v[168:171], v[210:213], v[70:73]
	v_mfma_f32_16x16x32_bf16 v[66:69], v[176:179], v[210:213], v[66:69]
	v_mfma_f32_16x16x32_bf16 v[110:113], v[172:175], v[188:191], v[110:113]
	v_mfma_f32_16x16x32_bf16 v[106:109], v[180:183], v[188:191], v[106:109]
	v_mfma_f32_16x16x32_bf16 v[94:97], v[172:175], v[196:199], v[94:97]
	v_mfma_f32_16x16x32_bf16 v[90:93], v[180:183], v[196:199], v[90:93]
	v_mfma_f32_16x16x32_bf16 v[78:81], v[172:175], v[206:209], v[78:81]
	v_mfma_f32_16x16x32_bf16 v[74:77], v[180:183], v[206:209], v[74:77]
	v_mfma_f32_16x16x32_bf16 v[70:73], v[172:175], v[214:217], v[70:73]
	v_mfma_f32_16x16x32_bf16 v[66:69], v[180:183], v[214:217], v[66:69]
	s_setprio 0
	s_barrier
	s_mov_b32 m0, s62
	v_lshl_add_u64 v[218:219], v[218:219], 0, s[10:11]
	s_add_u32 s42, s46, 0x20080
	ds_read_b128 v[184:187], v148 offset:49152
	ds_read_b128 v[188:191], v148 offset:50176
	ds_read_b128 v[192:195], v148 offset:51200
	ds_read_b128 v[196:199], v148 offset:52224
	ds_read_b128 v[200:203], v148 offset:53248
	ds_read_b128 v[206:209], v148 offset:54272
	ds_read_b128 v[210:213], v148 offset:55296
	ds_read_b128 v[214:217], v148 offset:56320
	global_load_lds_dwordx4 v[218:219], off
	v_lshl_add_u64 v[218:219], v[220:221], 0, s[10:11]
	s_mov_b32 m0, s63
	s_addc_u32 s43, s47, 0
	global_load_lds_dwordx4 v[218:219], off
	s_mov_b32 m0, s64
	v_lshl_add_u64 v[218:219], s[42:43], 0, v[134:135]
	global_load_lds_dwordx4 v[218:219], off
	s_mov_b32 m0, s65
	v_lshl_add_u64 v[218:219], s[42:43], 0, v[130:131]
	global_load_lds_dwordx4 v[218:219], off
	s_mov_b32 m0, s25
	v_lshl_add_u64 v[218:219], v[222:223], 0, s[10:11]
	global_load_lds_dwordx4 v[218:219], off
	s_mov_b32 m0, s28
	v_lshl_add_u64 v[218:219], v[224:225], 0, s[10:11]
	global_load_lds_dwordx4 v[218:219], off
	s_waitcnt vmcnt(8) lgkmcnt(0)
	s_setprio 1
	s_barrier
	v_mfma_f32_16x16x32_bf16 v[62:65], v[152:155], v[184:187], v[62:65]
	v_mfma_f32_16x16x32_bf16 v[58:61], v[160:163], v[184:187], v[58:61]
	v_mfma_f32_16x16x32_bf16 v[54:57], v[152:155], v[192:195], v[54:57]
	v_mfma_f32_16x16x32_bf16 v[50:53], v[160:163], v[192:195], v[50:53]
	v_mfma_f32_16x16x32_bf16 v[38:41], v[152:155], v[200:203], v[38:41]
	v_mfma_f32_16x16x32_bf16 v[34:37], v[160:163], v[200:203], v[34:37]
	v_mfma_f32_16x16x32_bf16 v[22:25], v[152:155], v[210:213], v[22:25]
	v_mfma_f32_16x16x32_bf16 v[18:21], v[160:163], v[210:213], v[18:21]
	v_mfma_f32_16x16x32_bf16 v[62:65], v[156:159], v[188:191], v[62:65]
	v_mfma_f32_16x16x32_bf16 v[58:61], v[164:167], v[188:191], v[58:61]
	v_mfma_f32_16x16x32_bf16 v[54:57], v[156:159], v[196:199], v[54:57]
	v_mfma_f32_16x16x32_bf16 v[50:53], v[164:167], v[196:199], v[50:53]
	v_mfma_f32_16x16x32_bf16 v[38:41], v[156:159], v[206:209], v[38:41]
	v_mfma_f32_16x16x32_bf16 v[34:37], v[164:167], v[206:209], v[34:37]
	v_mfma_f32_16x16x32_bf16 v[22:25], v[156:159], v[214:217], v[22:25]
	v_mfma_f32_16x16x32_bf16 v[18:21], v[164:167], v[214:217], v[18:21]
	v_mfma_f32_16x16x32_bf16 v[46:49], v[168:171], v[184:187], v[46:49]
	v_mfma_f32_16x16x32_bf16 v[42:45], v[176:179], v[184:187], v[42:45]
	v_mfma_f32_16x16x32_bf16 v[30:33], v[168:171], v[192:195], v[30:33]
	v_mfma_f32_16x16x32_bf16 v[26:29], v[176:179], v[192:195], v[26:29]
	v_mfma_f32_16x16x32_bf16 v[14:17], v[168:171], v[200:203], v[14:17]
	v_mfma_f32_16x16x32_bf16 v[10:13], v[176:179], v[200:203], v[10:13]
	v_mfma_f32_16x16x32_bf16 v[6:9], v[168:171], v[210:213], v[6:9]
	v_mfma_f32_16x16x32_bf16 v[2:5], v[176:179], v[210:213], v[2:5]
	v_mfma_f32_16x16x32_bf16 v[46:49], v[172:175], v[188:191], v[46:49]
	v_mfma_f32_16x16x32_bf16 v[42:45], v[180:183], v[188:191], v[42:45]
	v_mfma_f32_16x16x32_bf16 v[30:33], v[172:175], v[196:199], v[30:33]
	v_mfma_f32_16x16x32_bf16 v[26:29], v[180:183], v[196:199], v[26:29]
	v_mfma_f32_16x16x32_bf16 v[14:17], v[172:175], v[206:209], v[14:17]
	v_mfma_f32_16x16x32_bf16 v[10:13], v[180:183], v[206:209], v[10:13]
	v_mfma_f32_16x16x32_bf16 v[6:9], v[172:175], v[214:217], v[6:9]
	v_mfma_f32_16x16x32_bf16 v[2:5], v[180:183], v[214:217], v[2:5]
	s_setprio 0
	s_barrier
	s_add_i32 s68, s68, 2
	s_cmp_gt_u32 s68, 5
	s_mov_b64 s[42:43], s[44:45]
	s_cbranch_scc0 .LBB0_384
	s_and_b64 vcc, exec, s[12:13]
	s_cbranch_vccz .LBB0_387
	s_barrier

.LBB0_406:
	s_lshl_b32 s74, s12, 7
	s_add_i32 s12, s12, 2
	v_cndmask_b32_e64 v138, 0, 1, s[66:67]
	s_lshl_b64 s[66:67], s[12:13], 7
	s_and_b64 s[68:69], s[64:65], exec
	s_cselect_b32 s66, 0, s66
	s_cselect_b32 s67, 0, s67
	s_add_u32 s70, s8, s66
	s_addc_u32 s71, s9, s67
	s_lshl_b64 s[66:67], s[12:13], 12
	s_add_u32 s12, s48, s66
	s_addc_u32 s66, s49, s67
	s_and_b64 s[64:65], s[64:65], exec
	s_cselect_b32 s73, s14, s66
	s_cselect_b32 s72, s15, s12
	s_add_u32 s76, s10, s74
	s_addc_u32 s77, s11, 0
	s_add_i32 s91, s62, s16
	s_add_i32 m0, s17, 0xc000
	s_add_i32 s92, s17, 0xe000
	s_add_i32 s88, s91, 0x2000
	s_add_u32 s74, s72, 0x10000
	ds_read_b128 v[146:149], v141
	ds_read_b128 v[150:153], v141 offset:1024
	ds_read_b128 v[154:157], v141 offset:2048
	ds_read_b128 v[158:161], v141 offset:3072
	ds_read_b128 v[162:165], v143
	ds_read_b128 v[166:169], v143 offset:1024
	ds_read_b128 v[170:173], v143 offset:2048
	ds_read_b128 v[174:177], v143 offset:3072
	s_addc_u32 s75, s73, 0
	s_add_i32 s90, s63, s16
	s_add_i32 s89, s90, 0x2000
	s_add_i32 s87, 0, 0x18000
	s_add_i32 s86, 0, 0x1c000
	s_add_u32 s68, s70, 0x10000
	s_addc_u32 s69, s71, 0
	s_add_u32 s64, s72, 0x1000
	s_addc_u32 s65, s73, 0
	s_add_i32 s85, s87, s16
	s_add_i32 s83, s85, 0x2000
	s_add_u32 s66, s72, 0x11000
	s_addc_u32 s67, s73, 0
	s_add_i32 s84, s86, s16
	s_add_i32 s12, s84, 0x2000
	v_cmp_ne_u32_e32 vcc, 1, v138
	v_lshl_add_u64 v[202:203], s[76:77], 0, v[136:137]
	v_lshl_add_u64 v[202:203], v[202:203], 0, s[36:37]
	ds_read_b128 v[178:181], v144
	ds_read_b128 v[182:185], v144 offset:1024
	ds_read_b128 v[186:189], v144 offset:2048
	ds_read_b128 v[190:193], v144 offset:3072
	ds_read_b128 v[194:197], v144 offset:4096
	ds_read_b128 v[198:201], v144 offset:5120
	ds_read_b128 v[206:209], v144 offset:6144
	ds_read_b128 v[210:213], v144 offset:7168
	global_load_lds_dwordx4 v[202:203], off
	v_lshl_add_u64 v[202:203], s[76:77], 0, v[132:133]
	s_mov_b32 m0, s92
	v_lshl_add_u64 v[202:203], v[202:203], 0, s[36:37]
	global_load_lds_dwordx4 v[202:203], off
	s_waitcnt vmcnt(8) lgkmcnt(0)
	s_setprio 1
	s_barrier
	v_mfma_f32_16x16x32_bf16 v[126:129], v[146:149], v[178:181], v[126:129]
	v_mfma_f32_16x16x32_bf16 v[122:125], v[154:157], v[178:181], v[122:125]
	v_mfma_f32_16x16x32_bf16 v[118:121], v[146:149], v[186:189], v[118:121]
	v_mfma_f32_16x16x32_bf16 v[110:113], v[154:157], v[186:189], v[110:113]
	v_mfma_f32_16x16x32_bf16 v[102:105], v[146:149], v[194:197], v[102:105]
	v_mfma_f32_16x16x32_bf16 v[98:101], v[154:157], v[194:197], v[98:101]
	v_mfma_f32_16x16x32_bf16 v[86:89], v[146:149], v[206:209], v[86:89]
	v_mfma_f32_16x16x32_bf16 v[82:85], v[154:157], v[206:209], v[82:85]
	v_mfma_f32_16x16x32_bf16 v[126:129], v[150:153], v[182:185], v[126:129]
	v_mfma_f32_16x16x32_bf16 v[122:125], v[158:161], v[182:185], v[122:125]
	v_mfma_f32_16x16x32_bf16 v[118:121], v[150:153], v[190:193], v[118:121]
	v_mfma_f32_16x16x32_bf16 v[110:113], v[158:161], v[190:193], v[110:113]
	v_mfma_f32_16x16x32_bf16 v[102:105], v[150:153], v[198:201], v[102:105]
	v_mfma_f32_16x16x32_bf16 v[98:101], v[158:161], v[198:201], v[98:101]
	v_mfma_f32_16x16x32_bf16 v[86:89], v[150:153], v[210:213], v[86:89]
	v_mfma_f32_16x16x32_bf16 v[82:85], v[158:161], v[210:213], v[82:85]
	v_mfma_f32_16x16x32_bf16 v[114:117], v[162:165], v[178:181], v[114:117]
	v_mfma_f32_16x16x32_bf16 v[106:109], v[170:173], v[178:181], v[106:109]
	v_mfma_f32_16x16x32_bf16 v[94:97], v[162:165], v[186:189], v[94:97]
	v_mfma_f32_16x16x32_bf16 v[90:93], v[170:173], v[186:189], v[90:93]
	v_mfma_f32_16x16x32_bf16 v[78:81], v[162:165], v[194:197], v[78:81]
	v_mfma_f32_16x16x32_bf16 v[74:77], v[170:173], v[194:197], v[74:77]
	v_mfma_f32_16x16x32_bf16 v[70:73], v[162:165], v[206:209], v[70:73]
	v_mfma_f32_16x16x32_bf16 v[66:69], v[170:173], v[206:209], v[66:69]
	v_mfma_f32_16x16x32_bf16 v[114:117], v[166:169], v[182:185], v[114:117]
	v_mfma_f32_16x16x32_bf16 v[106:109], v[174:177], v[182:185], v[106:109]
	v_mfma_f32_16x16x32_bf16 v[94:97], v[166:169], v[190:193], v[94:97]
	v_mfma_f32_16x16x32_bf16 v[90:93], v[174:177], v[190:193], v[90:93]
	v_mfma_f32_16x16x32_bf16 v[78:81], v[166:169], v[198:201], v[78:81]
	v_mfma_f32_16x16x32_bf16 v[74:77], v[174:177], v[198:201], v[74:77]
	v_mfma_f32_16x16x32_bf16 v[70:73], v[166:169], v[210:213], v[70:73]
	v_mfma_f32_16x16x32_bf16 v[66:69], v[174:177], v[210:213], v[66:69]
	s_setprio 0
	s_barrier
	s_mov_b32 m0, s91
	v_lshl_add_u64 v[202:203], s[72:73], 0, v[134:135]
	ds_read_b128 v[178:181], v144 offset:16384
	ds_read_b128 v[182:185], v144 offset:17408
	ds_read_b128 v[186:189], v144 offset:18432
	ds_read_b128 v[190:193], v144 offset:19456
	ds_read_b128 v[194:197], v144 offset:20480
	ds_read_b128 v[198:201], v144 offset:21504
	ds_read_b128 v[206:209], v144 offset:22528
	ds_read_b128 v[210:213], v144 offset:23552
	global_load_lds_dwordx4 v[202:203], off
	v_lshl_add_u64 v[202:203], s[72:73], 0, v[130:131]
	s_mov_b32 m0, s88
	v_lshl_add_u64 v[214:215], s[70:71], 0, v[132:133]
	global_load_lds_dwordx4 v[202:203], off
	s_mov_b32 m0, s90
	v_lshl_add_u64 v[202:203], s[74:75], 0, v[134:135]
	global_load_lds_dwordx4 v[202:203], off
	s_mov_b32 m0, s89
	v_lshl_add_u64 v[202:203], s[74:75], 0, v[130:131]
	global_load_lds_dwordx4 v[202:203], off
	s_mov_b32 m0, s17
	v_lshl_add_u64 v[202:203], s[70:71], 0, v[136:137]
	global_load_lds_dwordx4 v[202:203], off
	s_mov_b32 m0, s18
	s_nop 0
	global_load_lds_dwordx4 v[214:215], off
	s_waitcnt vmcnt(8) lgkmcnt(0)
	s_setprio 1
	s_barrier
	v_mfma_f32_16x16x32_bf16 v[62:65], v[146:149], v[178:181], v[62:65]
	v_mfma_f32_16x16x32_bf16 v[58:61], v[154:157], v[178:181], v[58:61]
	v_mfma_f32_16x16x32_bf16 v[54:57], v[146:149], v[186:189], v[54:57]
	v_mfma_f32_16x16x32_bf16 v[50:53], v[154:157], v[186:189], v[50:53]
	v_mfma_f32_16x16x32_bf16 v[38:41], v[146:149], v[194:197], v[38:41]
	v_mfma_f32_16x16x32_bf16 v[34:37], v[154:157], v[194:197], v[34:37]
	v_mfma_f32_16x16x32_bf16 v[22:25], v[146:149], v[206:209], v[22:25]
	v_mfma_f32_16x16x32_bf16 v[18:21], v[154:157], v[206:209], v[18:21]
	v_mfma_f32_16x16x32_bf16 v[62:65], v[150:153], v[182:185], v[62:65]
	v_mfma_f32_16x16x32_bf16 v[58:61], v[158:161], v[182:185], v[58:61]
	v_mfma_f32_16x16x32_bf16 v[54:57], v[150:153], v[190:193], v[54:57]
	v_mfma_f32_16x16x32_bf16 v[50:53], v[158:161], v[190:193], v[50:53]
	v_mfma_f32_16x16x32_bf16 v[38:41], v[150:153], v[198:201], v[38:41]
	v_mfma_f32_16x16x32_bf16 v[34:37], v[158:161], v[198:201], v[34:37]
	v_mfma_f32_16x16x32_bf16 v[22:25], v[150:153], v[210:213], v[22:25]
	v_mfma_f32_16x16x32_bf16 v[18:21], v[158:161], v[210:213], v[18:21]
	v_mfma_f32_16x16x32_bf16 v[46:49], v[162:165], v[178:181], v[46:49]
	v_mfma_f32_16x16x32_bf16 v[42:45], v[170:173], v[178:181], v[42:45]
	v_mfma_f32_16x16x32_bf16 v[30:33], v[162:165], v[186:189], v[30:33]
	v_mfma_f32_16x16x32_bf16 v[26:29], v[170:173], v[186:189], v[26:29]
	v_mfma_f32_16x16x32_bf16 v[14:17], v[162:165], v[194:197], v[14:17]
	v_mfma_f32_16x16x32_bf16 v[10:13], v[170:173], v[194:197], v[10:13]
	v_mfma_f32_16x16x32_bf16 v[6:9], v[162:165], v[206:209], v[6:9]
	v_mfma_f32_16x16x32_bf16 v[2:5], v[170:173], v[206:209], v[2:5]
	v_mfma_f32_16x16x32_bf16 v[46:49], v[166:169], v[182:185], v[46:49]
	v_mfma_f32_16x16x32_bf16 v[42:45], v[174:177], v[182:185], v[42:45]
	v_mfma_f32_16x16x32_bf16 v[30:33], v[166:169], v[190:193], v[30:33]
	v_mfma_f32_16x16x32_bf16 v[26:29], v[174:177], v[190:193], v[26:29]
	v_mfma_f32_16x16x32_bf16 v[14:17], v[166:169], v[198:201], v[14:17]
	v_mfma_f32_16x16x32_bf16 v[10:13], v[174:177], v[198:201], v[10:13]
	v_mfma_f32_16x16x32_bf16 v[6:9], v[166:169], v[210:213], v[6:9]
	v_mfma_f32_16x16x32_bf16 v[2:5], v[174:177], v[210:213], v[2:5]
	s_setprio 0
	s_barrier
	v_add_u32_e32 v138, s87, v140
	ds_read_b128 v[146:149], v138
	ds_read_b128 v[150:153], v138 offset:1024
	ds_read_b128 v[154:157], v138 offset:2048
	ds_read_b128 v[158:161], v138 offset:3072
	v_add_u32_e32 v138, s86, v140
	ds_read_b128 v[162:165], v138
	ds_read_b128 v[166:169], v138 offset:1024
	ds_read_b128 v[170:173], v138 offset:2048
	ds_read_b128 v[174:177], v138 offset:3072
	s_mov_b32 m0, s19
	v_lshl_add_u64 v[216:217], s[68:69], 0, v[136:137]
	ds_read_b128 v[178:181], v144 offset:32768
	ds_read_b128 v[182:185], v144 offset:33792
	ds_read_b128 v[186:189], v144 offset:34816
	ds_read_b128 v[190:193], v144 offset:35840
	ds_read_b128 v[194:197], v144 offset:36864
	ds_read_b128 v[198:201], v144 offset:37888
	ds_read_b128 v[206:209], v144 offset:38912
	ds_read_b128 v[210:213], v144 offset:39936
	global_load_lds_dwordx4 v[216:217], off
	s_mov_b32 m0, s24
	v_lshl_add_u64 v[216:217], s[68:69], 0, v[132:133]
	global_load_lds_dwordx4 v[216:217], off
	s_waitcnt vmcnt(8) lgkmcnt(0)
	s_setprio 1
	s_barrier
	v_mfma_f32_16x16x32_bf16 v[126:129], v[146:149], v[178:181], v[126:129]
	v_mfma_f32_16x16x32_bf16 v[122:125], v[154:157], v[178:181], v[122:125]
	v_mfma_f32_16x16x32_bf16 v[118:121], v[146:149], v[186:189], v[118:121]
	v_mfma_f32_16x16x32_bf16 v[110:113], v[154:157], v[186:189], v[110:113]
	v_mfma_f32_16x16x32_bf16 v[102:105], v[146:149], v[194:197], v[102:105]
	v_mfma_f32_16x16x32_bf16 v[98:101], v[154:157], v[194:197], v[98:101]
	v_mfma_f32_16x16x32_bf16 v[86:89], v[146:149], v[206:209], v[86:89]
	v_mfma_f32_16x16x32_bf16 v[82:85], v[154:157], v[206:209], v[82:85]
	v_mfma_f32_16x16x32_bf16 v[126:129], v[150:153], v[182:185], v[126:129]
	v_mfma_f32_16x16x32_bf16 v[122:125], v[158:161], v[182:185], v[122:125]
	v_mfma_f32_16x16x32_bf16 v[118:121], v[150:153], v[190:193], v[118:121]
	v_mfma_f32_16x16x32_bf16 v[110:113], v[158:161], v[190:193], v[110:113]
	v_mfma_f32_16x16x32_bf16 v[102:105], v[150:153], v[198:201], v[102:105]
	v_mfma_f32_16x16x32_bf16 v[98:101], v[158:161], v[198:201], v[98:101]
	v_mfma_f32_16x16x32_bf16 v[86:89], v[150:153], v[210:213], v[86:89]
	v_mfma_f32_16x16x32_bf16 v[82:85], v[158:161], v[210:213], v[82:85]
	v_mfma_f32_16x16x32_bf16 v[114:117], v[162:165], v[178:181], v[114:117]
	v_mfma_f32_16x16x32_bf16 v[106:109], v[170:173], v[178:181], v[106:109]
	v_mfma_f32_16x16x32_bf16 v[94:97], v[162:165], v[186:189], v[94:97]
	v_mfma_f32_16x16x32_bf16 v[90:93], v[170:173], v[186:189], v[90:93]
	v_mfma_f32_16x16x32_bf16 v[78:81], v[162:165], v[194:197], v[78:81]
	v_mfma_f32_16x16x32_bf16 v[74:77], v[170:173], v[194:197], v[74:77]
	v_mfma_f32_16x16x32_bf16 v[70:73], v[162:165], v[206:209], v[70:73]
	v_mfma_f32_16x16x32_bf16 v[66:69], v[170:173], v[206:209], v[66:69]
	v_mfma_f32_16x16x32_bf16 v[114:117], v[166:169], v[182:185], v[114:117]
	v_mfma_f32_16x16x32_bf16 v[106:109], v[174:177], v[182:185], v[106:109]
	v_mfma_f32_16x16x32_bf16 v[94:97], v[166:169], v[190:193], v[94:97]
	v_mfma_f32_16x16x32_bf16 v[90:93], v[174:177], v[190:193], v[90:93]
	v_mfma_f32_16x16x32_bf16 v[78:81], v[166:169], v[198:201], v[78:81]
	v_mfma_f32_16x16x32_bf16 v[74:77], v[174:177], v[198:201], v[74:77]
	v_mfma_f32_16x16x32_bf16 v[70:73], v[166:169], v[210:213], v[70:73]
	v_mfma_f32_16x16x32_bf16 v[66:69], v[174:177], v[210:213], v[66:69]
	s_setprio 0
	s_barrier
	s_mov_b32 m0, s85
	v_lshl_add_u64 v[216:217], s[64:65], 0, v[134:135]
	ds_read_b128 v[178:181], v144 offset:49152
	ds_read_b128 v[182:185], v144 offset:50176
	ds_read_b128 v[186:189], v144 offset:51200
	ds_read_b128 v[190:193], v144 offset:52224
	ds_read_b128 v[194:197], v144 offset:53248
	ds_read_b128 v[198:201], v144 offset:54272
	ds_read_b128 v[206:209], v144 offset:55296
	ds_read_b128 v[210:213], v144 offset:56320
	global_load_lds_dwordx4 v[216:217], off
	v_lshl_add_u64 v[216:217], s[64:65], 0, v[130:131]
	s_mov_b32 m0, s83
	v_lshl_add_u64 v[202:203], v[202:203], 0, s[36:37]
	global_load_lds_dwordx4 v[216:217], off
	s_mov_b32 m0, s84
	v_lshl_add_u64 v[216:217], s[66:67], 0, v[134:135]
	global_load_lds_dwordx4 v[216:217], off
	s_mov_b32 m0, s12
	v_lshl_add_u64 v[216:217], s[66:67], 0, v[130:131]
	global_load_lds_dwordx4 v[216:217], off
	s_mov_b32 m0, s31
	s_nop 0
	global_load_lds_dwordx4 v[202:203], off
	s_mov_b32 m0, s33
	v_lshl_add_u64 v[202:203], v[214:215], 0, s[36:37]
	global_load_lds_dwordx4 v[202:203], off
	s_waitcnt vmcnt(8) lgkmcnt(0)
	s_setprio 1
	s_barrier
	v_mfma_f32_16x16x32_bf16 v[62:65], v[146:149], v[178:181], v[62:65]
	v_mfma_f32_16x16x32_bf16 v[58:61], v[154:157], v[178:181], v[58:61]
	v_mfma_f32_16x16x32_bf16 v[54:57], v[146:149], v[186:189], v[54:57]
	v_mfma_f32_16x16x32_bf16 v[50:53], v[154:157], v[186:189], v[50:53]
	v_mfma_f32_16x16x32_bf16 v[38:41], v[146:149], v[194:197], v[38:41]
	v_mfma_f32_16x16x32_bf16 v[34:37], v[154:157], v[194:197], v[34:37]
	v_mfma_f32_16x16x32_bf16 v[22:25], v[146:149], v[206:209], v[22:25]
	v_mfma_f32_16x16x32_bf16 v[18:21], v[154:157], v[206:209], v[18:21]
	v_mfma_f32_16x16x32_bf16 v[62:65], v[150:153], v[182:185], v[62:65]
	v_mfma_f32_16x16x32_bf16 v[58:61], v[158:161], v[182:185], v[58:61]
	v_mfma_f32_16x16x32_bf16 v[54:57], v[150:153], v[190:193], v[54:57]
	v_mfma_f32_16x16x32_bf16 v[50:53], v[158:161], v[190:193], v[50:53]
	v_mfma_f32_16x16x32_bf16 v[38:41], v[150:153], v[198:201], v[38:41]
	v_mfma_f32_16x16x32_bf16 v[34:37], v[158:161], v[198:201], v[34:37]
	v_mfma_f32_16x16x32_bf16 v[22:25], v[150:153], v[210:213], v[22:25]
	v_mfma_f32_16x16x32_bf16 v[18:21], v[158:161], v[210:213], v[18:21]
	v_mfma_f32_16x16x32_bf16 v[46:49], v[162:165], v[178:181], v[46:49]
	v_mfma_f32_16x16x32_bf16 v[42:45], v[170:173], v[178:181], v[42:45]
	v_mfma_f32_16x16x32_bf16 v[30:33], v[162:165], v[186:189], v[30:33]
	v_mfma_f32_16x16x32_bf16 v[26:29], v[170:173], v[186:189], v[26:29]
	v_mfma_f32_16x16x32_bf16 v[14:17], v[162:165], v[194:197], v[14:17]
	v_mfma_f32_16x16x32_bf16 v[10:13], v[170:173], v[194:197], v[10:13]
	v_mfma_f32_16x16x32_bf16 v[6:9], v[162:165], v[206:209], v[6:9]
	v_mfma_f32_16x16x32_bf16 v[2:5], v[170:173], v[206:209], v[2:5]
	v_mfma_f32_16x16x32_bf16 v[46:49], v[166:169], v[182:185], v[46:49]
	v_mfma_f32_16x16x32_bf16 v[42:45], v[174:177], v[182:185], v[42:45]
	v_mfma_f32_16x16x32_bf16 v[30:33], v[166:169], v[190:193], v[30:33]
	v_mfma_f32_16x16x32_bf16 v[26:29], v[174:177], v[190:193], v[26:29]
	v_mfma_f32_16x16x32_bf16 v[14:17], v[166:169], v[198:201], v[14:17]
	v_mfma_f32_16x16x32_bf16 v[10:13], v[174:177], v[198:201], v[10:13]
	v_mfma_f32_16x16x32_bf16 v[6:9], v[166:169], v[210:213], v[6:9]
	v_mfma_f32_16x16x32_bf16 v[2:5], v[174:177], v[210:213], v[2:5]
	s_setprio 0
	s_barrier
	s_mov_b64 s[66:67], 0
	s_mov_b64 s[64:65], -1
	s_mov_b32 s12, 2
	s_cbranch_vccz .LBB0_406
	s_and_b64 vcc, exec, s[22:23]
	s_cbranch_vccz .LBB0_409
	s_barrier

.LBB0_476:
	s_add_u32 s22, s2, s49
	s_addc_u32 s23, s3, s29
	s_and_b64 s[26:27], s[20:21], exec
	s_cselect_b32 s63, s23, s37
	s_cselect_b32 s64, s22, s36
	s_add_u32 s26, s16, s12
	s_addc_u32 s27, s17, s13
	s_and_b64 s[42:43], s[20:21], exec
	s_cselect_b32 s65, s27, s39
	s_cselect_b32 s66, s26, s38
	s_add_u32 s36, s36, 0x20080
	s_addc_u32 s37, s37, 0
	s_add_u32 s67, s38, 0x100
	s_addc_u32 s68, s39, 0
	s_mov_b32 s69, -2
	ds_read_b128 v[148:151], v144
	ds_read_b128 v[152:155], v144 offset:1024
	ds_read_b128 v[156:159], v144 offset:2048
	ds_read_b128 v[160:163], v144 offset:3072
	ds_read_b128 v[164:167], v145
	ds_read_b128 v[168:171], v145 offset:1024
	ds_read_b128 v[172:175], v145 offset:2048
	ds_read_b128 v[176:179], v145 offset:3072
	s_add_u32 s38, s36, 0xfffe0080
	s_addc_u32 s39, s37, -1
	s_cmp_eq_u32 s69, 4
	s_cselect_b32 s43, s63, s39
	s_cselect_b32 s42, s64, s38
	s_cselect_b32 s39, s65, s68
	s_cselect_b32 s38, s66, s67
	v_lshl_add_u64 v[214:215], s[36:37], 0, v[138:139]
	s_add_i32 m0, s19, 0xc000
	ds_read_b128 v[180:183], v146
	ds_read_b128 v[184:187], v146 offset:1024
	ds_read_b128 v[188:191], v146 offset:2048
	ds_read_b128 v[192:195], v146 offset:3072
	ds_read_b128 v[196:199], v146 offset:4096
	ds_read_b128 v[200:203], v146 offset:5120
	ds_read_b128 v[206:209], v146 offset:6144
	ds_read_b128 v[210:213], v146 offset:7168
	global_load_lds_dwordx4 v[214:215], off
	s_add_i32 m0, s19, 0xe000
	v_lshl_add_u64 v[214:215], s[36:37], 0, v[140:141]
	global_load_lds_dwordx4 v[214:215], off
	s_waitcnt vmcnt(8) lgkmcnt(0)
	s_setprio 1
	s_barrier
	v_mfma_f32_16x16x32_bf16 v[126:129], v[148:151], v[180:183], 0
	v_mfma_f32_16x16x32_bf16 v[122:125], v[156:159], v[180:183], 0
	v_mfma_f32_16x16x32_bf16 v[118:121], v[148:151], v[188:191], 0
	v_mfma_f32_16x16x32_bf16 v[114:117], v[156:159], v[188:191], 0
	v_mfma_f32_16x16x32_bf16 v[102:105], v[148:151], v[196:199], 0
	v_mfma_f32_16x16x32_bf16 v[98:101], v[156:159], v[196:199], 0
	v_mfma_f32_16x16x32_bf16 v[86:89], v[148:151], v[206:209], 0
	v_mfma_f32_16x16x32_bf16 v[82:85], v[156:159], v[206:209], 0
	v_mfma_f32_16x16x32_bf16 v[126:129], v[152:155], v[184:187], v[126:129]
	v_mfma_f32_16x16x32_bf16 v[122:125], v[160:163], v[184:187], v[122:125]
	v_mfma_f32_16x16x32_bf16 v[118:121], v[152:155], v[192:195], v[118:121]
	v_mfma_f32_16x16x32_bf16 v[114:117], v[160:163], v[192:195], v[114:117]
	v_mfma_f32_16x16x32_bf16 v[102:105], v[152:155], v[200:203], v[102:105]
	v_mfma_f32_16x16x32_bf16 v[98:101], v[160:163], v[200:203], v[98:101]
	v_mfma_f32_16x16x32_bf16 v[86:89], v[152:155], v[210:213], v[86:89]
	v_mfma_f32_16x16x32_bf16 v[82:85], v[160:163], v[210:213], v[82:85]
	v_mfma_f32_16x16x32_bf16 v[110:113], v[164:167], v[180:183], 0
	v_mfma_f32_16x16x32_bf16 v[106:109], v[172:175], v[180:183], 0
	v_mfma_f32_16x16x32_bf16 v[94:97], v[164:167], v[188:191], 0
	v_mfma_f32_16x16x32_bf16 v[90:93], v[172:175], v[188:191], 0
	v_mfma_f32_16x16x32_bf16 v[78:81], v[164:167], v[196:199], 0
	v_mfma_f32_16x16x32_bf16 v[74:77], v[172:175], v[196:199], 0
	v_mfma_f32_16x16x32_bf16 v[70:73], v[164:167], v[206:209], 0
	v_mfma_f32_16x16x32_bf16 v[66:69], v[172:175], v[206:209], 0
	v_mfma_f32_16x16x32_bf16 v[110:113], v[168:171], v[184:187], v[110:113]
	v_mfma_f32_16x16x32_bf16 v[106:109], v[176:179], v[184:187], v[106:109]
	v_mfma_f32_16x16x32_bf16 v[94:97], v[168:171], v[192:195], v[94:97]
	v_mfma_f32_16x16x32_bf16 v[90:93], v[176:179], v[192:195], v[90:93]
	v_mfma_f32_16x16x32_bf16 v[78:81], v[168:171], v[200:203], v[78:81]
	v_mfma_f32_16x16x32_bf16 v[74:77], v[176:179], v[200:203], v[74:77]
	v_mfma_f32_16x16x32_bf16 v[70:73], v[168:171], v[210:213], v[70:73]
	v_mfma_f32_16x16x32_bf16 v[66:69], v[176:179], v[210:213], v[66:69]
	s_setprio 0
	s_barrier
	s_add_i32 s70, s35, s18
	v_lshl_add_u64 v[214:215], s[38:39], 0, v[134:135]
	s_mov_b32 m0, s70
	ds_read_b128 v[180:183], v146 offset:16384
	ds_read_b128 v[184:187], v146 offset:17408
	ds_read_b128 v[188:191], v146 offset:18432
	ds_read_b128 v[192:195], v146 offset:19456
	ds_read_b128 v[196:199], v146 offset:20480
	ds_read_b128 v[200:203], v146 offset:21504
	ds_read_b128 v[206:209], v146 offset:22528
	ds_read_b128 v[210:213], v146 offset:23552
	global_load_lds_dwordx4 v[214:215], off
	s_add_i32 m0, s70, 0x2000
	s_add_u32 s70, s38, 0x200000
	v_lshl_add_u64 v[216:217], s[38:39], 0, v[130:131]
	s_addc_u32 s71, s39, 0
	s_add_i32 s72, s44, s18
	global_load_lds_dwordx4 v[216:217], off
	v_lshl_add_u64 v[218:219], s[70:71], 0, v[134:135]
	s_mov_b32 m0, s72
	v_lshl_add_u64 v[220:221], s[42:43], 0, v[132:133]
	global_load_lds_dwordx4 v[218:219], off
	s_add_i32 m0, s72, 0x2000
	v_lshl_add_u64 v[218:219], s[70:71], 0, v[130:131]
	global_load_lds_dwordx4 v[218:219], off
	s_mov_b32 m0, s19
	v_lshl_add_u64 v[218:219], s[42:43], 0, v[136:137]
	global_load_lds_dwordx4 v[218:219], off
	s_mov_b32 m0, s24
	s_nop 0
	global_load_lds_dwordx4 v[220:221], off
	s_waitcnt vmcnt(8) lgkmcnt(0)
	s_setprio 1
	s_barrier
	v_mfma_f32_16x16x32_bf16 v[62:65], v[148:151], v[180:183], 0
	v_mfma_f32_16x16x32_bf16 v[58:61], v[156:159], v[180:183], 0
	v_mfma_f32_16x16x32_bf16 v[54:57], v[148:151], v[188:191], 0
	v_mfma_f32_16x16x32_bf16 v[50:53], v[156:159], v[188:191], 0
	v_mfma_f32_16x16x32_bf16 v[38:41], v[148:151], v[196:199], 0
	v_mfma_f32_16x16x32_bf16 v[34:37], v[156:159], v[196:199], 0
	v_mfma_f32_16x16x32_bf16 v[22:25], v[148:151], v[206:209], 0
	v_mfma_f32_16x16x32_bf16 v[18:21], v[156:159], v[206:209], 0
	v_mfma_f32_16x16x32_bf16 v[62:65], v[152:155], v[184:187], v[62:65]
	v_mfma_f32_16x16x32_bf16 v[58:61], v[160:163], v[184:187], v[58:61]
	v_mfma_f32_16x16x32_bf16 v[54:57], v[152:155], v[192:195], v[54:57]
	v_mfma_f32_16x16x32_bf16 v[50:53], v[160:163], v[192:195], v[50:53]
	v_mfma_f32_16x16x32_bf16 v[38:41], v[152:155], v[200:203], v[38:41]
	v_mfma_f32_16x16x32_bf16 v[34:37], v[160:163], v[200:203], v[34:37]
	v_mfma_f32_16x16x32_bf16 v[22:25], v[152:155], v[210:213], v[22:25]
	v_mfma_f32_16x16x32_bf16 v[18:21], v[160:163], v[210:213], v[18:21]
	v_mfma_f32_16x16x32_bf16 v[46:49], v[164:167], v[180:183], 0
	v_mfma_f32_16x16x32_bf16 v[42:45], v[172:175], v[180:183], 0
	v_mfma_f32_16x16x32_bf16 v[30:33], v[164:167], v[188:191], 0
	v_mfma_f32_16x16x32_bf16 v[26:29], v[172:175], v[188:191], 0
	v_mfma_f32_16x16x32_bf16 v[14:17], v[164:167], v[196:199], 0
	v_mfma_f32_16x16x32_bf16 v[10:13], v[172:175], v[196:199], 0
	v_mfma_f32_16x16x32_bf16 v[6:9], v[164:167], v[206:209], 0
	v_mfma_f32_16x16x32_bf16 v[2:5], v[172:175], v[206:209], 0
	v_mfma_f32_16x16x32_bf16 v[46:49], v[168:171], v[184:187], v[46:49]
	v_mfma_f32_16x16x32_bf16 v[42:45], v[176:179], v[184:187], v[42:45]
	v_mfma_f32_16x16x32_bf16 v[30:33], v[168:171], v[192:195], v[30:33]
	v_mfma_f32_16x16x32_bf16 v[26:29], v[176:179], v[192:195], v[26:29]
	v_mfma_f32_16x16x32_bf16 v[14:17], v[168:171], v[200:203], v[14:17]
	v_mfma_f32_16x16x32_bf16 v[10:13], v[176:179], v[200:203], v[10:13]
	v_mfma_f32_16x16x32_bf16 v[6:9], v[168:171], v[210:213], v[6:9]
	v_mfma_f32_16x16x32_bf16 v[2:5], v[176:179], v[210:213], v[2:5]
	s_setprio 0
	s_barrier
	s_add_i32 s70, 0, 0x18000
	v_add_u32_e32 v147, s70, v143
	s_add_i32 s71, 0, 0x1c000
	ds_read_b128 v[148:151], v147
	ds_read_b128 v[152:155], v147 offset:1024
	ds_read_b128 v[156:159], v147 offset:2048
	ds_read_b128 v[160:163], v147 offset:3072
	v_add_u32_e32 v147, s71, v143
	ds_read_b128 v[164:167], v147
	ds_read_b128 v[168:171], v147 offset:1024
	ds_read_b128 v[172:175], v147 offset:2048
	ds_read_b128 v[176:179], v147 offset:3072
	s_add_u32 s42, s42, 0x20000
	s_addc_u32 s43, s43, 0
	s_mov_b32 m0, s25
	v_lshl_add_u64 v[222:223], s[42:43], 0, v[136:137]
	ds_read_b128 v[180:183], v146 offset:32768
	ds_read_b128 v[184:187], v146 offset:33792
	ds_read_b128 v[188:191], v146 offset:34816
	ds_read_b128 v[192:195], v146 offset:35840
	ds_read_b128 v[196:199], v146 offset:36864
	ds_read_b128 v[200:203], v146 offset:37888
	ds_read_b128 v[206:209], v146 offset:38912
	ds_read_b128 v[210:213], v146 offset:39936
	global_load_lds_dwordx4 v[222:223], off
	s_mov_b32 m0, s28
	v_lshl_add_u64 v[222:223], s[42:43], 0, v[132:133]
	global_load_lds_dwordx4 v[222:223], off
	s_waitcnt vmcnt(8) lgkmcnt(0)
	s_setprio 1
	s_barrier
	v_mfma_f32_16x16x32_bf16 v[126:129], v[148:151], v[180:183], v[126:129]
	v_mfma_f32_16x16x32_bf16 v[122:125], v[156:159], v[180:183], v[122:125]
	v_mfma_f32_16x16x32_bf16 v[118:121], v[148:151], v[188:191], v[118:121]
	v_mfma_f32_16x16x32_bf16 v[114:117], v[156:159], v[188:191], v[114:117]
	v_mfma_f32_16x16x32_bf16 v[102:105], v[148:151], v[196:199], v[102:105]
	v_mfma_f32_16x16x32_bf16 v[98:101], v[156:159], v[196:199], v[98:101]
	v_mfma_f32_16x16x32_bf16 v[86:89], v[148:151], v[206:209], v[86:89]
	v_mfma_f32_16x16x32_bf16 v[82:85], v[156:159], v[206:209], v[82:85]
	v_mfma_f32_16x16x32_bf16 v[126:129], v[152:155], v[184:187], v[126:129]
	v_mfma_f32_16x16x32_bf16 v[122:125], v[160:163], v[184:187], v[122:125]
	v_mfma_f32_16x16x32_bf16 v[118:121], v[152:155], v[192:195], v[118:121]
	v_mfma_f32_16x16x32_bf16 v[114:117], v[160:163], v[192:195], v[114:117]
	v_mfma_f32_16x16x32_bf16 v[102:105], v[152:155], v[200:203], v[102:105]
	v_mfma_f32_16x16x32_bf16 v[98:101], v[160:163], v[200:203], v[98:101]
	v_mfma_f32_16x16x32_bf16 v[86:89], v[152:155], v[210:213], v[86:89]
	v_mfma_f32_16x16x32_bf16 v[82:85], v[160:163], v[210:213], v[82:85]
	v_mfma_f32_16x16x32_bf16 v[110:113], v[164:167], v[180:183], v[110:113]
	v_mfma_f32_16x16x32_bf16 v[106:109], v[172:175], v[180:183], v[106:109]
	v_mfma_f32_16x16x32_bf16 v[94:97], v[164:167], v[188:191], v[94:97]
	v_mfma_f32_16x16x32_bf16 v[90:93], v[172:175], v[188:191], v[90:93]
	v_mfma_f32_16x16x32_bf16 v[78:81], v[164:167], v[196:199], v[78:81]
	v_mfma_f32_16x16x32_bf16 v[74:77], v[172:175], v[196:199], v[74:77]
	v_mfma_f32_16x16x32_bf16 v[70:73], v[164:167], v[206:209], v[70:73]
	v_mfma_f32_16x16x32_bf16 v[66:69], v[172:175], v[206:209], v[66:69]
	v_mfma_f32_16x16x32_bf16 v[110:113], v[168:171], v[184:187], v[110:113]
	v_mfma_f32_16x16x32_bf16 v[106:109], v[176:179], v[184:187], v[106:109]
	v_mfma_f32_16x16x32_bf16 v[94:97], v[168:171], v[192:195], v[94:97]
	v_mfma_f32_16x16x32_bf16 v[90:93], v[176:179], v[192:195], v[90:93]
	v_mfma_f32_16x16x32_bf16 v[78:81], v[168:171], v[200:203], v[78:81]
	v_mfma_f32_16x16x32_bf16 v[74:77], v[176:179], v[200:203], v[74:77]
	v_mfma_f32_16x16x32_bf16 v[70:73], v[168:171], v[210:213], v[70:73]
	v_mfma_f32_16x16x32_bf16 v[66:69], v[176:179], v[210:213], v[66:69]
	s_setprio 0
	s_barrier
	s_add_i32 s42, s70, s18
	v_lshl_add_u64 v[214:215], v[214:215], 0, s[8:9]
	s_mov_b32 m0, s42
	ds_read_b128 v[180:183], v146 offset:49152
	ds_read_b128 v[184:187], v146 offset:50176
	ds_read_b128 v[188:191], v146 offset:51200
	ds_read_b128 v[192:195], v146 offset:52224
	ds_read_b128 v[196:199], v146 offset:53248
	ds_read_b128 v[200:203], v146 offset:54272
	ds_read_b128 v[206:209], v146 offset:55296
	ds_read_b128 v[210:213], v146 offset:56320
	global_load_lds_dwordx4 v[214:215], off
	s_add_i32 m0, s42, 0x2000
	s_add_u32 s38, s38, 0x200080
	v_lshl_add_u64 v[214:215], v[216:217], 0, s[8:9]
	s_addc_u32 s39, s39, 0
	s_add_i32 s42, s71, s18
	global_load_lds_dwordx4 v[214:215], off
	s_mov_b32 m0, s42
	v_lshl_add_u64 v[214:215], s[38:39], 0, v[134:135]
	global_load_lds_dwordx4 v[214:215], off
	s_add_i32 m0, s42, 0x2000
	v_lshl_add_u64 v[214:215], s[38:39], 0, v[130:131]
	global_load_lds_dwordx4 v[214:215], off
	s_mov_b32 m0, s33
	v_lshl_add_u64 v[214:215], v[218:219], 0, s[8:9]
	global_load_lds_dwordx4 v[214:215], off
	s_mov_b32 m0, s34
	v_lshl_add_u64 v[214:215], v[220:221], 0, s[8:9]
	global_load_lds_dwordx4 v[214:215], off
	s_waitcnt vmcnt(8) lgkmcnt(0)
	s_setprio 1
	s_barrier
	v_mfma_f32_16x16x32_bf16 v[62:65], v[148:151], v[180:183], v[62:65]
	v_mfma_f32_16x16x32_bf16 v[58:61], v[156:159], v[180:183], v[58:61]
	v_mfma_f32_16x16x32_bf16 v[54:57], v[148:151], v[188:191], v[54:57]
	v_mfma_f32_16x16x32_bf16 v[50:53], v[156:159], v[188:191], v[50:53]
	v_mfma_f32_16x16x32_bf16 v[38:41], v[148:151], v[196:199], v[38:41]
	v_mfma_f32_16x16x32_bf16 v[34:37], v[156:159], v[196:199], v[34:37]
	v_mfma_f32_16x16x32_bf16 v[22:25], v[148:151], v[206:209], v[22:25]
	v_mfma_f32_16x16x32_bf16 v[18:21], v[156:159], v[206:209], v[18:21]
	v_mfma_f32_16x16x32_bf16 v[62:65], v[152:155], v[184:187], v[62:65]
	v_mfma_f32_16x16x32_bf16 v[58:61], v[160:163], v[184:187], v[58:61]
	v_mfma_f32_16x16x32_bf16 v[54:57], v[152:155], v[192:195], v[54:57]
	v_mfma_f32_16x16x32_bf16 v[50:53], v[160:163], v[192:195], v[50:53]
	v_mfma_f32_16x16x32_bf16 v[38:41], v[152:155], v[200:203], v[38:41]
	v_mfma_f32_16x16x32_bf16 v[34:37], v[160:163], v[200:203], v[34:37]
	v_mfma_f32_16x16x32_bf16 v[22:25], v[152:155], v[210:213], v[22:25]
	v_mfma_f32_16x16x32_bf16 v[18:21], v[160:163], v[210:213], v[18:21]
	v_mfma_f32_16x16x32_bf16 v[46:49], v[164:167], v[180:183], v[46:49]
	v_mfma_f32_16x16x32_bf16 v[42:45], v[172:175], v[180:183], v[42:45]
	v_mfma_f32_16x16x32_bf16 v[30:33], v[164:167], v[188:191], v[30:33]
	v_mfma_f32_16x16x32_bf16 v[26:29], v[172:175], v[188:191], v[26:29]
	v_mfma_f32_16x16x32_bf16 v[14:17], v[164:167], v[196:199], v[14:17]
	v_mfma_f32_16x16x32_bf16 v[10:13], v[172:175], v[196:199], v[10:13]
	v_mfma_f32_16x16x32_bf16 v[6:9], v[164:167], v[206:209], v[6:9]
	v_mfma_f32_16x16x32_bf16 v[2:5], v[172:175], v[206:209], v[2:5]
	v_mfma_f32_16x16x32_bf16 v[46:49], v[168:171], v[184:187], v[46:49]
	v_mfma_f32_16x16x32_bf16 v[42:45], v[176:179], v[184:187], v[42:45]
	v_mfma_f32_16x16x32_bf16 v[30:33], v[168:171], v[192:195], v[30:33]
	v_mfma_f32_16x16x32_bf16 v[26:29], v[176:179], v[192:195], v[26:29]
	v_mfma_f32_16x16x32_bf16 v[14:17], v[168:171], v[200:203], v[14:17]
	v_mfma_f32_16x16x32_bf16 v[10:13], v[176:179], v[200:203], v[10:13]
	v_mfma_f32_16x16x32_bf16 v[6:9], v[168:171], v[210:213], v[6:9]
	v_mfma_f32_16x16x32_bf16 v[2:5], v[176:179], v[210:213], v[2:5]
	s_setprio 0
	s_barrier
	s_add_i32 s69, s69, 2
	s_add_u32 s36, s36, 0x100
	s_addc_u32 s37, s37, 0
	s_add_u32 s67, s67, 0x100
	s_addc_u32 s68, s68, 0
	s_cmp_gt_u32 s69, 5
.LBB0_477:
	ds_read_b128 v[148:151], v144
	ds_read_b128 v[152:155], v144 offset:1024
	ds_read_b128 v[156:159], v144 offset:2048
	ds_read_b128 v[160:163], v144 offset:3072
	ds_read_b128 v[164:167], v145
	ds_read_b128 v[168:171], v145 offset:1024
	ds_read_b128 v[172:175], v145 offset:2048
	ds_read_b128 v[176:179], v145 offset:3072
	s_add_u32 s38, s36, 0xfffe0080
	s_addc_u32 s39, s37, -1
	s_cmp_eq_u32 s69, 4
	s_cselect_b32 s43, s63, s39
	s_cselect_b32 s42, s64, s38
	s_cselect_b32 s39, s65, s68
	s_cselect_b32 s38, s66, s67
	v_lshl_add_u64 v[214:215], s[36:37], 0, v[138:139]
	s_add_i32 m0, s19, 0xc000
	ds_read_b128 v[180:183], v146
	ds_read_b128 v[184:187], v146 offset:1024
	ds_read_b128 v[188:191], v146 offset:2048
	ds_read_b128 v[192:195], v146 offset:3072
	ds_read_b128 v[196:199], v146 offset:4096
	ds_read_b128 v[200:203], v146 offset:5120
	ds_read_b128 v[206:209], v146 offset:6144
	ds_read_b128 v[210:213], v146 offset:7168
	global_load_lds_dwordx4 v[214:215], off
	s_add_i32 m0, s19, 0xe000
	v_lshl_add_u64 v[214:215], s[36:37], 0, v[140:141]
	global_load_lds_dwordx4 v[214:215], off
	s_waitcnt vmcnt(8) lgkmcnt(0)
	s_setprio 1
	s_barrier
	v_mfma_f32_16x16x32_bf16 v[126:129], v[148:151], v[180:183], v[126:129]
	v_mfma_f32_16x16x32_bf16 v[122:125], v[156:159], v[180:183], v[122:125]
	v_mfma_f32_16x16x32_bf16 v[118:121], v[148:151], v[188:191], v[118:121]
	v_mfma_f32_16x16x32_bf16 v[114:117], v[156:159], v[188:191], v[114:117]
	v_mfma_f32_16x16x32_bf16 v[102:105], v[148:151], v[196:199], v[102:105]
	v_mfma_f32_16x16x32_bf16 v[98:101], v[156:159], v[196:199], v[98:101]
	v_mfma_f32_16x16x32_bf16 v[86:89], v[148:151], v[206:209], v[86:89]
	v_mfma_f32_16x16x32_bf16 v[82:85], v[156:159], v[206:209], v[82:85]
	v_mfma_f32_16x16x32_bf16 v[126:129], v[152:155], v[184:187], v[126:129]
	v_mfma_f32_16x16x32_bf16 v[122:125], v[160:163], v[184:187], v[122:125]
	v_mfma_f32_16x16x32_bf16 v[118:121], v[152:155], v[192:195], v[118:121]
	v_mfma_f32_16x16x32_bf16 v[114:117], v[160:163], v[192:195], v[114:117]
	v_mfma_f32_16x16x32_bf16 v[102:105], v[152:155], v[200:203], v[102:105]
	v_mfma_f32_16x16x32_bf16 v[98:101], v[160:163], v[200:203], v[98:101]
	v_mfma_f32_16x16x32_bf16 v[86:89], v[152:155], v[210:213], v[86:89]
	v_mfma_f32_16x16x32_bf16 v[82:85], v[160:163], v[210:213], v[82:85]
	v_mfma_f32_16x16x32_bf16 v[110:113], v[164:167], v[180:183], v[110:113]
	v_mfma_f32_16x16x32_bf16 v[106:109], v[172:175], v[180:183], v[106:109]
	v_mfma_f32_16x16x32_bf16 v[94:97], v[164:167], v[188:191], v[94:97]
	v_mfma_f32_16x16x32_bf16 v[90:93], v[172:175], v[188:191], v[90:93]
	v_mfma_f32_16x16x32_bf16 v[78:81], v[164:167], v[196:199], v[78:81]
	v_mfma_f32_16x16x32_bf16 v[74:77], v[172:175], v[196:199], v[74:77]
	v_mfma_f32_16x16x32_bf16 v[70:73], v[164:167], v[206:209], v[70:73]
	v_mfma_f32_16x16x32_bf16 v[66:69], v[172:175], v[206:209], v[66:69]
	v_mfma_f32_16x16x32_bf16 v[110:113], v[168:171], v[184:187], v[110:113]
	v_mfma_f32_16x16x32_bf16 v[106:109], v[176:179], v[184:187], v[106:109]
	v_mfma_f32_16x16x32_bf16 v[94:97], v[168:171], v[192:195], v[94:97]
	v_mfma_f32_16x16x32_bf16 v[90:93], v[176:179], v[192:195], v[90:93]
	v_mfma_f32_16x16x32_bf16 v[78:81], v[168:171], v[200:203], v[78:81]
	v_mfma_f32_16x16x32_bf16 v[74:77], v[176:179], v[200:203], v[74:77]
	v_mfma_f32_16x16x32_bf16 v[70:73], v[168:171], v[210:213], v[70:73]
	v_mfma_f32_16x16x32_bf16 v[66:69], v[176:179], v[210:213], v[66:69]
	s_setprio 0
	s_barrier
	s_add_i32 s70, s35, s18
	v_lshl_add_u64 v[214:215], s[38:39], 0, v[134:135]
	s_mov_b32 m0, s70
	ds_read_b128 v[180:183], v146 offset:16384
	ds_read_b128 v[184:187], v146 offset:17408
	ds_read_b128 v[188:191], v146 offset:18432
	ds_read_b128 v[192:195], v146 offset:19456
	ds_read_b128 v[196:199], v146 offset:20480
	ds_read_b128 v[200:203], v146 offset:21504
	ds_read_b128 v[206:209], v146 offset:22528
	ds_read_b128 v[210:213], v146 offset:23552
	global_load_lds_dwordx4 v[214:215], off
	s_add_i32 m0, s70, 0x2000
	s_add_u32 s70, s38, 0x200000
	v_lshl_add_u64 v[216:217], s[38:39], 0, v[130:131]
	s_addc_u32 s71, s39, 0
	s_add_i32 s72, s44, s18
	global_load_lds_dwordx4 v[216:217], off
	v_lshl_add_u64 v[218:219], s[70:71], 0, v[134:135]
	s_mov_b32 m0, s72
	v_lshl_add_u64 v[220:221], s[42:43], 0, v[132:133]
	global_load_lds_dwordx4 v[218:219], off
	s_add_i32 m0, s72, 0x2000
	v_lshl_add_u64 v[218:219], s[70:71], 0, v[130:131]
	global_load_lds_dwordx4 v[218:219], off
	s_mov_b32 m0, s19
	v_lshl_add_u64 v[218:219], s[42:43], 0, v[136:137]
	global_load_lds_dwordx4 v[218:219], off
	s_mov_b32 m0, s24
	s_nop 0
	global_load_lds_dwordx4 v[220:221], off
	s_waitcnt vmcnt(8) lgkmcnt(0)
	s_setprio 1
	s_barrier
	v_mfma_f32_16x16x32_bf16 v[62:65], v[148:151], v[180:183], v[62:65]
	v_mfma_f32_16x16x32_bf16 v[58:61], v[156:159], v[180:183], v[58:61]
	v_mfma_f32_16x16x32_bf16 v[54:57], v[148:151], v[188:191], v[54:57]
	v_mfma_f32_16x16x32_bf16 v[50:53], v[156:159], v[188:191], v[50:53]
	v_mfma_f32_16x16x32_bf16 v[38:41], v[148:151], v[196:199], v[38:41]
	v_mfma_f32_16x16x32_bf16 v[34:37], v[156:159], v[196:199], v[34:37]
	v_mfma_f32_16x16x32_bf16 v[22:25], v[148:151], v[206:209], v[22:25]
	v_mfma_f32_16x16x32_bf16 v[18:21], v[156:159], v[206:209], v[18:21]
	v_mfma_f32_16x16x32_bf16 v[62:65], v[152:155], v[184:187], v[62:65]
	v_mfma_f32_16x16x32_bf16 v[58:61], v[160:163], v[184:187], v[58:61]
	v_mfma_f32_16x16x32_bf16 v[54:57], v[152:155], v[192:195], v[54:57]
	v_mfma_f32_16x16x32_bf16 v[50:53], v[160:163], v[192:195], v[50:53]
	v_mfma_f32_16x16x32_bf16 v[38:41], v[152:155], v[200:203], v[38:41]
	v_mfma_f32_16x16x32_bf16 v[34:37], v[160:163], v[200:203], v[34:37]
	v_mfma_f32_16x16x32_bf16 v[22:25], v[152:155], v[210:213], v[22:25]
	v_mfma_f32_16x16x32_bf16 v[18:21], v[160:163], v[210:213], v[18:21]
	v_mfma_f32_16x16x32_bf16 v[46:49], v[164:167], v[180:183], v[46:49]
	v_mfma_f32_16x16x32_bf16 v[42:45], v[172:175], v[180:183], v[42:45]
	v_mfma_f32_16x16x32_bf16 v[30:33], v[164:167], v[188:191], v[30:33]
	v_mfma_f32_16x16x32_bf16 v[26:29], v[172:175], v[188:191], v[26:29]
	v_mfma_f32_16x16x32_bf16 v[14:17], v[164:167], v[196:199], v[14:17]
	v_mfma_f32_16x16x32_bf16 v[10:13], v[172:175], v[196:199], v[10:13]
	v_mfma_f32_16x16x32_bf16 v[6:9], v[164:167], v[206:209], v[6:9]
	v_mfma_f32_16x16x32_bf16 v[2:5], v[172:175], v[206:209], v[2:5]
	v_mfma_f32_16x16x32_bf16 v[46:49], v[168:171], v[184:187], v[46:49]
	v_mfma_f32_16x16x32_bf16 v[42:45], v[176:179], v[184:187], v[42:45]
	v_mfma_f32_16x16x32_bf16 v[30:33], v[168:171], v[192:195], v[30:33]
	v_mfma_f32_16x16x32_bf16 v[26:29], v[176:179], v[192:195], v[26:29]
	v_mfma_f32_16x16x32_bf16 v[14:17], v[168:171], v[200:203], v[14:17]
	v_mfma_f32_16x16x32_bf16 v[10:13], v[176:179], v[200:203], v[10:13]
	v_mfma_f32_16x16x32_bf16 v[6:9], v[168:171], v[210:213], v[6:9]
	v_mfma_f32_16x16x32_bf16 v[2:5], v[176:179], v[210:213], v[2:5]
	s_setprio 0
	s_barrier
	s_add_i32 s70, 0, 0x18000
	v_add_u32_e32 v147, s70, v143
	s_add_i32 s71, 0, 0x1c000
	ds_read_b128 v[148:151], v147
	ds_read_b128 v[152:155], v147 offset:1024
	ds_read_b128 v[156:159], v147 offset:2048
	ds_read_b128 v[160:163], v147 offset:3072
	v_add_u32_e32 v147, s71, v143
	ds_read_b128 v[164:167], v147
	ds_read_b128 v[168:171], v147 offset:1024
	ds_read_b128 v[172:175], v147 offset:2048
	ds_read_b128 v[176:179], v147 offset:3072
	s_add_u32 s42, s42, 0x20000
	s_addc_u32 s43, s43, 0
	s_mov_b32 m0, s25
	v_lshl_add_u64 v[222:223], s[42:43], 0, v[136:137]
	ds_read_b128 v[180:183], v146 offset:32768
	ds_read_b128 v[184:187], v146 offset:33792
	ds_read_b128 v[188:191], v146 offset:34816
	ds_read_b128 v[192:195], v146 offset:35840
	ds_read_b128 v[196:199], v146 offset:36864
	ds_read_b128 v[200:203], v146 offset:37888
	ds_read_b128 v[206:209], v146 offset:38912
	ds_read_b128 v[210:213], v146 offset:39936
	global_load_lds_dwordx4 v[222:223], off
	s_mov_b32 m0, s28
	v_lshl_add_u64 v[222:223], s[42:43], 0, v[132:133]
	global_load_lds_dwordx4 v[222:223], off
	s_waitcnt vmcnt(8) lgkmcnt(0)
	s_setprio 1
	s_barrier
	v_mfma_f32_16x16x32_bf16 v[126:129], v[148:151], v[180:183], v[126:129]
	v_mfma_f32_16x16x32_bf16 v[122:125], v[156:159], v[180:183], v[122:125]
	v_mfma_f32_16x16x32_bf16 v[118:121], v[148:151], v[188:191], v[118:121]
	v_mfma_f32_16x16x32_bf16 v[114:117], v[156:159], v[188:191], v[114:117]
	v_mfma_f32_16x16x32_bf16 v[102:105], v[148:151], v[196:199], v[102:105]
	v_mfma_f32_16x16x32_bf16 v[98:101], v[156:159], v[196:199], v[98:101]
	v_mfma_f32_16x16x32_bf16 v[86:89], v[148:151], v[206:209], v[86:89]
	v_mfma_f32_16x16x32_bf16 v[82:85], v[156:159], v[206:209], v[82:85]
	v_mfma_f32_16x16x32_bf16 v[126:129], v[152:155], v[184:187], v[126:129]
	v_mfma_f32_16x16x32_bf16 v[122:125], v[160:163], v[184:187], v[122:125]
	v_mfma_f32_16x16x32_bf16 v[118:121], v[152:155], v[192:195], v[118:121]
	v_mfma_f32_16x16x32_bf16 v[114:117], v[160:163], v[192:195], v[114:117]
	v_mfma_f32_16x16x32_bf16 v[102:105], v[152:155], v[200:203], v[102:105]
	v_mfma_f32_16x16x32_bf16 v[98:101], v[160:163], v[200:203], v[98:101]
	v_mfma_f32_16x16x32_bf16 v[86:89], v[152:155], v[210:213], v[86:89]
	v_mfma_f32_16x16x32_bf16 v[82:85], v[160:163], v[210:213], v[82:85]
	v_mfma_f32_16x16x32_bf16 v[110:113], v[164:167], v[180:183], v[110:113]
	v_mfma_f32_16x16x32_bf16 v[106:109], v[172:175], v[180:183], v[106:109]
	v_mfma_f32_16x16x32_bf16 v[94:97], v[164:167], v[188:191], v[94:97]
	v_mfma_f32_16x16x32_bf16 v[90:93], v[172:175], v[188:191], v[90:93]
	v_mfma_f32_16x16x32_bf16 v[78:81], v[164:167], v[196:199], v[78:81]
	v_mfma_f32_16x16x32_bf16 v[74:77], v[172:175], v[196:199], v[74:77]
	v_mfma_f32_16x16x32_bf16 v[70:73], v[164:167], v[206:209], v[70:73]
	v_mfma_f32_16x16x32_bf16 v[66:69], v[172:175], v[206:209], v[66:69]
	v_mfma_f32_16x16x32_bf16 v[110:113], v[168:171], v[184:187], v[110:113]
	v_mfma_f32_16x16x32_bf16 v[106:109], v[176:179], v[184:187], v[106:109]
	v_mfma_f32_16x16x32_bf16 v[94:97], v[168:171], v[192:195], v[94:97]
	v_mfma_f32_16x16x32_bf16 v[90:93], v[176:179], v[192:195], v[90:93]
	v_mfma_f32_16x16x32_bf16 v[78:81], v[168:171], v[200:203], v[78:81]
	v_mfma_f32_16x16x32_bf16 v[74:77], v[176:179], v[200:203], v[74:77]
	v_mfma_f32_16x16x32_bf16 v[70:73], v[168:171], v[210:213], v[70:73]
	v_mfma_f32_16x16x32_bf16 v[66:69], v[176:179], v[210:213], v[66:69]
	s_setprio 0
	s_barrier
	s_add_i32 s42, s70, s18
	v_lshl_add_u64 v[214:215], v[214:215], 0, s[8:9]
	s_mov_b32 m0, s42
	ds_read_b128 v[180:183], v146 offset:49152
	ds_read_b128 v[184:187], v146 offset:50176
	ds_read_b128 v[188:191], v146 offset:51200
	ds_read_b128 v[192:195], v146 offset:52224
	ds_read_b128 v[196:199], v146 offset:53248
	ds_read_b128 v[200:203], v146 offset:54272
	ds_read_b128 v[206:209], v146 offset:55296
	ds_read_b128 v[210:213], v146 offset:56320
	global_load_lds_dwordx4 v[214:215], off
	s_add_i32 m0, s42, 0x2000
	s_add_u32 s38, s38, 0x200080
	v_lshl_add_u64 v[214:215], v[216:217], 0, s[8:9]
	s_addc_u32 s39, s39, 0
	s_add_i32 s42, s71, s18
	global_load_lds_dwordx4 v[214:215], off
	s_mov_b32 m0, s42
	v_lshl_add_u64 v[214:215], s[38:39], 0, v[134:135]
	global_load_lds_dwordx4 v[214:215], off
	s_add_i32 m0, s42, 0x2000
	v_lshl_add_u64 v[214:215], s[38:39], 0, v[130:131]
	global_load_lds_dwordx4 v[214:215], off
	s_mov_b32 m0, s33
	v_lshl_add_u64 v[214:215], v[218:219], 0, s[8:9]
	global_load_lds_dwordx4 v[214:215], off
	s_mov_b32 m0, s34
	v_lshl_add_u64 v[214:215], v[220:221], 0, s[8:9]
	global_load_lds_dwordx4 v[214:215], off
	s_waitcnt vmcnt(8) lgkmcnt(0)
	s_setprio 1
	s_barrier
	v_mfma_f32_16x16x32_bf16 v[62:65], v[148:151], v[180:183], v[62:65]
	v_mfma_f32_16x16x32_bf16 v[58:61], v[156:159], v[180:183], v[58:61]
	v_mfma_f32_16x16x32_bf16 v[54:57], v[148:151], v[188:191], v[54:57]
	v_mfma_f32_16x16x32_bf16 v[50:53], v[156:159], v[188:191], v[50:53]
	v_mfma_f32_16x16x32_bf16 v[38:41], v[148:151], v[196:199], v[38:41]
	v_mfma_f32_16x16x32_bf16 v[34:37], v[156:159], v[196:199], v[34:37]
	v_mfma_f32_16x16x32_bf16 v[22:25], v[148:151], v[206:209], v[22:25]
	v_mfma_f32_16x16x32_bf16 v[18:21], v[156:159], v[206:209], v[18:21]
	v_mfma_f32_16x16x32_bf16 v[62:65], v[152:155], v[184:187], v[62:65]
	v_mfma_f32_16x16x32_bf16 v[58:61], v[160:163], v[184:187], v[58:61]
	v_mfma_f32_16x16x32_bf16 v[54:57], v[152:155], v[192:195], v[54:57]
	v_mfma_f32_16x16x32_bf16 v[50:53], v[160:163], v[192:195], v[50:53]
	v_mfma_f32_16x16x32_bf16 v[38:41], v[152:155], v[200:203], v[38:41]
	v_mfma_f32_16x16x32_bf16 v[34:37], v[160:163], v[200:203], v[34:37]
	v_mfma_f32_16x16x32_bf16 v[22:25], v[152:155], v[210:213], v[22:25]
	v_mfma_f32_16x16x32_bf16 v[18:21], v[160:163], v[210:213], v[18:21]
	v_mfma_f32_16x16x32_bf16 v[46:49], v[164:167], v[180:183], v[46:49]
	v_mfma_f32_16x16x32_bf16 v[42:45], v[172:175], v[180:183], v[42:45]
	v_mfma_f32_16x16x32_bf16 v[30:33], v[164:167], v[188:191], v[30:33]
	v_mfma_f32_16x16x32_bf16 v[26:29], v[172:175], v[188:191], v[26:29]
	v_mfma_f32_16x16x32_bf16 v[14:17], v[164:167], v[196:199], v[14:17]
	v_mfma_f32_16x16x32_bf16 v[10:13], v[172:175], v[196:199], v[10:13]
	v_mfma_f32_16x16x32_bf16 v[6:9], v[164:167], v[206:209], v[6:9]
	v_mfma_f32_16x16x32_bf16 v[2:5], v[172:175], v[206:209], v[2:5]
	v_mfma_f32_16x16x32_bf16 v[46:49], v[168:171], v[184:187], v[46:49]
	v_mfma_f32_16x16x32_bf16 v[42:45], v[176:179], v[184:187], v[42:45]
	v_mfma_f32_16x16x32_bf16 v[30:33], v[168:171], v[192:195], v[30:33]
	v_mfma_f32_16x16x32_bf16 v[26:29], v[176:179], v[192:195], v[26:29]
	v_mfma_f32_16x16x32_bf16 v[14:17], v[168:171], v[200:203], v[14:17]
	v_mfma_f32_16x16x32_bf16 v[10:13], v[176:179], v[200:203], v[10:13]
	v_mfma_f32_16x16x32_bf16 v[6:9], v[168:171], v[210:213], v[6:9]
	v_mfma_f32_16x16x32_bf16 v[2:5], v[176:179], v[210:213], v[2:5]
	s_setprio 0
	s_barrier
	s_add_i32 s69, s69, 2
	s_add_u32 s36, s36, 0x100
	s_addc_u32 s37, s37, 0
	s_add_u32 s67, s67, 0x100
	s_addc_u32 s68, s68, 0
	s_cmp_gt_u32 s69, 5
	s_cbranch_scc0 .LBB0_477
	s_and_b64 vcc, exec, s[10:11]
	s_cbranch_vccz .LBB0_480
	s_barrier

.LBB0_565:
	v_readlane_b32 s62, v249, 27
	v_readlane_b32 s63, v249, 28
	s_add_u32 s72, s62, s68
	s_addc_u32 s73, s63, s69
	s_and_b64 s[62:63], s[70:71], exec
	s_cselect_b32 s31, s73, s77
	s_cselect_b32 s33, s72, s76
	s_add_u32 s74, s35, s66
	s_addc_u32 s75, s85, s67
	s_and_b64 s[62:63], s[70:71], exec
	s_cselect_b32 s34, s75, s79
	s_cselect_b32 s39, s74, s78
	s_add_i32 s45, s7, -2
	s_add_u32 s76, s76, 0x40080
	s_addc_u32 s77, s77, 0
	s_add_u32 s47, s78, 0x100
	s_addc_u32 s62, s79, 0
	s_mov_b32 s63, 0
	s_waitcnt vmcnt(0)
	ds_read_b128 v[114:117], v190
	ds_read_b128 v[118:121], v190 offset:1024
	ds_read_b128 v[122:125], v190 offset:2048
	ds_read_b128 v[126:129], v190 offset:3072
	ds_read_b128 v[146:149], v191
	ds_read_b128 v[150:153], v191 offset:1024
	ds_read_b128 v[154:157], v191 offset:2048
	ds_read_b128 v[158:161], v191 offset:3072
	s_add_i32 s82, s63, 2
	s_add_u32 s78, s76, 0xfffc0080
	s_addc_u32 s79, s77, -1
	s_cmp_eq_u32 s45, s63
	s_cselect_b32 s81, s31, s79
	s_cselect_b32 s80, s33, s78
	s_cselect_b32 s79, s34, s62
	s_cselect_b32 s78, s39, s47
	v_lshl_add_u64 v[186:187], s[76:77], 0, v[180:181]
	s_add_i32 m0, s87, 0xc000
	ds_read_b128 v[162:165], v192
	ds_read_b128 v[166:169], v192 offset:1024
	ds_read_b128 v[194:197], v192 offset:2048
	ds_read_b128 v[198:201], v192 offset:3072
	ds_read_b128 v[206:209], v192 offset:4096
	ds_read_b128 v[210:213], v192 offset:5120
	ds_read_b128 v[214:217], v192 offset:6144
	ds_read_b128 v[218:221], v192 offset:7168
	global_load_lds_dwordx4 v[186:187], off
	s_add_i32 m0, s87, 0xe000
	v_lshl_add_u64 v[186:187], s[76:77], 0, v[182:183]
	global_load_lds_dwordx4 v[186:187], off
	s_waitcnt vmcnt(8)
	s_waitcnt lgkmcnt(0)
	s_setprio 1
	s_barrier
	v_mfma_f32_16x16x32_bf16 v[142:145], v[114:117], v[162:165], 0
	v_mfma_f32_16x16x32_bf16 v[138:141], v[122:125], v[162:165], 0
	v_mfma_f32_16x16x32_bf16 v[110:113], v[114:117], v[194:197], 0
	v_mfma_f32_16x16x32_bf16 v[106:109], v[122:125], v[194:197], 0
	v_mfma_f32_16x16x32_bf16 v[98:101], v[114:117], v[206:209], 0
	v_mfma_f32_16x16x32_bf16 v[90:93], v[122:125], v[206:209], 0
	v_mfma_f32_16x16x32_bf16 v[82:85], v[114:117], v[214:217], 0
	v_mfma_f32_16x16x32_bf16 v[74:77], v[122:125], v[214:217], 0
	v_mfma_f32_16x16x32_bf16 v[142:145], v[118:121], v[166:169], v[142:145]
	v_mfma_f32_16x16x32_bf16 v[138:141], v[126:129], v[166:169], v[138:141]
	v_mfma_f32_16x16x32_bf16 v[110:113], v[118:121], v[198:201], v[110:113]
	v_mfma_f32_16x16x32_bf16 v[106:109], v[126:129], v[198:201], v[106:109]
	v_mfma_f32_16x16x32_bf16 v[98:101], v[118:121], v[210:213], v[98:101]
	v_mfma_f32_16x16x32_bf16 v[90:93], v[126:129], v[210:213], v[90:93]
	v_mfma_f32_16x16x32_bf16 v[82:85], v[118:121], v[218:221], v[82:85]
	v_mfma_f32_16x16x32_bf16 v[74:77], v[126:129], v[218:221], v[74:77]
	v_mfma_f32_16x16x32_bf16 v[134:137], v[146:149], v[162:165], 0
	v_mfma_f32_16x16x32_bf16 v[130:133], v[154:157], v[162:165], 0
	v_mfma_f32_16x16x32_bf16 v[102:105], v[146:149], v[194:197], 0
	v_mfma_f32_16x16x32_bf16 v[94:97], v[154:157], v[194:197], 0
	v_mfma_f32_16x16x32_bf16 v[86:89], v[146:149], v[206:209], 0
	v_mfma_f32_16x16x32_bf16 v[78:81], v[154:157], v[206:209], 0
	v_mfma_f32_16x16x32_bf16 v[70:73], v[146:149], v[214:217], 0
	v_mfma_f32_16x16x32_bf16 v[66:69], v[154:157], v[214:217], 0
	v_mfma_f32_16x16x32_bf16 v[134:137], v[150:153], v[166:169], v[134:137]
	v_mfma_f32_16x16x32_bf16 v[130:133], v[158:161], v[166:169], v[130:133]
	v_mfma_f32_16x16x32_bf16 v[102:105], v[150:153], v[198:201], v[102:105]
	v_mfma_f32_16x16x32_bf16 v[94:97], v[158:161], v[198:201], v[94:97]
	v_mfma_f32_16x16x32_bf16 v[86:89], v[150:153], v[210:213], v[86:89]
	v_mfma_f32_16x16x32_bf16 v[78:81], v[158:161], v[210:213], v[78:81]
	v_mfma_f32_16x16x32_bf16 v[70:73], v[150:153], v[218:221], v[70:73]
	v_mfma_f32_16x16x32_bf16 v[66:69], v[158:161], v[218:221], v[66:69]
	s_setprio 0
	s_barrier
	s_add_i32 s63, s24, s86
	v_lshl_add_u64 v[186:187], s[78:79], 0, v[172:173]
	s_mov_b32 m0, s63
	ds_read_b128 v[162:165], v192 offset:16384
	ds_read_b128 v[166:169], v192 offset:17408
	ds_read_b128 v[194:197], v192 offset:18432
	ds_read_b128 v[198:201], v192 offset:19456
	ds_read_b128 v[206:209], v192 offset:20480
	ds_read_b128 v[210:213], v192 offset:21504
	ds_read_b128 v[214:217], v192 offset:22528
	ds_read_b128 v[218:221], v192 offset:23552
	global_load_lds_dwordx4 v[186:187], off
	s_add_i32 m0, s63, 0x2000
	s_add_u32 vcc_lo, s78, 0x40000
	v_lshl_add_u64 v[202:203], s[78:79], 0, v[176:177]
	s_addc_u32 vcc_hi, s79, 0
	s_add_i32 s63, s25, s86
	global_load_lds_dwordx4 v[202:203], off
	v_lshl_add_u64 v[222:223], vcc, 0, v[172:173]
	s_mov_b32 m0, s63
	v_lshl_add_u64 v[224:225], s[80:81], 0, v[174:175]
	global_load_lds_dwordx4 v[222:223], off
	s_add_i32 m0, s63, 0x2000
	v_lshl_add_u64 v[222:223], vcc, 0, v[176:177]
	global_load_lds_dwordx4 v[222:223], off
	s_mov_b32 m0, s87
	v_lshl_add_u64 v[222:223], s[80:81], 0, v[170:171]
	global_load_lds_dwordx4 v[222:223], off
	s_mov_b32 m0, s88
	s_nop 0
	global_load_lds_dwordx4 v[224:225], off
	s_waitcnt vmcnt(8) lgkmcnt(0)
	s_setprio 1
	s_barrier
	v_mfma_f32_16x16x32_bf16 v[62:65], v[114:117], v[162:165], 0
	v_mfma_f32_16x16x32_bf16 v[58:61], v[122:125], v[162:165], 0
	v_mfma_f32_16x16x32_bf16 v[50:53], v[114:117], v[194:197], 0
	v_mfma_f32_16x16x32_bf16 v[42:45], v[122:125], v[194:197], 0
	v_mfma_f32_16x16x32_bf16 v[34:37], v[114:117], v[206:209], 0
	v_mfma_f32_16x16x32_bf16 v[26:29], v[122:125], v[206:209], 0
	v_mfma_f32_16x16x32_bf16 v[18:21], v[114:117], v[214:217], 0
	v_mfma_f32_16x16x32_bf16 v[10:13], v[122:125], v[214:217], 0
	v_mfma_f32_16x16x32_bf16 v[62:65], v[118:121], v[166:169], v[62:65]
	v_mfma_f32_16x16x32_bf16 v[58:61], v[126:129], v[166:169], v[58:61]
	v_mfma_f32_16x16x32_bf16 v[50:53], v[118:121], v[198:201], v[50:53]
	v_mfma_f32_16x16x32_bf16 v[42:45], v[126:129], v[198:201], v[42:45]
	v_mfma_f32_16x16x32_bf16 v[34:37], v[118:121], v[210:213], v[34:37]
	v_mfma_f32_16x16x32_bf16 v[26:29], v[126:129], v[210:213], v[26:29]
	v_mfma_f32_16x16x32_bf16 v[18:21], v[118:121], v[218:221], v[18:21]
	v_mfma_f32_16x16x32_bf16 v[10:13], v[126:129], v[218:221], v[10:13]
	v_mfma_f32_16x16x32_bf16 v[54:57], v[146:149], v[162:165], 0
	v_mfma_f32_16x16x32_bf16 v[46:49], v[154:157], v[162:165], 0
	v_mfma_f32_16x16x32_bf16 v[38:41], v[146:149], v[194:197], 0
	v_mfma_f32_16x16x32_bf16 v[30:33], v[154:157], v[194:197], 0
	v_mfma_f32_16x16x32_bf16 v[22:25], v[146:149], v[206:209], 0
	v_mfma_f32_16x16x32_bf16 v[14:17], v[154:157], v[206:209], 0
	v_mfma_f32_16x16x32_bf16 v[6:9], v[146:149], v[214:217], 0
	v_mfma_f32_16x16x32_bf16 v[2:5], v[154:157], v[214:217], 0
	v_mfma_f32_16x16x32_bf16 v[54:57], v[150:153], v[166:169], v[54:57]
	v_mfma_f32_16x16x32_bf16 v[46:49], v[158:161], v[166:169], v[46:49]
	v_mfma_f32_16x16x32_bf16 v[38:41], v[150:153], v[198:201], v[38:41]
	v_mfma_f32_16x16x32_bf16 v[30:33], v[158:161], v[198:201], v[30:33]
	v_mfma_f32_16x16x32_bf16 v[22:25], v[150:153], v[210:213], v[22:25]
	v_mfma_f32_16x16x32_bf16 v[14:17], v[158:161], v[210:213], v[14:17]
	v_mfma_f32_16x16x32_bf16 v[6:9], v[150:153], v[218:221], v[6:9]
	v_mfma_f32_16x16x32_bf16 v[2:5], v[158:161], v[218:221], v[2:5]
	s_setprio 0
	s_barrier
	s_add_i32 s63, 0, 0x18000
	s_add_i32 s83, 0, 0x1c000
	v_add_u32_e32 v126, s63, v189
	v_add_u32_e32 v158, s83, v189
	ds_read_b128 v[114:117], v126
	ds_read_b128 v[118:121], v126 offset:1024
	ds_read_b128 v[122:125], v126 offset:2048
	ds_read_b128 v[126:129], v126 offset:3072
	ds_read_b128 v[146:149], v158
	ds_read_b128 v[150:153], v158 offset:1024
	ds_read_b128 v[154:157], v158 offset:2048
	ds_read_b128 v[158:161], v158 offset:3072
	s_add_u32 s80, s80, 0x40000
	s_addc_u32 s81, s81, 0
	s_mov_b32 m0, s89
	v_lshl_add_u64 v[226:227], s[80:81], 0, v[170:171]
	ds_read_b128 v[162:165], v192 offset:32768
	ds_read_b128 v[166:169], v192 offset:33792
	ds_read_b128 v[194:197], v192 offset:34816
	ds_read_b128 v[198:201], v192 offset:35840
	ds_read_b128 v[206:209], v192 offset:36864
	ds_read_b128 v[210:213], v192 offset:37888
	ds_read_b128 v[214:217], v192 offset:38912
	ds_read_b128 v[218:221], v192 offset:39936
	global_load_lds_dwordx4 v[226:227], off
	s_mov_b32 m0, s90
	v_lshl_add_u64 v[226:227], s[80:81], 0, v[174:175]
	global_load_lds_dwordx4 v[226:227], off
	s_waitcnt vmcnt(8) lgkmcnt(0)
	s_setprio 1
	s_barrier
	v_mfma_f32_16x16x32_bf16 v[142:145], v[114:117], v[162:165], v[142:145]
	v_mfma_f32_16x16x32_bf16 v[138:141], v[122:125], v[162:165], v[138:141]
	v_mfma_f32_16x16x32_bf16 v[110:113], v[114:117], v[194:197], v[110:113]
	v_mfma_f32_16x16x32_bf16 v[106:109], v[122:125], v[194:197], v[106:109]
	v_mfma_f32_16x16x32_bf16 v[98:101], v[114:117], v[206:209], v[98:101]
	v_mfma_f32_16x16x32_bf16 v[90:93], v[122:125], v[206:209], v[90:93]
	v_mfma_f32_16x16x32_bf16 v[82:85], v[114:117], v[214:217], v[82:85]
	v_mfma_f32_16x16x32_bf16 v[74:77], v[122:125], v[214:217], v[74:77]
	v_mfma_f32_16x16x32_bf16 v[142:145], v[118:121], v[166:169], v[142:145]
	v_mfma_f32_16x16x32_bf16 v[138:141], v[126:129], v[166:169], v[138:141]
	v_mfma_f32_16x16x32_bf16 v[110:113], v[118:121], v[198:201], v[110:113]
	v_mfma_f32_16x16x32_bf16 v[106:109], v[126:129], v[198:201], v[106:109]
	v_mfma_f32_16x16x32_bf16 v[98:101], v[118:121], v[210:213], v[98:101]
	v_mfma_f32_16x16x32_bf16 v[90:93], v[126:129], v[210:213], v[90:93]
	v_mfma_f32_16x16x32_bf16 v[82:85], v[118:121], v[218:221], v[82:85]
	v_mfma_f32_16x16x32_bf16 v[74:77], v[126:129], v[218:221], v[74:77]
	v_mfma_f32_16x16x32_bf16 v[134:137], v[146:149], v[162:165], v[134:137]
	v_mfma_f32_16x16x32_bf16 v[130:133], v[154:157], v[162:165], v[130:133]
	v_mfma_f32_16x16x32_bf16 v[102:105], v[146:149], v[194:197], v[102:105]
	v_mfma_f32_16x16x32_bf16 v[94:97], v[154:157], v[194:197], v[94:97]
	v_mfma_f32_16x16x32_bf16 v[86:89], v[146:149], v[206:209], v[86:89]
	v_mfma_f32_16x16x32_bf16 v[78:81], v[154:157], v[206:209], v[78:81]
	v_mfma_f32_16x16x32_bf16 v[70:73], v[146:149], v[214:217], v[70:73]
	v_mfma_f32_16x16x32_bf16 v[66:69], v[154:157], v[214:217], v[66:69]
	v_mfma_f32_16x16x32_bf16 v[134:137], v[150:153], v[166:169], v[134:137]
	v_mfma_f32_16x16x32_bf16 v[130:133], v[158:161], v[166:169], v[130:133]
	v_mfma_f32_16x16x32_bf16 v[102:105], v[150:153], v[198:201], v[102:105]
	v_mfma_f32_16x16x32_bf16 v[94:97], v[158:161], v[198:201], v[94:97]
	v_mfma_f32_16x16x32_bf16 v[86:89], v[150:153], v[210:213], v[86:89]
	v_mfma_f32_16x16x32_bf16 v[78:81], v[158:161], v[210:213], v[78:81]
	v_mfma_f32_16x16x32_bf16 v[70:73], v[150:153], v[218:221], v[70:73]
	v_mfma_f32_16x16x32_bf16 v[66:69], v[158:161], v[218:221], v[66:69]
	s_setprio 0
	s_barrier
	s_add_i32 s63, s63, s86
	v_lshl_add_u64 v[186:187], v[186:187], 0, s[22:23]
	s_mov_b32 m0, s63
	ds_read_b128 v[162:165], v192 offset:49152
	ds_read_b128 v[166:169], v192 offset:50176
	ds_read_b128 v[194:197], v192 offset:51200
	ds_read_b128 v[198:201], v192 offset:52224
	ds_read_b128 v[206:209], v192 offset:53248
	ds_read_b128 v[210:213], v192 offset:54272
	ds_read_b128 v[214:217], v192 offset:55296
	ds_read_b128 v[218:221], v192 offset:56320
	global_load_lds_dwordx4 v[186:187], off
	s_add_i32 m0, s63, 0x2000
	s_add_u32 s78, s78, 0x40080
	v_lshl_add_u64 v[186:187], v[202:203], 0, s[22:23]
	s_addc_u32 s79, s79, 0
	s_add_i32 s63, s83, s86
	global_load_lds_dwordx4 v[186:187], off
	s_mov_b32 m0, s63
	v_lshl_add_u64 v[186:187], s[78:79], 0, v[172:173]
	global_load_lds_dwordx4 v[186:187], off
	s_add_i32 m0, s63, 0x2000
	v_lshl_add_u64 v[186:187], s[78:79], 0, v[176:177]
	global_load_lds_dwordx4 v[186:187], off
	s_mov_b32 m0, s95
	v_lshl_add_u64 v[186:187], v[222:223], 0, s[22:23]
	global_load_lds_dwordx4 v[186:187], off
	s_mov_b32 m0, s96
	v_lshl_add_u64 v[186:187], v[224:225], 0, s[22:23]
	global_load_lds_dwordx4 v[186:187], off
	s_waitcnt vmcnt(8) lgkmcnt(0)
	s_setprio 1
	s_barrier
	v_mfma_f32_16x16x32_bf16 v[62:65], v[114:117], v[162:165], v[62:65]
	v_mfma_f32_16x16x32_bf16 v[58:61], v[122:125], v[162:165], v[58:61]
	v_mfma_f32_16x16x32_bf16 v[50:53], v[114:117], v[194:197], v[50:53]
	v_mfma_f32_16x16x32_bf16 v[42:45], v[122:125], v[194:197], v[42:45]
	v_mfma_f32_16x16x32_bf16 v[34:37], v[114:117], v[206:209], v[34:37]
	v_mfma_f32_16x16x32_bf16 v[26:29], v[122:125], v[206:209], v[26:29]
	v_mfma_f32_16x16x32_bf16 v[18:21], v[114:117], v[214:217], v[18:21]
	v_mfma_f32_16x16x32_bf16 v[10:13], v[122:125], v[214:217], v[10:13]
	v_mfma_f32_16x16x32_bf16 v[62:65], v[118:121], v[166:169], v[62:65]
	v_mfma_f32_16x16x32_bf16 v[58:61], v[126:129], v[166:169], v[58:61]
	v_mfma_f32_16x16x32_bf16 v[50:53], v[118:121], v[198:201], v[50:53]
	v_mfma_f32_16x16x32_bf16 v[42:45], v[126:129], v[198:201], v[42:45]
	v_mfma_f32_16x16x32_bf16 v[34:37], v[118:121], v[210:213], v[34:37]
	v_mfma_f32_16x16x32_bf16 v[26:29], v[126:129], v[210:213], v[26:29]
	v_mfma_f32_16x16x32_bf16 v[18:21], v[118:121], v[218:221], v[18:21]
	v_mfma_f32_16x16x32_bf16 v[10:13], v[126:129], v[218:221], v[10:13]
	v_mfma_f32_16x16x32_bf16 v[54:57], v[146:149], v[162:165], v[54:57]
	v_mfma_f32_16x16x32_bf16 v[46:49], v[154:157], v[162:165], v[46:49]
	v_mfma_f32_16x16x32_bf16 v[38:41], v[146:149], v[194:197], v[38:41]
	v_mfma_f32_16x16x32_bf16 v[30:33], v[154:157], v[194:197], v[30:33]
	v_mfma_f32_16x16x32_bf16 v[22:25], v[146:149], v[206:209], v[22:25]
	v_mfma_f32_16x16x32_bf16 v[14:17], v[154:157], v[206:209], v[14:17]
	v_mfma_f32_16x16x32_bf16 v[6:9], v[146:149], v[214:217], v[6:9]
	v_mfma_f32_16x16x32_bf16 v[2:5], v[154:157], v[214:217], v[2:5]
	v_mfma_f32_16x16x32_bf16 v[54:57], v[150:153], v[166:169], v[54:57]
	v_mfma_f32_16x16x32_bf16 v[46:49], v[158:161], v[166:169], v[46:49]
	v_mfma_f32_16x16x32_bf16 v[38:41], v[150:153], v[198:201], v[38:41]
	v_mfma_f32_16x16x32_bf16 v[30:33], v[158:161], v[198:201], v[30:33]
	v_mfma_f32_16x16x32_bf16 v[22:25], v[150:153], v[210:213], v[22:25]
	v_mfma_f32_16x16x32_bf16 v[14:17], v[158:161], v[210:213], v[14:17]
	v_mfma_f32_16x16x32_bf16 v[6:9], v[150:153], v[218:221], v[6:9]
	v_mfma_f32_16x16x32_bf16 v[2:5], v[158:161], v[218:221], v[2:5]
	s_setprio 0
	s_barrier
	s_add_u32 s76, s76, 0x100
	s_addc_u32 s77, s77, 0
	s_add_u32 s47, s47, 0x100
	s_addc_u32 s62, s62, 0
	s_cmp_ge_i32 s82, s7
	s_mov_b32 s63, s82
.LBB0_566:
	s_waitcnt vmcnt(0)
	ds_read_b128 v[114:117], v190
	ds_read_b128 v[118:121], v190 offset:1024
	ds_read_b128 v[122:125], v190 offset:2048
	ds_read_b128 v[126:129], v190 offset:3072
	ds_read_b128 v[146:149], v191
	ds_read_b128 v[150:153], v191 offset:1024
	ds_read_b128 v[154:157], v191 offset:2048
	ds_read_b128 v[158:161], v191 offset:3072
	s_add_i32 s82, s63, 2
	s_add_u32 s78, s76, 0xfffc0080
	s_addc_u32 s79, s77, -1
	s_cmp_eq_u32 s45, s63
	s_cselect_b32 s81, s31, s79
	s_cselect_b32 s80, s33, s78
	s_cselect_b32 s79, s34, s62
	s_cselect_b32 s78, s39, s47
	v_lshl_add_u64 v[186:187], s[76:77], 0, v[180:181]
	s_add_i32 m0, s87, 0xc000
	ds_read_b128 v[162:165], v192
	ds_read_b128 v[166:169], v192 offset:1024
	ds_read_b128 v[194:197], v192 offset:2048
	ds_read_b128 v[198:201], v192 offset:3072
	ds_read_b128 v[206:209], v192 offset:4096
	ds_read_b128 v[210:213], v192 offset:5120
	ds_read_b128 v[214:217], v192 offset:6144
	ds_read_b128 v[218:221], v192 offset:7168
	global_load_lds_dwordx4 v[186:187], off
	s_add_i32 m0, s87, 0xe000
	v_lshl_add_u64 v[186:187], s[76:77], 0, v[182:183]
	global_load_lds_dwordx4 v[186:187], off
	s_waitcnt vmcnt(8)
	s_waitcnt lgkmcnt(0)
	s_setprio 1
	s_barrier
	v_mfma_f32_16x16x32_bf16 v[142:145], v[114:117], v[162:165], v[142:145]
	v_mfma_f32_16x16x32_bf16 v[138:141], v[122:125], v[162:165], v[138:141]
	v_mfma_f32_16x16x32_bf16 v[110:113], v[114:117], v[194:197], v[110:113]
	v_mfma_f32_16x16x32_bf16 v[106:109], v[122:125], v[194:197], v[106:109]
	v_mfma_f32_16x16x32_bf16 v[98:101], v[114:117], v[206:209], v[98:101]
	v_mfma_f32_16x16x32_bf16 v[90:93], v[122:125], v[206:209], v[90:93]
	v_mfma_f32_16x16x32_bf16 v[82:85], v[114:117], v[214:217], v[82:85]
	v_mfma_f32_16x16x32_bf16 v[74:77], v[122:125], v[214:217], v[74:77]
	v_mfma_f32_16x16x32_bf16 v[142:145], v[118:121], v[166:169], v[142:145]
	v_mfma_f32_16x16x32_bf16 v[138:141], v[126:129], v[166:169], v[138:141]
	v_mfma_f32_16x16x32_bf16 v[110:113], v[118:121], v[198:201], v[110:113]
	v_mfma_f32_16x16x32_bf16 v[106:109], v[126:129], v[198:201], v[106:109]
	v_mfma_f32_16x16x32_bf16 v[98:101], v[118:121], v[210:213], v[98:101]
	v_mfma_f32_16x16x32_bf16 v[90:93], v[126:129], v[210:213], v[90:93]
	v_mfma_f32_16x16x32_bf16 v[82:85], v[118:121], v[218:221], v[82:85]
	v_mfma_f32_16x16x32_bf16 v[74:77], v[126:129], v[218:221], v[74:77]
	v_mfma_f32_16x16x32_bf16 v[134:137], v[146:149], v[162:165], v[134:137]
	v_mfma_f32_16x16x32_bf16 v[130:133], v[154:157], v[162:165], v[130:133]
	v_mfma_f32_16x16x32_bf16 v[102:105], v[146:149], v[194:197], v[102:105]
	v_mfma_f32_16x16x32_bf16 v[94:97], v[154:157], v[194:197], v[94:97]
	v_mfma_f32_16x16x32_bf16 v[86:89], v[146:149], v[206:209], v[86:89]
	v_mfma_f32_16x16x32_bf16 v[78:81], v[154:157], v[206:209], v[78:81]
	v_mfma_f32_16x16x32_bf16 v[70:73], v[146:149], v[214:217], v[70:73]
	v_mfma_f32_16x16x32_bf16 v[66:69], v[154:157], v[214:217], v[66:69]
	v_mfma_f32_16x16x32_bf16 v[134:137], v[150:153], v[166:169], v[134:137]
	v_mfma_f32_16x16x32_bf16 v[130:133], v[158:161], v[166:169], v[130:133]
	v_mfma_f32_16x16x32_bf16 v[102:105], v[150:153], v[198:201], v[102:105]
	v_mfma_f32_16x16x32_bf16 v[94:97], v[158:161], v[198:201], v[94:97]
	v_mfma_f32_16x16x32_bf16 v[86:89], v[150:153], v[210:213], v[86:89]
	v_mfma_f32_16x16x32_bf16 v[78:81], v[158:161], v[210:213], v[78:81]
	v_mfma_f32_16x16x32_bf16 v[70:73], v[150:153], v[218:221], v[70:73]
	v_mfma_f32_16x16x32_bf16 v[66:69], v[158:161], v[218:221], v[66:69]
	s_setprio 0
	s_barrier
	s_add_i32 s63, s24, s86
	v_lshl_add_u64 v[186:187], s[78:79], 0, v[172:173]
	s_mov_b32 m0, s63
	ds_read_b128 v[162:165], v192 offset:16384
	ds_read_b128 v[166:169], v192 offset:17408
	ds_read_b128 v[194:197], v192 offset:18432
	ds_read_b128 v[198:201], v192 offset:19456
	ds_read_b128 v[206:209], v192 offset:20480
	ds_read_b128 v[210:213], v192 offset:21504
	ds_read_b128 v[214:217], v192 offset:22528
	ds_read_b128 v[218:221], v192 offset:23552
	global_load_lds_dwordx4 v[186:187], off
	s_add_i32 m0, s63, 0x2000
	s_add_u32 vcc_lo, s78, 0x40000
	v_lshl_add_u64 v[202:203], s[78:79], 0, v[176:177]
	s_addc_u32 vcc_hi, s79, 0
	s_add_i32 s63, s25, s86
	global_load_lds_dwordx4 v[202:203], off
	v_lshl_add_u64 v[222:223], vcc, 0, v[172:173]
	s_mov_b32 m0, s63
	v_lshl_add_u64 v[224:225], s[80:81], 0, v[174:175]
	global_load_lds_dwordx4 v[222:223], off
	s_add_i32 m0, s63, 0x2000
	v_lshl_add_u64 v[222:223], vcc, 0, v[176:177]
	global_load_lds_dwordx4 v[222:223], off
	s_mov_b32 m0, s87
	v_lshl_add_u64 v[222:223], s[80:81], 0, v[170:171]
	global_load_lds_dwordx4 v[222:223], off
	s_mov_b32 m0, s88
	s_nop 0
	global_load_lds_dwordx4 v[224:225], off
	s_waitcnt vmcnt(8) lgkmcnt(0)
	s_setprio 1
	s_barrier
	v_mfma_f32_16x16x32_bf16 v[62:65], v[114:117], v[162:165], v[62:65]
	v_mfma_f32_16x16x32_bf16 v[58:61], v[122:125], v[162:165], v[58:61]
	v_mfma_f32_16x16x32_bf16 v[50:53], v[114:117], v[194:197], v[50:53]
	v_mfma_f32_16x16x32_bf16 v[42:45], v[122:125], v[194:197], v[42:45]
	v_mfma_f32_16x16x32_bf16 v[34:37], v[114:117], v[206:209], v[34:37]
	v_mfma_f32_16x16x32_bf16 v[26:29], v[122:125], v[206:209], v[26:29]
	v_mfma_f32_16x16x32_bf16 v[18:21], v[114:117], v[214:217], v[18:21]
	v_mfma_f32_16x16x32_bf16 v[10:13], v[122:125], v[214:217], v[10:13]
	v_mfma_f32_16x16x32_bf16 v[62:65], v[118:121], v[166:169], v[62:65]
	v_mfma_f32_16x16x32_bf16 v[58:61], v[126:129], v[166:169], v[58:61]
	v_mfma_f32_16x16x32_bf16 v[50:53], v[118:121], v[198:201], v[50:53]
	v_mfma_f32_16x16x32_bf16 v[42:45], v[126:129], v[198:201], v[42:45]
	v_mfma_f32_16x16x32_bf16 v[34:37], v[118:121], v[210:213], v[34:37]
	v_mfma_f32_16x16x32_bf16 v[26:29], v[126:129], v[210:213], v[26:29]
	v_mfma_f32_16x16x32_bf16 v[18:21], v[118:121], v[218:221], v[18:21]
	v_mfma_f32_16x16x32_bf16 v[10:13], v[126:129], v[218:221], v[10:13]
	v_mfma_f32_16x16x32_bf16 v[54:57], v[146:149], v[162:165], v[54:57]
	v_mfma_f32_16x16x32_bf16 v[46:49], v[154:157], v[162:165], v[46:49]
	v_mfma_f32_16x16x32_bf16 v[38:41], v[146:149], v[194:197], v[38:41]
	v_mfma_f32_16x16x32_bf16 v[30:33], v[154:157], v[194:197], v[30:33]
	v_mfma_f32_16x16x32_bf16 v[22:25], v[146:149], v[206:209], v[22:25]
	v_mfma_f32_16x16x32_bf16 v[14:17], v[154:157], v[206:209], v[14:17]
	v_mfma_f32_16x16x32_bf16 v[6:9], v[146:149], v[214:217], v[6:9]
	v_mfma_f32_16x16x32_bf16 v[2:5], v[154:157], v[214:217], v[2:5]
	v_mfma_f32_16x16x32_bf16 v[54:57], v[150:153], v[166:169], v[54:57]
	v_mfma_f32_16x16x32_bf16 v[46:49], v[158:161], v[166:169], v[46:49]
	v_mfma_f32_16x16x32_bf16 v[38:41], v[150:153], v[198:201], v[38:41]
	v_mfma_f32_16x16x32_bf16 v[30:33], v[158:161], v[198:201], v[30:33]
	v_mfma_f32_16x16x32_bf16 v[22:25], v[150:153], v[210:213], v[22:25]
	v_mfma_f32_16x16x32_bf16 v[14:17], v[158:161], v[210:213], v[14:17]
	v_mfma_f32_16x16x32_bf16 v[6:9], v[150:153], v[218:221], v[6:9]
	v_mfma_f32_16x16x32_bf16 v[2:5], v[158:161], v[218:221], v[2:5]
	s_setprio 0
	s_barrier
	s_add_i32 s63, 0, 0x18000
	s_add_i32 s83, 0, 0x1c000
	v_add_u32_e32 v126, s63, v189
	v_add_u32_e32 v158, s83, v189
	ds_read_b128 v[114:117], v126
	ds_read_b128 v[118:121], v126 offset:1024
	ds_read_b128 v[122:125], v126 offset:2048
	ds_read_b128 v[126:129], v126 offset:3072
	ds_read_b128 v[146:149], v158
	ds_read_b128 v[150:153], v158 offset:1024
	ds_read_b128 v[154:157], v158 offset:2048
	ds_read_b128 v[158:161], v158 offset:3072
	s_add_u32 s80, s80, 0x40000
	s_addc_u32 s81, s81, 0
	s_mov_b32 m0, s89
	v_lshl_add_u64 v[226:227], s[80:81], 0, v[170:171]
	ds_read_b128 v[162:165], v192 offset:32768
	ds_read_b128 v[166:169], v192 offset:33792
	ds_read_b128 v[194:197], v192 offset:34816
	ds_read_b128 v[198:201], v192 offset:35840
	ds_read_b128 v[206:209], v192 offset:36864
	ds_read_b128 v[210:213], v192 offset:37888
	ds_read_b128 v[214:217], v192 offset:38912
	ds_read_b128 v[218:221], v192 offset:39936
	global_load_lds_dwordx4 v[226:227], off
	s_mov_b32 m0, s90
	v_lshl_add_u64 v[226:227], s[80:81], 0, v[174:175]
	global_load_lds_dwordx4 v[226:227], off
	s_waitcnt vmcnt(8) lgkmcnt(0)
	s_setprio 1
	s_barrier
	v_mfma_f32_16x16x32_bf16 v[142:145], v[114:117], v[162:165], v[142:145]
	v_mfma_f32_16x16x32_bf16 v[138:141], v[122:125], v[162:165], v[138:141]
	v_mfma_f32_16x16x32_bf16 v[110:113], v[114:117], v[194:197], v[110:113]
	v_mfma_f32_16x16x32_bf16 v[106:109], v[122:125], v[194:197], v[106:109]
	v_mfma_f32_16x16x32_bf16 v[98:101], v[114:117], v[206:209], v[98:101]
	v_mfma_f32_16x16x32_bf16 v[90:93], v[122:125], v[206:209], v[90:93]
	v_mfma_f32_16x16x32_bf16 v[82:85], v[114:117], v[214:217], v[82:85]
	v_mfma_f32_16x16x32_bf16 v[74:77], v[122:125], v[214:217], v[74:77]
	v_mfma_f32_16x16x32_bf16 v[142:145], v[118:121], v[166:169], v[142:145]
	v_mfma_f32_16x16x32_bf16 v[138:141], v[126:129], v[166:169], v[138:141]
	v_mfma_f32_16x16x32_bf16 v[110:113], v[118:121], v[198:201], v[110:113]
	v_mfma_f32_16x16x32_bf16 v[106:109], v[126:129], v[198:201], v[106:109]
	v_mfma_f32_16x16x32_bf16 v[98:101], v[118:121], v[210:213], v[98:101]
	v_mfma_f32_16x16x32_bf16 v[90:93], v[126:129], v[210:213], v[90:93]
	v_mfma_f32_16x16x32_bf16 v[82:85], v[118:121], v[218:221], v[82:85]
	v_mfma_f32_16x16x32_bf16 v[74:77], v[126:129], v[218:221], v[74:77]
	v_mfma_f32_16x16x32_bf16 v[134:137], v[146:149], v[162:165], v[134:137]
	v_mfma_f32_16x16x32_bf16 v[130:133], v[154:157], v[162:165], v[130:133]
	v_mfma_f32_16x16x32_bf16 v[102:105], v[146:149], v[194:197], v[102:105]
	v_mfma_f32_16x16x32_bf16 v[94:97], v[154:157], v[194:197], v[94:97]
	v_mfma_f32_16x16x32_bf16 v[86:89], v[146:149], v[206:209], v[86:89]
	v_mfma_f32_16x16x32_bf16 v[78:81], v[154:157], v[206:209], v[78:81]
	v_mfma_f32_16x16x32_bf16 v[70:73], v[146:149], v[214:217], v[70:73]
	v_mfma_f32_16x16x32_bf16 v[66:69], v[154:157], v[214:217], v[66:69]
	v_mfma_f32_16x16x32_bf16 v[134:137], v[150:153], v[166:169], v[134:137]
	v_mfma_f32_16x16x32_bf16 v[130:133], v[158:161], v[166:169], v[130:133]
	v_mfma_f32_16x16x32_bf16 v[102:105], v[150:153], v[198:201], v[102:105]
	v_mfma_f32_16x16x32_bf16 v[94:97], v[158:161], v[198:201], v[94:97]
	v_mfma_f32_16x16x32_bf16 v[86:89], v[150:153], v[210:213], v[86:89]
	v_mfma_f32_16x16x32_bf16 v[78:81], v[158:161], v[210:213], v[78:81]
	v_mfma_f32_16x16x32_bf16 v[70:73], v[150:153], v[218:221], v[70:73]
	v_mfma_f32_16x16x32_bf16 v[66:69], v[158:161], v[218:221], v[66:69]
	s_setprio 0
	s_barrier
	s_add_i32 s63, s63, s86
	v_lshl_add_u64 v[186:187], v[186:187], 0, s[22:23]
	s_mov_b32 m0, s63
	ds_read_b128 v[162:165], v192 offset:49152
	ds_read_b128 v[166:169], v192 offset:50176
	ds_read_b128 v[194:197], v192 offset:51200
	ds_read_b128 v[198:201], v192 offset:52224
	ds_read_b128 v[206:209], v192 offset:53248
	ds_read_b128 v[210:213], v192 offset:54272
	ds_read_b128 v[214:217], v192 offset:55296
	ds_read_b128 v[218:221], v192 offset:56320
	global_load_lds_dwordx4 v[186:187], off
	s_add_i32 m0, s63, 0x2000
	s_add_u32 s78, s78, 0x40080
	v_lshl_add_u64 v[186:187], v[202:203], 0, s[22:23]
	s_addc_u32 s79, s79, 0
	s_add_i32 s63, s83, s86
	global_load_lds_dwordx4 v[186:187], off
	s_mov_b32 m0, s63
	v_lshl_add_u64 v[186:187], s[78:79], 0, v[172:173]
	global_load_lds_dwordx4 v[186:187], off
	s_add_i32 m0, s63, 0x2000
	v_lshl_add_u64 v[186:187], s[78:79], 0, v[176:177]
	global_load_lds_dwordx4 v[186:187], off
	s_mov_b32 m0, s95
	v_lshl_add_u64 v[186:187], v[222:223], 0, s[22:23]
	global_load_lds_dwordx4 v[186:187], off
	s_mov_b32 m0, s96
	v_lshl_add_u64 v[186:187], v[224:225], 0, s[22:23]
	global_load_lds_dwordx4 v[186:187], off
	s_waitcnt vmcnt(8) lgkmcnt(0)
	s_setprio 1
	s_barrier
	v_mfma_f32_16x16x32_bf16 v[62:65], v[114:117], v[162:165], v[62:65]
	v_mfma_f32_16x16x32_bf16 v[58:61], v[122:125], v[162:165], v[58:61]
	v_mfma_f32_16x16x32_bf16 v[50:53], v[114:117], v[194:197], v[50:53]
	v_mfma_f32_16x16x32_bf16 v[42:45], v[122:125], v[194:197], v[42:45]
	v_mfma_f32_16x16x32_bf16 v[34:37], v[114:117], v[206:209], v[34:37]
	v_mfma_f32_16x16x32_bf16 v[26:29], v[122:125], v[206:209], v[26:29]
	v_mfma_f32_16x16x32_bf16 v[18:21], v[114:117], v[214:217], v[18:21]
	v_mfma_f32_16x16x32_bf16 v[10:13], v[122:125], v[214:217], v[10:13]
	v_mfma_f32_16x16x32_bf16 v[62:65], v[118:121], v[166:169], v[62:65]
	v_mfma_f32_16x16x32_bf16 v[58:61], v[126:129], v[166:169], v[58:61]
	v_mfma_f32_16x16x32_bf16 v[50:53], v[118:121], v[198:201], v[50:53]
	v_mfma_f32_16x16x32_bf16 v[42:45], v[126:129], v[198:201], v[42:45]
	v_mfma_f32_16x16x32_bf16 v[34:37], v[118:121], v[210:213], v[34:37]
	v_mfma_f32_16x16x32_bf16 v[26:29], v[126:129], v[210:213], v[26:29]
	v_mfma_f32_16x16x32_bf16 v[18:21], v[118:121], v[218:221], v[18:21]
	v_mfma_f32_16x16x32_bf16 v[10:13], v[126:129], v[218:221], v[10:13]
	v_mfma_f32_16x16x32_bf16 v[54:57], v[146:149], v[162:165], v[54:57]
	v_mfma_f32_16x16x32_bf16 v[46:49], v[154:157], v[162:165], v[46:49]
	v_mfma_f32_16x16x32_bf16 v[38:41], v[146:149], v[194:197], v[38:41]
	v_mfma_f32_16x16x32_bf16 v[30:33], v[154:157], v[194:197], v[30:33]
	v_mfma_f32_16x16x32_bf16 v[22:25], v[146:149], v[206:209], v[22:25]
	v_mfma_f32_16x16x32_bf16 v[14:17], v[154:157], v[206:209], v[14:17]
	v_mfma_f32_16x16x32_bf16 v[6:9], v[146:149], v[214:217], v[6:9]
	v_mfma_f32_16x16x32_bf16 v[2:5], v[154:157], v[214:217], v[2:5]
	v_mfma_f32_16x16x32_bf16 v[54:57], v[150:153], v[166:169], v[54:57]
	v_mfma_f32_16x16x32_bf16 v[46:49], v[158:161], v[166:169], v[46:49]
	v_mfma_f32_16x16x32_bf16 v[38:41], v[150:153], v[198:201], v[38:41]
	v_mfma_f32_16x16x32_bf16 v[30:33], v[158:161], v[198:201], v[30:33]
	v_mfma_f32_16x16x32_bf16 v[22:25], v[150:153], v[210:213], v[22:25]
	v_mfma_f32_16x16x32_bf16 v[14:17], v[158:161], v[210:213], v[14:17]
	v_mfma_f32_16x16x32_bf16 v[6:9], v[150:153], v[218:221], v[6:9]
	v_mfma_f32_16x16x32_bf16 v[2:5], v[158:161], v[218:221], v[2:5]
	s_setprio 0
	s_barrier
	s_add_u32 s76, s76, 0x100
	s_addc_u32 s77, s77, 0
	s_add_u32 s47, s47, 0x100
	s_addc_u32 s62, s62, 0
	s_cmp_ge_i32 s82, s7
	s_mov_b32 s63, s82
	s_cbranch_scc0 .LBB0_566
	s_and_b64 vcc, exec, s[26:27]
	s_cbranch_vccz .LBB0_569
	s_barrier

.LBB0_744:
	s_add_u32 s36, s96, s22
	s_addc_u32 s37, s97, s23
	s_and_b64 s[14:15], s[4:5], exec
	s_cselect_b32 s14, s37, s43
	s_cselect_b32 s15, s36, s42
	s_add_u32 s38, s2, s26
	s_addc_u32 s39, s3, s27
	s_and_b64 s[46:47], s[4:5], exec
	s_cselect_b32 s21, s39, s45
	s_cselect_b32 s65, s38, s44
	s_add_u32 s42, s42, 0x40080
	s_addc_u32 s43, s43, 0
	s_add_u32 s66, s44, 0x100
	s_addc_u32 s67, s45, 0
	s_mov_b32 s68, -2
	ds_read_b128 v[154:157], v150
	ds_read_b128 v[158:161], v150 offset:1024
	ds_read_b128 v[162:165], v150 offset:2048
	ds_read_b128 v[166:169], v150 offset:3072
	ds_read_b128 v[170:173], v151
	ds_read_b128 v[174:177], v151 offset:1024
	ds_read_b128 v[178:181], v151 offset:2048
	ds_read_b128 v[182:185], v151 offset:3072
	s_add_u32 s44, s42, 0xfffc0080
	s_addc_u32 s45, s43, -1
	s_cmp_eq_u32 s68, 12
	s_cselect_b32 s47, s14, s45
	s_cselect_b32 s46, s15, s44
	s_cselect_b32 s45, s21, s67
	s_cselect_b32 s44, s65, s66
	v_lshl_add_u64 v[146:147], s[42:43], 0, v[138:139]
	s_add_i32 m0, s19, 0xc000
	ds_read_b128 v[186:189], v152
	ds_read_b128 v[190:193], v152 offset:1024
	ds_read_b128 v[194:197], v152 offset:2048
	ds_read_b128 v[198:201], v152 offset:3072
	ds_read_b128 v[206:209], v152 offset:4096
	ds_read_b128 v[210:213], v152 offset:5120
	ds_read_b128 v[214:217], v152 offset:6144
	ds_read_b128 v[218:221], v152 offset:7168
	global_load_lds_dwordx4 v[146:147], off
	s_add_i32 m0, s19, 0xe000
	v_lshl_add_u64 v[146:147], s[42:43], 0, v[140:141]
	global_load_lds_dwordx4 v[146:147], off
	s_waitcnt vmcnt(8) lgkmcnt(0)
	s_setprio 1
	s_barrier
	v_mfma_f32_16x16x32_bf16 v[126:129], v[154:157], v[186:189], 0
	v_mfma_f32_16x16x32_bf16 v[122:125], v[162:165], v[186:189], 0
	v_mfma_f32_16x16x32_bf16 v[110:113], v[154:157], v[194:197], 0
	v_mfma_f32_16x16x32_bf16 v[106:109], v[162:165], v[194:197], 0
	v_mfma_f32_16x16x32_bf16 v[94:97], v[154:157], v[206:209], 0
	v_mfma_f32_16x16x32_bf16 v[90:93], v[162:165], v[206:209], 0
	v_mfma_f32_16x16x32_bf16 v[78:81], v[154:157], v[214:217], 0
	v_mfma_f32_16x16x32_bf16 v[74:77], v[162:165], v[214:217], 0
	v_mfma_f32_16x16x32_bf16 v[126:129], v[158:161], v[190:193], v[126:129]
	v_mfma_f32_16x16x32_bf16 v[122:125], v[166:169], v[190:193], v[122:125]
	v_mfma_f32_16x16x32_bf16 v[110:113], v[158:161], v[198:201], v[110:113]
	v_mfma_f32_16x16x32_bf16 v[106:109], v[166:169], v[198:201], v[106:109]
	v_mfma_f32_16x16x32_bf16 v[94:97], v[158:161], v[210:213], v[94:97]
	v_mfma_f32_16x16x32_bf16 v[90:93], v[166:169], v[210:213], v[90:93]
	v_mfma_f32_16x16x32_bf16 v[78:81], v[158:161], v[218:221], v[78:81]
	v_mfma_f32_16x16x32_bf16 v[74:77], v[166:169], v[218:221], v[74:77]
	v_mfma_f32_16x16x32_bf16 v[118:121], v[170:173], v[186:189], 0
	v_mfma_f32_16x16x32_bf16 v[114:117], v[178:181], v[186:189], 0
	v_mfma_f32_16x16x32_bf16 v[102:105], v[170:173], v[194:197], 0
	v_mfma_f32_16x16x32_bf16 v[98:101], v[178:181], v[194:197], 0
	v_mfma_f32_16x16x32_bf16 v[86:89], v[170:173], v[206:209], 0
	v_mfma_f32_16x16x32_bf16 v[82:85], v[178:181], v[206:209], 0
	v_mfma_f32_16x16x32_bf16 v[70:73], v[170:173], v[214:217], 0
	v_mfma_f32_16x16x32_bf16 v[66:69], v[178:181], v[214:217], 0
	v_mfma_f32_16x16x32_bf16 v[118:121], v[174:177], v[190:193], v[118:121]
	v_mfma_f32_16x16x32_bf16 v[114:117], v[182:185], v[190:193], v[114:117]
	v_mfma_f32_16x16x32_bf16 v[102:105], v[174:177], v[198:201], v[102:105]
	v_mfma_f32_16x16x32_bf16 v[98:101], v[182:185], v[198:201], v[98:101]
	v_mfma_f32_16x16x32_bf16 v[86:89], v[174:177], v[210:213], v[86:89]
	v_mfma_f32_16x16x32_bf16 v[82:85], v[182:185], v[210:213], v[82:85]
	v_mfma_f32_16x16x32_bf16 v[70:73], v[174:177], v[218:221], v[70:73]
	v_mfma_f32_16x16x32_bf16 v[66:69], v[182:185], v[218:221], v[66:69]
	s_setprio 0
	s_barrier
	s_add_i32 s69, s49, s16
	v_lshl_add_u64 v[146:147], s[44:45], 0, v[134:135]
	s_mov_b32 m0, s69
	ds_read_b128 v[186:189], v152 offset:16384
	ds_read_b128 v[190:193], v152 offset:17408
	ds_read_b128 v[194:197], v152 offset:18432
	ds_read_b128 v[198:201], v152 offset:19456
	ds_read_b128 v[206:209], v152 offset:20480
	ds_read_b128 v[210:213], v152 offset:21504
	ds_read_b128 v[214:217], v152 offset:22528
	ds_read_b128 v[218:221], v152 offset:23552
	global_load_lds_dwordx4 v[146:147], off
	s_add_i32 m0, s69, 0x2000
	s_add_u32 s70, s44, 0x40000
	v_lshl_add_u64 v[202:203], s[44:45], 0, v[130:131]
	s_addc_u32 s71, s45, 0
	s_add_i32 s69, s62, s16
	global_load_lds_dwordx4 v[202:203], off
	v_lshl_add_u64 v[222:223], s[70:71], 0, v[134:135]
	s_mov_b32 m0, s69
	v_lshl_add_u64 v[224:225], s[46:47], 0, v[132:133]
	global_load_lds_dwordx4 v[222:223], off
	s_add_i32 m0, s69, 0x2000
	v_lshl_add_u64 v[222:223], s[70:71], 0, v[130:131]
	global_load_lds_dwordx4 v[222:223], off
	s_mov_b32 m0, s19
	v_lshl_add_u64 v[222:223], s[46:47], 0, v[136:137]
	global_load_lds_dwordx4 v[222:223], off
	s_mov_b32 m0, s24
	s_nop 0
	global_load_lds_dwordx4 v[224:225], off
	s_waitcnt vmcnt(8) lgkmcnt(0)
	s_setprio 1
	s_barrier
	v_mfma_f32_16x16x32_bf16 v[62:65], v[154:157], v[186:189], 0
	v_mfma_f32_16x16x32_bf16 v[58:61], v[162:165], v[186:189], 0
	v_mfma_f32_16x16x32_bf16 v[46:49], v[154:157], v[194:197], 0
	v_mfma_f32_16x16x32_bf16 v[42:45], v[162:165], v[194:197], 0
	v_mfma_f32_16x16x32_bf16 v[30:33], v[154:157], v[206:209], 0
	v_mfma_f32_16x16x32_bf16 v[26:29], v[162:165], v[206:209], 0
	v_mfma_f32_16x16x32_bf16 v[14:17], v[154:157], v[214:217], 0
	v_mfma_f32_16x16x32_bf16 v[10:13], v[162:165], v[214:217], 0
	v_mfma_f32_16x16x32_bf16 v[62:65], v[158:161], v[190:193], v[62:65]
	v_mfma_f32_16x16x32_bf16 v[58:61], v[166:169], v[190:193], v[58:61]
	v_mfma_f32_16x16x32_bf16 v[46:49], v[158:161], v[198:201], v[46:49]
	v_mfma_f32_16x16x32_bf16 v[42:45], v[166:169], v[198:201], v[42:45]
	v_mfma_f32_16x16x32_bf16 v[30:33], v[158:161], v[210:213], v[30:33]
	v_mfma_f32_16x16x32_bf16 v[26:29], v[166:169], v[210:213], v[26:29]
	v_mfma_f32_16x16x32_bf16 v[14:17], v[158:161], v[218:221], v[14:17]
	v_mfma_f32_16x16x32_bf16 v[10:13], v[166:169], v[218:221], v[10:13]
	v_mfma_f32_16x16x32_bf16 v[54:57], v[170:173], v[186:189], 0
	v_mfma_f32_16x16x32_bf16 v[50:53], v[178:181], v[186:189], 0
	v_mfma_f32_16x16x32_bf16 v[38:41], v[170:173], v[194:197], 0
	v_mfma_f32_16x16x32_bf16 v[34:37], v[178:181], v[194:197], 0
	v_mfma_f32_16x16x32_bf16 v[22:25], v[170:173], v[206:209], 0
	v_mfma_f32_16x16x32_bf16 v[18:21], v[178:181], v[206:209], 0
	v_mfma_f32_16x16x32_bf16 v[6:9], v[170:173], v[214:217], 0
	v_mfma_f32_16x16x32_bf16 v[2:5], v[178:181], v[214:217], 0
	v_mfma_f32_16x16x32_bf16 v[54:57], v[174:177], v[190:193], v[54:57]
	v_mfma_f32_16x16x32_bf16 v[50:53], v[182:185], v[190:193], v[50:53]
	v_mfma_f32_16x16x32_bf16 v[38:41], v[174:177], v[198:201], v[38:41]
	v_mfma_f32_16x16x32_bf16 v[34:37], v[182:185], v[198:201], v[34:37]
	v_mfma_f32_16x16x32_bf16 v[22:25], v[174:177], v[210:213], v[22:25]
	v_mfma_f32_16x16x32_bf16 v[18:21], v[182:185], v[210:213], v[18:21]
	v_mfma_f32_16x16x32_bf16 v[6:9], v[174:177], v[218:221], v[6:9]
	v_mfma_f32_16x16x32_bf16 v[2:5], v[182:185], v[218:221], v[2:5]
	s_setprio 0
	s_barrier
	s_add_i32 s69, 0, 0x18000
	v_add_u32_e32 v153, s69, v149
	s_add_i32 s70, 0, 0x1c000
	ds_read_b128 v[154:157], v153
	ds_read_b128 v[158:161], v153 offset:1024
	ds_read_b128 v[162:165], v153 offset:2048
	ds_read_b128 v[166:169], v153 offset:3072
	v_add_u32_e32 v153, s70, v149
	ds_read_b128 v[170:173], v153
	ds_read_b128 v[174:177], v153 offset:1024
	ds_read_b128 v[178:181], v153 offset:2048
	ds_read_b128 v[182:185], v153 offset:3072
	s_add_u32 s46, s46, 0x40000
	s_addc_u32 s47, s47, 0
	s_mov_b32 m0, s25
	v_lshl_add_u64 v[226:227], s[46:47], 0, v[136:137]
	ds_read_b128 v[186:189], v152 offset:32768
	ds_read_b128 v[190:193], v152 offset:33792
	ds_read_b128 v[194:197], v152 offset:34816
	ds_read_b128 v[198:201], v152 offset:35840
	ds_read_b128 v[206:209], v152 offset:36864
	ds_read_b128 v[210:213], v152 offset:37888
	ds_read_b128 v[214:217], v152 offset:38912
	ds_read_b128 v[218:221], v152 offset:39936
	global_load_lds_dwordx4 v[226:227], off
	s_mov_b32 m0, s28
	v_lshl_add_u64 v[226:227], s[46:47], 0, v[132:133]
	global_load_lds_dwordx4 v[226:227], off
	s_waitcnt vmcnt(8) lgkmcnt(0)
	s_setprio 1
	s_barrier
	v_mfma_f32_16x16x32_bf16 v[126:129], v[154:157], v[186:189], v[126:129]
	v_mfma_f32_16x16x32_bf16 v[122:125], v[162:165], v[186:189], v[122:125]
	v_mfma_f32_16x16x32_bf16 v[110:113], v[154:157], v[194:197], v[110:113]
	v_mfma_f32_16x16x32_bf16 v[106:109], v[162:165], v[194:197], v[106:109]
	v_mfma_f32_16x16x32_bf16 v[94:97], v[154:157], v[206:209], v[94:97]
	v_mfma_f32_16x16x32_bf16 v[90:93], v[162:165], v[206:209], v[90:93]
	v_mfma_f32_16x16x32_bf16 v[78:81], v[154:157], v[214:217], v[78:81]
	v_mfma_f32_16x16x32_bf16 v[74:77], v[162:165], v[214:217], v[74:77]
	v_mfma_f32_16x16x32_bf16 v[126:129], v[158:161], v[190:193], v[126:129]
	v_mfma_f32_16x16x32_bf16 v[122:125], v[166:169], v[190:193], v[122:125]
	v_mfma_f32_16x16x32_bf16 v[110:113], v[158:161], v[198:201], v[110:113]
	v_mfma_f32_16x16x32_bf16 v[106:109], v[166:169], v[198:201], v[106:109]
	v_mfma_f32_16x16x32_bf16 v[94:97], v[158:161], v[210:213], v[94:97]
	v_mfma_f32_16x16x32_bf16 v[90:93], v[166:169], v[210:213], v[90:93]
	v_mfma_f32_16x16x32_bf16 v[78:81], v[158:161], v[218:221], v[78:81]
	v_mfma_f32_16x16x32_bf16 v[74:77], v[166:169], v[218:221], v[74:77]
	v_mfma_f32_16x16x32_bf16 v[118:121], v[170:173], v[186:189], v[118:121]
	v_mfma_f32_16x16x32_bf16 v[114:117], v[178:181], v[186:189], v[114:117]
	v_mfma_f32_16x16x32_bf16 v[102:105], v[170:173], v[194:197], v[102:105]
	v_mfma_f32_16x16x32_bf16 v[98:101], v[178:181], v[194:197], v[98:101]
	v_mfma_f32_16x16x32_bf16 v[86:89], v[170:173], v[206:209], v[86:89]
	v_mfma_f32_16x16x32_bf16 v[82:85], v[178:181], v[206:209], v[82:85]
	v_mfma_f32_16x16x32_bf16 v[70:73], v[170:173], v[214:217], v[70:73]
	v_mfma_f32_16x16x32_bf16 v[66:69], v[178:181], v[214:217], v[66:69]
	v_mfma_f32_16x16x32_bf16 v[118:121], v[174:177], v[190:193], v[118:121]
	v_mfma_f32_16x16x32_bf16 v[114:117], v[182:185], v[190:193], v[114:117]
	v_mfma_f32_16x16x32_bf16 v[102:105], v[174:177], v[198:201], v[102:105]
	v_mfma_f32_16x16x32_bf16 v[98:101], v[182:185], v[198:201], v[98:101]
	v_mfma_f32_16x16x32_bf16 v[86:89], v[174:177], v[210:213], v[86:89]
	v_mfma_f32_16x16x32_bf16 v[82:85], v[182:185], v[210:213], v[82:85]
	v_mfma_f32_16x16x32_bf16 v[70:73], v[174:177], v[218:221], v[70:73]
	v_mfma_f32_16x16x32_bf16 v[66:69], v[182:185], v[218:221], v[66:69]
	s_setprio 0
	s_barrier
	s_add_i32 s46, s69, s16
	v_lshl_add_u64 v[146:147], v[146:147], 0, s[10:11]
	s_mov_b32 m0, s46
	ds_read_b128 v[186:189], v152 offset:49152
	ds_read_b128 v[190:193], v152 offset:50176
	ds_read_b128 v[194:197], v152 offset:51200
	ds_read_b128 v[198:201], v152 offset:52224
	ds_read_b128 v[206:209], v152 offset:53248
	ds_read_b128 v[210:213], v152 offset:54272
	ds_read_b128 v[214:217], v152 offset:55296
	ds_read_b128 v[218:221], v152 offset:56320
	global_load_lds_dwordx4 v[146:147], off
	s_add_i32 m0, s46, 0x2000
	s_add_u32 s44, s44, 0x40080
	v_lshl_add_u64 v[146:147], v[202:203], 0, s[10:11]
	s_addc_u32 s45, s45, 0
	s_add_i32 s46, s70, s16
	global_load_lds_dwordx4 v[146:147], off
	s_mov_b32 m0, s46
	v_lshl_add_u64 v[146:147], s[44:45], 0, v[134:135]
	global_load_lds_dwordx4 v[146:147], off
	s_add_i32 m0, s46, 0x2000
	v_lshl_add_u64 v[146:147], s[44:45], 0, v[130:131]
	global_load_lds_dwordx4 v[146:147], off
	s_mov_b32 m0, s33
	v_lshl_add_u64 v[146:147], v[222:223], 0, s[10:11]
	global_load_lds_dwordx4 v[146:147], off
	s_mov_b32 m0, s35
	v_lshl_add_u64 v[146:147], v[224:225], 0, s[10:11]
	global_load_lds_dwordx4 v[146:147], off
	s_waitcnt vmcnt(8) lgkmcnt(0)
	s_setprio 1
	s_barrier
	v_mfma_f32_16x16x32_bf16 v[62:65], v[154:157], v[186:189], v[62:65]
	v_mfma_f32_16x16x32_bf16 v[58:61], v[162:165], v[186:189], v[58:61]
	v_mfma_f32_16x16x32_bf16 v[46:49], v[154:157], v[194:197], v[46:49]
	v_mfma_f32_16x16x32_bf16 v[42:45], v[162:165], v[194:197], v[42:45]
	v_mfma_f32_16x16x32_bf16 v[30:33], v[154:157], v[206:209], v[30:33]
	v_mfma_f32_16x16x32_bf16 v[26:29], v[162:165], v[206:209], v[26:29]
	v_mfma_f32_16x16x32_bf16 v[14:17], v[154:157], v[214:217], v[14:17]
	v_mfma_f32_16x16x32_bf16 v[10:13], v[162:165], v[214:217], v[10:13]
	v_mfma_f32_16x16x32_bf16 v[62:65], v[158:161], v[190:193], v[62:65]
	v_mfma_f32_16x16x32_bf16 v[58:61], v[166:169], v[190:193], v[58:61]
	v_mfma_f32_16x16x32_bf16 v[46:49], v[158:161], v[198:201], v[46:49]
	v_mfma_f32_16x16x32_bf16 v[42:45], v[166:169], v[198:201], v[42:45]
	v_mfma_f32_16x16x32_bf16 v[30:33], v[158:161], v[210:213], v[30:33]
	v_mfma_f32_16x16x32_bf16 v[26:29], v[166:169], v[210:213], v[26:29]
	v_mfma_f32_16x16x32_bf16 v[14:17], v[158:161], v[218:221], v[14:17]
	v_mfma_f32_16x16x32_bf16 v[10:13], v[166:169], v[218:221], v[10:13]
	v_mfma_f32_16x16x32_bf16 v[54:57], v[170:173], v[186:189], v[54:57]
	v_mfma_f32_16x16x32_bf16 v[50:53], v[178:181], v[186:189], v[50:53]
	v_mfma_f32_16x16x32_bf16 v[38:41], v[170:173], v[194:197], v[38:41]
	v_mfma_f32_16x16x32_bf16 v[34:37], v[178:181], v[194:197], v[34:37]
	v_mfma_f32_16x16x32_bf16 v[22:25], v[170:173], v[206:209], v[22:25]
	v_mfma_f32_16x16x32_bf16 v[18:21], v[178:181], v[206:209], v[18:21]
	v_mfma_f32_16x16x32_bf16 v[6:9], v[170:173], v[214:217], v[6:9]
	v_mfma_f32_16x16x32_bf16 v[2:5], v[178:181], v[214:217], v[2:5]
	v_mfma_f32_16x16x32_bf16 v[54:57], v[174:177], v[190:193], v[54:57]
	v_mfma_f32_16x16x32_bf16 v[50:53], v[182:185], v[190:193], v[50:53]
	v_mfma_f32_16x16x32_bf16 v[38:41], v[174:177], v[198:201], v[38:41]
	v_mfma_f32_16x16x32_bf16 v[34:37], v[182:185], v[198:201], v[34:37]
	v_mfma_f32_16x16x32_bf16 v[22:25], v[174:177], v[210:213], v[22:25]
	v_mfma_f32_16x16x32_bf16 v[18:21], v[182:185], v[210:213], v[18:21]
	v_mfma_f32_16x16x32_bf16 v[6:9], v[174:177], v[218:221], v[6:9]
	v_mfma_f32_16x16x32_bf16 v[2:5], v[182:185], v[218:221], v[2:5]
	s_setprio 0
	s_barrier
	s_add_i32 s68, s68, 2
	s_add_u32 s42, s42, 0x100
	s_addc_u32 s43, s43, 0
	s_add_u32 s66, s66, 0x100
	s_addc_u32 s67, s67, 0
	s_cmp_gt_u32 s68, 13
.LBB0_745:
	ds_read_b128 v[154:157], v150
	ds_read_b128 v[158:161], v150 offset:1024
	ds_read_b128 v[162:165], v150 offset:2048
	ds_read_b128 v[166:169], v150 offset:3072
	ds_read_b128 v[170:173], v151
	ds_read_b128 v[174:177], v151 offset:1024
	ds_read_b128 v[178:181], v151 offset:2048
	ds_read_b128 v[182:185], v151 offset:3072
	s_add_u32 s44, s42, 0xfffc0080
	s_addc_u32 s45, s43, -1
	s_cmp_eq_u32 s68, 12
	s_cselect_b32 s47, s14, s45
	s_cselect_b32 s46, s15, s44
	s_cselect_b32 s45, s21, s67
	s_cselect_b32 s44, s65, s66
	v_lshl_add_u64 v[146:147], s[42:43], 0, v[138:139]
	s_add_i32 m0, s19, 0xc000
	ds_read_b128 v[186:189], v152
	ds_read_b128 v[190:193], v152 offset:1024
	ds_read_b128 v[194:197], v152 offset:2048
	ds_read_b128 v[198:201], v152 offset:3072
	ds_read_b128 v[206:209], v152 offset:4096
	ds_read_b128 v[210:213], v152 offset:5120
	ds_read_b128 v[214:217], v152 offset:6144
	ds_read_b128 v[218:221], v152 offset:7168
	global_load_lds_dwordx4 v[146:147], off
	s_add_i32 m0, s19, 0xe000
	v_lshl_add_u64 v[146:147], s[42:43], 0, v[140:141]
	global_load_lds_dwordx4 v[146:147], off
	s_waitcnt vmcnt(8) lgkmcnt(0)
	s_setprio 1
	s_barrier
	v_mfma_f32_16x16x32_bf16 v[126:129], v[154:157], v[186:189], v[126:129]
	v_mfma_f32_16x16x32_bf16 v[122:125], v[162:165], v[186:189], v[122:125]
	v_mfma_f32_16x16x32_bf16 v[110:113], v[154:157], v[194:197], v[110:113]
	v_mfma_f32_16x16x32_bf16 v[106:109], v[162:165], v[194:197], v[106:109]
	v_mfma_f32_16x16x32_bf16 v[94:97], v[154:157], v[206:209], v[94:97]
	v_mfma_f32_16x16x32_bf16 v[90:93], v[162:165], v[206:209], v[90:93]
	v_mfma_f32_16x16x32_bf16 v[78:81], v[154:157], v[214:217], v[78:81]
	v_mfma_f32_16x16x32_bf16 v[74:77], v[162:165], v[214:217], v[74:77]
	v_mfma_f32_16x16x32_bf16 v[126:129], v[158:161], v[190:193], v[126:129]
	v_mfma_f32_16x16x32_bf16 v[122:125], v[166:169], v[190:193], v[122:125]
	v_mfma_f32_16x16x32_bf16 v[110:113], v[158:161], v[198:201], v[110:113]
	v_mfma_f32_16x16x32_bf16 v[106:109], v[166:169], v[198:201], v[106:109]
	v_mfma_f32_16x16x32_bf16 v[94:97], v[158:161], v[210:213], v[94:97]
	v_mfma_f32_16x16x32_bf16 v[90:93], v[166:169], v[210:213], v[90:93]
	v_mfma_f32_16x16x32_bf16 v[78:81], v[158:161], v[218:221], v[78:81]
	v_mfma_f32_16x16x32_bf16 v[74:77], v[166:169], v[218:221], v[74:77]
	v_mfma_f32_16x16x32_bf16 v[118:121], v[170:173], v[186:189], v[118:121]
	v_mfma_f32_16x16x32_bf16 v[114:117], v[178:181], v[186:189], v[114:117]
	v_mfma_f32_16x16x32_bf16 v[102:105], v[170:173], v[194:197], v[102:105]
	v_mfma_f32_16x16x32_bf16 v[98:101], v[178:181], v[194:197], v[98:101]
	v_mfma_f32_16x16x32_bf16 v[86:89], v[170:173], v[206:209], v[86:89]
	v_mfma_f32_16x16x32_bf16 v[82:85], v[178:181], v[206:209], v[82:85]
	v_mfma_f32_16x16x32_bf16 v[70:73], v[170:173], v[214:217], v[70:73]
	v_mfma_f32_16x16x32_bf16 v[66:69], v[178:181], v[214:217], v[66:69]
	v_mfma_f32_16x16x32_bf16 v[118:121], v[174:177], v[190:193], v[118:121]
	v_mfma_f32_16x16x32_bf16 v[114:117], v[182:185], v[190:193], v[114:117]
	v_mfma_f32_16x16x32_bf16 v[102:105], v[174:177], v[198:201], v[102:105]
	v_mfma_f32_16x16x32_bf16 v[98:101], v[182:185], v[198:201], v[98:101]
	v_mfma_f32_16x16x32_bf16 v[86:89], v[174:177], v[210:213], v[86:89]
	v_mfma_f32_16x16x32_bf16 v[82:85], v[182:185], v[210:213], v[82:85]
	v_mfma_f32_16x16x32_bf16 v[70:73], v[174:177], v[218:221], v[70:73]
	v_mfma_f32_16x16x32_bf16 v[66:69], v[182:185], v[218:221], v[66:69]
	s_setprio 0
	s_barrier
	s_add_i32 s69, s49, s16
	v_lshl_add_u64 v[146:147], s[44:45], 0, v[134:135]
	s_mov_b32 m0, s69
	ds_read_b128 v[186:189], v152 offset:16384
	ds_read_b128 v[190:193], v152 offset:17408
	ds_read_b128 v[194:197], v152 offset:18432
	ds_read_b128 v[198:201], v152 offset:19456
	ds_read_b128 v[206:209], v152 offset:20480
	ds_read_b128 v[210:213], v152 offset:21504
	ds_read_b128 v[214:217], v152 offset:22528
	ds_read_b128 v[218:221], v152 offset:23552
	global_load_lds_dwordx4 v[146:147], off
	s_add_i32 m0, s69, 0x2000
	s_add_u32 s70, s44, 0x40000
	v_lshl_add_u64 v[202:203], s[44:45], 0, v[130:131]
	s_addc_u32 s71, s45, 0
	s_add_i32 s69, s62, s16
	global_load_lds_dwordx4 v[202:203], off
	v_lshl_add_u64 v[222:223], s[70:71], 0, v[134:135]
	s_mov_b32 m0, s69
	v_lshl_add_u64 v[224:225], s[46:47], 0, v[132:133]
	global_load_lds_dwordx4 v[222:223], off
	s_add_i32 m0, s69, 0x2000
	v_lshl_add_u64 v[222:223], s[70:71], 0, v[130:131]
	global_load_lds_dwordx4 v[222:223], off
	s_mov_b32 m0, s19
	v_lshl_add_u64 v[222:223], s[46:47], 0, v[136:137]
	global_load_lds_dwordx4 v[222:223], off
	s_mov_b32 m0, s24
	s_nop 0
	global_load_lds_dwordx4 v[224:225], off
	s_waitcnt vmcnt(8) lgkmcnt(0)
	s_setprio 1
	s_barrier
	v_mfma_f32_16x16x32_bf16 v[62:65], v[154:157], v[186:189], v[62:65]
	v_mfma_f32_16x16x32_bf16 v[58:61], v[162:165], v[186:189], v[58:61]
	v_mfma_f32_16x16x32_bf16 v[46:49], v[154:157], v[194:197], v[46:49]
	v_mfma_f32_16x16x32_bf16 v[42:45], v[162:165], v[194:197], v[42:45]
	v_mfma_f32_16x16x32_bf16 v[30:33], v[154:157], v[206:209], v[30:33]
	v_mfma_f32_16x16x32_bf16 v[26:29], v[162:165], v[206:209], v[26:29]
	v_mfma_f32_16x16x32_bf16 v[14:17], v[154:157], v[214:217], v[14:17]
	v_mfma_f32_16x16x32_bf16 v[10:13], v[162:165], v[214:217], v[10:13]
	v_mfma_f32_16x16x32_bf16 v[62:65], v[158:161], v[190:193], v[62:65]
	v_mfma_f32_16x16x32_bf16 v[58:61], v[166:169], v[190:193], v[58:61]
	v_mfma_f32_16x16x32_bf16 v[46:49], v[158:161], v[198:201], v[46:49]
	v_mfma_f32_16x16x32_bf16 v[42:45], v[166:169], v[198:201], v[42:45]
	v_mfma_f32_16x16x32_bf16 v[30:33], v[158:161], v[210:213], v[30:33]
	v_mfma_f32_16x16x32_bf16 v[26:29], v[166:169], v[210:213], v[26:29]
	v_mfma_f32_16x16x32_bf16 v[14:17], v[158:161], v[218:221], v[14:17]
	v_mfma_f32_16x16x32_bf16 v[10:13], v[166:169], v[218:221], v[10:13]
	v_mfma_f32_16x16x32_bf16 v[54:57], v[170:173], v[186:189], v[54:57]
	v_mfma_f32_16x16x32_bf16 v[50:53], v[178:181], v[186:189], v[50:53]
	v_mfma_f32_16x16x32_bf16 v[38:41], v[170:173], v[194:197], v[38:41]
	v_mfma_f32_16x16x32_bf16 v[34:37], v[178:181], v[194:197], v[34:37]
	v_mfma_f32_16x16x32_bf16 v[22:25], v[170:173], v[206:209], v[22:25]
	v_mfma_f32_16x16x32_bf16 v[18:21], v[178:181], v[206:209], v[18:21]
	v_mfma_f32_16x16x32_bf16 v[6:9], v[170:173], v[214:217], v[6:9]
	v_mfma_f32_16x16x32_bf16 v[2:5], v[178:181], v[214:217], v[2:5]
	v_mfma_f32_16x16x32_bf16 v[54:57], v[174:177], v[190:193], v[54:57]
	v_mfma_f32_16x16x32_bf16 v[50:53], v[182:185], v[190:193], v[50:53]
	v_mfma_f32_16x16x32_bf16 v[38:41], v[174:177], v[198:201], v[38:41]
	v_mfma_f32_16x16x32_bf16 v[34:37], v[182:185], v[198:201], v[34:37]
	v_mfma_f32_16x16x32_bf16 v[22:25], v[174:177], v[210:213], v[22:25]
	v_mfma_f32_16x16x32_bf16 v[18:21], v[182:185], v[210:213], v[18:21]
	v_mfma_f32_16x16x32_bf16 v[6:9], v[174:177], v[218:221], v[6:9]
	v_mfma_f32_16x16x32_bf16 v[2:5], v[182:185], v[218:221], v[2:5]
	s_setprio 0
	s_barrier
	s_add_i32 s69, 0, 0x18000
	v_add_u32_e32 v153, s69, v149
	s_add_i32 s70, 0, 0x1c000
	ds_read_b128 v[154:157], v153
	ds_read_b128 v[158:161], v153 offset:1024
	ds_read_b128 v[162:165], v153 offset:2048
	ds_read_b128 v[166:169], v153 offset:3072
	v_add_u32_e32 v153, s70, v149
	ds_read_b128 v[170:173], v153
	ds_read_b128 v[174:177], v153 offset:1024
	ds_read_b128 v[178:181], v153 offset:2048
	ds_read_b128 v[182:185], v153 offset:3072
	s_add_u32 s46, s46, 0x40000
	s_addc_u32 s47, s47, 0
	s_mov_b32 m0, s25
	v_lshl_add_u64 v[226:227], s[46:47], 0, v[136:137]
	ds_read_b128 v[186:189], v152 offset:32768
	ds_read_b128 v[190:193], v152 offset:33792
	ds_read_b128 v[194:197], v152 offset:34816
	ds_read_b128 v[198:201], v152 offset:35840
	ds_read_b128 v[206:209], v152 offset:36864
	ds_read_b128 v[210:213], v152 offset:37888
	ds_read_b128 v[214:217], v152 offset:38912
	ds_read_b128 v[218:221], v152 offset:39936
	global_load_lds_dwordx4 v[226:227], off
	s_mov_b32 m0, s28
	v_lshl_add_u64 v[226:227], s[46:47], 0, v[132:133]
	global_load_lds_dwordx4 v[226:227], off
	s_waitcnt vmcnt(8) lgkmcnt(0)
	s_setprio 1
	s_barrier
	v_mfma_f32_16x16x32_bf16 v[126:129], v[154:157], v[186:189], v[126:129]
	v_mfma_f32_16x16x32_bf16 v[122:125], v[162:165], v[186:189], v[122:125]
	v_mfma_f32_16x16x32_bf16 v[110:113], v[154:157], v[194:197], v[110:113]
	v_mfma_f32_16x16x32_bf16 v[106:109], v[162:165], v[194:197], v[106:109]
	v_mfma_f32_16x16x32_bf16 v[94:97], v[154:157], v[206:209], v[94:97]
	v_mfma_f32_16x16x32_bf16 v[90:93], v[162:165], v[206:209], v[90:93]
	v_mfma_f32_16x16x32_bf16 v[78:81], v[154:157], v[214:217], v[78:81]
	v_mfma_f32_16x16x32_bf16 v[74:77], v[162:165], v[214:217], v[74:77]
	v_mfma_f32_16x16x32_bf16 v[126:129], v[158:161], v[190:193], v[126:129]
	v_mfma_f32_16x16x32_bf16 v[122:125], v[166:169], v[190:193], v[122:125]
	v_mfma_f32_16x16x32_bf16 v[110:113], v[158:161], v[198:201], v[110:113]
	v_mfma_f32_16x16x32_bf16 v[106:109], v[166:169], v[198:201], v[106:109]
	v_mfma_f32_16x16x32_bf16 v[94:97], v[158:161], v[210:213], v[94:97]
	v_mfma_f32_16x16x32_bf16 v[90:93], v[166:169], v[210:213], v[90:93]
	v_mfma_f32_16x16x32_bf16 v[78:81], v[158:161], v[218:221], v[78:81]
	v_mfma_f32_16x16x32_bf16 v[74:77], v[166:169], v[218:221], v[74:77]
	v_mfma_f32_16x16x32_bf16 v[118:121], v[170:173], v[186:189], v[118:121]
	v_mfma_f32_16x16x32_bf16 v[114:117], v[178:181], v[186:189], v[114:117]
	v_mfma_f32_16x16x32_bf16 v[102:105], v[170:173], v[194:197], v[102:105]
	v_mfma_f32_16x16x32_bf16 v[98:101], v[178:181], v[194:197], v[98:101]
	v_mfma_f32_16x16x32_bf16 v[86:89], v[170:173], v[206:209], v[86:89]
	v_mfma_f32_16x16x32_bf16 v[82:85], v[178:181], v[206:209], v[82:85]
	v_mfma_f32_16x16x32_bf16 v[70:73], v[170:173], v[214:217], v[70:73]
	v_mfma_f32_16x16x32_bf16 v[66:69], v[178:181], v[214:217], v[66:69]
	v_mfma_f32_16x16x32_bf16 v[118:121], v[174:177], v[190:193], v[118:121]
	v_mfma_f32_16x16x32_bf16 v[114:117], v[182:185], v[190:193], v[114:117]
	v_mfma_f32_16x16x32_bf16 v[102:105], v[174:177], v[198:201], v[102:105]
	v_mfma_f32_16x16x32_bf16 v[98:101], v[182:185], v[198:201], v[98:101]
	v_mfma_f32_16x16x32_bf16 v[86:89], v[174:177], v[210:213], v[86:89]
	v_mfma_f32_16x16x32_bf16 v[82:85], v[182:185], v[210:213], v[82:85]
	v_mfma_f32_16x16x32_bf16 v[70:73], v[174:177], v[218:221], v[70:73]
	v_mfma_f32_16x16x32_bf16 v[66:69], v[182:185], v[218:221], v[66:69]
	s_setprio 0
	s_barrier
	s_add_i32 s46, s69, s16
	v_lshl_add_u64 v[146:147], v[146:147], 0, s[10:11]
	s_mov_b32 m0, s46
	ds_read_b128 v[186:189], v152 offset:49152
	ds_read_b128 v[190:193], v152 offset:50176
	ds_read_b128 v[194:197], v152 offset:51200
	ds_read_b128 v[198:201], v152 offset:52224
	ds_read_b128 v[206:209], v152 offset:53248
	ds_read_b128 v[210:213], v152 offset:54272
	ds_read_b128 v[214:217], v152 offset:55296
	ds_read_b128 v[218:221], v152 offset:56320
	global_load_lds_dwordx4 v[146:147], off
	s_add_i32 m0, s46, 0x2000
	s_add_u32 s44, s44, 0x40080
	v_lshl_add_u64 v[146:147], v[202:203], 0, s[10:11]
	s_addc_u32 s45, s45, 0
	s_add_i32 s46, s70, s16
	global_load_lds_dwordx4 v[146:147], off
	s_mov_b32 m0, s46
	v_lshl_add_u64 v[146:147], s[44:45], 0, v[134:135]
	global_load_lds_dwordx4 v[146:147], off
	s_add_i32 m0, s46, 0x2000
	v_lshl_add_u64 v[146:147], s[44:45], 0, v[130:131]
	global_load_lds_dwordx4 v[146:147], off
	s_mov_b32 m0, s33
	v_lshl_add_u64 v[146:147], v[222:223], 0, s[10:11]
	global_load_lds_dwordx4 v[146:147], off
	s_mov_b32 m0, s35
	v_lshl_add_u64 v[146:147], v[224:225], 0, s[10:11]
	global_load_lds_dwordx4 v[146:147], off
	s_waitcnt vmcnt(8) lgkmcnt(0)
	s_setprio 1
	s_barrier
	v_mfma_f32_16x16x32_bf16 v[62:65], v[154:157], v[186:189], v[62:65]
	v_mfma_f32_16x16x32_bf16 v[58:61], v[162:165], v[186:189], v[58:61]
	v_mfma_f32_16x16x32_bf16 v[46:49], v[154:157], v[194:197], v[46:49]
	v_mfma_f32_16x16x32_bf16 v[42:45], v[162:165], v[194:197], v[42:45]
	v_mfma_f32_16x16x32_bf16 v[30:33], v[154:157], v[206:209], v[30:33]
	v_mfma_f32_16x16x32_bf16 v[26:29], v[162:165], v[206:209], v[26:29]
	v_mfma_f32_16x16x32_bf16 v[14:17], v[154:157], v[214:217], v[14:17]
	v_mfma_f32_16x16x32_bf16 v[10:13], v[162:165], v[214:217], v[10:13]
	v_mfma_f32_16x16x32_bf16 v[62:65], v[158:161], v[190:193], v[62:65]
	v_mfma_f32_16x16x32_bf16 v[58:61], v[166:169], v[190:193], v[58:61]
	v_mfma_f32_16x16x32_bf16 v[46:49], v[158:161], v[198:201], v[46:49]
	v_mfma_f32_16x16x32_bf16 v[42:45], v[166:169], v[198:201], v[42:45]
	v_mfma_f32_16x16x32_bf16 v[30:33], v[158:161], v[210:213], v[30:33]
	v_mfma_f32_16x16x32_bf16 v[26:29], v[166:169], v[210:213], v[26:29]
	v_mfma_f32_16x16x32_bf16 v[14:17], v[158:161], v[218:221], v[14:17]
	v_mfma_f32_16x16x32_bf16 v[10:13], v[166:169], v[218:221], v[10:13]
	v_mfma_f32_16x16x32_bf16 v[54:57], v[170:173], v[186:189], v[54:57]
	v_mfma_f32_16x16x32_bf16 v[50:53], v[178:181], v[186:189], v[50:53]
	v_mfma_f32_16x16x32_bf16 v[38:41], v[170:173], v[194:197], v[38:41]
	v_mfma_f32_16x16x32_bf16 v[34:37], v[178:181], v[194:197], v[34:37]
	v_mfma_f32_16x16x32_bf16 v[22:25], v[170:173], v[206:209], v[22:25]
	v_mfma_f32_16x16x32_bf16 v[18:21], v[178:181], v[206:209], v[18:21]
	v_mfma_f32_16x16x32_bf16 v[6:9], v[170:173], v[214:217], v[6:9]
	v_mfma_f32_16x16x32_bf16 v[2:5], v[178:181], v[214:217], v[2:5]
	v_mfma_f32_16x16x32_bf16 v[54:57], v[174:177], v[190:193], v[54:57]
	v_mfma_f32_16x16x32_bf16 v[50:53], v[182:185], v[190:193], v[50:53]
	v_mfma_f32_16x16x32_bf16 v[38:41], v[174:177], v[198:201], v[38:41]
	v_mfma_f32_16x16x32_bf16 v[34:37], v[182:185], v[198:201], v[34:37]
	v_mfma_f32_16x16x32_bf16 v[22:25], v[174:177], v[210:213], v[22:25]
	v_mfma_f32_16x16x32_bf16 v[18:21], v[182:185], v[210:213], v[18:21]
	v_mfma_f32_16x16x32_bf16 v[6:9], v[174:177], v[218:221], v[6:9]
	v_mfma_f32_16x16x32_bf16 v[2:5], v[182:185], v[218:221], v[2:5]
	s_setprio 0
	s_barrier
	s_add_i32 s68, s68, 2
	s_add_u32 s42, s42, 0x100
	s_addc_u32 s43, s43, 0
	s_add_u32 s66, s66, 0x100
	s_addc_u32 s67, s67, 0
	s_cmp_gt_u32 s68, 13
	s_cbranch_scc0 .LBB0_745
	s_and_b64 vcc, exec, s[12:13]
	s_cbranch_vccz .LBB0_748
	s_barrier

.LBB0_833:
	s_add_u32 s72, s0, s68
	s_addc_u32 s73, s1, s69
	s_and_b64 s[62:63], s[70:71], exec
	s_cselect_b32 s15, s73, s77
	s_cselect_b32 s33, s72, s76
	s_add_u32 s74, s35, s66
	s_addc_u32 s75, s85, s67
	s_and_b64 s[62:63], s[70:71], exec
	s_cselect_b32 s34, s75, s79
	s_cselect_b32 s39, s74, s78
	s_add_i32 s45, s7, -2
	s_add_u32 s76, s76, 0x100080
	s_addc_u32 s77, s77, 0
	s_add_u32 s47, s78, 0x100
	s_addc_u32 s62, s79, 0
	s_mov_b32 s63, 0
	s_waitcnt vmcnt(0)
	ds_read_b128 v[114:117], v190
	ds_read_b128 v[118:121], v190 offset:1024
	ds_read_b128 v[122:125], v190 offset:2048
	ds_read_b128 v[126:129], v190 offset:3072
	ds_read_b128 v[146:149], v191
	ds_read_b128 v[150:153], v191 offset:1024
	ds_read_b128 v[154:157], v191 offset:2048
	ds_read_b128 v[158:161], v191 offset:3072
	s_add_i32 s82, s63, 2
	s_add_u32 s78, s76, 0xfff00080
	s_addc_u32 s79, s77, -1
	s_cmp_eq_u32 s45, s63
	s_cselect_b32 s81, s15, s79
	s_cselect_b32 s80, s33, s78
	s_cselect_b32 s79, s34, s62
	s_cselect_b32 s78, s39, s47
	v_lshl_add_u64 v[186:187], s[76:77], 0, v[180:181]
	s_add_i32 m0, s87, 0xc000
	ds_read_b128 v[162:165], v192
	ds_read_b128 v[166:169], v192 offset:1024
	ds_read_b128 v[194:197], v192 offset:2048
	ds_read_b128 v[198:201], v192 offset:3072
	ds_read_b128 v[206:209], v192 offset:4096
	ds_read_b128 v[210:213], v192 offset:5120
	ds_read_b128 v[214:217], v192 offset:6144
	ds_read_b128 v[218:221], v192 offset:7168
	global_load_lds_dwordx4 v[186:187], off
	s_add_i32 m0, s87, 0xe000
	v_lshl_add_u64 v[186:187], s[76:77], 0, v[182:183]
	global_load_lds_dwordx4 v[186:187], off
	s_waitcnt vmcnt(8) lgkmcnt(0)
	s_setprio 1
	s_barrier
	v_mfma_f32_16x16x32_bf16 v[142:145], v[114:117], v[162:165], 0
	v_mfma_f32_16x16x32_bf16 v[138:141], v[122:125], v[162:165], 0
	v_mfma_f32_16x16x32_bf16 v[110:113], v[114:117], v[194:197], 0
	v_mfma_f32_16x16x32_bf16 v[106:109], v[122:125], v[194:197], 0
	v_mfma_f32_16x16x32_bf16 v[98:101], v[114:117], v[206:209], 0
	v_mfma_f32_16x16x32_bf16 v[90:93], v[122:125], v[206:209], 0
	v_mfma_f32_16x16x32_bf16 v[82:85], v[114:117], v[214:217], 0
	v_mfma_f32_16x16x32_bf16 v[74:77], v[122:125], v[214:217], 0
	v_mfma_f32_16x16x32_bf16 v[142:145], v[118:121], v[166:169], v[142:145]
	v_mfma_f32_16x16x32_bf16 v[138:141], v[126:129], v[166:169], v[138:141]
	v_mfma_f32_16x16x32_bf16 v[110:113], v[118:121], v[198:201], v[110:113]
	v_mfma_f32_16x16x32_bf16 v[106:109], v[126:129], v[198:201], v[106:109]
	v_mfma_f32_16x16x32_bf16 v[98:101], v[118:121], v[210:213], v[98:101]
	v_mfma_f32_16x16x32_bf16 v[90:93], v[126:129], v[210:213], v[90:93]
	v_mfma_f32_16x16x32_bf16 v[82:85], v[118:121], v[218:221], v[82:85]
	v_mfma_f32_16x16x32_bf16 v[74:77], v[126:129], v[218:221], v[74:77]
	v_mfma_f32_16x16x32_bf16 v[134:137], v[146:149], v[162:165], 0
	v_mfma_f32_16x16x32_bf16 v[130:133], v[154:157], v[162:165], 0
	v_mfma_f32_16x16x32_bf16 v[102:105], v[146:149], v[194:197], 0
	v_mfma_f32_16x16x32_bf16 v[94:97], v[154:157], v[194:197], 0
	v_mfma_f32_16x16x32_bf16 v[86:89], v[146:149], v[206:209], 0
	v_mfma_f32_16x16x32_bf16 v[78:81], v[154:157], v[206:209], 0
	v_mfma_f32_16x16x32_bf16 v[70:73], v[146:149], v[214:217], 0
	v_mfma_f32_16x16x32_bf16 v[66:69], v[154:157], v[214:217], 0
	v_mfma_f32_16x16x32_bf16 v[134:137], v[150:153], v[166:169], v[134:137]
	v_mfma_f32_16x16x32_bf16 v[130:133], v[158:161], v[166:169], v[130:133]
	v_mfma_f32_16x16x32_bf16 v[102:105], v[150:153], v[198:201], v[102:105]
	v_mfma_f32_16x16x32_bf16 v[94:97], v[158:161], v[198:201], v[94:97]
	v_mfma_f32_16x16x32_bf16 v[86:89], v[150:153], v[210:213], v[86:89]
	v_mfma_f32_16x16x32_bf16 v[78:81], v[158:161], v[210:213], v[78:81]
	v_mfma_f32_16x16x32_bf16 v[70:73], v[150:153], v[218:221], v[70:73]
	v_mfma_f32_16x16x32_bf16 v[66:69], v[158:161], v[218:221], v[66:69]
	s_setprio 0
	s_barrier
	s_add_i32 s63, s24, s86
	v_lshl_add_u64 v[186:187], s[78:79], 0, v[172:173]
	s_mov_b32 m0, s63
	ds_read_b128 v[162:165], v192 offset:16384
	ds_read_b128 v[166:169], v192 offset:17408
	ds_read_b128 v[194:197], v192 offset:18432
	ds_read_b128 v[198:201], v192 offset:19456
	ds_read_b128 v[206:209], v192 offset:20480
	ds_read_b128 v[210:213], v192 offset:21504
	ds_read_b128 v[214:217], v192 offset:22528
	ds_read_b128 v[218:221], v192 offset:23552
	global_load_lds_dwordx4 v[186:187], off
	s_add_i32 m0, s63, 0x2000
	s_add_u32 vcc_lo, s78, 0x100000
	v_lshl_add_u64 v[202:203], s[78:79], 0, v[176:177]
	s_addc_u32 vcc_hi, s79, 0
	s_add_i32 s63, s25, s86
	global_load_lds_dwordx4 v[202:203], off
	v_lshl_add_u64 v[222:223], vcc, 0, v[172:173]
	s_mov_b32 m0, s63
	v_lshl_add_u64 v[224:225], s[80:81], 0, v[174:175]
	global_load_lds_dwordx4 v[222:223], off
	s_add_i32 m0, s63, 0x2000
	v_lshl_add_u64 v[222:223], vcc, 0, v[176:177]
	global_load_lds_dwordx4 v[222:223], off
	s_mov_b32 m0, s87
	v_lshl_add_u64 v[222:223], s[80:81], 0, v[170:171]
	global_load_lds_dwordx4 v[222:223], off
	s_mov_b32 m0, s88
	s_nop 0
	global_load_lds_dwordx4 v[224:225], off
	s_waitcnt vmcnt(8) lgkmcnt(0)
	s_setprio 1
	s_barrier
	v_mfma_f32_16x16x32_bf16 v[62:65], v[114:117], v[162:165], 0
	v_mfma_f32_16x16x32_bf16 v[58:61], v[122:125], v[162:165], 0
	v_mfma_f32_16x16x32_bf16 v[50:53], v[114:117], v[194:197], 0
	v_mfma_f32_16x16x32_bf16 v[42:45], v[122:125], v[194:197], 0
	v_mfma_f32_16x16x32_bf16 v[34:37], v[114:117], v[206:209], 0
	v_mfma_f32_16x16x32_bf16 v[26:29], v[122:125], v[206:209], 0
	v_mfma_f32_16x16x32_bf16 v[18:21], v[114:117], v[214:217], 0
	v_mfma_f32_16x16x32_bf16 v[10:13], v[122:125], v[214:217], 0
	v_mfma_f32_16x16x32_bf16 v[62:65], v[118:121], v[166:169], v[62:65]
	v_mfma_f32_16x16x32_bf16 v[58:61], v[126:129], v[166:169], v[58:61]
	v_mfma_f32_16x16x32_bf16 v[50:53], v[118:121], v[198:201], v[50:53]
	v_mfma_f32_16x16x32_bf16 v[42:45], v[126:129], v[198:201], v[42:45]
	v_mfma_f32_16x16x32_bf16 v[34:37], v[118:121], v[210:213], v[34:37]
	v_mfma_f32_16x16x32_bf16 v[26:29], v[126:129], v[210:213], v[26:29]
	v_mfma_f32_16x16x32_bf16 v[18:21], v[118:121], v[218:221], v[18:21]
	v_mfma_f32_16x16x32_bf16 v[10:13], v[126:129], v[218:221], v[10:13]
	v_mfma_f32_16x16x32_bf16 v[54:57], v[146:149], v[162:165], 0
	v_mfma_f32_16x16x32_bf16 v[46:49], v[154:157], v[162:165], 0
	v_mfma_f32_16x16x32_bf16 v[38:41], v[146:149], v[194:197], 0
	v_mfma_f32_16x16x32_bf16 v[30:33], v[154:157], v[194:197], 0
	v_mfma_f32_16x16x32_bf16 v[22:25], v[146:149], v[206:209], 0
	v_mfma_f32_16x16x32_bf16 v[14:17], v[154:157], v[206:209], 0
	v_mfma_f32_16x16x32_bf16 v[6:9], v[146:149], v[214:217], 0
	v_mfma_f32_16x16x32_bf16 v[2:5], v[154:157], v[214:217], 0
	v_mfma_f32_16x16x32_bf16 v[54:57], v[150:153], v[166:169], v[54:57]
	v_mfma_f32_16x16x32_bf16 v[46:49], v[158:161], v[166:169], v[46:49]
	v_mfma_f32_16x16x32_bf16 v[38:41], v[150:153], v[198:201], v[38:41]
	v_mfma_f32_16x16x32_bf16 v[30:33], v[158:161], v[198:201], v[30:33]
	v_mfma_f32_16x16x32_bf16 v[22:25], v[150:153], v[210:213], v[22:25]
	v_mfma_f32_16x16x32_bf16 v[14:17], v[158:161], v[210:213], v[14:17]
	v_mfma_f32_16x16x32_bf16 v[6:9], v[150:153], v[218:221], v[6:9]
	v_mfma_f32_16x16x32_bf16 v[2:5], v[158:161], v[218:221], v[2:5]
	s_setprio 0
	s_barrier
	s_add_i32 s63, 0, 0x18000
	s_add_i32 s83, 0, 0x1c000
	v_add_u32_e32 v126, s63, v189
	v_add_u32_e32 v158, s83, v189
	ds_read_b128 v[114:117], v126
	ds_read_b128 v[118:121], v126 offset:1024
	ds_read_b128 v[122:125], v126 offset:2048
	ds_read_b128 v[126:129], v126 offset:3072
	ds_read_b128 v[146:149], v158
	ds_read_b128 v[150:153], v158 offset:1024
	ds_read_b128 v[154:157], v158 offset:2048
	ds_read_b128 v[158:161], v158 offset:3072
	s_add_u32 s80, s80, 0x100000
	s_addc_u32 s81, s81, 0
	s_mov_b32 m0, s89
	v_lshl_add_u64 v[226:227], s[80:81], 0, v[170:171]
	ds_read_b128 v[162:165], v192 offset:32768
	ds_read_b128 v[166:169], v192 offset:33792
	ds_read_b128 v[194:197], v192 offset:34816
	ds_read_b128 v[198:201], v192 offset:35840
	ds_read_b128 v[206:209], v192 offset:36864
	ds_read_b128 v[210:213], v192 offset:37888
	ds_read_b128 v[214:217], v192 offset:38912
	ds_read_b128 v[218:221], v192 offset:39936
	global_load_lds_dwordx4 v[226:227], off
	s_mov_b32 m0, s90
	v_lshl_add_u64 v[226:227], s[80:81], 0, v[174:175]
	global_load_lds_dwordx4 v[226:227], off
	s_waitcnt vmcnt(8) lgkmcnt(0)
	s_setprio 1
	s_barrier
	v_mfma_f32_16x16x32_bf16 v[142:145], v[114:117], v[162:165], v[142:145]
	v_mfma_f32_16x16x32_bf16 v[138:141], v[122:125], v[162:165], v[138:141]
	v_mfma_f32_16x16x32_bf16 v[110:113], v[114:117], v[194:197], v[110:113]
	v_mfma_f32_16x16x32_bf16 v[106:109], v[122:125], v[194:197], v[106:109]
	v_mfma_f32_16x16x32_bf16 v[98:101], v[114:117], v[206:209], v[98:101]
	v_mfma_f32_16x16x32_bf16 v[90:93], v[122:125], v[206:209], v[90:93]
	v_mfma_f32_16x16x32_bf16 v[82:85], v[114:117], v[214:217], v[82:85]
	v_mfma_f32_16x16x32_bf16 v[74:77], v[122:125], v[214:217], v[74:77]
	v_mfma_f32_16x16x32_bf16 v[142:145], v[118:121], v[166:169], v[142:145]
	v_mfma_f32_16x16x32_bf16 v[138:141], v[126:129], v[166:169], v[138:141]
	v_mfma_f32_16x16x32_bf16 v[110:113], v[118:121], v[198:201], v[110:113]
	v_mfma_f32_16x16x32_bf16 v[106:109], v[126:129], v[198:201], v[106:109]
	v_mfma_f32_16x16x32_bf16 v[98:101], v[118:121], v[210:213], v[98:101]
	v_mfma_f32_16x16x32_bf16 v[90:93], v[126:129], v[210:213], v[90:93]
	v_mfma_f32_16x16x32_bf16 v[82:85], v[118:121], v[218:221], v[82:85]
	v_mfma_f32_16x16x32_bf16 v[74:77], v[126:129], v[218:221], v[74:77]
	v_mfma_f32_16x16x32_bf16 v[134:137], v[146:149], v[162:165], v[134:137]
	v_mfma_f32_16x16x32_bf16 v[130:133], v[154:157], v[162:165], v[130:133]
	v_mfma_f32_16x16x32_bf16 v[102:105], v[146:149], v[194:197], v[102:105]
	v_mfma_f32_16x16x32_bf16 v[94:97], v[154:157], v[194:197], v[94:97]
	v_mfma_f32_16x16x32_bf16 v[86:89], v[146:149], v[206:209], v[86:89]
	v_mfma_f32_16x16x32_bf16 v[78:81], v[154:157], v[206:209], v[78:81]
	v_mfma_f32_16x16x32_bf16 v[70:73], v[146:149], v[214:217], v[70:73]
	v_mfma_f32_16x16x32_bf16 v[66:69], v[154:157], v[214:217], v[66:69]
	v_mfma_f32_16x16x32_bf16 v[134:137], v[150:153], v[166:169], v[134:137]
	v_mfma_f32_16x16x32_bf16 v[130:133], v[158:161], v[166:169], v[130:133]
	v_mfma_f32_16x16x32_bf16 v[102:105], v[150:153], v[198:201], v[102:105]
	v_mfma_f32_16x16x32_bf16 v[94:97], v[158:161], v[198:201], v[94:97]
	v_mfma_f32_16x16x32_bf16 v[86:89], v[150:153], v[210:213], v[86:89]
	v_mfma_f32_16x16x32_bf16 v[78:81], v[158:161], v[210:213], v[78:81]
	v_mfma_f32_16x16x32_bf16 v[70:73], v[150:153], v[218:221], v[70:73]
	v_mfma_f32_16x16x32_bf16 v[66:69], v[158:161], v[218:221], v[66:69]
	s_setprio 0
	s_barrier
	s_add_i32 s63, s63, s86
	v_lshl_add_u64 v[186:187], v[186:187], 0, s[22:23]
	s_mov_b32 m0, s63
	ds_read_b128 v[162:165], v192 offset:49152
	ds_read_b128 v[166:169], v192 offset:50176
	ds_read_b128 v[194:197], v192 offset:51200
	ds_read_b128 v[198:201], v192 offset:52224
	ds_read_b128 v[206:209], v192 offset:53248
	ds_read_b128 v[210:213], v192 offset:54272
	ds_read_b128 v[214:217], v192 offset:55296
	ds_read_b128 v[218:221], v192 offset:56320
	global_load_lds_dwordx4 v[186:187], off
	s_add_i32 m0, s63, 0x2000
	s_add_u32 s78, s78, 0x100080
	v_lshl_add_u64 v[186:187], v[202:203], 0, s[22:23]
	s_addc_u32 s79, s79, 0
	s_add_i32 s63, s83, s86
	global_load_lds_dwordx4 v[186:187], off
	s_mov_b32 m0, s63
	v_lshl_add_u64 v[186:187], s[78:79], 0, v[172:173]
	global_load_lds_dwordx4 v[186:187], off
	s_add_i32 m0, s63, 0x2000
	v_lshl_add_u64 v[186:187], s[78:79], 0, v[176:177]
	global_load_lds_dwordx4 v[186:187], off
	s_mov_b32 m0, s95
	v_lshl_add_u64 v[186:187], v[222:223], 0, s[22:23]
	global_load_lds_dwordx4 v[186:187], off
	s_mov_b32 m0, s96
	v_lshl_add_u64 v[186:187], v[224:225], 0, s[22:23]
	global_load_lds_dwordx4 v[186:187], off
	s_waitcnt vmcnt(8) lgkmcnt(0)
	s_setprio 1
	s_barrier
	v_mfma_f32_16x16x32_bf16 v[62:65], v[114:117], v[162:165], v[62:65]
	v_mfma_f32_16x16x32_bf16 v[58:61], v[122:125], v[162:165], v[58:61]
	v_mfma_f32_16x16x32_bf16 v[50:53], v[114:117], v[194:197], v[50:53]
	v_mfma_f32_16x16x32_bf16 v[42:45], v[122:125], v[194:197], v[42:45]
	v_mfma_f32_16x16x32_bf16 v[34:37], v[114:117], v[206:209], v[34:37]
	v_mfma_f32_16x16x32_bf16 v[26:29], v[122:125], v[206:209], v[26:29]
	v_mfma_f32_16x16x32_bf16 v[18:21], v[114:117], v[214:217], v[18:21]
	v_mfma_f32_16x16x32_bf16 v[10:13], v[122:125], v[214:217], v[10:13]
	v_mfma_f32_16x16x32_bf16 v[62:65], v[118:121], v[166:169], v[62:65]
	v_mfma_f32_16x16x32_bf16 v[58:61], v[126:129], v[166:169], v[58:61]
	v_mfma_f32_16x16x32_bf16 v[50:53], v[118:121], v[198:201], v[50:53]
	v_mfma_f32_16x16x32_bf16 v[42:45], v[126:129], v[198:201], v[42:45]
	v_mfma_f32_16x16x32_bf16 v[34:37], v[118:121], v[210:213], v[34:37]
	v_mfma_f32_16x16x32_bf16 v[26:29], v[126:129], v[210:213], v[26:29]
	v_mfma_f32_16x16x32_bf16 v[18:21], v[118:121], v[218:221], v[18:21]
	v_mfma_f32_16x16x32_bf16 v[10:13], v[126:129], v[218:221], v[10:13]
	v_mfma_f32_16x16x32_bf16 v[54:57], v[146:149], v[162:165], v[54:57]
	v_mfma_f32_16x16x32_bf16 v[46:49], v[154:157], v[162:165], v[46:49]
	v_mfma_f32_16x16x32_bf16 v[38:41], v[146:149], v[194:197], v[38:41]
	v_mfma_f32_16x16x32_bf16 v[30:33], v[154:157], v[194:197], v[30:33]
	v_mfma_f32_16x16x32_bf16 v[22:25], v[146:149], v[206:209], v[22:25]
	v_mfma_f32_16x16x32_bf16 v[14:17], v[154:157], v[206:209], v[14:17]
	v_mfma_f32_16x16x32_bf16 v[6:9], v[146:149], v[214:217], v[6:9]
	v_mfma_f32_16x16x32_bf16 v[2:5], v[154:157], v[214:217], v[2:5]
	v_mfma_f32_16x16x32_bf16 v[54:57], v[150:153], v[166:169], v[54:57]
	v_mfma_f32_16x16x32_bf16 v[46:49], v[158:161], v[166:169], v[46:49]
	v_mfma_f32_16x16x32_bf16 v[38:41], v[150:153], v[198:201], v[38:41]
	v_mfma_f32_16x16x32_bf16 v[30:33], v[158:161], v[198:201], v[30:33]
	v_mfma_f32_16x16x32_bf16 v[22:25], v[150:153], v[210:213], v[22:25]
	v_mfma_f32_16x16x32_bf16 v[14:17], v[158:161], v[210:213], v[14:17]
	v_mfma_f32_16x16x32_bf16 v[6:9], v[150:153], v[218:221], v[6:9]
	v_mfma_f32_16x16x32_bf16 v[2:5], v[158:161], v[218:221], v[2:5]
	s_setprio 0
	s_barrier
	s_add_u32 s76, s76, 0x100
	s_addc_u32 s77, s77, 0
	s_add_u32 s47, s47, 0x100
	s_addc_u32 s62, s62, 0
	s_cmp_ge_i32 s82, s7
	s_mov_b32 s63, s82
.LBB0_834:
	ds_read_b128 v[114:117], v190
	ds_read_b128 v[118:121], v190 offset:1024
	ds_read_b128 v[122:125], v190 offset:2048
	ds_read_b128 v[126:129], v190 offset:3072
	ds_read_b128 v[146:149], v191
	ds_read_b128 v[150:153], v191 offset:1024
	ds_read_b128 v[154:157], v191 offset:2048
	ds_read_b128 v[158:161], v191 offset:3072
	s_add_i32 s82, s63, 2
	s_add_u32 s78, s76, 0xfff00080
	s_addc_u32 s79, s77, -1
	s_cmp_eq_u32 s45, s63
	s_cselect_b32 s81, s15, s79
	s_cselect_b32 s80, s33, s78
	s_cselect_b32 s79, s34, s62
	s_cselect_b32 s78, s39, s47
	v_lshl_add_u64 v[186:187], s[76:77], 0, v[180:181]
	s_add_i32 m0, s87, 0xc000
	ds_read_b128 v[162:165], v192
	ds_read_b128 v[166:169], v192 offset:1024
	ds_read_b128 v[194:197], v192 offset:2048
	ds_read_b128 v[198:201], v192 offset:3072
	ds_read_b128 v[206:209], v192 offset:4096
	ds_read_b128 v[210:213], v192 offset:5120
	ds_read_b128 v[214:217], v192 offset:6144
	ds_read_b128 v[218:221], v192 offset:7168
	global_load_lds_dwordx4 v[186:187], off
	s_add_i32 m0, s87, 0xe000
	v_lshl_add_u64 v[186:187], s[76:77], 0, v[182:183]
	global_load_lds_dwordx4 v[186:187], off
	s_waitcnt vmcnt(8) lgkmcnt(0)
	s_setprio 1
	s_barrier
	v_mfma_f32_16x16x32_bf16 v[142:145], v[114:117], v[162:165], v[142:145]
	v_mfma_f32_16x16x32_bf16 v[138:141], v[122:125], v[162:165], v[138:141]
	v_mfma_f32_16x16x32_bf16 v[110:113], v[114:117], v[194:197], v[110:113]
	v_mfma_f32_16x16x32_bf16 v[106:109], v[122:125], v[194:197], v[106:109]
	v_mfma_f32_16x16x32_bf16 v[98:101], v[114:117], v[206:209], v[98:101]
	v_mfma_f32_16x16x32_bf16 v[90:93], v[122:125], v[206:209], v[90:93]
	v_mfma_f32_16x16x32_bf16 v[82:85], v[114:117], v[214:217], v[82:85]
	v_mfma_f32_16x16x32_bf16 v[74:77], v[122:125], v[214:217], v[74:77]
	v_mfma_f32_16x16x32_bf16 v[142:145], v[118:121], v[166:169], v[142:145]
	v_mfma_f32_16x16x32_bf16 v[138:141], v[126:129], v[166:169], v[138:141]
	v_mfma_f32_16x16x32_bf16 v[110:113], v[118:121], v[198:201], v[110:113]
	v_mfma_f32_16x16x32_bf16 v[106:109], v[126:129], v[198:201], v[106:109]
	v_mfma_f32_16x16x32_bf16 v[98:101], v[118:121], v[210:213], v[98:101]
	v_mfma_f32_16x16x32_bf16 v[90:93], v[126:129], v[210:213], v[90:93]
	v_mfma_f32_16x16x32_bf16 v[82:85], v[118:121], v[218:221], v[82:85]
	v_mfma_f32_16x16x32_bf16 v[74:77], v[126:129], v[218:221], v[74:77]
	v_mfma_f32_16x16x32_bf16 v[134:137], v[146:149], v[162:165], v[134:137]
	v_mfma_f32_16x16x32_bf16 v[130:133], v[154:157], v[162:165], v[130:133]
	v_mfma_f32_16x16x32_bf16 v[102:105], v[146:149], v[194:197], v[102:105]
	v_mfma_f32_16x16x32_bf16 v[94:97], v[154:157], v[194:197], v[94:97]
	v_mfma_f32_16x16x32_bf16 v[86:89], v[146:149], v[206:209], v[86:89]
	v_mfma_f32_16x16x32_bf16 v[78:81], v[154:157], v[206:209], v[78:81]
	v_mfma_f32_16x16x32_bf16 v[70:73], v[146:149], v[214:217], v[70:73]
	v_mfma_f32_16x16x32_bf16 v[66:69], v[154:157], v[214:217], v[66:69]
	v_mfma_f32_16x16x32_bf16 v[134:137], v[150:153], v[166:169], v[134:137]
	v_mfma_f32_16x16x32_bf16 v[130:133], v[158:161], v[166:169], v[130:133]
	v_mfma_f32_16x16x32_bf16 v[102:105], v[150:153], v[198:201], v[102:105]
	v_mfma_f32_16x16x32_bf16 v[94:97], v[158:161], v[198:201], v[94:97]
	v_mfma_f32_16x16x32_bf16 v[86:89], v[150:153], v[210:213], v[86:89]
	v_mfma_f32_16x16x32_bf16 v[78:81], v[158:161], v[210:213], v[78:81]
	v_mfma_f32_16x16x32_bf16 v[70:73], v[150:153], v[218:221], v[70:73]
	v_mfma_f32_16x16x32_bf16 v[66:69], v[158:161], v[218:221], v[66:69]
	s_setprio 0
	s_barrier
	s_add_i32 s63, s24, s86
	v_lshl_add_u64 v[186:187], s[78:79], 0, v[172:173]
	s_mov_b32 m0, s63
	ds_read_b128 v[162:165], v192 offset:16384
	ds_read_b128 v[166:169], v192 offset:17408
	ds_read_b128 v[194:197], v192 offset:18432
	ds_read_b128 v[198:201], v192 offset:19456
	ds_read_b128 v[206:209], v192 offset:20480
	ds_read_b128 v[210:213], v192 offset:21504
	ds_read_b128 v[214:217], v192 offset:22528
	ds_read_b128 v[218:221], v192 offset:23552
	global_load_lds_dwordx4 v[186:187], off
	s_add_i32 m0, s63, 0x2000
	s_add_u32 vcc_lo, s78, 0x100000
	v_lshl_add_u64 v[202:203], s[78:79], 0, v[176:177]
	s_addc_u32 vcc_hi, s79, 0
	s_add_i32 s63, s25, s86
	global_load_lds_dwordx4 v[202:203], off
	v_lshl_add_u64 v[222:223], vcc, 0, v[172:173]
	s_mov_b32 m0, s63
	v_lshl_add_u64 v[224:225], s[80:81], 0, v[174:175]
	global_load_lds_dwordx4 v[222:223], off
	s_add_i32 m0, s63, 0x2000
	v_lshl_add_u64 v[222:223], vcc, 0, v[176:177]
	global_load_lds_dwordx4 v[222:223], off
	s_mov_b32 m0, s87
	v_lshl_add_u64 v[222:223], s[80:81], 0, v[170:171]
	global_load_lds_dwordx4 v[222:223], off
	s_mov_b32 m0, s88
	s_nop 0
	global_load_lds_dwordx4 v[224:225], off
	s_waitcnt vmcnt(8) lgkmcnt(0)
	s_setprio 1
	s_barrier
	v_mfma_f32_16x16x32_bf16 v[62:65], v[114:117], v[162:165], v[62:65]
	v_mfma_f32_16x16x32_bf16 v[58:61], v[122:125], v[162:165], v[58:61]
	v_mfma_f32_16x16x32_bf16 v[50:53], v[114:117], v[194:197], v[50:53]
	v_mfma_f32_16x16x32_bf16 v[42:45], v[122:125], v[194:197], v[42:45]
	v_mfma_f32_16x16x32_bf16 v[34:37], v[114:117], v[206:209], v[34:37]
	v_mfma_f32_16x16x32_bf16 v[26:29], v[122:125], v[206:209], v[26:29]
	v_mfma_f32_16x16x32_bf16 v[18:21], v[114:117], v[214:217], v[18:21]
	v_mfma_f32_16x16x32_bf16 v[10:13], v[122:125], v[214:217], v[10:13]
	v_mfma_f32_16x16x32_bf16 v[62:65], v[118:121], v[166:169], v[62:65]
	v_mfma_f32_16x16x32_bf16 v[58:61], v[126:129], v[166:169], v[58:61]
	v_mfma_f32_16x16x32_bf16 v[50:53], v[118:121], v[198:201], v[50:53]
	v_mfma_f32_16x16x32_bf16 v[42:45], v[126:129], v[198:201], v[42:45]
	v_mfma_f32_16x16x32_bf16 v[34:37], v[118:121], v[210:213], v[34:37]
	v_mfma_f32_16x16x32_bf16 v[26:29], v[126:129], v[210:213], v[26:29]
	v_mfma_f32_16x16x32_bf16 v[18:21], v[118:121], v[218:221], v[18:21]
	v_mfma_f32_16x16x32_bf16 v[10:13], v[126:129], v[218:221], v[10:13]
	v_mfma_f32_16x16x32_bf16 v[54:57], v[146:149], v[162:165], v[54:57]
	v_mfma_f32_16x16x32_bf16 v[46:49], v[154:157], v[162:165], v[46:49]
	v_mfma_f32_16x16x32_bf16 v[38:41], v[146:149], v[194:197], v[38:41]
	v_mfma_f32_16x16x32_bf16 v[30:33], v[154:157], v[194:197], v[30:33]
	v_mfma_f32_16x16x32_bf16 v[22:25], v[146:149], v[206:209], v[22:25]
	v_mfma_f32_16x16x32_bf16 v[14:17], v[154:157], v[206:209], v[14:17]
	v_mfma_f32_16x16x32_bf16 v[6:9], v[146:149], v[214:217], v[6:9]
	v_mfma_f32_16x16x32_bf16 v[2:5], v[154:157], v[214:217], v[2:5]
	v_mfma_f32_16x16x32_bf16 v[54:57], v[150:153], v[166:169], v[54:57]
	v_mfma_f32_16x16x32_bf16 v[46:49], v[158:161], v[166:169], v[46:49]
	v_mfma_f32_16x16x32_bf16 v[38:41], v[150:153], v[198:201], v[38:41]
	v_mfma_f32_16x16x32_bf16 v[30:33], v[158:161], v[198:201], v[30:33]
	v_mfma_f32_16x16x32_bf16 v[22:25], v[150:153], v[210:213], v[22:25]
	v_mfma_f32_16x16x32_bf16 v[14:17], v[158:161], v[210:213], v[14:17]
	v_mfma_f32_16x16x32_bf16 v[6:9], v[150:153], v[218:221], v[6:9]
	v_mfma_f32_16x16x32_bf16 v[2:5], v[158:161], v[218:221], v[2:5]
	s_setprio 0
	s_barrier
	s_add_i32 s63, 0, 0x18000
	s_add_i32 s83, 0, 0x1c000
	v_add_u32_e32 v126, s63, v189
	v_add_u32_e32 v158, s83, v189
	ds_read_b128 v[114:117], v126
	ds_read_b128 v[118:121], v126 offset:1024
	ds_read_b128 v[122:125], v126 offset:2048
	ds_read_b128 v[126:129], v126 offset:3072
	ds_read_b128 v[146:149], v158
	ds_read_b128 v[150:153], v158 offset:1024
	ds_read_b128 v[154:157], v158 offset:2048
	ds_read_b128 v[158:161], v158 offset:3072
	s_add_u32 s80, s80, 0x100000
	s_addc_u32 s81, s81, 0
	s_mov_b32 m0, s89
	v_lshl_add_u64 v[226:227], s[80:81], 0, v[170:171]
	ds_read_b128 v[162:165], v192 offset:32768
	ds_read_b128 v[166:169], v192 offset:33792
	ds_read_b128 v[194:197], v192 offset:34816
	ds_read_b128 v[198:201], v192 offset:35840
	ds_read_b128 v[206:209], v192 offset:36864
	ds_read_b128 v[210:213], v192 offset:37888
	ds_read_b128 v[214:217], v192 offset:38912
	ds_read_b128 v[218:221], v192 offset:39936
	global_load_lds_dwordx4 v[226:227], off
	s_mov_b32 m0, s90
	v_lshl_add_u64 v[226:227], s[80:81], 0, v[174:175]
	global_load_lds_dwordx4 v[226:227], off
	s_waitcnt vmcnt(8) lgkmcnt(0)
	s_setprio 1
	s_barrier
	v_mfma_f32_16x16x32_bf16 v[142:145], v[114:117], v[162:165], v[142:145]
	v_mfma_f32_16x16x32_bf16 v[138:141], v[122:125], v[162:165], v[138:141]
	v_mfma_f32_16x16x32_bf16 v[110:113], v[114:117], v[194:197], v[110:113]
	v_mfma_f32_16x16x32_bf16 v[106:109], v[122:125], v[194:197], v[106:109]
	v_mfma_f32_16x16x32_bf16 v[98:101], v[114:117], v[206:209], v[98:101]
	v_mfma_f32_16x16x32_bf16 v[90:93], v[122:125], v[206:209], v[90:93]
	v_mfma_f32_16x16x32_bf16 v[82:85], v[114:117], v[214:217], v[82:85]
	v_mfma_f32_16x16x32_bf16 v[74:77], v[122:125], v[214:217], v[74:77]
	v_mfma_f32_16x16x32_bf16 v[142:145], v[118:121], v[166:169], v[142:145]
	v_mfma_f32_16x16x32_bf16 v[138:141], v[126:129], v[166:169], v[138:141]
	v_mfma_f32_16x16x32_bf16 v[110:113], v[118:121], v[198:201], v[110:113]
	v_mfma_f32_16x16x32_bf16 v[106:109], v[126:129], v[198:201], v[106:109]
	v_mfma_f32_16x16x32_bf16 v[98:101], v[118:121], v[210:213], v[98:101]
	v_mfma_f32_16x16x32_bf16 v[90:93], v[126:129], v[210:213], v[90:93]
	v_mfma_f32_16x16x32_bf16 v[82:85], v[118:121], v[218:221], v[82:85]
	v_mfma_f32_16x16x32_bf16 v[74:77], v[126:129], v[218:221], v[74:77]
	v_mfma_f32_16x16x32_bf16 v[134:137], v[146:149], v[162:165], v[134:137]
	v_mfma_f32_16x16x32_bf16 v[130:133], v[154:157], v[162:165], v[130:133]
	v_mfma_f32_16x16x32_bf16 v[102:105], v[146:149], v[194:197], v[102:105]
	v_mfma_f32_16x16x32_bf16 v[94:97], v[154:157], v[194:197], v[94:97]
	v_mfma_f32_16x16x32_bf16 v[86:89], v[146:149], v[206:209], v[86:89]
	v_mfma_f32_16x16x32_bf16 v[78:81], v[154:157], v[206:209], v[78:81]
	v_mfma_f32_16x16x32_bf16 v[70:73], v[146:149], v[214:217], v[70:73]
	v_mfma_f32_16x16x32_bf16 v[66:69], v[154:157], v[214:217], v[66:69]
	v_mfma_f32_16x16x32_bf16 v[134:137], v[150:153], v[166:169], v[134:137]
	v_mfma_f32_16x16x32_bf16 v[130:133], v[158:161], v[166:169], v[130:133]
	v_mfma_f32_16x16x32_bf16 v[102:105], v[150:153], v[198:201], v[102:105]
	v_mfma_f32_16x16x32_bf16 v[94:97], v[158:161], v[198:201], v[94:97]
	v_mfma_f32_16x16x32_bf16 v[86:89], v[150:153], v[210:213], v[86:89]
	v_mfma_f32_16x16x32_bf16 v[78:81], v[158:161], v[210:213], v[78:81]
	v_mfma_f32_16x16x32_bf16 v[70:73], v[150:153], v[218:221], v[70:73]
	v_mfma_f32_16x16x32_bf16 v[66:69], v[158:161], v[218:221], v[66:69]
	s_setprio 0
	s_barrier
	s_add_i32 s63, s63, s86
	v_lshl_add_u64 v[186:187], v[186:187], 0, s[22:23]
	s_mov_b32 m0, s63
	ds_read_b128 v[162:165], v192 offset:49152
	ds_read_b128 v[166:169], v192 offset:50176
	ds_read_b128 v[194:197], v192 offset:51200
	ds_read_b128 v[198:201], v192 offset:52224
	ds_read_b128 v[206:209], v192 offset:53248
	ds_read_b128 v[210:213], v192 offset:54272
	ds_read_b128 v[214:217], v192 offset:55296
	ds_read_b128 v[218:221], v192 offset:56320
	global_load_lds_dwordx4 v[186:187], off
	s_add_i32 m0, s63, 0x2000
	s_add_u32 s78, s78, 0x100080
	v_lshl_add_u64 v[186:187], v[202:203], 0, s[22:23]
	s_addc_u32 s79, s79, 0
	s_add_i32 s63, s83, s86
	global_load_lds_dwordx4 v[186:187], off
	s_mov_b32 m0, s63
	v_lshl_add_u64 v[186:187], s[78:79], 0, v[172:173]
	global_load_lds_dwordx4 v[186:187], off
	s_add_i32 m0, s63, 0x2000
	v_lshl_add_u64 v[186:187], s[78:79], 0, v[176:177]
	global_load_lds_dwordx4 v[186:187], off
	s_mov_b32 m0, s95
	v_lshl_add_u64 v[186:187], v[222:223], 0, s[22:23]
	global_load_lds_dwordx4 v[186:187], off
	s_mov_b32 m0, s96
	v_lshl_add_u64 v[186:187], v[224:225], 0, s[22:23]
	global_load_lds_dwordx4 v[186:187], off
	s_waitcnt vmcnt(8) lgkmcnt(0)
	s_setprio 1
	s_barrier
	v_mfma_f32_16x16x32_bf16 v[62:65], v[114:117], v[162:165], v[62:65]
	v_mfma_f32_16x16x32_bf16 v[58:61], v[122:125], v[162:165], v[58:61]
	v_mfma_f32_16x16x32_bf16 v[50:53], v[114:117], v[194:197], v[50:53]
	v_mfma_f32_16x16x32_bf16 v[42:45], v[122:125], v[194:197], v[42:45]
	v_mfma_f32_16x16x32_bf16 v[34:37], v[114:117], v[206:209], v[34:37]
	v_mfma_f32_16x16x32_bf16 v[26:29], v[122:125], v[206:209], v[26:29]
	v_mfma_f32_16x16x32_bf16 v[18:21], v[114:117], v[214:217], v[18:21]
	v_mfma_f32_16x16x32_bf16 v[10:13], v[122:125], v[214:217], v[10:13]
	v_mfma_f32_16x16x32_bf16 v[62:65], v[118:121], v[166:169], v[62:65]
	v_mfma_f32_16x16x32_bf16 v[58:61], v[126:129], v[166:169], v[58:61]
	v_mfma_f32_16x16x32_bf16 v[50:53], v[118:121], v[198:201], v[50:53]
	v_mfma_f32_16x16x32_bf16 v[42:45], v[126:129], v[198:201], v[42:45]
	v_mfma_f32_16x16x32_bf16 v[34:37], v[118:121], v[210:213], v[34:37]
	v_mfma_f32_16x16x32_bf16 v[26:29], v[126:129], v[210:213], v[26:29]
	v_mfma_f32_16x16x32_bf16 v[18:21], v[118:121], v[218:221], v[18:21]
	v_mfma_f32_16x16x32_bf16 v[10:13], v[126:129], v[218:221], v[10:13]
	v_mfma_f32_16x16x32_bf16 v[54:57], v[146:149], v[162:165], v[54:57]
	v_mfma_f32_16x16x32_bf16 v[46:49], v[154:157], v[162:165], v[46:49]
	v_mfma_f32_16x16x32_bf16 v[38:41], v[146:149], v[194:197], v[38:41]
	v_mfma_f32_16x16x32_bf16 v[30:33], v[154:157], v[194:197], v[30:33]
	v_mfma_f32_16x16x32_bf16 v[22:25], v[146:149], v[206:209], v[22:25]
	v_mfma_f32_16x16x32_bf16 v[14:17], v[154:157], v[206:209], v[14:17]
	v_mfma_f32_16x16x32_bf16 v[6:9], v[146:149], v[214:217], v[6:9]
	v_mfma_f32_16x16x32_bf16 v[2:5], v[154:157], v[214:217], v[2:5]
	v_mfma_f32_16x16x32_bf16 v[54:57], v[150:153], v[166:169], v[54:57]
	v_mfma_f32_16x16x32_bf16 v[46:49], v[158:161], v[166:169], v[46:49]
	v_mfma_f32_16x16x32_bf16 v[38:41], v[150:153], v[198:201], v[38:41]
	v_mfma_f32_16x16x32_bf16 v[30:33], v[158:161], v[198:201], v[30:33]
	v_mfma_f32_16x16x32_bf16 v[22:25], v[150:153], v[210:213], v[22:25]
	v_mfma_f32_16x16x32_bf16 v[14:17], v[158:161], v[210:213], v[14:17]
	v_mfma_f32_16x16x32_bf16 v[6:9], v[150:153], v[218:221], v[6:9]
	v_mfma_f32_16x16x32_bf16 v[2:5], v[158:161], v[218:221], v[2:5]
	s_setprio 0
	s_barrier
	s_add_u32 s76, s76, 0x100
	s_addc_u32 s77, s77, 0
	s_add_u32 s47, s47, 0x100
	s_addc_u32 s62, s62, 0
	s_cmp_ge_i32 s82, s7
	s_mov_b32 s63, s82
	s_cbranch_scc0 .LBB0_834
	s_and_b64 vcc, exec, s[26:27]
	s_cbranch_vccz .LBB0_837
	s_barrier

.LBB0_1012:
	s_add_u32 s48, s96, s44
	s_addc_u32 s49, s97, s45
	s_and_b64 s[14:15], s[4:5], exec
	s_cselect_b32 s6, s49, s65
	s_cselect_b32 s14, s48, s64
	s_add_u32 s50, s3, s46
	s_addc_u32 s51, s35, s47
	s_and_b64 s[18:19], s[4:5], exec
	s_cselect_b32 s15, s51, s67
	s_cselect_b32 s17, s50, s66
	s_add_u32 s64, s64, 0x40080
	s_addc_u32 s65, s65, 0
	s_add_u32 s18, s66, 0x100
	s_addc_u32 s19, s67, 0
	s_mov_b32 s24, -2
	s_waitcnt vmcnt(0)
	ds_read_b128 v[130:133], v172
	ds_read_b128 v[134:137], v172 offset:1024
	ds_read_b128 v[138:141], v172 offset:2048
	ds_read_b128 v[142:145], v172 offset:3072
	ds_read_b128 v[164:167], v173
	ds_read_b128 v[176:179], v173 offset:1024
	ds_read_b128 v[180:183], v173 offset:2048
	ds_read_b128 v[184:187], v173 offset:3072
	s_add_u32 s25, s64, 0xfffc0080
	s_addc_u32 s28, s65, -1
	s_cmp_eq_u32 s24, 12
	s_cselect_b32 s69, s6, s28
	s_cselect_b32 s68, s14, s25
	s_cselect_b32 s67, s15, s19
	s_cselect_b32 s66, s17, s18
	v_lshl_add_u64 v[168:169], s[64:65], 0, v[156:157]
	s_add_i32 m0, s73, 0xc000
	ds_read_b128 v[188:191], v174
	ds_read_b128 v[192:195], v174 offset:1024
	ds_read_b128 v[196:199], v174 offset:2048
	ds_read_b128 v[200:203], v174 offset:3072
	ds_read_b128 v[206:209], v174 offset:4096
	ds_read_b128 v[210:213], v174 offset:5120
	ds_read_b128 v[214:217], v174 offset:6144
	ds_read_b128 v[218:221], v174 offset:7168
	global_load_lds_dwordx4 v[168:169], off
	s_add_i32 m0, s73, 0xe000
	v_lshl_add_u64 v[168:169], s[64:65], 0, v[158:159]
	global_load_lds_dwordx4 v[168:169], off
	s_waitcnt vmcnt(8) lgkmcnt(0)
	s_setprio 1
	s_barrier
	v_mfma_f32_16x16x32_bf16 v[126:129], v[130:133], v[188:191], 0
	v_mfma_f32_16x16x32_bf16 v[122:125], v[138:141], v[188:191], 0
	v_mfma_f32_16x16x32_bf16 v[110:113], v[130:133], v[196:199], 0
	v_mfma_f32_16x16x32_bf16 v[106:109], v[138:141], v[196:199], 0
	v_mfma_f32_16x16x32_bf16 v[94:97], v[130:133], v[206:209], 0
	v_mfma_f32_16x16x32_bf16 v[90:93], v[138:141], v[206:209], 0
	v_mfma_f32_16x16x32_bf16 v[78:81], v[130:133], v[214:217], 0
	v_mfma_f32_16x16x32_bf16 v[74:77], v[138:141], v[214:217], 0
	v_mfma_f32_16x16x32_bf16 v[126:129], v[134:137], v[192:195], v[126:129]
	v_mfma_f32_16x16x32_bf16 v[122:125], v[142:145], v[192:195], v[122:125]
	v_mfma_f32_16x16x32_bf16 v[110:113], v[134:137], v[200:203], v[110:113]
	v_mfma_f32_16x16x32_bf16 v[106:109], v[142:145], v[200:203], v[106:109]
	v_mfma_f32_16x16x32_bf16 v[94:97], v[134:137], v[210:213], v[94:97]
	v_mfma_f32_16x16x32_bf16 v[90:93], v[142:145], v[210:213], v[90:93]
	v_mfma_f32_16x16x32_bf16 v[78:81], v[134:137], v[218:221], v[78:81]
	v_mfma_f32_16x16x32_bf16 v[74:77], v[142:145], v[218:221], v[74:77]
	v_mfma_f32_16x16x32_bf16 v[118:121], v[164:167], v[188:191], 0
	v_mfma_f32_16x16x32_bf16 v[114:117], v[180:183], v[188:191], 0
	v_mfma_f32_16x16x32_bf16 v[102:105], v[164:167], v[196:199], 0
	v_mfma_f32_16x16x32_bf16 v[98:101], v[180:183], v[196:199], 0
	v_mfma_f32_16x16x32_bf16 v[86:89], v[164:167], v[206:209], 0
	v_mfma_f32_16x16x32_bf16 v[82:85], v[180:183], v[206:209], 0
	v_mfma_f32_16x16x32_bf16 v[70:73], v[164:167], v[214:217], 0
	v_mfma_f32_16x16x32_bf16 v[66:69], v[180:183], v[214:217], 0
	v_mfma_f32_16x16x32_bf16 v[118:121], v[176:179], v[192:195], v[118:121]
	v_mfma_f32_16x16x32_bf16 v[114:117], v[184:187], v[192:195], v[114:117]
	v_mfma_f32_16x16x32_bf16 v[102:105], v[176:179], v[200:203], v[102:105]
	v_mfma_f32_16x16x32_bf16 v[98:101], v[184:187], v[200:203], v[98:101]
	v_mfma_f32_16x16x32_bf16 v[86:89], v[176:179], v[210:213], v[86:89]
	v_mfma_f32_16x16x32_bf16 v[82:85], v[184:187], v[210:213], v[82:85]
	v_mfma_f32_16x16x32_bf16 v[70:73], v[176:179], v[218:221], v[70:73]
	v_mfma_f32_16x16x32_bf16 v[66:69], v[184:187], v[218:221], v[66:69]
	s_setprio 0
	s_barrier
	s_add_i32 s25, s82, s70
	v_lshl_add_u64 v[168:169], s[66:67], 0, v[150:151]
	s_mov_b32 m0, s25
	ds_read_b128 v[188:191], v174 offset:16384
	ds_read_b128 v[192:195], v174 offset:17408
	ds_read_b128 v[196:199], v174 offset:18432
	ds_read_b128 v[200:203], v174 offset:19456
	ds_read_b128 v[206:209], v174 offset:20480
	ds_read_b128 v[210:213], v174 offset:21504
	ds_read_b128 v[214:217], v174 offset:22528
	ds_read_b128 v[218:221], v174 offset:23552
	global_load_lds_dwordx4 v[168:169], off
	s_add_i32 m0, s25, 0x2000
	s_add_u32 s28, s66, 0x40000
	v_lshl_add_u64 v[222:223], s[66:67], 0, v[146:147]
	s_addc_u32 s29, s67, 0
	s_add_i32 s25, s83, s70
	global_load_lds_dwordx4 v[222:223], off
	v_lshl_add_u64 v[224:225], s[28:29], 0, v[150:151]
	s_mov_b32 m0, s25
	v_lshl_add_u64 v[226:227], s[68:69], 0, v[148:149]
	global_load_lds_dwordx4 v[224:225], off
	s_add_i32 m0, s25, 0x2000
	v_lshl_add_u64 v[224:225], s[28:29], 0, v[146:147]
	global_load_lds_dwordx4 v[224:225], off
	s_mov_b32 m0, s73
	v_lshl_add_u64 v[224:225], s[68:69], 0, v[152:153]
	global_load_lds_dwordx4 v[224:225], off
	s_mov_b32 m0, s74
	s_nop 0
	global_load_lds_dwordx4 v[226:227], off
	s_waitcnt vmcnt(8) lgkmcnt(0)
	s_setprio 1
	s_barrier
	v_mfma_f32_16x16x32_bf16 v[62:65], v[130:133], v[188:191], 0
	v_mfma_f32_16x16x32_bf16 v[58:61], v[138:141], v[188:191], 0
	v_mfma_f32_16x16x32_bf16 v[46:49], v[130:133], v[196:199], 0
	v_mfma_f32_16x16x32_bf16 v[42:45], v[138:141], v[196:199], 0
	v_mfma_f32_16x16x32_bf16 v[30:33], v[130:133], v[206:209], 0
	v_mfma_f32_16x16x32_bf16 v[26:29], v[138:141], v[206:209], 0
	v_mfma_f32_16x16x32_bf16 v[14:17], v[130:133], v[214:217], 0
	v_mfma_f32_16x16x32_bf16 v[10:13], v[138:141], v[214:217], 0
	v_mfma_f32_16x16x32_bf16 v[62:65], v[134:137], v[192:195], v[62:65]
	v_mfma_f32_16x16x32_bf16 v[58:61], v[142:145], v[192:195], v[58:61]
	v_mfma_f32_16x16x32_bf16 v[46:49], v[134:137], v[200:203], v[46:49]
	v_mfma_f32_16x16x32_bf16 v[42:45], v[142:145], v[200:203], v[42:45]
	v_mfma_f32_16x16x32_bf16 v[30:33], v[134:137], v[210:213], v[30:33]
	v_mfma_f32_16x16x32_bf16 v[26:29], v[142:145], v[210:213], v[26:29]
	v_mfma_f32_16x16x32_bf16 v[14:17], v[134:137], v[218:221], v[14:17]
	v_mfma_f32_16x16x32_bf16 v[10:13], v[142:145], v[218:221], v[10:13]
	v_mfma_f32_16x16x32_bf16 v[54:57], v[164:167], v[188:191], 0
	v_mfma_f32_16x16x32_bf16 v[50:53], v[180:183], v[188:191], 0
	v_mfma_f32_16x16x32_bf16 v[38:41], v[164:167], v[196:199], 0
	v_mfma_f32_16x16x32_bf16 v[34:37], v[180:183], v[196:199], 0
	v_mfma_f32_16x16x32_bf16 v[22:25], v[164:167], v[206:209], 0
	v_mfma_f32_16x16x32_bf16 v[18:21], v[180:183], v[206:209], 0
	v_mfma_f32_16x16x32_bf16 v[6:9], v[164:167], v[214:217], 0
	v_mfma_f32_16x16x32_bf16 v[2:5], v[180:183], v[214:217], 0
	v_mfma_f32_16x16x32_bf16 v[54:57], v[176:179], v[192:195], v[54:57]
	v_mfma_f32_16x16x32_bf16 v[50:53], v[184:187], v[192:195], v[50:53]
	v_mfma_f32_16x16x32_bf16 v[38:41], v[176:179], v[200:203], v[38:41]
	v_mfma_f32_16x16x32_bf16 v[34:37], v[184:187], v[200:203], v[34:37]
	v_mfma_f32_16x16x32_bf16 v[22:25], v[176:179], v[210:213], v[22:25]
	v_mfma_f32_16x16x32_bf16 v[18:21], v[184:187], v[210:213], v[18:21]
	v_mfma_f32_16x16x32_bf16 v[6:9], v[176:179], v[218:221], v[6:9]
	v_mfma_f32_16x16x32_bf16 v[2:5], v[184:187], v[218:221], v[2:5]
	s_setprio 0
	s_barrier
	s_add_i32 s25, 0, 0x18000
	s_add_i32 s30, 0, 0x1c000
	v_add_u32_e32 v142, s25, v171
	v_add_u32_e32 v175, s30, v171
	ds_read_b128 v[130:133], v142
	ds_read_b128 v[134:137], v142 offset:1024
	ds_read_b128 v[138:141], v142 offset:2048
	ds_read_b128 v[142:145], v142 offset:3072
	ds_read_b128 v[164:167], v175
	ds_read_b128 v[176:179], v175 offset:1024
	ds_read_b128 v[180:183], v175 offset:2048
	ds_read_b128 v[184:187], v175 offset:3072
	s_add_u32 s28, s68, 0x40000
	s_addc_u32 s29, s69, 0
	s_mov_b32 m0, s75
	v_lshl_add_u64 v[228:229], s[28:29], 0, v[152:153]
	ds_read_b128 v[188:191], v174 offset:32768
	ds_read_b128 v[192:195], v174 offset:33792
	ds_read_b128 v[196:199], v174 offset:34816
	ds_read_b128 v[200:203], v174 offset:35840
	ds_read_b128 v[206:209], v174 offset:36864
	ds_read_b128 v[210:213], v174 offset:37888
	ds_read_b128 v[214:217], v174 offset:38912
	ds_read_b128 v[218:221], v174 offset:39936
	global_load_lds_dwordx4 v[228:229], off
	s_mov_b32 m0, s76
	v_lshl_add_u64 v[228:229], s[28:29], 0, v[148:149]
	global_load_lds_dwordx4 v[228:229], off
	s_waitcnt vmcnt(8) lgkmcnt(0)
	s_setprio 1
	s_barrier
	v_mfma_f32_16x16x32_bf16 v[126:129], v[130:133], v[188:191], v[126:129]
	v_mfma_f32_16x16x32_bf16 v[122:125], v[138:141], v[188:191], v[122:125]
	v_mfma_f32_16x16x32_bf16 v[110:113], v[130:133], v[196:199], v[110:113]
	v_mfma_f32_16x16x32_bf16 v[106:109], v[138:141], v[196:199], v[106:109]
	v_mfma_f32_16x16x32_bf16 v[94:97], v[130:133], v[206:209], v[94:97]
	v_mfma_f32_16x16x32_bf16 v[90:93], v[138:141], v[206:209], v[90:93]
	v_mfma_f32_16x16x32_bf16 v[78:81], v[130:133], v[214:217], v[78:81]
	v_mfma_f32_16x16x32_bf16 v[74:77], v[138:141], v[214:217], v[74:77]
	v_mfma_f32_16x16x32_bf16 v[126:129], v[134:137], v[192:195], v[126:129]
	v_mfma_f32_16x16x32_bf16 v[122:125], v[142:145], v[192:195], v[122:125]
	v_mfma_f32_16x16x32_bf16 v[110:113], v[134:137], v[200:203], v[110:113]
	v_mfma_f32_16x16x32_bf16 v[106:109], v[142:145], v[200:203], v[106:109]
	v_mfma_f32_16x16x32_bf16 v[94:97], v[134:137], v[210:213], v[94:97]
	v_mfma_f32_16x16x32_bf16 v[90:93], v[142:145], v[210:213], v[90:93]
	v_mfma_f32_16x16x32_bf16 v[78:81], v[134:137], v[218:221], v[78:81]
	v_mfma_f32_16x16x32_bf16 v[74:77], v[142:145], v[218:221], v[74:77]
	v_mfma_f32_16x16x32_bf16 v[118:121], v[164:167], v[188:191], v[118:121]
	v_mfma_f32_16x16x32_bf16 v[114:117], v[180:183], v[188:191], v[114:117]
	v_mfma_f32_16x16x32_bf16 v[102:105], v[164:167], v[196:199], v[102:105]
	v_mfma_f32_16x16x32_bf16 v[98:101], v[180:183], v[196:199], v[98:101]
	v_mfma_f32_16x16x32_bf16 v[86:89], v[164:167], v[206:209], v[86:89]
	v_mfma_f32_16x16x32_bf16 v[82:85], v[180:183], v[206:209], v[82:85]
	v_mfma_f32_16x16x32_bf16 v[70:73], v[164:167], v[214:217], v[70:73]
	v_mfma_f32_16x16x32_bf16 v[66:69], v[180:183], v[214:217], v[66:69]
	v_mfma_f32_16x16x32_bf16 v[118:121], v[176:179], v[192:195], v[118:121]
	v_mfma_f32_16x16x32_bf16 v[114:117], v[184:187], v[192:195], v[114:117]
	v_mfma_f32_16x16x32_bf16 v[102:105], v[176:179], v[200:203], v[102:105]
	v_mfma_f32_16x16x32_bf16 v[98:101], v[184:187], v[200:203], v[98:101]
	v_mfma_f32_16x16x32_bf16 v[86:89], v[176:179], v[210:213], v[86:89]
	v_mfma_f32_16x16x32_bf16 v[82:85], v[184:187], v[210:213], v[82:85]
	v_mfma_f32_16x16x32_bf16 v[70:73], v[176:179], v[218:221], v[70:73]
	v_mfma_f32_16x16x32_bf16 v[66:69], v[184:187], v[218:221], v[66:69]
	s_setprio 0
	s_barrier
	s_add_i32 s25, s25, s70
	v_lshl_add_u64 v[168:169], v[168:169], 0, s[36:37]
	s_mov_b32 m0, s25
	ds_read_b128 v[188:191], v174 offset:49152
	ds_read_b128 v[192:195], v174 offset:50176
	ds_read_b128 v[196:199], v174 offset:51200
	ds_read_b128 v[200:203], v174 offset:52224
	ds_read_b128 v[206:209], v174 offset:53248
	ds_read_b128 v[210:213], v174 offset:54272
	ds_read_b128 v[214:217], v174 offset:55296
	ds_read_b128 v[218:221], v174 offset:56320
	global_load_lds_dwordx4 v[168:169], off
	s_add_i32 m0, s25, 0x2000
	s_add_u32 s28, s66, 0x40080
	v_lshl_add_u64 v[168:169], v[222:223], 0, s[36:37]
	s_addc_u32 s29, s67, 0
	s_add_i32 s25, s30, s70
	global_load_lds_dwordx4 v[168:169], off
	s_mov_b32 m0, s25
	v_lshl_add_u64 v[168:169], s[28:29], 0, v[150:151]
	global_load_lds_dwordx4 v[168:169], off
	s_add_i32 m0, s25, 0x2000
	v_lshl_add_u64 v[168:169], s[28:29], 0, v[146:147]
	global_load_lds_dwordx4 v[168:169], off
	s_mov_b32 m0, s79
	v_lshl_add_u64 v[168:169], v[224:225], 0, s[36:37]
	global_load_lds_dwordx4 v[168:169], off
	s_mov_b32 m0, s80
	v_lshl_add_u64 v[168:169], v[226:227], 0, s[36:37]
	global_load_lds_dwordx4 v[168:169], off
	s_waitcnt vmcnt(8) lgkmcnt(0)
	s_setprio 1
	s_barrier
	v_mfma_f32_16x16x32_bf16 v[62:65], v[130:133], v[188:191], v[62:65]
	v_mfma_f32_16x16x32_bf16 v[58:61], v[138:141], v[188:191], v[58:61]
	v_mfma_f32_16x16x32_bf16 v[46:49], v[130:133], v[196:199], v[46:49]
	v_mfma_f32_16x16x32_bf16 v[42:45], v[138:141], v[196:199], v[42:45]
	v_mfma_f32_16x16x32_bf16 v[30:33], v[130:133], v[206:209], v[30:33]
	v_mfma_f32_16x16x32_bf16 v[26:29], v[138:141], v[206:209], v[26:29]
	v_mfma_f32_16x16x32_bf16 v[14:17], v[130:133], v[214:217], v[14:17]
	v_mfma_f32_16x16x32_bf16 v[10:13], v[138:141], v[214:217], v[10:13]
	v_mfma_f32_16x16x32_bf16 v[62:65], v[134:137], v[192:195], v[62:65]
	v_mfma_f32_16x16x32_bf16 v[58:61], v[142:145], v[192:195], v[58:61]
	v_mfma_f32_16x16x32_bf16 v[46:49], v[134:137], v[200:203], v[46:49]
	v_mfma_f32_16x16x32_bf16 v[42:45], v[142:145], v[200:203], v[42:45]
	v_mfma_f32_16x16x32_bf16 v[30:33], v[134:137], v[210:213], v[30:33]
	v_mfma_f32_16x16x32_bf16 v[26:29], v[142:145], v[210:213], v[26:29]
	v_mfma_f32_16x16x32_bf16 v[14:17], v[134:137], v[218:221], v[14:17]
	v_mfma_f32_16x16x32_bf16 v[10:13], v[142:145], v[218:221], v[10:13]
	v_mfma_f32_16x16x32_bf16 v[54:57], v[164:167], v[188:191], v[54:57]
	v_mfma_f32_16x16x32_bf16 v[50:53], v[180:183], v[188:191], v[50:53]
	v_mfma_f32_16x16x32_bf16 v[38:41], v[164:167], v[196:199], v[38:41]
	v_mfma_f32_16x16x32_bf16 v[34:37], v[180:183], v[196:199], v[34:37]
	v_mfma_f32_16x16x32_bf16 v[22:25], v[164:167], v[206:209], v[22:25]
	v_mfma_f32_16x16x32_bf16 v[18:21], v[180:183], v[206:209], v[18:21]
	v_mfma_f32_16x16x32_bf16 v[6:9], v[164:167], v[214:217], v[6:9]
	v_mfma_f32_16x16x32_bf16 v[2:5], v[180:183], v[214:217], v[2:5]
	v_mfma_f32_16x16x32_bf16 v[54:57], v[176:179], v[192:195], v[54:57]
	v_mfma_f32_16x16x32_bf16 v[50:53], v[184:187], v[192:195], v[50:53]
	v_mfma_f32_16x16x32_bf16 v[38:41], v[176:179], v[200:203], v[38:41]
	v_mfma_f32_16x16x32_bf16 v[34:37], v[184:187], v[200:203], v[34:37]
	v_mfma_f32_16x16x32_bf16 v[22:25], v[176:179], v[210:213], v[22:25]
	v_mfma_f32_16x16x32_bf16 v[18:21], v[184:187], v[210:213], v[18:21]
	v_mfma_f32_16x16x32_bf16 v[6:9], v[176:179], v[218:221], v[6:9]
	v_mfma_f32_16x16x32_bf16 v[2:5], v[184:187], v[218:221], v[2:5]
	s_setprio 0
	s_barrier
	s_add_i32 s24, s24, 2
	s_add_u32 s64, s64, 0x100
	s_addc_u32 s65, s65, 0
	s_add_u32 s18, s18, 0x100
	s_addc_u32 s19, s19, 0
	s_cmp_gt_u32 s24, 13
.LBB0_1013:
	ds_read_b128 v[130:133], v172
	ds_read_b128 v[134:137], v172 offset:1024
	ds_read_b128 v[138:141], v172 offset:2048
	ds_read_b128 v[142:145], v172 offset:3072
	ds_read_b128 v[164:167], v173
	ds_read_b128 v[176:179], v173 offset:1024
	ds_read_b128 v[180:183], v173 offset:2048
	ds_read_b128 v[184:187], v173 offset:3072
	s_add_u32 s25, s64, 0xfffc0080
	s_addc_u32 s28, s65, -1
	s_cmp_eq_u32 s24, 12
	s_cselect_b32 s69, s6, s28
	s_cselect_b32 s68, s14, s25
	s_cselect_b32 s67, s15, s19
	s_cselect_b32 s66, s17, s18
	v_lshl_add_u64 v[168:169], s[64:65], 0, v[156:157]
	s_add_i32 m0, s73, 0xc000
	ds_read_b128 v[188:191], v174
	ds_read_b128 v[192:195], v174 offset:1024
	ds_read_b128 v[196:199], v174 offset:2048
	ds_read_b128 v[200:203], v174 offset:3072
	ds_read_b128 v[206:209], v174 offset:4096
	ds_read_b128 v[210:213], v174 offset:5120
	ds_read_b128 v[214:217], v174 offset:6144
	ds_read_b128 v[218:221], v174 offset:7168
	global_load_lds_dwordx4 v[168:169], off
	s_add_i32 m0, s73, 0xe000
	v_lshl_add_u64 v[168:169], s[64:65], 0, v[158:159]
	global_load_lds_dwordx4 v[168:169], off
	s_waitcnt vmcnt(8) lgkmcnt(0)
	s_setprio 1
	s_barrier
	v_mfma_f32_16x16x32_bf16 v[126:129], v[130:133], v[188:191], v[126:129]
	v_mfma_f32_16x16x32_bf16 v[122:125], v[138:141], v[188:191], v[122:125]
	v_mfma_f32_16x16x32_bf16 v[110:113], v[130:133], v[196:199], v[110:113]
	v_mfma_f32_16x16x32_bf16 v[106:109], v[138:141], v[196:199], v[106:109]
	v_mfma_f32_16x16x32_bf16 v[94:97], v[130:133], v[206:209], v[94:97]
	v_mfma_f32_16x16x32_bf16 v[90:93], v[138:141], v[206:209], v[90:93]
	v_mfma_f32_16x16x32_bf16 v[78:81], v[130:133], v[214:217], v[78:81]
	v_mfma_f32_16x16x32_bf16 v[74:77], v[138:141], v[214:217], v[74:77]
	v_mfma_f32_16x16x32_bf16 v[126:129], v[134:137], v[192:195], v[126:129]
	v_mfma_f32_16x16x32_bf16 v[122:125], v[142:145], v[192:195], v[122:125]
	v_mfma_f32_16x16x32_bf16 v[110:113], v[134:137], v[200:203], v[110:113]
	v_mfma_f32_16x16x32_bf16 v[106:109], v[142:145], v[200:203], v[106:109]
	v_mfma_f32_16x16x32_bf16 v[94:97], v[134:137], v[210:213], v[94:97]
	v_mfma_f32_16x16x32_bf16 v[90:93], v[142:145], v[210:213], v[90:93]
	v_mfma_f32_16x16x32_bf16 v[78:81], v[134:137], v[218:221], v[78:81]
	v_mfma_f32_16x16x32_bf16 v[74:77], v[142:145], v[218:221], v[74:77]
	v_mfma_f32_16x16x32_bf16 v[118:121], v[164:167], v[188:191], v[118:121]
	v_mfma_f32_16x16x32_bf16 v[114:117], v[180:183], v[188:191], v[114:117]
	v_mfma_f32_16x16x32_bf16 v[102:105], v[164:167], v[196:199], v[102:105]
	v_mfma_f32_16x16x32_bf16 v[98:101], v[180:183], v[196:199], v[98:101]
	v_mfma_f32_16x16x32_bf16 v[86:89], v[164:167], v[206:209], v[86:89]
	v_mfma_f32_16x16x32_bf16 v[82:85], v[180:183], v[206:209], v[82:85]
	v_mfma_f32_16x16x32_bf16 v[70:73], v[164:167], v[214:217], v[70:73]
	v_mfma_f32_16x16x32_bf16 v[66:69], v[180:183], v[214:217], v[66:69]
	v_mfma_f32_16x16x32_bf16 v[118:121], v[176:179], v[192:195], v[118:121]
	v_mfma_f32_16x16x32_bf16 v[114:117], v[184:187], v[192:195], v[114:117]
	v_mfma_f32_16x16x32_bf16 v[102:105], v[176:179], v[200:203], v[102:105]
	v_mfma_f32_16x16x32_bf16 v[98:101], v[184:187], v[200:203], v[98:101]
	v_mfma_f32_16x16x32_bf16 v[86:89], v[176:179], v[210:213], v[86:89]
	v_mfma_f32_16x16x32_bf16 v[82:85], v[184:187], v[210:213], v[82:85]
	v_mfma_f32_16x16x32_bf16 v[70:73], v[176:179], v[218:221], v[70:73]
	v_mfma_f32_16x16x32_bf16 v[66:69], v[184:187], v[218:221], v[66:69]
	s_setprio 0
	s_barrier
	s_add_i32 s25, s82, s70
	v_lshl_add_u64 v[168:169], s[66:67], 0, v[150:151]
	s_mov_b32 m0, s25
	ds_read_b128 v[188:191], v174 offset:16384
	ds_read_b128 v[192:195], v174 offset:17408
	ds_read_b128 v[196:199], v174 offset:18432
	ds_read_b128 v[200:203], v174 offset:19456
	ds_read_b128 v[206:209], v174 offset:20480
	ds_read_b128 v[210:213], v174 offset:21504
	ds_read_b128 v[214:217], v174 offset:22528
	ds_read_b128 v[218:221], v174 offset:23552
	global_load_lds_dwordx4 v[168:169], off
	s_add_i32 m0, s25, 0x2000
	s_add_u32 s28, s66, 0x40000
	v_lshl_add_u64 v[222:223], s[66:67], 0, v[146:147]
	s_addc_u32 s29, s67, 0
	s_add_i32 s25, s83, s70
	global_load_lds_dwordx4 v[222:223], off
	v_lshl_add_u64 v[224:225], s[28:29], 0, v[150:151]
	s_mov_b32 m0, s25
	v_lshl_add_u64 v[226:227], s[68:69], 0, v[148:149]
	global_load_lds_dwordx4 v[224:225], off
	s_add_i32 m0, s25, 0x2000
	v_lshl_add_u64 v[224:225], s[28:29], 0, v[146:147]
	global_load_lds_dwordx4 v[224:225], off
	s_mov_b32 m0, s73
	v_lshl_add_u64 v[224:225], s[68:69], 0, v[152:153]
	global_load_lds_dwordx4 v[224:225], off
	s_mov_b32 m0, s74
	s_nop 0
	global_load_lds_dwordx4 v[226:227], off
	s_waitcnt vmcnt(8) lgkmcnt(0)
	s_setprio 1
	s_barrier
	v_mfma_f32_16x16x32_bf16 v[62:65], v[130:133], v[188:191], v[62:65]
	v_mfma_f32_16x16x32_bf16 v[58:61], v[138:141], v[188:191], v[58:61]
	v_mfma_f32_16x16x32_bf16 v[46:49], v[130:133], v[196:199], v[46:49]
	v_mfma_f32_16x16x32_bf16 v[42:45], v[138:141], v[196:199], v[42:45]
	v_mfma_f32_16x16x32_bf16 v[30:33], v[130:133], v[206:209], v[30:33]
	v_mfma_f32_16x16x32_bf16 v[26:29], v[138:141], v[206:209], v[26:29]
	v_mfma_f32_16x16x32_bf16 v[14:17], v[130:133], v[214:217], v[14:17]
	v_mfma_f32_16x16x32_bf16 v[10:13], v[138:141], v[214:217], v[10:13]
	v_mfma_f32_16x16x32_bf16 v[62:65], v[134:137], v[192:195], v[62:65]
	v_mfma_f32_16x16x32_bf16 v[58:61], v[142:145], v[192:195], v[58:61]
	v_mfma_f32_16x16x32_bf16 v[46:49], v[134:137], v[200:203], v[46:49]
	v_mfma_f32_16x16x32_bf16 v[42:45], v[142:145], v[200:203], v[42:45]
	v_mfma_f32_16x16x32_bf16 v[30:33], v[134:137], v[210:213], v[30:33]
	v_mfma_f32_16x16x32_bf16 v[26:29], v[142:145], v[210:213], v[26:29]
	v_mfma_f32_16x16x32_bf16 v[14:17], v[134:137], v[218:221], v[14:17]
	v_mfma_f32_16x16x32_bf16 v[10:13], v[142:145], v[218:221], v[10:13]
	v_mfma_f32_16x16x32_bf16 v[54:57], v[164:167], v[188:191], v[54:57]
	v_mfma_f32_16x16x32_bf16 v[50:53], v[180:183], v[188:191], v[50:53]
	v_mfma_f32_16x16x32_bf16 v[38:41], v[164:167], v[196:199], v[38:41]
	v_mfma_f32_16x16x32_bf16 v[34:37], v[180:183], v[196:199], v[34:37]
	v_mfma_f32_16x16x32_bf16 v[22:25], v[164:167], v[206:209], v[22:25]
	v_mfma_f32_16x16x32_bf16 v[18:21], v[180:183], v[206:209], v[18:21]
	v_mfma_f32_16x16x32_bf16 v[6:9], v[164:167], v[214:217], v[6:9]
	v_mfma_f32_16x16x32_bf16 v[2:5], v[180:183], v[214:217], v[2:5]
	v_mfma_f32_16x16x32_bf16 v[54:57], v[176:179], v[192:195], v[54:57]
	v_mfma_f32_16x16x32_bf16 v[50:53], v[184:187], v[192:195], v[50:53]
	v_mfma_f32_16x16x32_bf16 v[38:41], v[176:179], v[200:203], v[38:41]
	v_mfma_f32_16x16x32_bf16 v[34:37], v[184:187], v[200:203], v[34:37]
	v_mfma_f32_16x16x32_bf16 v[22:25], v[176:179], v[210:213], v[22:25]
	v_mfma_f32_16x16x32_bf16 v[18:21], v[184:187], v[210:213], v[18:21]
	v_mfma_f32_16x16x32_bf16 v[6:9], v[176:179], v[218:221], v[6:9]
	v_mfma_f32_16x16x32_bf16 v[2:5], v[184:187], v[218:221], v[2:5]
	s_setprio 0
	s_barrier
	s_add_i32 s25, 0, 0x18000
	s_add_i32 s30, 0, 0x1c000
	v_add_u32_e32 v142, s25, v171
	v_add_u32_e32 v175, s30, v171
	ds_read_b128 v[130:133], v142
	ds_read_b128 v[134:137], v142 offset:1024
	ds_read_b128 v[138:141], v142 offset:2048
	ds_read_b128 v[142:145], v142 offset:3072
	ds_read_b128 v[164:167], v175
	ds_read_b128 v[176:179], v175 offset:1024
	ds_read_b128 v[180:183], v175 offset:2048
	ds_read_b128 v[184:187], v175 offset:3072
	s_add_u32 s28, s68, 0x40000
	s_addc_u32 s29, s69, 0
	s_mov_b32 m0, s75
	v_lshl_add_u64 v[228:229], s[28:29], 0, v[152:153]
	ds_read_b128 v[188:191], v174 offset:32768
	ds_read_b128 v[192:195], v174 offset:33792
	ds_read_b128 v[196:199], v174 offset:34816
	ds_read_b128 v[200:203], v174 offset:35840
	ds_read_b128 v[206:209], v174 offset:36864
	ds_read_b128 v[210:213], v174 offset:37888
	ds_read_b128 v[214:217], v174 offset:38912
	ds_read_b128 v[218:221], v174 offset:39936
	global_load_lds_dwordx4 v[228:229], off
	s_mov_b32 m0, s76
	v_lshl_add_u64 v[228:229], s[28:29], 0, v[148:149]
	global_load_lds_dwordx4 v[228:229], off
	s_waitcnt vmcnt(8) lgkmcnt(0)
	s_setprio 1
	s_barrier
	v_mfma_f32_16x16x32_bf16 v[126:129], v[130:133], v[188:191], v[126:129]
	v_mfma_f32_16x16x32_bf16 v[122:125], v[138:141], v[188:191], v[122:125]
	v_mfma_f32_16x16x32_bf16 v[110:113], v[130:133], v[196:199], v[110:113]
	v_mfma_f32_16x16x32_bf16 v[106:109], v[138:141], v[196:199], v[106:109]
	v_mfma_f32_16x16x32_bf16 v[94:97], v[130:133], v[206:209], v[94:97]
	v_mfma_f32_16x16x32_bf16 v[90:93], v[138:141], v[206:209], v[90:93]
	v_mfma_f32_16x16x32_bf16 v[78:81], v[130:133], v[214:217], v[78:81]
	v_mfma_f32_16x16x32_bf16 v[74:77], v[138:141], v[214:217], v[74:77]
	v_mfma_f32_16x16x32_bf16 v[126:129], v[134:137], v[192:195], v[126:129]
	v_mfma_f32_16x16x32_bf16 v[122:125], v[142:145], v[192:195], v[122:125]
	v_mfma_f32_16x16x32_bf16 v[110:113], v[134:137], v[200:203], v[110:113]
	v_mfma_f32_16x16x32_bf16 v[106:109], v[142:145], v[200:203], v[106:109]
	v_mfma_f32_16x16x32_bf16 v[94:97], v[134:137], v[210:213], v[94:97]
	v_mfma_f32_16x16x32_bf16 v[90:93], v[142:145], v[210:213], v[90:93]
	v_mfma_f32_16x16x32_bf16 v[78:81], v[134:137], v[218:221], v[78:81]
	v_mfma_f32_16x16x32_bf16 v[74:77], v[142:145], v[218:221], v[74:77]
	v_mfma_f32_16x16x32_bf16 v[118:121], v[164:167], v[188:191], v[118:121]
	v_mfma_f32_16x16x32_bf16 v[114:117], v[180:183], v[188:191], v[114:117]
	v_mfma_f32_16x16x32_bf16 v[102:105], v[164:167], v[196:199], v[102:105]
	v_mfma_f32_16x16x32_bf16 v[98:101], v[180:183], v[196:199], v[98:101]
	v_mfma_f32_16x16x32_bf16 v[86:89], v[164:167], v[206:209], v[86:89]
	v_mfma_f32_16x16x32_bf16 v[82:85], v[180:183], v[206:209], v[82:85]
	v_mfma_f32_16x16x32_bf16 v[70:73], v[164:167], v[214:217], v[70:73]
	v_mfma_f32_16x16x32_bf16 v[66:69], v[180:183], v[214:217], v[66:69]
	v_mfma_f32_16x16x32_bf16 v[118:121], v[176:179], v[192:195], v[118:121]
	v_mfma_f32_16x16x32_bf16 v[114:117], v[184:187], v[192:195], v[114:117]
	v_mfma_f32_16x16x32_bf16 v[102:105], v[176:179], v[200:203], v[102:105]
	v_mfma_f32_16x16x32_bf16 v[98:101], v[184:187], v[200:203], v[98:101]
	v_mfma_f32_16x16x32_bf16 v[86:89], v[176:179], v[210:213], v[86:89]
	v_mfma_f32_16x16x32_bf16 v[82:85], v[184:187], v[210:213], v[82:85]
	v_mfma_f32_16x16x32_bf16 v[70:73], v[176:179], v[218:221], v[70:73]
	v_mfma_f32_16x16x32_bf16 v[66:69], v[184:187], v[218:221], v[66:69]
	s_setprio 0
	s_barrier
	s_add_i32 s25, s25, s70
	v_lshl_add_u64 v[168:169], v[168:169], 0, s[36:37]
	s_mov_b32 m0, s25
	ds_read_b128 v[188:191], v174 offset:49152
	ds_read_b128 v[192:195], v174 offset:50176
	ds_read_b128 v[196:199], v174 offset:51200
	ds_read_b128 v[200:203], v174 offset:52224
	ds_read_b128 v[206:209], v174 offset:53248
	ds_read_b128 v[210:213], v174 offset:54272
	ds_read_b128 v[214:217], v174 offset:55296
	ds_read_b128 v[218:221], v174 offset:56320
	global_load_lds_dwordx4 v[168:169], off
	s_add_i32 m0, s25, 0x2000
	s_add_u32 s28, s66, 0x40080
	v_lshl_add_u64 v[168:169], v[222:223], 0, s[36:37]
	s_addc_u32 s29, s67, 0
	s_add_i32 s25, s30, s70
	global_load_lds_dwordx4 v[168:169], off
	s_mov_b32 m0, s25
	v_lshl_add_u64 v[168:169], s[28:29], 0, v[150:151]
	global_load_lds_dwordx4 v[168:169], off
	s_add_i32 m0, s25, 0x2000
	v_lshl_add_u64 v[168:169], s[28:29], 0, v[146:147]
	global_load_lds_dwordx4 v[168:169], off
	s_mov_b32 m0, s79
	v_lshl_add_u64 v[168:169], v[224:225], 0, s[36:37]
	global_load_lds_dwordx4 v[168:169], off
	s_mov_b32 m0, s80
	v_lshl_add_u64 v[168:169], v[226:227], 0, s[36:37]
	global_load_lds_dwordx4 v[168:169], off
	s_waitcnt vmcnt(8) lgkmcnt(0)
	s_setprio 1
	s_barrier
	v_mfma_f32_16x16x32_bf16 v[62:65], v[130:133], v[188:191], v[62:65]
	v_mfma_f32_16x16x32_bf16 v[58:61], v[138:141], v[188:191], v[58:61]
	v_mfma_f32_16x16x32_bf16 v[46:49], v[130:133], v[196:199], v[46:49]
	v_mfma_f32_16x16x32_bf16 v[42:45], v[138:141], v[196:199], v[42:45]
	v_mfma_f32_16x16x32_bf16 v[30:33], v[130:133], v[206:209], v[30:33]
	v_mfma_f32_16x16x32_bf16 v[26:29], v[138:141], v[206:209], v[26:29]
	v_mfma_f32_16x16x32_bf16 v[14:17], v[130:133], v[214:217], v[14:17]
	v_mfma_f32_16x16x32_bf16 v[10:13], v[138:141], v[214:217], v[10:13]
	v_mfma_f32_16x16x32_bf16 v[62:65], v[134:137], v[192:195], v[62:65]
	v_mfma_f32_16x16x32_bf16 v[58:61], v[142:145], v[192:195], v[58:61]
	v_mfma_f32_16x16x32_bf16 v[46:49], v[134:137], v[200:203], v[46:49]
	v_mfma_f32_16x16x32_bf16 v[42:45], v[142:145], v[200:203], v[42:45]
	v_mfma_f32_16x16x32_bf16 v[30:33], v[134:137], v[210:213], v[30:33]
	v_mfma_f32_16x16x32_bf16 v[26:29], v[142:145], v[210:213], v[26:29]
	v_mfma_f32_16x16x32_bf16 v[14:17], v[134:137], v[218:221], v[14:17]
	v_mfma_f32_16x16x32_bf16 v[10:13], v[142:145], v[218:221], v[10:13]
	v_mfma_f32_16x16x32_bf16 v[54:57], v[164:167], v[188:191], v[54:57]
	v_mfma_f32_16x16x32_bf16 v[50:53], v[180:183], v[188:191], v[50:53]
	v_mfma_f32_16x16x32_bf16 v[38:41], v[164:167], v[196:199], v[38:41]
	v_mfma_f32_16x16x32_bf16 v[34:37], v[180:183], v[196:199], v[34:37]
	v_mfma_f32_16x16x32_bf16 v[22:25], v[164:167], v[206:209], v[22:25]
	v_mfma_f32_16x16x32_bf16 v[18:21], v[180:183], v[206:209], v[18:21]
	v_mfma_f32_16x16x32_bf16 v[6:9], v[164:167], v[214:217], v[6:9]
	v_mfma_f32_16x16x32_bf16 v[2:5], v[180:183], v[214:217], v[2:5]
	v_mfma_f32_16x16x32_bf16 v[54:57], v[176:179], v[192:195], v[54:57]
	v_mfma_f32_16x16x32_bf16 v[50:53], v[184:187], v[192:195], v[50:53]
	v_mfma_f32_16x16x32_bf16 v[38:41], v[176:179], v[200:203], v[38:41]
	v_mfma_f32_16x16x32_bf16 v[34:37], v[184:187], v[200:203], v[34:37]
	v_mfma_f32_16x16x32_bf16 v[22:25], v[176:179], v[210:213], v[22:25]
	v_mfma_f32_16x16x32_bf16 v[18:21], v[184:187], v[210:213], v[18:21]
	v_mfma_f32_16x16x32_bf16 v[6:9], v[176:179], v[218:221], v[6:9]
	v_mfma_f32_16x16x32_bf16 v[2:5], v[184:187], v[218:221], v[2:5]
	s_setprio 0
	s_barrier
	s_add_i32 s24, s24, 2
	s_add_u32 s64, s64, 0x100
	s_addc_u32 s65, s65, 0
	s_add_u32 s18, s18, 0x100
	s_addc_u32 s19, s19, 0
	s_cmp_gt_u32 s24, 13
	s_cbranch_scc0 .LBB0_1013
	s_and_b64 vcc, exec, s[38:39]
	s_cbranch_vccz .LBB0_1016
	s_barrier

.LBB0_1427:
	s_add_u32 s90, s35, s86
	s_addc_u32 s91, s64, s87
	s_and_b64 s[14:15], s[88:89], exec
	s_cselect_b32 s14, s91, s11
	s_cselect_b32 s15, s90, s10
	s_add_u32 s92, s65, s74
	s_addc_u32 s93, s68, s75
	s_and_b64 s[66:67], s[88:89], exec
	s_cselect_b32 s51, s93, s95
	s_cselect_b32 s84, s92, s94
	s_add_i32 s85, s18, -2
	s_add_u32 s10, s10, 0x40080
	s_addc_u32 s11, s11, 0
	s_add_u32 vcc_lo, s94, 0x100
	s_addc_u32 vcc_hi, s95, 0
	s_mov_b32 s94, 0
	s_waitcnt vmcnt(0)
	s_add_i32 s66, s94, 2
	s_add_u32 s67, s10, 0xfffc0080
	s_addc_u32 s72, s11, -1
	s_cmp_eq_u32 s85, s94
	s_cselect_b32 s97, s14, s72
	s_cselect_b32 s96, s15, s67
	s_cselect_b32 s95, s51, vcc_hi
	s_cselect_b32 s94, s84, vcc_lo
	s_add_i32 s67, 0, 0x10000
	s_add_i32 s62, 0, 0x14000
	v_add_u32_e32 v126, s67, v199
	v_add_u32_e32 v158, s62, v199
	ds_read_b128 v[114:117], v126
	ds_read_b128 v[118:121], v126 offset:1024
	ds_read_b128 v[122:125], v126 offset:2048
	ds_read_b128 v[126:129], v126 offset:3072
	ds_read_b128 v[146:149], v158
	ds_read_b128 v[150:153], v158 offset:1024
	ds_read_b128 v[154:157], v158 offset:2048
	ds_read_b128 v[158:161], v158 offset:3072
	v_lshl_add_u64 v[202:203], s[10:11], 0, v[196:197]
	s_add_i32 m0, s28, 0xc000
	ds_read_b128 v[162:165], v214
	ds_read_b128 v[166:169], v214 offset:1024
	ds_read_b128 v[216:219], v214 offset:2048
	ds_read_b128 v[220:223], v214 offset:3072
	ds_read_b128 v[224:227], v214 offset:4096
	ds_read_b128 v[228:231], v214 offset:5120
	ds_read_b128 v[232:235], v214 offset:6144
	ds_read_b128 v[236:239], v214 offset:7168
	global_load_lds_dwordx4 v[202:203], off
	s_add_i32 m0, s28, 0xe000
	v_lshl_add_u64 v[202:203], s[10:11], 0, v[176:177]
	global_load_lds_dwordx4 v[202:203], off
	s_waitcnt vmcnt(8) lgkmcnt(0)
	s_setprio 1
	s_barrier
	v_mfma_f32_16x16x32_bf16 v[142:145], v[114:117], v[162:165], 0
	v_mfma_f32_16x16x32_bf16 v[138:141], v[122:125], v[162:165], 0
	v_mfma_f32_16x16x32_bf16 v[110:113], v[114:117], v[216:219], 0
	v_mfma_f32_16x16x32_bf16 v[106:109], v[122:125], v[216:219], 0
	v_mfma_f32_16x16x32_bf16 v[98:101], v[114:117], v[224:227], 0
	v_mfma_f32_16x16x32_bf16 v[90:93], v[122:125], v[224:227], 0
	v_mfma_f32_16x16x32_bf16 v[82:85], v[114:117], v[232:235], 0
	v_mfma_f32_16x16x32_bf16 v[74:77], v[122:125], v[232:235], 0
	v_mfma_f32_16x16x32_bf16 v[142:145], v[118:121], v[166:169], v[142:145]
	v_mfma_f32_16x16x32_bf16 v[138:141], v[126:129], v[166:169], v[138:141]
	v_mfma_f32_16x16x32_bf16 v[110:113], v[118:121], v[220:223], v[110:113]
	v_mfma_f32_16x16x32_bf16 v[106:109], v[126:129], v[220:223], v[106:109]
	v_mfma_f32_16x16x32_bf16 v[98:101], v[118:121], v[228:231], v[98:101]
	v_mfma_f32_16x16x32_bf16 v[90:93], v[126:129], v[228:231], v[90:93]
	v_mfma_f32_16x16x32_bf16 v[82:85], v[118:121], v[236:239], v[82:85]
	v_mfma_f32_16x16x32_bf16 v[74:77], v[126:129], v[236:239], v[74:77]
	v_mfma_f32_16x16x32_bf16 v[134:137], v[146:149], v[162:165], 0
	v_mfma_f32_16x16x32_bf16 v[130:133], v[154:157], v[162:165], 0
	v_mfma_f32_16x16x32_bf16 v[102:105], v[146:149], v[216:219], 0
	v_mfma_f32_16x16x32_bf16 v[94:97], v[154:157], v[216:219], 0
	v_mfma_f32_16x16x32_bf16 v[86:89], v[146:149], v[224:227], 0
	v_mfma_f32_16x16x32_bf16 v[78:81], v[154:157], v[224:227], 0
	v_mfma_f32_16x16x32_bf16 v[70:73], v[146:149], v[232:235], 0
	v_mfma_f32_16x16x32_bf16 v[66:69], v[154:157], v[232:235], 0
	v_mfma_f32_16x16x32_bf16 v[134:137], v[150:153], v[166:169], v[134:137]
	v_mfma_f32_16x16x32_bf16 v[130:133], v[158:161], v[166:169], v[130:133]
	v_mfma_f32_16x16x32_bf16 v[102:105], v[150:153], v[220:223], v[102:105]
	v_mfma_f32_16x16x32_bf16 v[94:97], v[158:161], v[220:223], v[94:97]
	v_mfma_f32_16x16x32_bf16 v[86:89], v[150:153], v[228:231], v[86:89]
	v_mfma_f32_16x16x32_bf16 v[78:81], v[158:161], v[228:231], v[78:81]
	v_mfma_f32_16x16x32_bf16 v[70:73], v[150:153], v[236:239], v[70:73]
	v_mfma_f32_16x16x32_bf16 v[66:69], v[158:161], v[236:239], v[66:69]
	s_setprio 0
	s_barrier
	s_add_i32 s63, s67, s17
	v_lshl_add_u64 v[202:203], s[94:95], 0, v[174:175]
	s_mov_b32 m0, s63
	ds_read_b128 v[162:165], v214 offset:16384
	ds_read_b128 v[166:169], v214 offset:17408
	ds_read_b128 v[216:219], v214 offset:18432
	ds_read_b128 v[220:223], v214 offset:19456
	ds_read_b128 v[224:227], v214 offset:20480
	ds_read_b128 v[228:231], v214 offset:21504
	ds_read_b128 v[232:235], v214 offset:22528
	ds_read_b128 v[236:239], v214 offset:23552
	global_load_lds_dwordx4 v[202:203], off
	s_add_i32 m0, s63, 0x2000
	s_add_u32 s72, s94, 0x40000
	v_lshl_add_u64 v[240:241], s[94:95], 0, v[178:179]
	s_addc_u32 s73, s95, 0
	s_add_i32 s62, s62, s17
	global_load_lds_dwordx4 v[240:241], off
	v_lshl_add_u64 v[242:243], s[72:73], 0, v[174:175]
	s_mov_b32 m0, s62
	v_lshl_add_u64 v[244:245], s[96:97], 0, v[176:177]
	global_load_lds_dwordx4 v[242:243], off
	s_add_i32 m0, s62, 0x2000
	v_lshl_add_u64 v[242:243], s[72:73], 0, v[178:179]
	global_load_lds_dwordx4 v[242:243], off
	s_mov_b32 m0, s28
	v_lshl_add_u64 v[242:243], s[96:97], 0, v[172:173]
	global_load_lds_dwordx4 v[242:243], off
	s_mov_b32 m0, s29
	s_nop 0
	global_load_lds_dwordx4 v[244:245], off
	s_waitcnt vmcnt(8) lgkmcnt(0)
	s_setprio 1
	s_barrier
	v_mfma_f32_16x16x32_bf16 v[62:65], v[114:117], v[162:165], 0
	v_mfma_f32_16x16x32_bf16 v[58:61], v[122:125], v[162:165], 0
	v_mfma_f32_16x16x32_bf16 v[50:53], v[114:117], v[216:219], 0
	v_mfma_f32_16x16x32_bf16 v[42:45], v[122:125], v[216:219], 0
	v_mfma_f32_16x16x32_bf16 v[34:37], v[114:117], v[224:227], 0
	v_mfma_f32_16x16x32_bf16 v[26:29], v[122:125], v[224:227], 0
	v_mfma_f32_16x16x32_bf16 v[18:21], v[114:117], v[232:235], 0
	v_mfma_f32_16x16x32_bf16 v[10:13], v[122:125], v[232:235], 0
	v_mfma_f32_16x16x32_bf16 v[62:65], v[118:121], v[166:169], v[62:65]
	v_mfma_f32_16x16x32_bf16 v[58:61], v[126:129], v[166:169], v[58:61]
	v_mfma_f32_16x16x32_bf16 v[50:53], v[118:121], v[220:223], v[50:53]
	v_mfma_f32_16x16x32_bf16 v[42:45], v[126:129], v[220:223], v[42:45]
	v_mfma_f32_16x16x32_bf16 v[34:37], v[118:121], v[228:231], v[34:37]
	v_mfma_f32_16x16x32_bf16 v[26:29], v[126:129], v[228:231], v[26:29]
	v_mfma_f32_16x16x32_bf16 v[18:21], v[118:121], v[236:239], v[18:21]
	v_mfma_f32_16x16x32_bf16 v[10:13], v[126:129], v[236:239], v[10:13]
	v_mfma_f32_16x16x32_bf16 v[54:57], v[146:149], v[162:165], 0
	v_mfma_f32_16x16x32_bf16 v[46:49], v[154:157], v[162:165], 0
	v_mfma_f32_16x16x32_bf16 v[38:41], v[146:149], v[216:219], 0
	v_mfma_f32_16x16x32_bf16 v[30:33], v[154:157], v[216:219], 0
	v_mfma_f32_16x16x32_bf16 v[22:25], v[146:149], v[224:227], 0
	v_mfma_f32_16x16x32_bf16 v[14:17], v[154:157], v[224:227], 0
	v_mfma_f32_16x16x32_bf16 v[6:9], v[146:149], v[232:235], 0
	v_mfma_f32_16x16x32_bf16 v[2:5], v[154:157], v[232:235], 0
	v_mfma_f32_16x16x32_bf16 v[54:57], v[150:153], v[166:169], v[54:57]
	v_mfma_f32_16x16x32_bf16 v[46:49], v[158:161], v[166:169], v[46:49]
	v_mfma_f32_16x16x32_bf16 v[38:41], v[150:153], v[220:223], v[38:41]
	v_mfma_f32_16x16x32_bf16 v[30:33], v[158:161], v[220:223], v[30:33]
	v_mfma_f32_16x16x32_bf16 v[22:25], v[150:153], v[228:231], v[22:25]
	v_mfma_f32_16x16x32_bf16 v[14:17], v[158:161], v[228:231], v[14:17]
	v_mfma_f32_16x16x32_bf16 v[6:9], v[150:153], v[236:239], v[6:9]
	v_mfma_f32_16x16x32_bf16 v[2:5], v[158:161], v[236:239], v[2:5]
	s_setprio 0
	s_barrier
	s_add_i32 s62, 0, 0x18000
	s_add_i32 s63, 0, 0x1c000
	v_add_u32_e32 v126, s62, v199
	v_add_u32_e32 v158, s63, v199
	ds_read_b128 v[114:117], v126
	ds_read_b128 v[118:121], v126 offset:1024
	ds_read_b128 v[122:125], v126 offset:2048
	ds_read_b128 v[126:129], v126 offset:3072
	ds_read_b128 v[146:149], v158
	ds_read_b128 v[150:153], v158 offset:1024
	ds_read_b128 v[154:157], v158 offset:2048
	ds_read_b128 v[158:161], v158 offset:3072
	s_add_u32 s72, s96, 0x40000
	s_addc_u32 s73, s97, 0
	s_mov_b32 m0, s30
	v_lshl_add_u64 v[246:247], s[72:73], 0, v[172:173]
	ds_read_b128 v[162:165], v214 offset:32768
	ds_read_b128 v[166:169], v214 offset:33792
	ds_read_b128 v[216:219], v214 offset:34816
	ds_read_b128 v[220:223], v214 offset:35840
	ds_read_b128 v[224:227], v214 offset:36864
	ds_read_b128 v[228:231], v214 offset:37888
	ds_read_b128 v[232:235], v214 offset:38912
	ds_read_b128 v[236:239], v214 offset:39936
	global_load_lds_dwordx4 v[246:247], off
	s_mov_b32 m0, s31
	v_lshl_add_u64 v[246:247], s[72:73], 0, v[176:177]
	global_load_lds_dwordx4 v[246:247], off
	s_waitcnt vmcnt(8) lgkmcnt(0)
	s_setprio 1
	s_barrier
	v_mfma_f32_16x16x32_bf16 v[142:145], v[114:117], v[162:165], v[142:145]
	v_mfma_f32_16x16x32_bf16 v[138:141], v[122:125], v[162:165], v[138:141]
	v_mfma_f32_16x16x32_bf16 v[110:113], v[114:117], v[216:219], v[110:113]
	v_mfma_f32_16x16x32_bf16 v[106:109], v[122:125], v[216:219], v[106:109]
	v_mfma_f32_16x16x32_bf16 v[98:101], v[114:117], v[224:227], v[98:101]
	v_mfma_f32_16x16x32_bf16 v[90:93], v[122:125], v[224:227], v[90:93]
	v_mfma_f32_16x16x32_bf16 v[82:85], v[114:117], v[232:235], v[82:85]
	v_mfma_f32_16x16x32_bf16 v[74:77], v[122:125], v[232:235], v[74:77]
	v_mfma_f32_16x16x32_bf16 v[142:145], v[118:121], v[166:169], v[142:145]
	v_mfma_f32_16x16x32_bf16 v[138:141], v[126:129], v[166:169], v[138:141]
	v_mfma_f32_16x16x32_bf16 v[110:113], v[118:121], v[220:223], v[110:113]
	v_mfma_f32_16x16x32_bf16 v[106:109], v[126:129], v[220:223], v[106:109]
	v_mfma_f32_16x16x32_bf16 v[98:101], v[118:121], v[228:231], v[98:101]
	v_mfma_f32_16x16x32_bf16 v[90:93], v[126:129], v[228:231], v[90:93]
	v_mfma_f32_16x16x32_bf16 v[82:85], v[118:121], v[236:239], v[82:85]
	v_mfma_f32_16x16x32_bf16 v[74:77], v[126:129], v[236:239], v[74:77]
	v_mfma_f32_16x16x32_bf16 v[134:137], v[146:149], v[162:165], v[134:137]
	v_mfma_f32_16x16x32_bf16 v[130:133], v[154:157], v[162:165], v[130:133]
	v_mfma_f32_16x16x32_bf16 v[102:105], v[146:149], v[216:219], v[102:105]
	v_mfma_f32_16x16x32_bf16 v[94:97], v[154:157], v[216:219], v[94:97]
	v_mfma_f32_16x16x32_bf16 v[86:89], v[146:149], v[224:227], v[86:89]
	v_mfma_f32_16x16x32_bf16 v[78:81], v[154:157], v[224:227], v[78:81]
	v_mfma_f32_16x16x32_bf16 v[70:73], v[146:149], v[232:235], v[70:73]
	v_mfma_f32_16x16x32_bf16 v[66:69], v[154:157], v[232:235], v[66:69]
	v_mfma_f32_16x16x32_bf16 v[134:137], v[150:153], v[166:169], v[134:137]
	v_mfma_f32_16x16x32_bf16 v[130:133], v[158:161], v[166:169], v[130:133]
	v_mfma_f32_16x16x32_bf16 v[102:105], v[150:153], v[220:223], v[102:105]
	v_mfma_f32_16x16x32_bf16 v[94:97], v[158:161], v[220:223], v[94:97]
	v_mfma_f32_16x16x32_bf16 v[86:89], v[150:153], v[228:231], v[86:89]
	v_mfma_f32_16x16x32_bf16 v[78:81], v[158:161], v[228:231], v[78:81]
	v_mfma_f32_16x16x32_bf16 v[70:73], v[150:153], v[236:239], v[70:73]
	v_mfma_f32_16x16x32_bf16 v[66:69], v[158:161], v[236:239], v[66:69]
	s_setprio 0
	s_barrier
	s_add_i32 s62, s62, s17
	v_lshl_add_u64 v[202:203], v[202:203], 0, s[76:77]
	s_mov_b32 m0, s62
	ds_read_b128 v[162:165], v214 offset:49152
	ds_read_b128 v[166:169], v214 offset:50176
	ds_read_b128 v[216:219], v214 offset:51200
	ds_read_b128 v[220:223], v214 offset:52224
	ds_read_b128 v[224:227], v214 offset:53248
	ds_read_b128 v[228:231], v214 offset:54272
	ds_read_b128 v[232:235], v214 offset:55296
	ds_read_b128 v[236:239], v214 offset:56320
	global_load_lds_dwordx4 v[202:203], off
	s_add_i32 m0, s62, 0x2000
	s_add_u32 s72, s94, 0x40080
	v_lshl_add_u64 v[202:203], v[240:241], 0, s[76:77]
	s_addc_u32 s73, s95, 0
	s_add_i32 s62, s63, s17
	global_load_lds_dwordx4 v[202:203], off
	s_mov_b32 m0, s62
	v_lshl_add_u64 v[202:203], s[72:73], 0, v[174:175]
	global_load_lds_dwordx4 v[202:203], off
	s_add_i32 m0, s62, 0x2000
	v_lshl_add_u64 v[202:203], s[72:73], 0, v[178:179]
	global_load_lds_dwordx4 v[202:203], off
	s_mov_b32 m0, s44
	v_lshl_add_u64 v[202:203], v[242:243], 0, s[76:77]
	global_load_lds_dwordx4 v[202:203], off
	s_mov_b32 m0, s36
	v_lshl_add_u64 v[202:203], v[244:245], 0, s[76:77]
	global_load_lds_dwordx4 v[202:203], off
	s_waitcnt vmcnt(8) lgkmcnt(0)
	s_setprio 1
	s_barrier
	v_mfma_f32_16x16x32_bf16 v[62:65], v[114:117], v[162:165], v[62:65]
	v_mfma_f32_16x16x32_bf16 v[58:61], v[122:125], v[162:165], v[58:61]
	v_mfma_f32_16x16x32_bf16 v[50:53], v[114:117], v[216:219], v[50:53]
	v_mfma_f32_16x16x32_bf16 v[42:45], v[122:125], v[216:219], v[42:45]
	v_mfma_f32_16x16x32_bf16 v[34:37], v[114:117], v[224:227], v[34:37]
	v_mfma_f32_16x16x32_bf16 v[26:29], v[122:125], v[224:227], v[26:29]
	v_mfma_f32_16x16x32_bf16 v[18:21], v[114:117], v[232:235], v[18:21]
	v_mfma_f32_16x16x32_bf16 v[10:13], v[122:125], v[232:235], v[10:13]
	v_mfma_f32_16x16x32_bf16 v[62:65], v[118:121], v[166:169], v[62:65]
	v_mfma_f32_16x16x32_bf16 v[58:61], v[126:129], v[166:169], v[58:61]
	v_mfma_f32_16x16x32_bf16 v[50:53], v[118:121], v[220:223], v[50:53]
	v_mfma_f32_16x16x32_bf16 v[42:45], v[126:129], v[220:223], v[42:45]
	v_mfma_f32_16x16x32_bf16 v[34:37], v[118:121], v[228:231], v[34:37]
	v_mfma_f32_16x16x32_bf16 v[26:29], v[126:129], v[228:231], v[26:29]
	v_mfma_f32_16x16x32_bf16 v[18:21], v[118:121], v[236:239], v[18:21]
	v_mfma_f32_16x16x32_bf16 v[10:13], v[126:129], v[236:239], v[10:13]
	v_mfma_f32_16x16x32_bf16 v[54:57], v[146:149], v[162:165], v[54:57]
	v_mfma_f32_16x16x32_bf16 v[46:49], v[154:157], v[162:165], v[46:49]
	v_mfma_f32_16x16x32_bf16 v[38:41], v[146:149], v[216:219], v[38:41]
	v_mfma_f32_16x16x32_bf16 v[30:33], v[154:157], v[216:219], v[30:33]
	v_mfma_f32_16x16x32_bf16 v[22:25], v[146:149], v[224:227], v[22:25]
	v_mfma_f32_16x16x32_bf16 v[14:17], v[154:157], v[224:227], v[14:17]
	v_mfma_f32_16x16x32_bf16 v[6:9], v[146:149], v[232:235], v[6:9]
	v_mfma_f32_16x16x32_bf16 v[2:5], v[154:157], v[232:235], v[2:5]
	v_mfma_f32_16x16x32_bf16 v[54:57], v[150:153], v[166:169], v[54:57]
	v_mfma_f32_16x16x32_bf16 v[46:49], v[158:161], v[166:169], v[46:49]
	v_mfma_f32_16x16x32_bf16 v[38:41], v[150:153], v[220:223], v[38:41]
	v_mfma_f32_16x16x32_bf16 v[30:33], v[158:161], v[220:223], v[30:33]
	v_mfma_f32_16x16x32_bf16 v[22:25], v[150:153], v[228:231], v[22:25]
	v_mfma_f32_16x16x32_bf16 v[14:17], v[158:161], v[228:231], v[14:17]
	v_mfma_f32_16x16x32_bf16 v[6:9], v[150:153], v[236:239], v[6:9]
	v_mfma_f32_16x16x32_bf16 v[2:5], v[158:161], v[236:239], v[2:5]
	s_setprio 0
	s_barrier
	s_add_u32 s10, s10, 0x100
	s_addc_u32 s11, s11, 0
	s_add_u32 vcc_lo, vcc_lo, 0x100
	s_addc_u32 vcc_hi, vcc_hi, 0
	s_cmp_ge_i32 s66, s18
	s_mov_b32 s94, s66
.LBB0_1428:
	s_add_i32 s66, s94, 2
	s_add_u32 s67, s10, 0xfffc0080
	s_addc_u32 s72, s11, -1
	s_cmp_eq_u32 s85, s94
	s_cselect_b32 s97, s14, s72
	s_cselect_b32 s96, s15, s67
	s_cselect_b32 s95, s51, vcc_hi
	s_cselect_b32 s94, s84, vcc_lo
	s_add_i32 s67, 0, 0x10000
	s_add_i32 s62, 0, 0x14000
	v_add_u32_e32 v126, s67, v199
	v_add_u32_e32 v158, s62, v199
	ds_read_b128 v[114:117], v126
	ds_read_b128 v[118:121], v126 offset:1024
	ds_read_b128 v[122:125], v126 offset:2048
	ds_read_b128 v[126:129], v126 offset:3072
	ds_read_b128 v[146:149], v158
	ds_read_b128 v[150:153], v158 offset:1024
	ds_read_b128 v[154:157], v158 offset:2048
	ds_read_b128 v[158:161], v158 offset:3072
	v_lshl_add_u64 v[202:203], s[10:11], 0, v[196:197]
	s_add_i32 m0, s28, 0xc000
	ds_read_b128 v[162:165], v214
	ds_read_b128 v[166:169], v214 offset:1024
	ds_read_b128 v[216:219], v214 offset:2048
	ds_read_b128 v[220:223], v214 offset:3072
	ds_read_b128 v[224:227], v214 offset:4096
	ds_read_b128 v[228:231], v214 offset:5120
	ds_read_b128 v[232:235], v214 offset:6144
	ds_read_b128 v[236:239], v214 offset:7168
	global_load_lds_dwordx4 v[202:203], off
	s_add_i32 m0, s28, 0xe000
	v_lshl_add_u64 v[202:203], s[10:11], 0, v[176:177]
	global_load_lds_dwordx4 v[202:203], off
	s_waitcnt vmcnt(8) lgkmcnt(0)
	s_setprio 1
	s_barrier
	v_mfma_f32_16x16x32_bf16 v[142:145], v[114:117], v[162:165], v[142:145]
	v_mfma_f32_16x16x32_bf16 v[138:141], v[122:125], v[162:165], v[138:141]
	v_mfma_f32_16x16x32_bf16 v[110:113], v[114:117], v[216:219], v[110:113]
	v_mfma_f32_16x16x32_bf16 v[106:109], v[122:125], v[216:219], v[106:109]
	v_mfma_f32_16x16x32_bf16 v[98:101], v[114:117], v[224:227], v[98:101]
	v_mfma_f32_16x16x32_bf16 v[90:93], v[122:125], v[224:227], v[90:93]
	v_mfma_f32_16x16x32_bf16 v[82:85], v[114:117], v[232:235], v[82:85]
	v_mfma_f32_16x16x32_bf16 v[74:77], v[122:125], v[232:235], v[74:77]
	v_mfma_f32_16x16x32_bf16 v[142:145], v[118:121], v[166:169], v[142:145]
	v_mfma_f32_16x16x32_bf16 v[138:141], v[126:129], v[166:169], v[138:141]
	v_mfma_f32_16x16x32_bf16 v[110:113], v[118:121], v[220:223], v[110:113]
	v_mfma_f32_16x16x32_bf16 v[106:109], v[126:129], v[220:223], v[106:109]
	v_mfma_f32_16x16x32_bf16 v[98:101], v[118:121], v[228:231], v[98:101]
	v_mfma_f32_16x16x32_bf16 v[90:93], v[126:129], v[228:231], v[90:93]
	v_mfma_f32_16x16x32_bf16 v[82:85], v[118:121], v[236:239], v[82:85]
	v_mfma_f32_16x16x32_bf16 v[74:77], v[126:129], v[236:239], v[74:77]
	v_mfma_f32_16x16x32_bf16 v[134:137], v[146:149], v[162:165], v[134:137]
	v_mfma_f32_16x16x32_bf16 v[130:133], v[154:157], v[162:165], v[130:133]
	v_mfma_f32_16x16x32_bf16 v[102:105], v[146:149], v[216:219], v[102:105]
	v_mfma_f32_16x16x32_bf16 v[94:97], v[154:157], v[216:219], v[94:97]
	v_mfma_f32_16x16x32_bf16 v[86:89], v[146:149], v[224:227], v[86:89]
	v_mfma_f32_16x16x32_bf16 v[78:81], v[154:157], v[224:227], v[78:81]
	v_mfma_f32_16x16x32_bf16 v[70:73], v[146:149], v[232:235], v[70:73]
	v_mfma_f32_16x16x32_bf16 v[66:69], v[154:157], v[232:235], v[66:69]
	v_mfma_f32_16x16x32_bf16 v[134:137], v[150:153], v[166:169], v[134:137]
	v_mfma_f32_16x16x32_bf16 v[130:133], v[158:161], v[166:169], v[130:133]
	v_mfma_f32_16x16x32_bf16 v[102:105], v[150:153], v[220:223], v[102:105]
	v_mfma_f32_16x16x32_bf16 v[94:97], v[158:161], v[220:223], v[94:97]
	v_mfma_f32_16x16x32_bf16 v[86:89], v[150:153], v[228:231], v[86:89]
	v_mfma_f32_16x16x32_bf16 v[78:81], v[158:161], v[228:231], v[78:81]
	v_mfma_f32_16x16x32_bf16 v[70:73], v[150:153], v[236:239], v[70:73]
	v_mfma_f32_16x16x32_bf16 v[66:69], v[158:161], v[236:239], v[66:69]
	s_setprio 0
	s_barrier
	s_add_i32 s63, s67, s17
	v_lshl_add_u64 v[202:203], s[94:95], 0, v[174:175]
	s_mov_b32 m0, s63
	ds_read_b128 v[162:165], v214 offset:16384
	ds_read_b128 v[166:169], v214 offset:17408
	ds_read_b128 v[216:219], v214 offset:18432
	ds_read_b128 v[220:223], v214 offset:19456
	ds_read_b128 v[224:227], v214 offset:20480
	ds_read_b128 v[228:231], v214 offset:21504
	ds_read_b128 v[232:235], v214 offset:22528
	ds_read_b128 v[236:239], v214 offset:23552
	global_load_lds_dwordx4 v[202:203], off
	s_add_i32 m0, s63, 0x2000
	s_add_u32 s72, s94, 0x40000
	v_lshl_add_u64 v[240:241], s[94:95], 0, v[178:179]
	s_addc_u32 s73, s95, 0
	s_add_i32 s62, s62, s17
	global_load_lds_dwordx4 v[240:241], off
	v_lshl_add_u64 v[242:243], s[72:73], 0, v[174:175]
	s_mov_b32 m0, s62
	v_lshl_add_u64 v[244:245], s[96:97], 0, v[176:177]
	global_load_lds_dwordx4 v[242:243], off
	s_add_i32 m0, s62, 0x2000
	v_lshl_add_u64 v[242:243], s[72:73], 0, v[178:179]
	global_load_lds_dwordx4 v[242:243], off
	s_mov_b32 m0, s28
	v_lshl_add_u64 v[242:243], s[96:97], 0, v[172:173]
	global_load_lds_dwordx4 v[242:243], off
	s_mov_b32 m0, s29
	s_nop 0
	global_load_lds_dwordx4 v[244:245], off
	s_waitcnt vmcnt(8) lgkmcnt(0)
	s_setprio 1
	s_barrier
	v_mfma_f32_16x16x32_bf16 v[62:65], v[114:117], v[162:165], v[62:65]
	v_mfma_f32_16x16x32_bf16 v[58:61], v[122:125], v[162:165], v[58:61]
	v_mfma_f32_16x16x32_bf16 v[50:53], v[114:117], v[216:219], v[50:53]
	v_mfma_f32_16x16x32_bf16 v[42:45], v[122:125], v[216:219], v[42:45]
	v_mfma_f32_16x16x32_bf16 v[34:37], v[114:117], v[224:227], v[34:37]
	v_mfma_f32_16x16x32_bf16 v[26:29], v[122:125], v[224:227], v[26:29]
	v_mfma_f32_16x16x32_bf16 v[18:21], v[114:117], v[232:235], v[18:21]
	v_mfma_f32_16x16x32_bf16 v[10:13], v[122:125], v[232:235], v[10:13]
	v_mfma_f32_16x16x32_bf16 v[62:65], v[118:121], v[166:169], v[62:65]
	v_mfma_f32_16x16x32_bf16 v[58:61], v[126:129], v[166:169], v[58:61]
	v_mfma_f32_16x16x32_bf16 v[50:53], v[118:121], v[220:223], v[50:53]
	v_mfma_f32_16x16x32_bf16 v[42:45], v[126:129], v[220:223], v[42:45]
	v_mfma_f32_16x16x32_bf16 v[34:37], v[118:121], v[228:231], v[34:37]
	v_mfma_f32_16x16x32_bf16 v[26:29], v[126:129], v[228:231], v[26:29]
	v_mfma_f32_16x16x32_bf16 v[18:21], v[118:121], v[236:239], v[18:21]
	v_mfma_f32_16x16x32_bf16 v[10:13], v[126:129], v[236:239], v[10:13]
	v_mfma_f32_16x16x32_bf16 v[54:57], v[146:149], v[162:165], v[54:57]
	v_mfma_f32_16x16x32_bf16 v[46:49], v[154:157], v[162:165], v[46:49]
	v_mfma_f32_16x16x32_bf16 v[38:41], v[146:149], v[216:219], v[38:41]
	v_mfma_f32_16x16x32_bf16 v[30:33], v[154:157], v[216:219], v[30:33]
	v_mfma_f32_16x16x32_bf16 v[22:25], v[146:149], v[224:227], v[22:25]
	v_mfma_f32_16x16x32_bf16 v[14:17], v[154:157], v[224:227], v[14:17]
	v_mfma_f32_16x16x32_bf16 v[6:9], v[146:149], v[232:235], v[6:9]
	v_mfma_f32_16x16x32_bf16 v[2:5], v[154:157], v[232:235], v[2:5]
	v_mfma_f32_16x16x32_bf16 v[54:57], v[150:153], v[166:169], v[54:57]
	v_mfma_f32_16x16x32_bf16 v[46:49], v[158:161], v[166:169], v[46:49]
	v_mfma_f32_16x16x32_bf16 v[38:41], v[150:153], v[220:223], v[38:41]
	v_mfma_f32_16x16x32_bf16 v[30:33], v[158:161], v[220:223], v[30:33]
	v_mfma_f32_16x16x32_bf16 v[22:25], v[150:153], v[228:231], v[22:25]
	v_mfma_f32_16x16x32_bf16 v[14:17], v[158:161], v[228:231], v[14:17]
	v_mfma_f32_16x16x32_bf16 v[6:9], v[150:153], v[236:239], v[6:9]
	v_mfma_f32_16x16x32_bf16 v[2:5], v[158:161], v[236:239], v[2:5]
	s_setprio 0
	s_barrier
	s_add_i32 s62, 0, 0x18000
	s_add_i32 s63, 0, 0x1c000
	v_add_u32_e32 v126, s62, v199
	v_add_u32_e32 v158, s63, v199
	ds_read_b128 v[114:117], v126
	ds_read_b128 v[118:121], v126 offset:1024
	ds_read_b128 v[122:125], v126 offset:2048
	ds_read_b128 v[126:129], v126 offset:3072
	ds_read_b128 v[146:149], v158
	ds_read_b128 v[150:153], v158 offset:1024
	ds_read_b128 v[154:157], v158 offset:2048
	ds_read_b128 v[158:161], v158 offset:3072
	s_add_u32 s72, s96, 0x40000
	s_addc_u32 s73, s97, 0
	s_mov_b32 m0, s30
	v_lshl_add_u64 v[246:247], s[72:73], 0, v[172:173]
	ds_read_b128 v[162:165], v214 offset:32768
	ds_read_b128 v[166:169], v214 offset:33792
	ds_read_b128 v[216:219], v214 offset:34816
	ds_read_b128 v[220:223], v214 offset:35840
	ds_read_b128 v[224:227], v214 offset:36864
	ds_read_b128 v[228:231], v214 offset:37888
	ds_read_b128 v[232:235], v214 offset:38912
	ds_read_b128 v[236:239], v214 offset:39936
	global_load_lds_dwordx4 v[246:247], off
	s_mov_b32 m0, s31
	v_lshl_add_u64 v[246:247], s[72:73], 0, v[176:177]
	global_load_lds_dwordx4 v[246:247], off
	s_waitcnt vmcnt(8) lgkmcnt(0)
	s_setprio 1
	s_barrier
	v_mfma_f32_16x16x32_bf16 v[142:145], v[114:117], v[162:165], v[142:145]
	v_mfma_f32_16x16x32_bf16 v[138:141], v[122:125], v[162:165], v[138:141]
	v_mfma_f32_16x16x32_bf16 v[110:113], v[114:117], v[216:219], v[110:113]
	v_mfma_f32_16x16x32_bf16 v[106:109], v[122:125], v[216:219], v[106:109]
	v_mfma_f32_16x16x32_bf16 v[98:101], v[114:117], v[224:227], v[98:101]
	v_mfma_f32_16x16x32_bf16 v[90:93], v[122:125], v[224:227], v[90:93]
	v_mfma_f32_16x16x32_bf16 v[82:85], v[114:117], v[232:235], v[82:85]
	v_mfma_f32_16x16x32_bf16 v[74:77], v[122:125], v[232:235], v[74:77]
	v_mfma_f32_16x16x32_bf16 v[142:145], v[118:121], v[166:169], v[142:145]
	v_mfma_f32_16x16x32_bf16 v[138:141], v[126:129], v[166:169], v[138:141]
	v_mfma_f32_16x16x32_bf16 v[110:113], v[118:121], v[220:223], v[110:113]
	v_mfma_f32_16x16x32_bf16 v[106:109], v[126:129], v[220:223], v[106:109]
	v_mfma_f32_16x16x32_bf16 v[98:101], v[118:121], v[228:231], v[98:101]
	v_mfma_f32_16x16x32_bf16 v[90:93], v[126:129], v[228:231], v[90:93]
	v_mfma_f32_16x16x32_bf16 v[82:85], v[118:121], v[236:239], v[82:85]
	v_mfma_f32_16x16x32_bf16 v[74:77], v[126:129], v[236:239], v[74:77]
	v_mfma_f32_16x16x32_bf16 v[134:137], v[146:149], v[162:165], v[134:137]
	v_mfma_f32_16x16x32_bf16 v[130:133], v[154:157], v[162:165], v[130:133]
	v_mfma_f32_16x16x32_bf16 v[102:105], v[146:149], v[216:219], v[102:105]
	v_mfma_f32_16x16x32_bf16 v[94:97], v[154:157], v[216:219], v[94:97]
	v_mfma_f32_16x16x32_bf16 v[86:89], v[146:149], v[224:227], v[86:89]
	v_mfma_f32_16x16x32_bf16 v[78:81], v[154:157], v[224:227], v[78:81]
	v_mfma_f32_16x16x32_bf16 v[70:73], v[146:149], v[232:235], v[70:73]
	v_mfma_f32_16x16x32_bf16 v[66:69], v[154:157], v[232:235], v[66:69]
	v_mfma_f32_16x16x32_bf16 v[134:137], v[150:153], v[166:169], v[134:137]
	v_mfma_f32_16x16x32_bf16 v[130:133], v[158:161], v[166:169], v[130:133]
	v_mfma_f32_16x16x32_bf16 v[102:105], v[150:153], v[220:223], v[102:105]
	v_mfma_f32_16x16x32_bf16 v[94:97], v[158:161], v[220:223], v[94:97]
	v_mfma_f32_16x16x32_bf16 v[86:89], v[150:153], v[228:231], v[86:89]
	v_mfma_f32_16x16x32_bf16 v[78:81], v[158:161], v[228:231], v[78:81]
	v_mfma_f32_16x16x32_bf16 v[70:73], v[150:153], v[236:239], v[70:73]
	v_mfma_f32_16x16x32_bf16 v[66:69], v[158:161], v[236:239], v[66:69]
	s_setprio 0
	s_barrier
	s_add_i32 s62, s62, s17
	v_lshl_add_u64 v[202:203], v[202:203], 0, s[76:77]
	s_mov_b32 m0, s62
	ds_read_b128 v[162:165], v214 offset:49152
	ds_read_b128 v[166:169], v214 offset:50176
	ds_read_b128 v[216:219], v214 offset:51200
	ds_read_b128 v[220:223], v214 offset:52224
	ds_read_b128 v[224:227], v214 offset:53248
	ds_read_b128 v[228:231], v214 offset:54272
	ds_read_b128 v[232:235], v214 offset:55296
	ds_read_b128 v[236:239], v214 offset:56320
	global_load_lds_dwordx4 v[202:203], off
	s_add_i32 m0, s62, 0x2000
	s_add_u32 s72, s94, 0x40080
	v_lshl_add_u64 v[202:203], v[240:241], 0, s[76:77]
	s_addc_u32 s73, s95, 0
	s_add_i32 s62, s63, s17
	global_load_lds_dwordx4 v[202:203], off
	s_mov_b32 m0, s62
	v_lshl_add_u64 v[202:203], s[72:73], 0, v[174:175]
	global_load_lds_dwordx4 v[202:203], off
	s_add_i32 m0, s62, 0x2000
	v_lshl_add_u64 v[202:203], s[72:73], 0, v[178:179]
	global_load_lds_dwordx4 v[202:203], off
	s_mov_b32 m0, s44
	v_lshl_add_u64 v[202:203], v[242:243], 0, s[76:77]
	global_load_lds_dwordx4 v[202:203], off
	s_mov_b32 m0, s36
	v_lshl_add_u64 v[202:203], v[244:245], 0, s[76:77]
	global_load_lds_dwordx4 v[202:203], off
	s_waitcnt vmcnt(8) lgkmcnt(0)
	s_setprio 1
	s_barrier
	v_mfma_f32_16x16x32_bf16 v[62:65], v[114:117], v[162:165], v[62:65]
	v_mfma_f32_16x16x32_bf16 v[58:61], v[122:125], v[162:165], v[58:61]
	v_mfma_f32_16x16x32_bf16 v[50:53], v[114:117], v[216:219], v[50:53]
	v_mfma_f32_16x16x32_bf16 v[42:45], v[122:125], v[216:219], v[42:45]
	v_mfma_f32_16x16x32_bf16 v[34:37], v[114:117], v[224:227], v[34:37]
	v_mfma_f32_16x16x32_bf16 v[26:29], v[122:125], v[224:227], v[26:29]
	v_mfma_f32_16x16x32_bf16 v[18:21], v[114:117], v[232:235], v[18:21]
	v_mfma_f32_16x16x32_bf16 v[10:13], v[122:125], v[232:235], v[10:13]
	v_mfma_f32_16x16x32_bf16 v[62:65], v[118:121], v[166:169], v[62:65]
	v_mfma_f32_16x16x32_bf16 v[58:61], v[126:129], v[166:169], v[58:61]
	v_mfma_f32_16x16x32_bf16 v[50:53], v[118:121], v[220:223], v[50:53]
	v_mfma_f32_16x16x32_bf16 v[42:45], v[126:129], v[220:223], v[42:45]
	v_mfma_f32_16x16x32_bf16 v[34:37], v[118:121], v[228:231], v[34:37]
	v_mfma_f32_16x16x32_bf16 v[26:29], v[126:129], v[228:231], v[26:29]
	v_mfma_f32_16x16x32_bf16 v[18:21], v[118:121], v[236:239], v[18:21]
	v_mfma_f32_16x16x32_bf16 v[10:13], v[126:129], v[236:239], v[10:13]
	v_mfma_f32_16x16x32_bf16 v[54:57], v[146:149], v[162:165], v[54:57]
	v_mfma_f32_16x16x32_bf16 v[46:49], v[154:157], v[162:165], v[46:49]
	v_mfma_f32_16x16x32_bf16 v[38:41], v[146:149], v[216:219], v[38:41]
	v_mfma_f32_16x16x32_bf16 v[30:33], v[154:157], v[216:219], v[30:33]
	v_mfma_f32_16x16x32_bf16 v[22:25], v[146:149], v[224:227], v[22:25]
	v_mfma_f32_16x16x32_bf16 v[14:17], v[154:157], v[224:227], v[14:17]
	v_mfma_f32_16x16x32_bf16 v[6:9], v[146:149], v[232:235], v[6:9]
	v_mfma_f32_16x16x32_bf16 v[2:5], v[154:157], v[232:235], v[2:5]
	v_mfma_f32_16x16x32_bf16 v[54:57], v[150:153], v[166:169], v[54:57]
	v_mfma_f32_16x16x32_bf16 v[46:49], v[158:161], v[166:169], v[46:49]
	v_mfma_f32_16x16x32_bf16 v[38:41], v[150:153], v[220:223], v[38:41]
	v_mfma_f32_16x16x32_bf16 v[30:33], v[158:161], v[220:223], v[30:33]
	v_mfma_f32_16x16x32_bf16 v[22:25], v[150:153], v[228:231], v[22:25]
	v_mfma_f32_16x16x32_bf16 v[14:17], v[158:161], v[228:231], v[14:17]
	v_mfma_f32_16x16x32_bf16 v[6:9], v[150:153], v[236:239], v[6:9]
	v_mfma_f32_16x16x32_bf16 v[2:5], v[158:161], v[236:239], v[2:5]
	s_setprio 0
	s_barrier
	s_add_u32 s10, s10, 0x100
	s_addc_u32 s11, s11, 0
	s_add_u32 vcc_lo, vcc_lo, 0x100
	s_addc_u32 vcc_hi, vcc_hi, 0
	s_cmp_ge_i32 s66, s18
	s_mov_b32 s94, s66
	s_cbranch_scc0 .LBB0_1428
	s_and_b64 vcc, exec, s[82:83]
	s_cbranch_vccz .LBB0_1431
	s_barrier

.LBB0_1618:
	s_add_u32 s24, s96, s20
	s_addc_u32 s25, s97, s21
	s_and_b64 s[14:15], s[4:5], exec
	s_cselect_b32 s14, s25, s29
	s_cselect_b32 s15, s24, s28
	s_add_u32 s26, s2, s22
	s_addc_u32 s27, s3, s23
	s_and_b64 s[36:37], s[4:5], exec
	s_cselect_b32 s17, s27, s31
	s_cselect_b32 s49, s26, s30
	s_add_u32 s28, s28, 0x40080
	s_addc_u32 s29, s29, 0
	s_add_u32 s50, s30, 0x100
	s_addc_u32 s51, s31, 0
	s_mov_b32 s62, -2
	ds_read_b128 v[154:157], v150
	ds_read_b128 v[158:161], v150 offset:1024
	ds_read_b128 v[162:165], v150 offset:2048
	ds_read_b128 v[166:169], v150 offset:3072
	ds_read_b128 v[170:173], v151
	ds_read_b128 v[174:177], v151 offset:1024
	ds_read_b128 v[178:181], v151 offset:2048
	ds_read_b128 v[182:185], v151 offset:3072
	s_add_u32 s30, s28, 0xfffc0080
	s_addc_u32 s31, s29, -1
	s_cmp_eq_u32 s62, 12
	s_cselect_b32 s37, s14, s31
	s_cselect_b32 s36, s15, s30
	s_cselect_b32 s31, s17, s51
	s_cselect_b32 s30, s49, s50
	v_lshl_add_u64 v[146:147], s[28:29], 0, v[138:139]
	s_add_i32 m0, s19, 0xc000
	ds_read_b128 v[186:189], v152
	ds_read_b128 v[190:193], v152 offset:1024
	ds_read_b128 v[194:197], v152 offset:2048
	ds_read_b128 v[198:201], v152 offset:3072
	ds_read_b128 v[206:209], v152 offset:4096
	ds_read_b128 v[210:213], v152 offset:5120
	ds_read_b128 v[214:217], v152 offset:6144
	ds_read_b128 v[218:221], v152 offset:7168
	global_load_lds_dwordx4 v[146:147], off
	s_add_i32 m0, s19, 0xe000
	v_lshl_add_u64 v[146:147], s[28:29], 0, v[140:141]
	global_load_lds_dwordx4 v[146:147], off
	s_waitcnt vmcnt(8) lgkmcnt(0)
	s_setprio 1
	s_barrier
	v_mfma_f32_16x16x32_bf16 v[126:129], v[154:157], v[186:189], 0
	v_mfma_f32_16x16x32_bf16 v[122:125], v[162:165], v[186:189], 0
	v_mfma_f32_16x16x32_bf16 v[110:113], v[154:157], v[194:197], 0
	v_mfma_f32_16x16x32_bf16 v[106:109], v[162:165], v[194:197], 0
	v_mfma_f32_16x16x32_bf16 v[94:97], v[154:157], v[206:209], 0
	v_mfma_f32_16x16x32_bf16 v[90:93], v[162:165], v[206:209], 0
	v_mfma_f32_16x16x32_bf16 v[78:81], v[154:157], v[214:217], 0
	v_mfma_f32_16x16x32_bf16 v[74:77], v[162:165], v[214:217], 0
	v_mfma_f32_16x16x32_bf16 v[126:129], v[158:161], v[190:193], v[126:129]
	v_mfma_f32_16x16x32_bf16 v[122:125], v[166:169], v[190:193], v[122:125]
	v_mfma_f32_16x16x32_bf16 v[110:113], v[158:161], v[198:201], v[110:113]
	v_mfma_f32_16x16x32_bf16 v[106:109], v[166:169], v[198:201], v[106:109]
	v_mfma_f32_16x16x32_bf16 v[94:97], v[158:161], v[210:213], v[94:97]
	v_mfma_f32_16x16x32_bf16 v[90:93], v[166:169], v[210:213], v[90:93]
	v_mfma_f32_16x16x32_bf16 v[78:81], v[158:161], v[218:221], v[78:81]
	v_mfma_f32_16x16x32_bf16 v[74:77], v[166:169], v[218:221], v[74:77]
	v_mfma_f32_16x16x32_bf16 v[118:121], v[170:173], v[186:189], 0
	v_mfma_f32_16x16x32_bf16 v[114:117], v[178:181], v[186:189], 0
	v_mfma_f32_16x16x32_bf16 v[102:105], v[170:173], v[194:197], 0
	v_mfma_f32_16x16x32_bf16 v[98:101], v[178:181], v[194:197], 0
	v_mfma_f32_16x16x32_bf16 v[86:89], v[170:173], v[206:209], 0
	v_mfma_f32_16x16x32_bf16 v[82:85], v[178:181], v[206:209], 0
	v_mfma_f32_16x16x32_bf16 v[70:73], v[170:173], v[214:217], 0
	v_mfma_f32_16x16x32_bf16 v[66:69], v[178:181], v[214:217], 0
	v_mfma_f32_16x16x32_bf16 v[118:121], v[174:177], v[190:193], v[118:121]
	v_mfma_f32_16x16x32_bf16 v[114:117], v[182:185], v[190:193], v[114:117]
	v_mfma_f32_16x16x32_bf16 v[102:105], v[174:177], v[198:201], v[102:105]
	v_mfma_f32_16x16x32_bf16 v[98:101], v[182:185], v[198:201], v[98:101]
	v_mfma_f32_16x16x32_bf16 v[86:89], v[174:177], v[210:213], v[86:89]
	v_mfma_f32_16x16x32_bf16 v[82:85], v[182:185], v[210:213], v[82:85]
	v_mfma_f32_16x16x32_bf16 v[70:73], v[174:177], v[218:221], v[70:73]
	v_mfma_f32_16x16x32_bf16 v[66:69], v[182:185], v[218:221], v[66:69]
	s_setprio 0
	s_barrier
	s_add_i32 s63, s45, s12
	v_lshl_add_u64 v[146:147], s[30:31], 0, v[134:135]
	s_mov_b32 m0, s63
	ds_read_b128 v[186:189], v152 offset:16384
	ds_read_b128 v[190:193], v152 offset:17408
	ds_read_b128 v[194:197], v152 offset:18432
	ds_read_b128 v[198:201], v152 offset:19456
	ds_read_b128 v[206:209], v152 offset:20480
	ds_read_b128 v[210:213], v152 offset:21504
	ds_read_b128 v[214:217], v152 offset:22528
	ds_read_b128 v[218:221], v152 offset:23552
	global_load_lds_dwordx4 v[146:147], off
	s_add_i32 m0, s63, 0x2000
	s_add_u32 s64, s30, 0x40000
	v_lshl_add_u64 v[202:203], s[30:31], 0, v[130:131]
	s_addc_u32 s65, s31, 0
	s_add_i32 s63, s46, s12
	global_load_lds_dwordx4 v[202:203], off
	v_lshl_add_u64 v[222:223], s[64:65], 0, v[134:135]
	s_mov_b32 m0, s63
	v_lshl_add_u64 v[224:225], s[36:37], 0, v[132:133]
	global_load_lds_dwordx4 v[222:223], off
	s_add_i32 m0, s63, 0x2000
	v_lshl_add_u64 v[222:223], s[64:65], 0, v[130:131]
	global_load_lds_dwordx4 v[222:223], off
	s_mov_b32 m0, s19
	v_lshl_add_u64 v[222:223], s[36:37], 0, v[136:137]
	global_load_lds_dwordx4 v[222:223], off
	s_mov_b32 m0, s33
	s_nop 0
	global_load_lds_dwordx4 v[224:225], off
	s_waitcnt vmcnt(8) lgkmcnt(0)
	s_setprio 1
	s_barrier
	v_mfma_f32_16x16x32_bf16 v[62:65], v[154:157], v[186:189], 0
	v_mfma_f32_16x16x32_bf16 v[58:61], v[162:165], v[186:189], 0
	v_mfma_f32_16x16x32_bf16 v[46:49], v[154:157], v[194:197], 0
	v_mfma_f32_16x16x32_bf16 v[42:45], v[162:165], v[194:197], 0
	v_mfma_f32_16x16x32_bf16 v[30:33], v[154:157], v[206:209], 0
	v_mfma_f32_16x16x32_bf16 v[26:29], v[162:165], v[206:209], 0
	v_mfma_f32_16x16x32_bf16 v[14:17], v[154:157], v[214:217], 0
	v_mfma_f32_16x16x32_bf16 v[10:13], v[162:165], v[214:217], 0
	v_mfma_f32_16x16x32_bf16 v[62:65], v[158:161], v[190:193], v[62:65]
	v_mfma_f32_16x16x32_bf16 v[58:61], v[166:169], v[190:193], v[58:61]
	v_mfma_f32_16x16x32_bf16 v[46:49], v[158:161], v[198:201], v[46:49]
	v_mfma_f32_16x16x32_bf16 v[42:45], v[166:169], v[198:201], v[42:45]
	v_mfma_f32_16x16x32_bf16 v[30:33], v[158:161], v[210:213], v[30:33]
	v_mfma_f32_16x16x32_bf16 v[26:29], v[166:169], v[210:213], v[26:29]
	v_mfma_f32_16x16x32_bf16 v[14:17], v[158:161], v[218:221], v[14:17]
	v_mfma_f32_16x16x32_bf16 v[10:13], v[166:169], v[218:221], v[10:13]
	v_mfma_f32_16x16x32_bf16 v[54:57], v[170:173], v[186:189], 0
	v_mfma_f32_16x16x32_bf16 v[50:53], v[178:181], v[186:189], 0
	v_mfma_f32_16x16x32_bf16 v[38:41], v[170:173], v[194:197], 0
	v_mfma_f32_16x16x32_bf16 v[34:37], v[178:181], v[194:197], 0
	v_mfma_f32_16x16x32_bf16 v[22:25], v[170:173], v[206:209], 0
	v_mfma_f32_16x16x32_bf16 v[18:21], v[178:181], v[206:209], 0
	v_mfma_f32_16x16x32_bf16 v[6:9], v[170:173], v[214:217], 0
	v_mfma_f32_16x16x32_bf16 v[2:5], v[178:181], v[214:217], 0
	v_mfma_f32_16x16x32_bf16 v[54:57], v[174:177], v[190:193], v[54:57]
	v_mfma_f32_16x16x32_bf16 v[50:53], v[182:185], v[190:193], v[50:53]
	v_mfma_f32_16x16x32_bf16 v[38:41], v[174:177], v[198:201], v[38:41]
	v_mfma_f32_16x16x32_bf16 v[34:37], v[182:185], v[198:201], v[34:37]
	v_mfma_f32_16x16x32_bf16 v[22:25], v[174:177], v[210:213], v[22:25]
	v_mfma_f32_16x16x32_bf16 v[18:21], v[182:185], v[210:213], v[18:21]
	v_mfma_f32_16x16x32_bf16 v[6:9], v[174:177], v[218:221], v[6:9]
	v_mfma_f32_16x16x32_bf16 v[2:5], v[182:185], v[218:221], v[2:5]
	s_setprio 0
	s_barrier
	s_add_i32 s63, 0, 0x18000
	v_add_u32_e32 v153, s63, v149
	s_add_i32 s64, 0, 0x1c000
	ds_read_b128 v[154:157], v153
	ds_read_b128 v[158:161], v153 offset:1024
	ds_read_b128 v[162:165], v153 offset:2048
	ds_read_b128 v[166:169], v153 offset:3072
	v_add_u32_e32 v153, s64, v149
	ds_read_b128 v[170:173], v153
	ds_read_b128 v[174:177], v153 offset:1024
	ds_read_b128 v[178:181], v153 offset:2048
	ds_read_b128 v[182:185], v153 offset:3072
	s_add_u32 s36, s36, 0x40000
	s_addc_u32 s37, s37, 0
	s_mov_b32 m0, s35
	v_lshl_add_u64 v[226:227], s[36:37], 0, v[136:137]
	ds_read_b128 v[186:189], v152 offset:32768
	ds_read_b128 v[190:193], v152 offset:33792
	ds_read_b128 v[194:197], v152 offset:34816
	ds_read_b128 v[198:201], v152 offset:35840
	ds_read_b128 v[206:209], v152 offset:36864
	ds_read_b128 v[210:213], v152 offset:37888
	ds_read_b128 v[214:217], v152 offset:38912
	ds_read_b128 v[218:221], v152 offset:39936
	global_load_lds_dwordx4 v[226:227], off
	s_mov_b32 m0, s38
	v_lshl_add_u64 v[226:227], s[36:37], 0, v[132:133]
	global_load_lds_dwordx4 v[226:227], off
	s_waitcnt vmcnt(8) lgkmcnt(0)
	s_setprio 1
	s_barrier
	v_mfma_f32_16x16x32_bf16 v[126:129], v[154:157], v[186:189], v[126:129]
	v_mfma_f32_16x16x32_bf16 v[122:125], v[162:165], v[186:189], v[122:125]
	v_mfma_f32_16x16x32_bf16 v[110:113], v[154:157], v[194:197], v[110:113]
	v_mfma_f32_16x16x32_bf16 v[106:109], v[162:165], v[194:197], v[106:109]
	v_mfma_f32_16x16x32_bf16 v[94:97], v[154:157], v[206:209], v[94:97]
	v_mfma_f32_16x16x32_bf16 v[90:93], v[162:165], v[206:209], v[90:93]
	v_mfma_f32_16x16x32_bf16 v[78:81], v[154:157], v[214:217], v[78:81]
	v_mfma_f32_16x16x32_bf16 v[74:77], v[162:165], v[214:217], v[74:77]
	v_mfma_f32_16x16x32_bf16 v[126:129], v[158:161], v[190:193], v[126:129]
	v_mfma_f32_16x16x32_bf16 v[122:125], v[166:169], v[190:193], v[122:125]
	v_mfma_f32_16x16x32_bf16 v[110:113], v[158:161], v[198:201], v[110:113]
	v_mfma_f32_16x16x32_bf16 v[106:109], v[166:169], v[198:201], v[106:109]
	v_mfma_f32_16x16x32_bf16 v[94:97], v[158:161], v[210:213], v[94:97]
	v_mfma_f32_16x16x32_bf16 v[90:93], v[166:169], v[210:213], v[90:93]
	v_mfma_f32_16x16x32_bf16 v[78:81], v[158:161], v[218:221], v[78:81]
	v_mfma_f32_16x16x32_bf16 v[74:77], v[166:169], v[218:221], v[74:77]
	v_mfma_f32_16x16x32_bf16 v[118:121], v[170:173], v[186:189], v[118:121]
	v_mfma_f32_16x16x32_bf16 v[114:117], v[178:181], v[186:189], v[114:117]
	v_mfma_f32_16x16x32_bf16 v[102:105], v[170:173], v[194:197], v[102:105]
	v_mfma_f32_16x16x32_bf16 v[98:101], v[178:181], v[194:197], v[98:101]
	v_mfma_f32_16x16x32_bf16 v[86:89], v[170:173], v[206:209], v[86:89]
	v_mfma_f32_16x16x32_bf16 v[82:85], v[178:181], v[206:209], v[82:85]
	v_mfma_f32_16x16x32_bf16 v[70:73], v[170:173], v[214:217], v[70:73]
	v_mfma_f32_16x16x32_bf16 v[66:69], v[178:181], v[214:217], v[66:69]
	v_mfma_f32_16x16x32_bf16 v[118:121], v[174:177], v[190:193], v[118:121]
	v_mfma_f32_16x16x32_bf16 v[114:117], v[182:185], v[190:193], v[114:117]
	v_mfma_f32_16x16x32_bf16 v[102:105], v[174:177], v[198:201], v[102:105]
	v_mfma_f32_16x16x32_bf16 v[98:101], v[182:185], v[198:201], v[98:101]
	v_mfma_f32_16x16x32_bf16 v[86:89], v[174:177], v[210:213], v[86:89]
	v_mfma_f32_16x16x32_bf16 v[82:85], v[182:185], v[210:213], v[82:85]
	v_mfma_f32_16x16x32_bf16 v[70:73], v[174:177], v[218:221], v[70:73]
	v_mfma_f32_16x16x32_bf16 v[66:69], v[182:185], v[218:221], v[66:69]
	s_setprio 0
	s_barrier
	s_add_i32 s36, s63, s12
	v_lshl_add_u64 v[146:147], v[146:147], 0, s[8:9]
	s_mov_b32 m0, s36
	ds_read_b128 v[186:189], v152 offset:49152
	ds_read_b128 v[190:193], v152 offset:50176
	ds_read_b128 v[194:197], v152 offset:51200
	ds_read_b128 v[198:201], v152 offset:52224
	ds_read_b128 v[206:209], v152 offset:53248
	ds_read_b128 v[210:213], v152 offset:54272
	ds_read_b128 v[214:217], v152 offset:55296
	ds_read_b128 v[218:221], v152 offset:56320
	global_load_lds_dwordx4 v[146:147], off
	s_add_i32 m0, s36, 0x2000
	s_add_u32 s30, s30, 0x40080
	v_lshl_add_u64 v[146:147], v[202:203], 0, s[8:9]
	s_addc_u32 s31, s31, 0
	s_add_i32 s36, s64, s12
	global_load_lds_dwordx4 v[146:147], off
	s_mov_b32 m0, s36
	v_lshl_add_u64 v[146:147], s[30:31], 0, v[134:135]
	global_load_lds_dwordx4 v[146:147], off
	s_add_i32 m0, s36, 0x2000
	v_lshl_add_u64 v[146:147], s[30:31], 0, v[130:131]
	global_load_lds_dwordx4 v[146:147], off
	s_mov_b32 m0, s42
	v_lshl_add_u64 v[146:147], v[222:223], 0, s[8:9]
	global_load_lds_dwordx4 v[146:147], off
	s_mov_b32 m0, s43
	v_lshl_add_u64 v[146:147], v[224:225], 0, s[8:9]
	global_load_lds_dwordx4 v[146:147], off
	s_waitcnt vmcnt(8) lgkmcnt(0)
	s_setprio 1
	s_barrier
	v_mfma_f32_16x16x32_bf16 v[62:65], v[154:157], v[186:189], v[62:65]
	v_mfma_f32_16x16x32_bf16 v[58:61], v[162:165], v[186:189], v[58:61]
	v_mfma_f32_16x16x32_bf16 v[46:49], v[154:157], v[194:197], v[46:49]
	v_mfma_f32_16x16x32_bf16 v[42:45], v[162:165], v[194:197], v[42:45]
	v_mfma_f32_16x16x32_bf16 v[30:33], v[154:157], v[206:209], v[30:33]
	v_mfma_f32_16x16x32_bf16 v[26:29], v[162:165], v[206:209], v[26:29]
	v_mfma_f32_16x16x32_bf16 v[14:17], v[154:157], v[214:217], v[14:17]
	v_mfma_f32_16x16x32_bf16 v[10:13], v[162:165], v[214:217], v[10:13]
	v_mfma_f32_16x16x32_bf16 v[62:65], v[158:161], v[190:193], v[62:65]
	v_mfma_f32_16x16x32_bf16 v[58:61], v[166:169], v[190:193], v[58:61]
	v_mfma_f32_16x16x32_bf16 v[46:49], v[158:161], v[198:201], v[46:49]
	v_mfma_f32_16x16x32_bf16 v[42:45], v[166:169], v[198:201], v[42:45]
	v_mfma_f32_16x16x32_bf16 v[30:33], v[158:161], v[210:213], v[30:33]
	v_mfma_f32_16x16x32_bf16 v[26:29], v[166:169], v[210:213], v[26:29]
	v_mfma_f32_16x16x32_bf16 v[14:17], v[158:161], v[218:221], v[14:17]
	v_mfma_f32_16x16x32_bf16 v[10:13], v[166:169], v[218:221], v[10:13]
	v_mfma_f32_16x16x32_bf16 v[54:57], v[170:173], v[186:189], v[54:57]
	v_mfma_f32_16x16x32_bf16 v[50:53], v[178:181], v[186:189], v[50:53]
	v_mfma_f32_16x16x32_bf16 v[38:41], v[170:173], v[194:197], v[38:41]
	v_mfma_f32_16x16x32_bf16 v[34:37], v[178:181], v[194:197], v[34:37]
	v_mfma_f32_16x16x32_bf16 v[22:25], v[170:173], v[206:209], v[22:25]
	v_mfma_f32_16x16x32_bf16 v[18:21], v[178:181], v[206:209], v[18:21]
	v_mfma_f32_16x16x32_bf16 v[6:9], v[170:173], v[214:217], v[6:9]
	v_mfma_f32_16x16x32_bf16 v[2:5], v[178:181], v[214:217], v[2:5]
	v_mfma_f32_16x16x32_bf16 v[54:57], v[174:177], v[190:193], v[54:57]
	v_mfma_f32_16x16x32_bf16 v[50:53], v[182:185], v[190:193], v[50:53]
	v_mfma_f32_16x16x32_bf16 v[38:41], v[174:177], v[198:201], v[38:41]
	v_mfma_f32_16x16x32_bf16 v[34:37], v[182:185], v[198:201], v[34:37]
	v_mfma_f32_16x16x32_bf16 v[22:25], v[174:177], v[210:213], v[22:25]
	v_mfma_f32_16x16x32_bf16 v[18:21], v[182:185], v[210:213], v[18:21]
	v_mfma_f32_16x16x32_bf16 v[6:9], v[174:177], v[218:221], v[6:9]
	v_mfma_f32_16x16x32_bf16 v[2:5], v[182:185], v[218:221], v[2:5]
	s_setprio 0
	s_barrier
	s_add_i32 s62, s62, 2
	s_add_u32 s28, s28, 0x100
	s_addc_u32 s29, s29, 0
	s_add_u32 s50, s50, 0x100
	s_addc_u32 s51, s51, 0
	s_cmp_gt_u32 s62, 13
.LBB0_1619:
	ds_read_b128 v[154:157], v150
	ds_read_b128 v[158:161], v150 offset:1024
	ds_read_b128 v[162:165], v150 offset:2048
	ds_read_b128 v[166:169], v150 offset:3072
	ds_read_b128 v[170:173], v151
	ds_read_b128 v[174:177], v151 offset:1024
	ds_read_b128 v[178:181], v151 offset:2048
	ds_read_b128 v[182:185], v151 offset:3072
	s_add_u32 s30, s28, 0xfffc0080
	s_addc_u32 s31, s29, -1
	s_cmp_eq_u32 s62, 12
	s_cselect_b32 s37, s14, s31
	s_cselect_b32 s36, s15, s30
	s_cselect_b32 s31, s17, s51
	s_cselect_b32 s30, s49, s50
	v_lshl_add_u64 v[146:147], s[28:29], 0, v[138:139]
	s_add_i32 m0, s19, 0xc000
	ds_read_b128 v[186:189], v152
	ds_read_b128 v[190:193], v152 offset:1024
	ds_read_b128 v[194:197], v152 offset:2048
	ds_read_b128 v[198:201], v152 offset:3072
	ds_read_b128 v[206:209], v152 offset:4096
	ds_read_b128 v[210:213], v152 offset:5120
	ds_read_b128 v[214:217], v152 offset:6144
	ds_read_b128 v[218:221], v152 offset:7168
	global_load_lds_dwordx4 v[146:147], off
	s_add_i32 m0, s19, 0xe000
	v_lshl_add_u64 v[146:147], s[28:29], 0, v[140:141]
	global_load_lds_dwordx4 v[146:147], off
	s_waitcnt vmcnt(8) lgkmcnt(0)
	s_setprio 1
	s_barrier
	v_mfma_f32_16x16x32_bf16 v[126:129], v[154:157], v[186:189], v[126:129]
	v_mfma_f32_16x16x32_bf16 v[122:125], v[162:165], v[186:189], v[122:125]
	v_mfma_f32_16x16x32_bf16 v[110:113], v[154:157], v[194:197], v[110:113]
	v_mfma_f32_16x16x32_bf16 v[106:109], v[162:165], v[194:197], v[106:109]
	v_mfma_f32_16x16x32_bf16 v[94:97], v[154:157], v[206:209], v[94:97]
	v_mfma_f32_16x16x32_bf16 v[90:93], v[162:165], v[206:209], v[90:93]
	v_mfma_f32_16x16x32_bf16 v[78:81], v[154:157], v[214:217], v[78:81]
	v_mfma_f32_16x16x32_bf16 v[74:77], v[162:165], v[214:217], v[74:77]
	v_mfma_f32_16x16x32_bf16 v[126:129], v[158:161], v[190:193], v[126:129]
	v_mfma_f32_16x16x32_bf16 v[122:125], v[166:169], v[190:193], v[122:125]
	v_mfma_f32_16x16x32_bf16 v[110:113], v[158:161], v[198:201], v[110:113]
	v_mfma_f32_16x16x32_bf16 v[106:109], v[166:169], v[198:201], v[106:109]
	v_mfma_f32_16x16x32_bf16 v[94:97], v[158:161], v[210:213], v[94:97]
	v_mfma_f32_16x16x32_bf16 v[90:93], v[166:169], v[210:213], v[90:93]
	v_mfma_f32_16x16x32_bf16 v[78:81], v[158:161], v[218:221], v[78:81]
	v_mfma_f32_16x16x32_bf16 v[74:77], v[166:169], v[218:221], v[74:77]
	v_mfma_f32_16x16x32_bf16 v[118:121], v[170:173], v[186:189], v[118:121]
	v_mfma_f32_16x16x32_bf16 v[114:117], v[178:181], v[186:189], v[114:117]
	v_mfma_f32_16x16x32_bf16 v[102:105], v[170:173], v[194:197], v[102:105]
	v_mfma_f32_16x16x32_bf16 v[98:101], v[178:181], v[194:197], v[98:101]
	v_mfma_f32_16x16x32_bf16 v[86:89], v[170:173], v[206:209], v[86:89]
	v_mfma_f32_16x16x32_bf16 v[82:85], v[178:181], v[206:209], v[82:85]
	v_mfma_f32_16x16x32_bf16 v[70:73], v[170:173], v[214:217], v[70:73]
	v_mfma_f32_16x16x32_bf16 v[66:69], v[178:181], v[214:217], v[66:69]
	v_mfma_f32_16x16x32_bf16 v[118:121], v[174:177], v[190:193], v[118:121]
	v_mfma_f32_16x16x32_bf16 v[114:117], v[182:185], v[190:193], v[114:117]
	v_mfma_f32_16x16x32_bf16 v[102:105], v[174:177], v[198:201], v[102:105]
	v_mfma_f32_16x16x32_bf16 v[98:101], v[182:185], v[198:201], v[98:101]
	v_mfma_f32_16x16x32_bf16 v[86:89], v[174:177], v[210:213], v[86:89]
	v_mfma_f32_16x16x32_bf16 v[82:85], v[182:185], v[210:213], v[82:85]
	v_mfma_f32_16x16x32_bf16 v[70:73], v[174:177], v[218:221], v[70:73]
	v_mfma_f32_16x16x32_bf16 v[66:69], v[182:185], v[218:221], v[66:69]
	s_setprio 0
	s_barrier
	s_add_i32 s63, s45, s12
	v_lshl_add_u64 v[146:147], s[30:31], 0, v[134:135]
	s_mov_b32 m0, s63
	ds_read_b128 v[186:189], v152 offset:16384
	ds_read_b128 v[190:193], v152 offset:17408
	ds_read_b128 v[194:197], v152 offset:18432
	ds_read_b128 v[198:201], v152 offset:19456
	ds_read_b128 v[206:209], v152 offset:20480
	ds_read_b128 v[210:213], v152 offset:21504
	ds_read_b128 v[214:217], v152 offset:22528
	ds_read_b128 v[218:221], v152 offset:23552
	global_load_lds_dwordx4 v[146:147], off
	s_add_i32 m0, s63, 0x2000
	s_add_u32 s64, s30, 0x40000
	v_lshl_add_u64 v[202:203], s[30:31], 0, v[130:131]
	s_addc_u32 s65, s31, 0
	s_add_i32 s63, s46, s12
	global_load_lds_dwordx4 v[202:203], off
	v_lshl_add_u64 v[222:223], s[64:65], 0, v[134:135]
	s_mov_b32 m0, s63
	v_lshl_add_u64 v[224:225], s[36:37], 0, v[132:133]
	global_load_lds_dwordx4 v[222:223], off
	s_add_i32 m0, s63, 0x2000
	v_lshl_add_u64 v[222:223], s[64:65], 0, v[130:131]
	global_load_lds_dwordx4 v[222:223], off
	s_mov_b32 m0, s19
	v_lshl_add_u64 v[222:223], s[36:37], 0, v[136:137]
	global_load_lds_dwordx4 v[222:223], off
	s_mov_b32 m0, s33
	s_nop 0
	global_load_lds_dwordx4 v[224:225], off
	s_waitcnt vmcnt(8) lgkmcnt(0)
	s_setprio 1
	s_barrier
	v_mfma_f32_16x16x32_bf16 v[62:65], v[154:157], v[186:189], v[62:65]
	v_mfma_f32_16x16x32_bf16 v[58:61], v[162:165], v[186:189], v[58:61]
	v_mfma_f32_16x16x32_bf16 v[46:49], v[154:157], v[194:197], v[46:49]
	v_mfma_f32_16x16x32_bf16 v[42:45], v[162:165], v[194:197], v[42:45]
	v_mfma_f32_16x16x32_bf16 v[30:33], v[154:157], v[206:209], v[30:33]
	v_mfma_f32_16x16x32_bf16 v[26:29], v[162:165], v[206:209], v[26:29]
	v_mfma_f32_16x16x32_bf16 v[14:17], v[154:157], v[214:217], v[14:17]
	v_mfma_f32_16x16x32_bf16 v[10:13], v[162:165], v[214:217], v[10:13]
	v_mfma_f32_16x16x32_bf16 v[62:65], v[158:161], v[190:193], v[62:65]
	v_mfma_f32_16x16x32_bf16 v[58:61], v[166:169], v[190:193], v[58:61]
	v_mfma_f32_16x16x32_bf16 v[46:49], v[158:161], v[198:201], v[46:49]
	v_mfma_f32_16x16x32_bf16 v[42:45], v[166:169], v[198:201], v[42:45]
	v_mfma_f32_16x16x32_bf16 v[30:33], v[158:161], v[210:213], v[30:33]
	v_mfma_f32_16x16x32_bf16 v[26:29], v[166:169], v[210:213], v[26:29]
	v_mfma_f32_16x16x32_bf16 v[14:17], v[158:161], v[218:221], v[14:17]
	v_mfma_f32_16x16x32_bf16 v[10:13], v[166:169], v[218:221], v[10:13]
	v_mfma_f32_16x16x32_bf16 v[54:57], v[170:173], v[186:189], v[54:57]
	v_mfma_f32_16x16x32_bf16 v[50:53], v[178:181], v[186:189], v[50:53]
	v_mfma_f32_16x16x32_bf16 v[38:41], v[170:173], v[194:197], v[38:41]
	v_mfma_f32_16x16x32_bf16 v[34:37], v[178:181], v[194:197], v[34:37]
	v_mfma_f32_16x16x32_bf16 v[22:25], v[170:173], v[206:209], v[22:25]
	v_mfma_f32_16x16x32_bf16 v[18:21], v[178:181], v[206:209], v[18:21]
	v_mfma_f32_16x16x32_bf16 v[6:9], v[170:173], v[214:217], v[6:9]
	v_mfma_f32_16x16x32_bf16 v[2:5], v[178:181], v[214:217], v[2:5]
	v_mfma_f32_16x16x32_bf16 v[54:57], v[174:177], v[190:193], v[54:57]
	v_mfma_f32_16x16x32_bf16 v[50:53], v[182:185], v[190:193], v[50:53]
	v_mfma_f32_16x16x32_bf16 v[38:41], v[174:177], v[198:201], v[38:41]
	v_mfma_f32_16x16x32_bf16 v[34:37], v[182:185], v[198:201], v[34:37]
	v_mfma_f32_16x16x32_bf16 v[22:25], v[174:177], v[210:213], v[22:25]
	v_mfma_f32_16x16x32_bf16 v[18:21], v[182:185], v[210:213], v[18:21]
	v_mfma_f32_16x16x32_bf16 v[6:9], v[174:177], v[218:221], v[6:9]
	v_mfma_f32_16x16x32_bf16 v[2:5], v[182:185], v[218:221], v[2:5]
	s_setprio 0
	s_barrier
	s_add_i32 s63, 0, 0x18000
	v_add_u32_e32 v153, s63, v149
	s_add_i32 s64, 0, 0x1c000
	ds_read_b128 v[154:157], v153
	ds_read_b128 v[158:161], v153 offset:1024
	ds_read_b128 v[162:165], v153 offset:2048
	ds_read_b128 v[166:169], v153 offset:3072
	v_add_u32_e32 v153, s64, v149
	ds_read_b128 v[170:173], v153
	ds_read_b128 v[174:177], v153 offset:1024
	ds_read_b128 v[178:181], v153 offset:2048
	ds_read_b128 v[182:185], v153 offset:3072
	s_add_u32 s36, s36, 0x40000
	s_addc_u32 s37, s37, 0
	s_mov_b32 m0, s35
	v_lshl_add_u64 v[226:227], s[36:37], 0, v[136:137]
	ds_read_b128 v[186:189], v152 offset:32768
	ds_read_b128 v[190:193], v152 offset:33792
	ds_read_b128 v[194:197], v152 offset:34816
	ds_read_b128 v[198:201], v152 offset:35840
	ds_read_b128 v[206:209], v152 offset:36864
	ds_read_b128 v[210:213], v152 offset:37888
	ds_read_b128 v[214:217], v152 offset:38912
	ds_read_b128 v[218:221], v152 offset:39936
	global_load_lds_dwordx4 v[226:227], off
	s_mov_b32 m0, s38
	v_lshl_add_u64 v[226:227], s[36:37], 0, v[132:133]
	global_load_lds_dwordx4 v[226:227], off
	s_waitcnt vmcnt(8) lgkmcnt(0)
	s_setprio 1
	s_barrier
	v_mfma_f32_16x16x32_bf16 v[126:129], v[154:157], v[186:189], v[126:129]
	v_mfma_f32_16x16x32_bf16 v[122:125], v[162:165], v[186:189], v[122:125]
	v_mfma_f32_16x16x32_bf16 v[110:113], v[154:157], v[194:197], v[110:113]
	v_mfma_f32_16x16x32_bf16 v[106:109], v[162:165], v[194:197], v[106:109]
	v_mfma_f32_16x16x32_bf16 v[94:97], v[154:157], v[206:209], v[94:97]
	v_mfma_f32_16x16x32_bf16 v[90:93], v[162:165], v[206:209], v[90:93]
	v_mfma_f32_16x16x32_bf16 v[78:81], v[154:157], v[214:217], v[78:81]
	v_mfma_f32_16x16x32_bf16 v[74:77], v[162:165], v[214:217], v[74:77]
	v_mfma_f32_16x16x32_bf16 v[126:129], v[158:161], v[190:193], v[126:129]
	v_mfma_f32_16x16x32_bf16 v[122:125], v[166:169], v[190:193], v[122:125]
	v_mfma_f32_16x16x32_bf16 v[110:113], v[158:161], v[198:201], v[110:113]
	v_mfma_f32_16x16x32_bf16 v[106:109], v[166:169], v[198:201], v[106:109]
	v_mfma_f32_16x16x32_bf16 v[94:97], v[158:161], v[210:213], v[94:97]
	v_mfma_f32_16x16x32_bf16 v[90:93], v[166:169], v[210:213], v[90:93]
	v_mfma_f32_16x16x32_bf16 v[78:81], v[158:161], v[218:221], v[78:81]
	v_mfma_f32_16x16x32_bf16 v[74:77], v[166:169], v[218:221], v[74:77]
	v_mfma_f32_16x16x32_bf16 v[118:121], v[170:173], v[186:189], v[118:121]
	v_mfma_f32_16x16x32_bf16 v[114:117], v[178:181], v[186:189], v[114:117]
	v_mfma_f32_16x16x32_bf16 v[102:105], v[170:173], v[194:197], v[102:105]
	v_mfma_f32_16x16x32_bf16 v[98:101], v[178:181], v[194:197], v[98:101]
	v_mfma_f32_16x16x32_bf16 v[86:89], v[170:173], v[206:209], v[86:89]
	v_mfma_f32_16x16x32_bf16 v[82:85], v[178:181], v[206:209], v[82:85]
	v_mfma_f32_16x16x32_bf16 v[70:73], v[170:173], v[214:217], v[70:73]
	v_mfma_f32_16x16x32_bf16 v[66:69], v[178:181], v[214:217], v[66:69]
	v_mfma_f32_16x16x32_bf16 v[118:121], v[174:177], v[190:193], v[118:121]
	v_mfma_f32_16x16x32_bf16 v[114:117], v[182:185], v[190:193], v[114:117]
	v_mfma_f32_16x16x32_bf16 v[102:105], v[174:177], v[198:201], v[102:105]
	v_mfma_f32_16x16x32_bf16 v[98:101], v[182:185], v[198:201], v[98:101]
	v_mfma_f32_16x16x32_bf16 v[86:89], v[174:177], v[210:213], v[86:89]
	v_mfma_f32_16x16x32_bf16 v[82:85], v[182:185], v[210:213], v[82:85]
	v_mfma_f32_16x16x32_bf16 v[70:73], v[174:177], v[218:221], v[70:73]
	v_mfma_f32_16x16x32_bf16 v[66:69], v[182:185], v[218:221], v[66:69]
	s_setprio 0
	s_barrier
	s_add_i32 s36, s63, s12
	v_lshl_add_u64 v[146:147], v[146:147], 0, s[8:9]
	s_mov_b32 m0, s36
	ds_read_b128 v[186:189], v152 offset:49152
	ds_read_b128 v[190:193], v152 offset:50176
	ds_read_b128 v[194:197], v152 offset:51200
	ds_read_b128 v[198:201], v152 offset:52224
	ds_read_b128 v[206:209], v152 offset:53248
	ds_read_b128 v[210:213], v152 offset:54272
	ds_read_b128 v[214:217], v152 offset:55296
	ds_read_b128 v[218:221], v152 offset:56320
	global_load_lds_dwordx4 v[146:147], off
	s_add_i32 m0, s36, 0x2000
	s_add_u32 s30, s30, 0x40080
	v_lshl_add_u64 v[146:147], v[202:203], 0, s[8:9]
	s_addc_u32 s31, s31, 0
	s_add_i32 s36, s64, s12
	global_load_lds_dwordx4 v[146:147], off
	s_mov_b32 m0, s36
	v_lshl_add_u64 v[146:147], s[30:31], 0, v[134:135]
	global_load_lds_dwordx4 v[146:147], off
	s_add_i32 m0, s36, 0x2000
	v_lshl_add_u64 v[146:147], s[30:31], 0, v[130:131]
	global_load_lds_dwordx4 v[146:147], off
	s_mov_b32 m0, s42
	v_lshl_add_u64 v[146:147], v[222:223], 0, s[8:9]
	global_load_lds_dwordx4 v[146:147], off
	s_mov_b32 m0, s43
	v_lshl_add_u64 v[146:147], v[224:225], 0, s[8:9]
	global_load_lds_dwordx4 v[146:147], off
	s_waitcnt vmcnt(8) lgkmcnt(0)
	s_setprio 1
	s_barrier
	v_mfma_f32_16x16x32_bf16 v[62:65], v[154:157], v[186:189], v[62:65]
	v_mfma_f32_16x16x32_bf16 v[58:61], v[162:165], v[186:189], v[58:61]
	v_mfma_f32_16x16x32_bf16 v[46:49], v[154:157], v[194:197], v[46:49]
	v_mfma_f32_16x16x32_bf16 v[42:45], v[162:165], v[194:197], v[42:45]
	v_mfma_f32_16x16x32_bf16 v[30:33], v[154:157], v[206:209], v[30:33]
	v_mfma_f32_16x16x32_bf16 v[26:29], v[162:165], v[206:209], v[26:29]
	v_mfma_f32_16x16x32_bf16 v[14:17], v[154:157], v[214:217], v[14:17]
	v_mfma_f32_16x16x32_bf16 v[10:13], v[162:165], v[214:217], v[10:13]
	v_mfma_f32_16x16x32_bf16 v[62:65], v[158:161], v[190:193], v[62:65]
	v_mfma_f32_16x16x32_bf16 v[58:61], v[166:169], v[190:193], v[58:61]
	v_mfma_f32_16x16x32_bf16 v[46:49], v[158:161], v[198:201], v[46:49]
	v_mfma_f32_16x16x32_bf16 v[42:45], v[166:169], v[198:201], v[42:45]
	v_mfma_f32_16x16x32_bf16 v[30:33], v[158:161], v[210:213], v[30:33]
	v_mfma_f32_16x16x32_bf16 v[26:29], v[166:169], v[210:213], v[26:29]
	v_mfma_f32_16x16x32_bf16 v[14:17], v[158:161], v[218:221], v[14:17]
	v_mfma_f32_16x16x32_bf16 v[10:13], v[166:169], v[218:221], v[10:13]
	v_mfma_f32_16x16x32_bf16 v[54:57], v[170:173], v[186:189], v[54:57]
	v_mfma_f32_16x16x32_bf16 v[50:53], v[178:181], v[186:189], v[50:53]
	v_mfma_f32_16x16x32_bf16 v[38:41], v[170:173], v[194:197], v[38:41]
	v_mfma_f32_16x16x32_bf16 v[34:37], v[178:181], v[194:197], v[34:37]
	v_mfma_f32_16x16x32_bf16 v[22:25], v[170:173], v[206:209], v[22:25]
	v_mfma_f32_16x16x32_bf16 v[18:21], v[178:181], v[206:209], v[18:21]
	v_mfma_f32_16x16x32_bf16 v[6:9], v[170:173], v[214:217], v[6:9]
	v_mfma_f32_16x16x32_bf16 v[2:5], v[178:181], v[214:217], v[2:5]
	v_mfma_f32_16x16x32_bf16 v[54:57], v[174:177], v[190:193], v[54:57]
	v_mfma_f32_16x16x32_bf16 v[50:53], v[182:185], v[190:193], v[50:53]
	v_mfma_f32_16x16x32_bf16 v[38:41], v[174:177], v[198:201], v[38:41]
	v_mfma_f32_16x16x32_bf16 v[34:37], v[182:185], v[198:201], v[34:37]
	v_mfma_f32_16x16x32_bf16 v[22:25], v[174:177], v[210:213], v[22:25]
	v_mfma_f32_16x16x32_bf16 v[18:21], v[182:185], v[210:213], v[18:21]
	v_mfma_f32_16x16x32_bf16 v[6:9], v[174:177], v[218:221], v[6:9]
	v_mfma_f32_16x16x32_bf16 v[2:5], v[182:185], v[218:221], v[2:5]
	s_setprio 0
	s_barrier
	s_add_i32 s62, s62, 2
	s_add_u32 s28, s28, 0x100
	s_addc_u32 s29, s29, 0
	s_add_u32 s50, s50, 0x100
	s_addc_u32 s51, s51, 0
	s_cmp_gt_u32 s62, 13
	s_cbranch_scc0 .LBB0_1619
	s_and_b64 vcc, exec, s[10:11]
	s_cbranch_vccz .LBB0_1622
	s_barrier

.LBB0_1707:
	v_readlane_b32 s46, v249, 32
	v_readlane_b32 s47, v249, 33
	s_add_u32 s46, s46, s42
	s_addc_u32 s47, s47, s43
	s_and_b64 s[48:49], s[44:45], exec
	s_cselect_b32 s34, s47, s51
	s_cselect_b32 s66, s46, s50
	s_add_u32 s48, s35, s40
	s_addc_u32 s49, s70, s41
	s_and_b64 s[64:65], s[44:45], exec
	s_cselect_b32 s67, s49, s63
	s_cselect_b32 s68, s48, s62
	s_add_i32 s69, s7, -2
	s_add_u32 s50, s50, 0x100080
	s_addc_u32 s51, s51, 0
	s_add_u32 s91, s62, 0x100
	s_addc_u32 s92, s63, 0
	s_mov_b32 s62, 0
	s_waitcnt vmcnt(0)
	ds_read_b128 v[130:133], v168
	ds_read_b128 v[134:137], v168 offset:1024
	ds_read_b128 v[138:141], v168 offset:2048
	ds_read_b128 v[142:145], v168 offset:3072
	ds_read_b128 v[162:165], v169
	ds_read_b128 v[172:175], v169 offset:1024
	ds_read_b128 v[176:179], v169 offset:2048
	ds_read_b128 v[180:183], v169 offset:3072
	s_add_i32 s93, s62, 2
	s_add_u32 s63, s50, 0xfff00080
	s_addc_u32 s64, s51, -1
	s_cmp_eq_u32 s69, s62
	s_cselect_b32 s62, s68, s91
	s_cselect_b32 s65, s34, s64
	s_cselect_b32 s64, s66, s63
	s_cselect_b32 s63, s67, s92
	v_lshl_add_u64 v[218:219], s[50:51], 0, v[156:157]
	s_add_i32 m0, s12, 0xc000
	ds_read_b128 v[184:187], v170
	ds_read_b128 v[188:191], v170 offset:1024
	ds_read_b128 v[192:195], v170 offset:2048
	ds_read_b128 v[196:199], v170 offset:3072
	ds_read_b128 v[200:203], v170 offset:4096
	ds_read_b128 v[206:209], v170 offset:5120
	ds_read_b128 v[210:213], v170 offset:6144
	ds_read_b128 v[214:217], v170 offset:7168
	global_load_lds_dwordx4 v[218:219], off
	s_add_i32 m0, s12, 0xe000
	v_lshl_add_u64 v[218:219], s[50:51], 0, v[158:159]
	global_load_lds_dwordx4 v[218:219], off
	s_waitcnt vmcnt(8) lgkmcnt(0)
	s_setprio 1
	s_barrier
	v_mfma_f32_16x16x32_bf16 v[126:129], v[130:133], v[184:187], 0
	v_mfma_f32_16x16x32_bf16 v[122:125], v[138:141], v[184:187], 0
	v_mfma_f32_16x16x32_bf16 v[110:113], v[130:133], v[192:195], 0
	v_mfma_f32_16x16x32_bf16 v[106:109], v[138:141], v[192:195], 0
	v_mfma_f32_16x16x32_bf16 v[98:101], v[130:133], v[200:203], 0
	v_mfma_f32_16x16x32_bf16 v[90:93], v[138:141], v[200:203], 0
	v_mfma_f32_16x16x32_bf16 v[82:85], v[130:133], v[210:213], 0
	v_mfma_f32_16x16x32_bf16 v[74:77], v[138:141], v[210:213], 0
	v_mfma_f32_16x16x32_bf16 v[126:129], v[134:137], v[188:191], v[126:129]
	v_mfma_f32_16x16x32_bf16 v[122:125], v[142:145], v[188:191], v[122:125]
	v_mfma_f32_16x16x32_bf16 v[110:113], v[134:137], v[196:199], v[110:113]
	v_mfma_f32_16x16x32_bf16 v[106:109], v[142:145], v[196:199], v[106:109]
	v_mfma_f32_16x16x32_bf16 v[98:101], v[134:137], v[206:209], v[98:101]
	v_mfma_f32_16x16x32_bf16 v[90:93], v[142:145], v[206:209], v[90:93]
	v_mfma_f32_16x16x32_bf16 v[82:85], v[134:137], v[214:217], v[82:85]
	v_mfma_f32_16x16x32_bf16 v[74:77], v[142:145], v[214:217], v[74:77]
	v_mfma_f32_16x16x32_bf16 v[118:121], v[162:165], v[184:187], 0
	v_mfma_f32_16x16x32_bf16 v[114:117], v[176:179], v[184:187], 0
	v_mfma_f32_16x16x32_bf16 v[102:105], v[162:165], v[192:195], 0
	v_mfma_f32_16x16x32_bf16 v[94:97], v[176:179], v[192:195], 0
	v_mfma_f32_16x16x32_bf16 v[86:89], v[162:165], v[200:203], 0
	v_mfma_f32_16x16x32_bf16 v[78:81], v[176:179], v[200:203], 0
	v_mfma_f32_16x16x32_bf16 v[70:73], v[162:165], v[210:213], 0
	v_mfma_f32_16x16x32_bf16 v[66:69], v[176:179], v[210:213], 0
	v_mfma_f32_16x16x32_bf16 v[118:121], v[172:175], v[188:191], v[118:121]
	v_mfma_f32_16x16x32_bf16 v[114:117], v[180:183], v[188:191], v[114:117]
	v_mfma_f32_16x16x32_bf16 v[102:105], v[172:175], v[196:199], v[102:105]
	v_mfma_f32_16x16x32_bf16 v[94:97], v[180:183], v[196:199], v[94:97]
	v_mfma_f32_16x16x32_bf16 v[86:89], v[172:175], v[206:209], v[86:89]
	v_mfma_f32_16x16x32_bf16 v[78:81], v[180:183], v[206:209], v[78:81]
	v_mfma_f32_16x16x32_bf16 v[70:73], v[172:175], v[214:217], v[70:73]
	v_mfma_f32_16x16x32_bf16 v[66:69], v[180:183], v[214:217], v[66:69]
	s_setprio 0
	s_barrier
	s_add_i32 s94, s31, s2
	v_lshl_add_u64 v[218:219], s[62:63], 0, v[148:149]
	s_mov_b32 m0, s94
	ds_read_b128 v[184:187], v170 offset:16384
	ds_read_b128 v[188:191], v170 offset:17408
	ds_read_b128 v[192:195], v170 offset:18432
	ds_read_b128 v[196:199], v170 offset:19456
	ds_read_b128 v[200:203], v170 offset:20480
	ds_read_b128 v[206:209], v170 offset:21504
	ds_read_b128 v[210:213], v170 offset:22528
	ds_read_b128 v[214:217], v170 offset:23552
	global_load_lds_dwordx4 v[218:219], off
	s_add_i32 m0, s94, 0x2000
	s_add_u32 s94, s62, 0x100000
	v_lshl_add_u64 v[220:221], s[62:63], 0, v[152:153]
	s_addc_u32 s95, s63, 0
	s_add_i32 s96, s82, s2
	global_load_lds_dwordx4 v[220:221], off
	v_lshl_add_u64 v[222:223], s[94:95], 0, v[148:149]
	s_mov_b32 m0, s96
	v_lshl_add_u64 v[224:225], s[64:65], 0, v[150:151]
	global_load_lds_dwordx4 v[222:223], off
	s_add_i32 m0, s96, 0x2000
	v_lshl_add_u64 v[222:223], s[94:95], 0, v[152:153]
	global_load_lds_dwordx4 v[222:223], off
	s_mov_b32 m0, s12
	v_lshl_add_u64 v[222:223], s[64:65], 0, v[146:147]
	global_load_lds_dwordx4 v[222:223], off
	s_mov_b32 m0, s13
	s_nop 0
	global_load_lds_dwordx4 v[224:225], off
	s_waitcnt vmcnt(8) lgkmcnt(0)
	s_setprio 1
	s_barrier
	v_mfma_f32_16x16x32_bf16 v[62:65], v[130:133], v[184:187], 0
	v_mfma_f32_16x16x32_bf16 v[58:61], v[138:141], v[184:187], 0
	v_mfma_f32_16x16x32_bf16 v[50:53], v[130:133], v[192:195], 0
	v_mfma_f32_16x16x32_bf16 v[42:45], v[138:141], v[192:195], 0
	v_mfma_f32_16x16x32_bf16 v[34:37], v[130:133], v[200:203], 0
	v_mfma_f32_16x16x32_bf16 v[26:29], v[138:141], v[200:203], 0
	v_mfma_f32_16x16x32_bf16 v[18:21], v[130:133], v[210:213], 0
	v_mfma_f32_16x16x32_bf16 v[10:13], v[138:141], v[210:213], 0
	v_mfma_f32_16x16x32_bf16 v[62:65], v[134:137], v[188:191], v[62:65]
	v_mfma_f32_16x16x32_bf16 v[58:61], v[142:145], v[188:191], v[58:61]
	v_mfma_f32_16x16x32_bf16 v[50:53], v[134:137], v[196:199], v[50:53]
	v_mfma_f32_16x16x32_bf16 v[42:45], v[142:145], v[196:199], v[42:45]
	v_mfma_f32_16x16x32_bf16 v[34:37], v[134:137], v[206:209], v[34:37]
	v_mfma_f32_16x16x32_bf16 v[26:29], v[142:145], v[206:209], v[26:29]
	v_mfma_f32_16x16x32_bf16 v[18:21], v[134:137], v[214:217], v[18:21]
	v_mfma_f32_16x16x32_bf16 v[10:13], v[142:145], v[214:217], v[10:13]
	v_mfma_f32_16x16x32_bf16 v[54:57], v[162:165], v[184:187], 0
	v_mfma_f32_16x16x32_bf16 v[46:49], v[176:179], v[184:187], 0
	v_mfma_f32_16x16x32_bf16 v[38:41], v[162:165], v[192:195], 0
	v_mfma_f32_16x16x32_bf16 v[30:33], v[176:179], v[192:195], 0
	v_mfma_f32_16x16x32_bf16 v[22:25], v[162:165], v[200:203], 0
	v_mfma_f32_16x16x32_bf16 v[14:17], v[176:179], v[200:203], 0
	v_mfma_f32_16x16x32_bf16 v[6:9], v[162:165], v[210:213], 0
	v_mfma_f32_16x16x32_bf16 v[2:5], v[176:179], v[210:213], 0
	v_mfma_f32_16x16x32_bf16 v[54:57], v[172:175], v[188:191], v[54:57]
	v_mfma_f32_16x16x32_bf16 v[46:49], v[180:183], v[188:191], v[46:49]
	v_mfma_f32_16x16x32_bf16 v[38:41], v[172:175], v[196:199], v[38:41]
	v_mfma_f32_16x16x32_bf16 v[30:33], v[180:183], v[196:199], v[30:33]
	v_mfma_f32_16x16x32_bf16 v[22:25], v[172:175], v[206:209], v[22:25]
	v_mfma_f32_16x16x32_bf16 v[14:17], v[180:183], v[206:209], v[14:17]
	v_mfma_f32_16x16x32_bf16 v[6:9], v[172:175], v[214:217], v[6:9]
	v_mfma_f32_16x16x32_bf16 v[2:5], v[180:183], v[214:217], v[2:5]
	s_setprio 0
	s_barrier
	s_add_i32 s94, 0, 0x18000
	s_add_i32 s95, 0, 0x1c000
	v_add_u32_e32 v142, s94, v167
	v_add_u32_e32 v154, s95, v167
	ds_read_b128 v[130:133], v142
	ds_read_b128 v[134:137], v142 offset:1024
	ds_read_b128 v[138:141], v142 offset:2048
	ds_read_b128 v[142:145], v142 offset:3072
	ds_read_b128 v[162:165], v154
	ds_read_b128 v[172:175], v154 offset:1024
	ds_read_b128 v[176:179], v154 offset:2048
	ds_read_b128 v[180:183], v154 offset:3072
	s_add_u32 s64, s64, 0x100000
	s_addc_u32 s65, s65, 0
	s_mov_b32 m0, s18
	v_lshl_add_u64 v[226:227], s[64:65], 0, v[146:147]
	ds_read_b128 v[184:187], v170 offset:32768
	ds_read_b128 v[188:191], v170 offset:33792
	ds_read_b128 v[192:195], v170 offset:34816
	ds_read_b128 v[196:199], v170 offset:35840
	ds_read_b128 v[200:203], v170 offset:36864
	ds_read_b128 v[206:209], v170 offset:37888
	ds_read_b128 v[210:213], v170 offset:38912
	ds_read_b128 v[214:217], v170 offset:39936
	global_load_lds_dwordx4 v[226:227], off
	s_mov_b32 m0, s19
	v_lshl_add_u64 v[226:227], s[64:65], 0, v[150:151]
	global_load_lds_dwordx4 v[226:227], off
	s_waitcnt vmcnt(8) lgkmcnt(0)
	s_setprio 1
	s_barrier
	v_mfma_f32_16x16x32_bf16 v[126:129], v[130:133], v[184:187], v[126:129]
	v_mfma_f32_16x16x32_bf16 v[122:125], v[138:141], v[184:187], v[122:125]
	v_mfma_f32_16x16x32_bf16 v[110:113], v[130:133], v[192:195], v[110:113]
	v_mfma_f32_16x16x32_bf16 v[106:109], v[138:141], v[192:195], v[106:109]
	v_mfma_f32_16x16x32_bf16 v[98:101], v[130:133], v[200:203], v[98:101]
	v_mfma_f32_16x16x32_bf16 v[90:93], v[138:141], v[200:203], v[90:93]
	v_mfma_f32_16x16x32_bf16 v[82:85], v[130:133], v[210:213], v[82:85]
	v_mfma_f32_16x16x32_bf16 v[74:77], v[138:141], v[210:213], v[74:77]
	v_mfma_f32_16x16x32_bf16 v[126:129], v[134:137], v[188:191], v[126:129]
	v_mfma_f32_16x16x32_bf16 v[122:125], v[142:145], v[188:191], v[122:125]
	v_mfma_f32_16x16x32_bf16 v[110:113], v[134:137], v[196:199], v[110:113]
	v_mfma_f32_16x16x32_bf16 v[106:109], v[142:145], v[196:199], v[106:109]
	v_mfma_f32_16x16x32_bf16 v[98:101], v[134:137], v[206:209], v[98:101]
	v_mfma_f32_16x16x32_bf16 v[90:93], v[142:145], v[206:209], v[90:93]
	v_mfma_f32_16x16x32_bf16 v[82:85], v[134:137], v[214:217], v[82:85]
	v_mfma_f32_16x16x32_bf16 v[74:77], v[142:145], v[214:217], v[74:77]
	v_mfma_f32_16x16x32_bf16 v[118:121], v[162:165], v[184:187], v[118:121]
	v_mfma_f32_16x16x32_bf16 v[114:117], v[176:179], v[184:187], v[114:117]
	v_mfma_f32_16x16x32_bf16 v[102:105], v[162:165], v[192:195], v[102:105]
	v_mfma_f32_16x16x32_bf16 v[94:97], v[176:179], v[192:195], v[94:97]
	v_mfma_f32_16x16x32_bf16 v[86:89], v[162:165], v[200:203], v[86:89]
	v_mfma_f32_16x16x32_bf16 v[78:81], v[176:179], v[200:203], v[78:81]
	v_mfma_f32_16x16x32_bf16 v[70:73], v[162:165], v[210:213], v[70:73]
	v_mfma_f32_16x16x32_bf16 v[66:69], v[176:179], v[210:213], v[66:69]
	v_mfma_f32_16x16x32_bf16 v[118:121], v[172:175], v[188:191], v[118:121]
	v_mfma_f32_16x16x32_bf16 v[114:117], v[180:183], v[188:191], v[114:117]
	v_mfma_f32_16x16x32_bf16 v[102:105], v[172:175], v[196:199], v[102:105]
	v_mfma_f32_16x16x32_bf16 v[94:97], v[180:183], v[196:199], v[94:97]
	v_mfma_f32_16x16x32_bf16 v[86:89], v[172:175], v[206:209], v[86:89]
	v_mfma_f32_16x16x32_bf16 v[78:81], v[180:183], v[206:209], v[78:81]
	v_mfma_f32_16x16x32_bf16 v[70:73], v[172:175], v[214:217], v[70:73]
	v_mfma_f32_16x16x32_bf16 v[66:69], v[180:183], v[214:217], v[66:69]
	s_setprio 0
	s_barrier
	s_add_i32 s64, s94, s2
	v_lshl_add_u64 v[218:219], v[218:219], 0, s[16:17]
	s_mov_b32 m0, s64
	ds_read_b128 v[184:187], v170 offset:49152
	ds_read_b128 v[188:191], v170 offset:50176
	ds_read_b128 v[192:195], v170 offset:51200
	ds_read_b128 v[196:199], v170 offset:52224
	ds_read_b128 v[200:203], v170 offset:53248
	ds_read_b128 v[206:209], v170 offset:54272
	ds_read_b128 v[210:213], v170 offset:55296
	ds_read_b128 v[214:217], v170 offset:56320
	global_load_lds_dwordx4 v[218:219], off
	s_add_i32 m0, s64, 0x2000
	s_add_u32 s62, s62, 0x100080
	v_lshl_add_u64 v[218:219], v[220:221], 0, s[16:17]
	s_addc_u32 s63, s63, 0
	s_add_i32 s64, s95, s2
	global_load_lds_dwordx4 v[218:219], off
	s_mov_b32 m0, s64
	v_lshl_add_u64 v[218:219], s[62:63], 0, v[148:149]
	global_load_lds_dwordx4 v[218:219], off
	s_add_i32 m0, s64, 0x2000
	v_lshl_add_u64 v[218:219], s[62:63], 0, v[152:153]
	global_load_lds_dwordx4 v[218:219], off
	s_mov_b32 m0, s74
	v_lshl_add_u64 v[218:219], v[222:223], 0, s[16:17]
	global_load_lds_dwordx4 v[218:219], off
	s_mov_b32 m0, s75
	v_lshl_add_u64 v[218:219], v[224:225], 0, s[16:17]
	global_load_lds_dwordx4 v[218:219], off
	s_waitcnt vmcnt(8) lgkmcnt(0)
	s_setprio 1
	s_barrier
	v_mfma_f32_16x16x32_bf16 v[62:65], v[130:133], v[184:187], v[62:65]
	v_mfma_f32_16x16x32_bf16 v[58:61], v[138:141], v[184:187], v[58:61]
	v_mfma_f32_16x16x32_bf16 v[50:53], v[130:133], v[192:195], v[50:53]
	v_mfma_f32_16x16x32_bf16 v[42:45], v[138:141], v[192:195], v[42:45]
	v_mfma_f32_16x16x32_bf16 v[34:37], v[130:133], v[200:203], v[34:37]
	v_mfma_f32_16x16x32_bf16 v[26:29], v[138:141], v[200:203], v[26:29]
	v_mfma_f32_16x16x32_bf16 v[18:21], v[130:133], v[210:213], v[18:21]
	v_mfma_f32_16x16x32_bf16 v[10:13], v[138:141], v[210:213], v[10:13]
	v_mfma_f32_16x16x32_bf16 v[62:65], v[134:137], v[188:191], v[62:65]
	v_mfma_f32_16x16x32_bf16 v[58:61], v[142:145], v[188:191], v[58:61]
	v_mfma_f32_16x16x32_bf16 v[50:53], v[134:137], v[196:199], v[50:53]
	v_mfma_f32_16x16x32_bf16 v[42:45], v[142:145], v[196:199], v[42:45]
	v_mfma_f32_16x16x32_bf16 v[34:37], v[134:137], v[206:209], v[34:37]
	v_mfma_f32_16x16x32_bf16 v[26:29], v[142:145], v[206:209], v[26:29]
	v_mfma_f32_16x16x32_bf16 v[18:21], v[134:137], v[214:217], v[18:21]
	v_mfma_f32_16x16x32_bf16 v[10:13], v[142:145], v[214:217], v[10:13]
	v_mfma_f32_16x16x32_bf16 v[54:57], v[162:165], v[184:187], v[54:57]
	v_mfma_f32_16x16x32_bf16 v[46:49], v[176:179], v[184:187], v[46:49]
	v_mfma_f32_16x16x32_bf16 v[38:41], v[162:165], v[192:195], v[38:41]
	v_mfma_f32_16x16x32_bf16 v[30:33], v[176:179], v[192:195], v[30:33]
	v_mfma_f32_16x16x32_bf16 v[22:25], v[162:165], v[200:203], v[22:25]
	v_mfma_f32_16x16x32_bf16 v[14:17], v[176:179], v[200:203], v[14:17]
	v_mfma_f32_16x16x32_bf16 v[6:9], v[162:165], v[210:213], v[6:9]
	v_mfma_f32_16x16x32_bf16 v[2:5], v[176:179], v[210:213], v[2:5]
	v_mfma_f32_16x16x32_bf16 v[54:57], v[172:175], v[188:191], v[54:57]
	v_mfma_f32_16x16x32_bf16 v[46:49], v[180:183], v[188:191], v[46:49]
	v_mfma_f32_16x16x32_bf16 v[38:41], v[172:175], v[196:199], v[38:41]
	v_mfma_f32_16x16x32_bf16 v[30:33], v[180:183], v[196:199], v[30:33]
	v_mfma_f32_16x16x32_bf16 v[22:25], v[172:175], v[206:209], v[22:25]
	v_mfma_f32_16x16x32_bf16 v[14:17], v[180:183], v[206:209], v[14:17]
	v_mfma_f32_16x16x32_bf16 v[6:9], v[172:175], v[214:217], v[6:9]
	v_mfma_f32_16x16x32_bf16 v[2:5], v[180:183], v[214:217], v[2:5]
	s_setprio 0
	s_barrier
	s_add_u32 s50, s50, 0x100
	s_addc_u32 s51, s51, 0
	s_add_u32 s91, s91, 0x100
	s_addc_u32 s92, s92, 0
	s_cmp_ge_i32 s93, s7
	s_mov_b32 s62, s93
.LBB0_1708:
	ds_read_b128 v[130:133], v168
	ds_read_b128 v[134:137], v168 offset:1024
	ds_read_b128 v[138:141], v168 offset:2048
	ds_read_b128 v[142:145], v168 offset:3072
	ds_read_b128 v[162:165], v169
	ds_read_b128 v[172:175], v169 offset:1024
	ds_read_b128 v[176:179], v169 offset:2048
	ds_read_b128 v[180:183], v169 offset:3072
	s_add_i32 s93, s62, 2
	s_add_u32 s63, s50, 0xfff00080
	s_addc_u32 s64, s51, -1
	s_cmp_eq_u32 s69, s62
	s_cselect_b32 s62, s68, s91
	s_cselect_b32 s65, s34, s64
	s_cselect_b32 s64, s66, s63
	s_cselect_b32 s63, s67, s92
	v_lshl_add_u64 v[218:219], s[50:51], 0, v[156:157]
	s_add_i32 m0, s12, 0xc000
	ds_read_b128 v[184:187], v170
	ds_read_b128 v[188:191], v170 offset:1024
	ds_read_b128 v[192:195], v170 offset:2048
	ds_read_b128 v[196:199], v170 offset:3072
	ds_read_b128 v[200:203], v170 offset:4096
	ds_read_b128 v[206:209], v170 offset:5120
	ds_read_b128 v[210:213], v170 offset:6144
	ds_read_b128 v[214:217], v170 offset:7168
	global_load_lds_dwordx4 v[218:219], off
	s_add_i32 m0, s12, 0xe000
	v_lshl_add_u64 v[218:219], s[50:51], 0, v[158:159]
	global_load_lds_dwordx4 v[218:219], off
	s_waitcnt vmcnt(8) lgkmcnt(0)
	s_setprio 1
	s_barrier
	v_mfma_f32_16x16x32_bf16 v[126:129], v[130:133], v[184:187], v[126:129]
	v_mfma_f32_16x16x32_bf16 v[122:125], v[138:141], v[184:187], v[122:125]
	v_mfma_f32_16x16x32_bf16 v[110:113], v[130:133], v[192:195], v[110:113]
	v_mfma_f32_16x16x32_bf16 v[106:109], v[138:141], v[192:195], v[106:109]
	v_mfma_f32_16x16x32_bf16 v[98:101], v[130:133], v[200:203], v[98:101]
	v_mfma_f32_16x16x32_bf16 v[90:93], v[138:141], v[200:203], v[90:93]
	v_mfma_f32_16x16x32_bf16 v[82:85], v[130:133], v[210:213], v[82:85]
	v_mfma_f32_16x16x32_bf16 v[74:77], v[138:141], v[210:213], v[74:77]
	v_mfma_f32_16x16x32_bf16 v[126:129], v[134:137], v[188:191], v[126:129]
	v_mfma_f32_16x16x32_bf16 v[122:125], v[142:145], v[188:191], v[122:125]
	v_mfma_f32_16x16x32_bf16 v[110:113], v[134:137], v[196:199], v[110:113]
	v_mfma_f32_16x16x32_bf16 v[106:109], v[142:145], v[196:199], v[106:109]
	v_mfma_f32_16x16x32_bf16 v[98:101], v[134:137], v[206:209], v[98:101]
	v_mfma_f32_16x16x32_bf16 v[90:93], v[142:145], v[206:209], v[90:93]
	v_mfma_f32_16x16x32_bf16 v[82:85], v[134:137], v[214:217], v[82:85]
	v_mfma_f32_16x16x32_bf16 v[74:77], v[142:145], v[214:217], v[74:77]
	v_mfma_f32_16x16x32_bf16 v[118:121], v[162:165], v[184:187], v[118:121]
	v_mfma_f32_16x16x32_bf16 v[114:117], v[176:179], v[184:187], v[114:117]
	v_mfma_f32_16x16x32_bf16 v[102:105], v[162:165], v[192:195], v[102:105]
	v_mfma_f32_16x16x32_bf16 v[94:97], v[176:179], v[192:195], v[94:97]
	v_mfma_f32_16x16x32_bf16 v[86:89], v[162:165], v[200:203], v[86:89]
	v_mfma_f32_16x16x32_bf16 v[78:81], v[176:179], v[200:203], v[78:81]
	v_mfma_f32_16x16x32_bf16 v[70:73], v[162:165], v[210:213], v[70:73]
	v_mfma_f32_16x16x32_bf16 v[66:69], v[176:179], v[210:213], v[66:69]
	v_mfma_f32_16x16x32_bf16 v[118:121], v[172:175], v[188:191], v[118:121]
	v_mfma_f32_16x16x32_bf16 v[114:117], v[180:183], v[188:191], v[114:117]
	v_mfma_f32_16x16x32_bf16 v[102:105], v[172:175], v[196:199], v[102:105]
	v_mfma_f32_16x16x32_bf16 v[94:97], v[180:183], v[196:199], v[94:97]
	v_mfma_f32_16x16x32_bf16 v[86:89], v[172:175], v[206:209], v[86:89]
	v_mfma_f32_16x16x32_bf16 v[78:81], v[180:183], v[206:209], v[78:81]
	v_mfma_f32_16x16x32_bf16 v[70:73], v[172:175], v[214:217], v[70:73]
	v_mfma_f32_16x16x32_bf16 v[66:69], v[180:183], v[214:217], v[66:69]
	s_setprio 0
	s_barrier
	s_add_i32 s94, s31, s2
	v_lshl_add_u64 v[218:219], s[62:63], 0, v[148:149]
	s_mov_b32 m0, s94
	ds_read_b128 v[184:187], v170 offset:16384
	ds_read_b128 v[188:191], v170 offset:17408
	ds_read_b128 v[192:195], v170 offset:18432
	ds_read_b128 v[196:199], v170 offset:19456
	ds_read_b128 v[200:203], v170 offset:20480
	ds_read_b128 v[206:209], v170 offset:21504
	ds_read_b128 v[210:213], v170 offset:22528
	ds_read_b128 v[214:217], v170 offset:23552
	global_load_lds_dwordx4 v[218:219], off
	s_add_i32 m0, s94, 0x2000
	s_add_u32 s94, s62, 0x100000
	v_lshl_add_u64 v[220:221], s[62:63], 0, v[152:153]
	s_addc_u32 s95, s63, 0
	s_add_i32 s96, s82, s2
	global_load_lds_dwordx4 v[220:221], off
	v_lshl_add_u64 v[222:223], s[94:95], 0, v[148:149]
	s_mov_b32 m0, s96
	v_lshl_add_u64 v[224:225], s[64:65], 0, v[150:151]
	global_load_lds_dwordx4 v[222:223], off
	s_add_i32 m0, s96, 0x2000
	v_lshl_add_u64 v[222:223], s[94:95], 0, v[152:153]
	global_load_lds_dwordx4 v[222:223], off
	s_mov_b32 m0, s12
	v_lshl_add_u64 v[222:223], s[64:65], 0, v[146:147]
	global_load_lds_dwordx4 v[222:223], off
	s_mov_b32 m0, s13
	s_nop 0
	global_load_lds_dwordx4 v[224:225], off
	s_waitcnt vmcnt(8) lgkmcnt(0)
	s_setprio 1
	s_barrier
	v_mfma_f32_16x16x32_bf16 v[62:65], v[130:133], v[184:187], v[62:65]
	v_mfma_f32_16x16x32_bf16 v[58:61], v[138:141], v[184:187], v[58:61]
	v_mfma_f32_16x16x32_bf16 v[50:53], v[130:133], v[192:195], v[50:53]
	v_mfma_f32_16x16x32_bf16 v[42:45], v[138:141], v[192:195], v[42:45]
	v_mfma_f32_16x16x32_bf16 v[34:37], v[130:133], v[200:203], v[34:37]
	v_mfma_f32_16x16x32_bf16 v[26:29], v[138:141], v[200:203], v[26:29]
	v_mfma_f32_16x16x32_bf16 v[18:21], v[130:133], v[210:213], v[18:21]
	v_mfma_f32_16x16x32_bf16 v[10:13], v[138:141], v[210:213], v[10:13]
	v_mfma_f32_16x16x32_bf16 v[62:65], v[134:137], v[188:191], v[62:65]
	v_mfma_f32_16x16x32_bf16 v[58:61], v[142:145], v[188:191], v[58:61]
	v_mfma_f32_16x16x32_bf16 v[50:53], v[134:137], v[196:199], v[50:53]
	v_mfma_f32_16x16x32_bf16 v[42:45], v[142:145], v[196:199], v[42:45]
	v_mfma_f32_16x16x32_bf16 v[34:37], v[134:137], v[206:209], v[34:37]
	v_mfma_f32_16x16x32_bf16 v[26:29], v[142:145], v[206:209], v[26:29]
	v_mfma_f32_16x16x32_bf16 v[18:21], v[134:137], v[214:217], v[18:21]
	v_mfma_f32_16x16x32_bf16 v[10:13], v[142:145], v[214:217], v[10:13]
	v_mfma_f32_16x16x32_bf16 v[54:57], v[162:165], v[184:187], v[54:57]
	v_mfma_f32_16x16x32_bf16 v[46:49], v[176:179], v[184:187], v[46:49]
	v_mfma_f32_16x16x32_bf16 v[38:41], v[162:165], v[192:195], v[38:41]
	v_mfma_f32_16x16x32_bf16 v[30:33], v[176:179], v[192:195], v[30:33]
	v_mfma_f32_16x16x32_bf16 v[22:25], v[162:165], v[200:203], v[22:25]
	v_mfma_f32_16x16x32_bf16 v[14:17], v[176:179], v[200:203], v[14:17]
	v_mfma_f32_16x16x32_bf16 v[6:9], v[162:165], v[210:213], v[6:9]
	v_mfma_f32_16x16x32_bf16 v[2:5], v[176:179], v[210:213], v[2:5]
	v_mfma_f32_16x16x32_bf16 v[54:57], v[172:175], v[188:191], v[54:57]
	v_mfma_f32_16x16x32_bf16 v[46:49], v[180:183], v[188:191], v[46:49]
	v_mfma_f32_16x16x32_bf16 v[38:41], v[172:175], v[196:199], v[38:41]
	v_mfma_f32_16x16x32_bf16 v[30:33], v[180:183], v[196:199], v[30:33]
	v_mfma_f32_16x16x32_bf16 v[22:25], v[172:175], v[206:209], v[22:25]
	v_mfma_f32_16x16x32_bf16 v[14:17], v[180:183], v[206:209], v[14:17]
	v_mfma_f32_16x16x32_bf16 v[6:9], v[172:175], v[214:217], v[6:9]
	v_mfma_f32_16x16x32_bf16 v[2:5], v[180:183], v[214:217], v[2:5]
	s_setprio 0
	s_barrier
	s_add_i32 s94, 0, 0x18000
	s_add_i32 s95, 0, 0x1c000
	v_add_u32_e32 v142, s94, v167
	v_add_u32_e32 v154, s95, v167
	ds_read_b128 v[130:133], v142
	ds_read_b128 v[134:137], v142 offset:1024
	ds_read_b128 v[138:141], v142 offset:2048
	ds_read_b128 v[142:145], v142 offset:3072
	ds_read_b128 v[162:165], v154
	ds_read_b128 v[172:175], v154 offset:1024
	ds_read_b128 v[176:179], v154 offset:2048
	ds_read_b128 v[180:183], v154 offset:3072
	s_add_u32 s64, s64, 0x100000
	s_addc_u32 s65, s65, 0
	s_mov_b32 m0, s18
	v_lshl_add_u64 v[226:227], s[64:65], 0, v[146:147]
	ds_read_b128 v[184:187], v170 offset:32768
	ds_read_b128 v[188:191], v170 offset:33792
	ds_read_b128 v[192:195], v170 offset:34816
	ds_read_b128 v[196:199], v170 offset:35840
	ds_read_b128 v[200:203], v170 offset:36864
	ds_read_b128 v[206:209], v170 offset:37888
	ds_read_b128 v[210:213], v170 offset:38912
	ds_read_b128 v[214:217], v170 offset:39936
	global_load_lds_dwordx4 v[226:227], off
	s_mov_b32 m0, s19
	v_lshl_add_u64 v[226:227], s[64:65], 0, v[150:151]
	global_load_lds_dwordx4 v[226:227], off
	s_waitcnt vmcnt(8) lgkmcnt(0)
	s_setprio 1
	s_barrier
	v_mfma_f32_16x16x32_bf16 v[126:129], v[130:133], v[184:187], v[126:129]
	v_mfma_f32_16x16x32_bf16 v[122:125], v[138:141], v[184:187], v[122:125]
	v_mfma_f32_16x16x32_bf16 v[110:113], v[130:133], v[192:195], v[110:113]
	v_mfma_f32_16x16x32_bf16 v[106:109], v[138:141], v[192:195], v[106:109]
	v_mfma_f32_16x16x32_bf16 v[98:101], v[130:133], v[200:203], v[98:101]
	v_mfma_f32_16x16x32_bf16 v[90:93], v[138:141], v[200:203], v[90:93]
	v_mfma_f32_16x16x32_bf16 v[82:85], v[130:133], v[210:213], v[82:85]
	v_mfma_f32_16x16x32_bf16 v[74:77], v[138:141], v[210:213], v[74:77]
	v_mfma_f32_16x16x32_bf16 v[126:129], v[134:137], v[188:191], v[126:129]
	v_mfma_f32_16x16x32_bf16 v[122:125], v[142:145], v[188:191], v[122:125]
	v_mfma_f32_16x16x32_bf16 v[110:113], v[134:137], v[196:199], v[110:113]
	v_mfma_f32_16x16x32_bf16 v[106:109], v[142:145], v[196:199], v[106:109]
	v_mfma_f32_16x16x32_bf16 v[98:101], v[134:137], v[206:209], v[98:101]
	v_mfma_f32_16x16x32_bf16 v[90:93], v[142:145], v[206:209], v[90:93]
	v_mfma_f32_16x16x32_bf16 v[82:85], v[134:137], v[214:217], v[82:85]
	v_mfma_f32_16x16x32_bf16 v[74:77], v[142:145], v[214:217], v[74:77]
	v_mfma_f32_16x16x32_bf16 v[118:121], v[162:165], v[184:187], v[118:121]
	v_mfma_f32_16x16x32_bf16 v[114:117], v[176:179], v[184:187], v[114:117]
	v_mfma_f32_16x16x32_bf16 v[102:105], v[162:165], v[192:195], v[102:105]
	v_mfma_f32_16x16x32_bf16 v[94:97], v[176:179], v[192:195], v[94:97]
	v_mfma_f32_16x16x32_bf16 v[86:89], v[162:165], v[200:203], v[86:89]
	v_mfma_f32_16x16x32_bf16 v[78:81], v[176:179], v[200:203], v[78:81]
	v_mfma_f32_16x16x32_bf16 v[70:73], v[162:165], v[210:213], v[70:73]
	v_mfma_f32_16x16x32_bf16 v[66:69], v[176:179], v[210:213], v[66:69]
	v_mfma_f32_16x16x32_bf16 v[118:121], v[172:175], v[188:191], v[118:121]
	v_mfma_f32_16x16x32_bf16 v[114:117], v[180:183], v[188:191], v[114:117]
	v_mfma_f32_16x16x32_bf16 v[102:105], v[172:175], v[196:199], v[102:105]
	v_mfma_f32_16x16x32_bf16 v[94:97], v[180:183], v[196:199], v[94:97]
	v_mfma_f32_16x16x32_bf16 v[86:89], v[172:175], v[206:209], v[86:89]
	v_mfma_f32_16x16x32_bf16 v[78:81], v[180:183], v[206:209], v[78:81]
	v_mfma_f32_16x16x32_bf16 v[70:73], v[172:175], v[214:217], v[70:73]
	v_mfma_f32_16x16x32_bf16 v[66:69], v[180:183], v[214:217], v[66:69]
	s_setprio 0
	s_barrier
	s_add_i32 s64, s94, s2
	v_lshl_add_u64 v[218:219], v[218:219], 0, s[16:17]
	s_mov_b32 m0, s64
	ds_read_b128 v[184:187], v170 offset:49152
	ds_read_b128 v[188:191], v170 offset:50176
	ds_read_b128 v[192:195], v170 offset:51200
	ds_read_b128 v[196:199], v170 offset:52224
	ds_read_b128 v[200:203], v170 offset:53248
	ds_read_b128 v[206:209], v170 offset:54272
	ds_read_b128 v[210:213], v170 offset:55296
	ds_read_b128 v[214:217], v170 offset:56320
	global_load_lds_dwordx4 v[218:219], off
	s_add_i32 m0, s64, 0x2000
	s_add_u32 s62, s62, 0x100080
	v_lshl_add_u64 v[218:219], v[220:221], 0, s[16:17]
	s_addc_u32 s63, s63, 0
	s_add_i32 s64, s95, s2
	global_load_lds_dwordx4 v[218:219], off
	s_mov_b32 m0, s64
	v_lshl_add_u64 v[218:219], s[62:63], 0, v[148:149]
	global_load_lds_dwordx4 v[218:219], off
	s_add_i32 m0, s64, 0x2000
	v_lshl_add_u64 v[218:219], s[62:63], 0, v[152:153]
	global_load_lds_dwordx4 v[218:219], off
	s_mov_b32 m0, s74
	v_lshl_add_u64 v[218:219], v[222:223], 0, s[16:17]
	global_load_lds_dwordx4 v[218:219], off
	s_mov_b32 m0, s75
	v_lshl_add_u64 v[218:219], v[224:225], 0, s[16:17]
	global_load_lds_dwordx4 v[218:219], off
	s_waitcnt vmcnt(8) lgkmcnt(0)
	s_setprio 1
	s_barrier
	v_mfma_f32_16x16x32_bf16 v[62:65], v[130:133], v[184:187], v[62:65]
	v_mfma_f32_16x16x32_bf16 v[58:61], v[138:141], v[184:187], v[58:61]
	v_mfma_f32_16x16x32_bf16 v[50:53], v[130:133], v[192:195], v[50:53]
	v_mfma_f32_16x16x32_bf16 v[42:45], v[138:141], v[192:195], v[42:45]
	v_mfma_f32_16x16x32_bf16 v[34:37], v[130:133], v[200:203], v[34:37]
	v_mfma_f32_16x16x32_bf16 v[26:29], v[138:141], v[200:203], v[26:29]
	v_mfma_f32_16x16x32_bf16 v[18:21], v[130:133], v[210:213], v[18:21]
	v_mfma_f32_16x16x32_bf16 v[10:13], v[138:141], v[210:213], v[10:13]
	v_mfma_f32_16x16x32_bf16 v[62:65], v[134:137], v[188:191], v[62:65]
	v_mfma_f32_16x16x32_bf16 v[58:61], v[142:145], v[188:191], v[58:61]
	v_mfma_f32_16x16x32_bf16 v[50:53], v[134:137], v[196:199], v[50:53]
	v_mfma_f32_16x16x32_bf16 v[42:45], v[142:145], v[196:199], v[42:45]
	v_mfma_f32_16x16x32_bf16 v[34:37], v[134:137], v[206:209], v[34:37]
	v_mfma_f32_16x16x32_bf16 v[26:29], v[142:145], v[206:209], v[26:29]
	v_mfma_f32_16x16x32_bf16 v[18:21], v[134:137], v[214:217], v[18:21]
	v_mfma_f32_16x16x32_bf16 v[10:13], v[142:145], v[214:217], v[10:13]
	v_mfma_f32_16x16x32_bf16 v[54:57], v[162:165], v[184:187], v[54:57]
	v_mfma_f32_16x16x32_bf16 v[46:49], v[176:179], v[184:187], v[46:49]
	v_mfma_f32_16x16x32_bf16 v[38:41], v[162:165], v[192:195], v[38:41]
	v_mfma_f32_16x16x32_bf16 v[30:33], v[176:179], v[192:195], v[30:33]
	v_mfma_f32_16x16x32_bf16 v[22:25], v[162:165], v[200:203], v[22:25]
	v_mfma_f32_16x16x32_bf16 v[14:17], v[176:179], v[200:203], v[14:17]
	v_mfma_f32_16x16x32_bf16 v[6:9], v[162:165], v[210:213], v[6:9]
	v_mfma_f32_16x16x32_bf16 v[2:5], v[176:179], v[210:213], v[2:5]
	v_mfma_f32_16x16x32_bf16 v[54:57], v[172:175], v[188:191], v[54:57]
	v_mfma_f32_16x16x32_bf16 v[46:49], v[180:183], v[188:191], v[46:49]
	v_mfma_f32_16x16x32_bf16 v[38:41], v[172:175], v[196:199], v[38:41]
	v_mfma_f32_16x16x32_bf16 v[30:33], v[180:183], v[196:199], v[30:33]
	v_mfma_f32_16x16x32_bf16 v[22:25], v[172:175], v[206:209], v[22:25]
	v_mfma_f32_16x16x32_bf16 v[14:17], v[180:183], v[206:209], v[14:17]
	v_mfma_f32_16x16x32_bf16 v[6:9], v[172:175], v[214:217], v[6:9]
	v_mfma_f32_16x16x32_bf16 v[2:5], v[180:183], v[214:217], v[2:5]
	s_setprio 0
	s_barrier
	s_add_u32 s50, s50, 0x100
	s_addc_u32 s51, s51, 0
	s_add_u32 s91, s91, 0x100
	s_addc_u32 s92, s92, 0
	s_cmp_ge_i32 s93, s7
	s_mov_b32 s62, s93
	s_cbranch_scc0 .LBB0_1708
	s_and_b64 vcc, exec, s[20:21]
	s_cbranch_vccz .LBB0_1711
	s_barrier
